# k-half-major GEMM loops (all waves MFMA-dense, region-granular LDS ring, full-line LDS-DMA pieces, 2 barriers per K-step) replacing the 8-phase loops
# baseline (speedup 1.0000x reference)
.LBB0_140:
	s_or_b64 exec, exec, s[0:1]
	s_add_u32 s96, s92, 0xfd00000
	s_addc_u32 s97, s93, 0
	s_add_u32 s80, s92, 0xbd00000
	s_addc_u32 s81, s93, 0
	v_lshlrev_b32_e32 v0, 6, v222
	v_lshlrev_b32_e32 v239, 2, v222
	s_ashr_i32 s77, s2, 31
	v_readfirstlane_b32 s3, v222
	v_and_b32_e32 v163, 15, v222
	v_and_b32_e32 v155, 0x3c0, v0
	v_and_b32_e32 v152, 32, v239
	s_cmpk_gt_i32 s2, 0x5ff
	v_bfe_u32 v157, v222, 2, 2
	v_bfe_u32 v218, v222, 2, 4
	v_lshrrev_b32_e32 v238, 5, v222
	v_lshrrev_b32_e32 v158, 1, v222
	v_lshlrev_b32_e32 v156, 4, v222
	v_and_b32_e32 v159, 32, v222
	v_and_b32_e32 v224, 64, v222
	v_lshrrev_b32_e32 v153, 3, v222
	s_cbranch_scc1 .LBB0_152
	v_and_b32_e32 v0, 4, v238
	v_and_b32_e32 v10, 24, v158
	v_add_u32_e32 v8, 0x2000, v156
	v_or3_b32 v0, v0, v157, v10
	v_lshrrev_b32_e32 v1, 7, v8
	s_movk_i32 s0, 0xe0
	v_and_or_b32 v2, v1, s0, v0
	s_movk_i32 s0, 0xf0
	v_bitop3_b32 v9, v156, v159, 48 bitop3:0x6c
	v_and_or_b32 v1, v1, s0, v218
	s_movk_i32 s0, 0x60
	s_add_u32 s22, s92, 0x100000
	v_or_b32_e32 v3, v9, v224
	v_and_or_b32 v0, v153, s0, v0
	s_movk_i32 s0, 0x70
	s_addc_u32 s23, s93, 0
	v_lshl_or_b32 v132, v0, 12, v3
	v_and_or_b32 v0, v153, s0, v218
	s_lshr_b32 s0, s77, 29
	s_add_i32 s0, s2, s0
	s_lshr_b32 s6, s3, 6
	s_ashr_i32 s1, s0, 3
	s_and_b32 s0, s0, -8
	s_lshr_b32 s5, s3, 8
	s_lshl_b32 s24, s6, 10
	s_sub_i32 s0, s2, s0
	s_cmp_lt_i32 s0, 0
	s_movk_i32 s25, 0xc1
	s_cselect_b32 s4, s25, 0xc0
	s_mul_i32 s0, s4, s0
	s_add_i32 s0, s0, s1
	s_mul_hi_i32 s1, s0, 0x2aaaaaab
	s_lshr_b32 s4, s1, 31
	s_ashr_i32 s1, s1, 4
	s_add_i32 s1, s1, s4
	s_lshl_b32 s7, s1, 2
	s_mulk_i32 s1, 0x60
	s_sub_i32 s0, s0, s1
	s_bfe_i32 s1, s0, 0x80000
	s_bfe_u32 s1, s1, 0x2000d
	s_add_i32 s1, s0, s1
	s_bfe_i32 s4, s1, 0x80000
	s_and_b32 s1, s1, 0xfc
	s_sub_i32 s0, s0, s1
	s_sext_i32_i16 s4, s4
	s_sext_i32_i8 s0, s0
	s_lshr_b32 s4, s4, 2
	s_add_i32 s0, s7, s0
	s_ashr_i32 s1, s0, 31
	s_bfe_i64 s[10:11], s[4:5], 0x100000
	s_lshl_b64 s[8:9], s[0:1], 20
	s_lshl_b64 s[10:11], s[10:11], 20
	s_add_u32 s18, s22, s10
	s_addc_u32 s19, s23, s11
	s_add_i32 s1, s24, 0
	s_add_i32 m0, s1, 0x10000
	v_lshl_or_b32 v128, v2, 12, v3
	v_and_b32_e32 v144, 63, v222
	v_lshrrev_b32_e32 v145, 3, v144
	v_lshrrev_b32_e32 v146, 6, v222
	v_lshl_add_u32 v147, v146, 3, v145
	v_and_b32_e32 v148, 7, v144
	v_and_b32_e32 v149, 6, v145
	v_xor_b32_e32 v148, v148, v149
	v_lshlrev_b32_e32 v148, 4, v148
	v_mul_u32_u24_e32 v149, 0x1000, v147
	v_add_u32_e32 v149, v149, v148
	v_mov_b32_e32 v134, v149
	v_add_u32_e32 v130, 0x40000, v149
	v_mov_b32_e32 v136, v149
	v_add_u32_e32 v138, 0x40000, v149
	v_add_u32_e32 v130, 0x40000, v149
	v_add_u32_e32 v138, 0x40000, v149
	v_and_b32_e32 v149, 31, v147
	v_and_b32_e32 v150, 12, v149
	v_lshlrev_b32_e32 v150, 1, v150
	v_lshrrev_b32_e32 v151, 4, v149
	v_lshlrev_b32_e32 v151, 2, v151
	v_and_b32_e32 v149, 3, v149
	v_or3_b32 v149, v150, v151, v149
	v_and_b32_e32 v150, 0x60, v147
	v_add_u32_e32 v149, v149, v150
	v_mul_u32_u24_e32 v149, 0x1000, v149
	v_add_u32_e32 v149, v149, v148
	v_mov_b32_e32 v132, v149
	v_add_u32_e32 v128, 0x40000, v149
	v_add_u32_e32 v128, 0x40000, v149
	v_and_b32_e32 v149, 15, v144
	v_lshrrev_b32_e32 v150, 4, v144
	v_and_b32_e32 v151, 6, v149
	v_xor_b32_e32 v150, v150, v151
	v_lshlrev_b32_e32 v150, 4, v150
	v_lshl_or_b32 v150, v149, 7, v150
	v_lshrrev_b32_e32 v151, 2, v146
	v_lshl_add_u32 v151, v151, 13, v150
	v_add_u32_e32 v166, 0x0, v151
	v_and_b32_e32 v149, 3, v146
	v_lshl_add_u32 v149, v149, 12, v150
	v_add_u32_e32 v161, 0x0, v149
	v_add_u32_e32 v165, 0x10000, v149
	v_add_u32_e32 v167, 0x14000, v149
	s_add_i32 m0, s1, 0x12000
	s_add_u32 s16, s80, s8
	s_addc_u32 s17, s81, s9
	s_mov_b32 m0, s1
	s_add_i32 s26, s1, 0x2000
	s_mov_b32 m0, s26
	s_add_u32 s8, s18, 0x80000
	s_addc_u32 s9, s19, 0
	s_add_i32 m0, s1, 0x14000
	v_mov_b32_e32 v133, 0
	s_add_i32 m0, s1, 0x16000
	v_mov_b32_e32 v129, v133
	s_add_u32 s8, s16, 0x80000
	s_addc_u32 s9, s17, 0
	s_add_i32 s27, s1, 0x4000
	s_mov_b32 m0, s27
	s_add_i32 s28, s1, 0x6000
	s_mov_b32 m0, s28
	v_mov_b32_e32 v135, v133
	v_mov_b32_e32 v131, v133
	s_mov_b32 s29, 0
	v_lshl_add_u64 v[6:7], s[18:19], 0, v[132:133]
	v_lshl_add_u64 v[4:5], s[18:19], 0, v[128:129]
	v_lshl_add_u64 v[2:3], s[16:17], 0, v[134:135]
	s_cmp_lg_u32 s5, 1
	v_lshl_add_u64 v[0:1], s[16:17], 0, v[130:131]
	s_cbranch_scc1 .LBB0_143
.LBB0_143:
	s_lshl_b32 s6, s6, 5
	s_and_b32 s11, s6, 0x60
	s_mov_b64 s[6:7], 0x80
	s_add_i32 m0, s1, 0x18000
	v_lshl_add_u64 v[6:7], v[6:7], 0, s[6:7]
	s_lshl_b32 s10, s5, 13
	s_lshl_b32 s12, s11, 7
	v_lshl_add_u64 v[4:5], v[4:5], 0, s[6:7]
	s_add_i32 m0, s1, 0x1a000
	s_add_i32 s30, s1, 0x8000
	s_add_i32 s31, s1, 0xa000
	v_lshl_add_u64 v[2:3], v[2:3], 0, s[6:7]
	s_mov_b32 m0, s30
	s_add_u32 s8, s18, 0x80080
	v_lshl_add_u64 v[0:1], v[0:1], 0, s[6:7]
	s_mov_b32 m0, s31
	s_addc_u32 s9, s19, 0
	s_add_i32 m0, s1, 0x1c000
	v_lshl_add_u64 v[0:1], s[8:9], 0, v[132:133]
	v_lshl_add_u64 v[0:1], s[8:9], 0, v[128:129]
	s_add_i32 m0, s1, 0x1e000
	v_lshlrev_b32_e32 v2, 2, v163
	v_lshlrev_b32_e32 v0, 1, v10
	v_lshl_or_b32 v1, v163, 6, v0
	v_or_b32_e32 v0, v0, v155
	v_and_b32_e32 v2, 32, v2
	v_lshlrev_b32_e32 v0, 9, v222
	v_bitop3_b32 v1, v1, s10, v2 bitop3:0xde
	v_and_b32_e32 v0, 0x70000, v0
	v_lshlrev_b32_e32 v2, 12, v218
	v_or3_b32 v0, v9, v0, v2
	v_lshlrev_b32_e32 v0, 5, v8
	v_and_b32_e32 v0, 0xf0000, v0
	v_or3_b32 v0, v9, v0, v2
	s_add_i32 s35, 0, 0x10000
	s_add_i32 s38, 0, 0x14000
	s_sext_i32_i8 s40, s4
	v_lshl_or_b32 v160, s5, 6, v163
	s_ashr_i32 s33, s94, 31
	s_mov_b32 s34, s94
	v_or_b32_e32 v164, s11, v10
	v_mov_b32_e32 v137, v133
	v_mov_b32_e32 v139, v133
	v_mov_b64_e32 v[140:141], 0x600
	v_mov_b64_e32 v[142:143], 0x5ff
	v_mov_b32_e32 v168, 0x3727c5ac
	s_movk_i32 s39, 0x3000
	v_and_b32_e32 v144, 63, v222
	v_lshrrev_b32_e32 v145, 6, v222
	v_lshrrev_b32_e32 v146, 3, v144
	v_lshl_add_u32 v147, v145, 3, v146
	v_and_b32_e32 v148, 7, v144
	v_and_b32_e32 v149, 6, v146
	v_xor_b32_e32 v148, v148, v149
	v_lshlrev_b32_e32 v148, 4, v148
	v_mul_u32_u24_e32 v149, 0x1000, v147
	v_add_u32_e32 v169, v149, v148
	v_and_b32_e32 v149, 31, v147
	v_and_b32_e32 v146, 12, v149
	v_lshlrev_b32_e32 v146, 1, v146
	v_lshrrev_b32_e32 v220, 4, v149
	v_lshlrev_b32_e32 v220, 2, v220
	v_and_b32_e32 v149, 3, v149
	v_or3_b32 v149, v146, v220, v149
	v_and_b32_e32 v146, 0x60, v147
	v_add_u32_e32 v149, v149, v146
	v_mul_u32_u24_e32 v149, 0x1000, v149
	v_add_u32_e32 v220, v149, v148
	v_and_b32_e32 v146, 15, v144
	v_lshrrev_b32_e32 v147, 4, v144
	v_and_b32_e32 v148, 6, v146
	v_xor_b32_e32 v147, v147, v148
	v_lshlrev_b32_e32 v147, 4, v147
	v_lshl_or_b32 v147, v146, 7, v147
	v_lshrrev_b32_e32 v148, 2, v145
	v_lshl_add_u32 v221, v148, 13, v147
	v_xor_b32_e32 v234, 64, v221
	v_and_b32_e32 v148, 3, v145
	v_lshl_add_u32 v235, v148, 12, v147
	v_add_u32_e32 v235, 0x10000, v235
	v_xor_b32_e32 v236, 64, v235
	v_readfirstlane_b32 s52, v222
	s_nop 3
	s_lshr_b32 s52, s52, 6
	s_lshl_b32 s52, s52, 10
	s_mov_b32 s98, 0
	s_mul_i32 s20, s98, s94
	s_add_i32 s20, s20, s2
	s_and_b32 s21, s20, 7
	s_lshr_b32 s20, s20, 3
	s_mul_i32 s21, s21, 0xc0
	s_add_i32 s20, s20, s21
	s_mul_i32 s21, s20, 0x2aaab
	s_lshr_b32 s21, s21, 24
	s_mul_i32 s47, s21, 0x60
	s_sub_i32 s20, s20, s47
	s_and_b32 s46, s20, 3
	s_lshl_b32 s21, s21, 2
	s_add_i32 s46, s46, s21
	s_lshr_b32 s47, s20, 2
	s_mul_i32 s100, s46, 0x100000
	s_add_u32 s16, s92, 0xbd00000
	s_addc_u32 s17, s93, 0
	s_add_u32 s16, s16, s100
	s_addc_u32 s17, s17, 0
	s_mul_i32 s100, s47, 0x100000
	s_add_u32 s18, s92, 0x100000
	s_addc_u32 s19, s93, 0
	s_add_u32 s18, s18, s100
	s_addc_u32 s19, s19, 0
	s_add_i32 m0, s52, 0x0
	s_nop 0
	global_load_lds_dwordx4 v169, s[16:17]
	s_add_i32 m0, s52, 0x2000
	s_add_u32 s48, s16, 0x40000
	s_addc_u32 s49, s17, 0
	s_nop 0
	global_load_lds_dwordx4 v169, s[48:49]
	s_add_i32 m0, s52, 0x4000
	s_add_u32 s48, s16, 0x80000
	s_addc_u32 s49, s17, 0
	s_nop 0
	global_load_lds_dwordx4 v169, s[48:49]
	s_add_i32 m0, s52, 0x6000
	s_add_u32 s48, s16, 0xc0000
	s_addc_u32 s49, s17, 0
	s_nop 0
	global_load_lds_dwordx4 v169, s[48:49]
	s_add_i32 m0, s52, 0x10000
	s_nop 0
	global_load_lds_dwordx4 v220, s[18:19]
	s_add_i32 m0, s52, 0x12000
	s_add_u32 s48, s18, 0x40000
	s_addc_u32 s49, s19, 0
	s_nop 0
	global_load_lds_dwordx4 v220, s[48:49]
	s_add_i32 m0, s52, 0x14000
	s_add_u32 s48, s18, 0x80000
	s_addc_u32 s49, s19, 0
	s_nop 0
	global_load_lds_dwordx4 v220, s[48:49]
	s_add_i32 m0, s52, 0x16000
	s_add_u32 s48, s18, 0xc0000
	s_addc_u32 s49, s19, 0
	s_nop 0
	global_load_lds_dwordx4 v220, s[48:49]
	s_add_u32 s16, s16, 128
	s_addc_u32 s17, s17, 0
	s_add_u32 s18, s18, 128
	s_addc_u32 s19, s19, 0
	s_add_i32 m0, s52, 0x8000
	s_nop 0
	global_load_lds_dwordx4 v169, s[16:17]
	s_add_i32 m0, s52, 0xa000
	s_add_u32 s48, s16, 0x40000
	s_addc_u32 s49, s17, 0
	s_nop 0
	global_load_lds_dwordx4 v169, s[48:49]
	s_add_i32 m0, s52, 0xc000
	s_add_u32 s48, s16, 0x80000
	s_addc_u32 s49, s17, 0
	s_nop 0
	global_load_lds_dwordx4 v169, s[48:49]
	s_add_i32 m0, s52, 0xe000
	s_add_u32 s48, s16, 0xc0000
	s_addc_u32 s49, s17, 0
	s_nop 0
	global_load_lds_dwordx4 v169, s[48:49]
	s_add_i32 m0, s52, 0x18000
	s_nop 0
	global_load_lds_dwordx4 v220, s[18:19]
	s_add_i32 m0, s52, 0x1a000
	s_add_u32 s48, s18, 0x40000
	s_addc_u32 s49, s19, 0
	s_nop 0
	global_load_lds_dwordx4 v220, s[48:49]
	s_add_i32 m0, s52, 0x1c000
	s_add_u32 s48, s18, 0x80000
	s_addc_u32 s49, s19, 0
	s_nop 0
	global_load_lds_dwordx4 v220, s[48:49]
	s_add_i32 m0, s52, 0x1e000
	s_add_u32 s48, s18, 0xc0000
	s_addc_u32 s49, s19, 0
	s_nop 0
	global_load_lds_dwordx4 v220, s[48:49]

.LBB0_146:
	s_ashr_i32 s11, s10, 31
	v_cmp_lt_i64_e32 vcc, s[12:13], v[140:141]
	s_lshl_b64 s[12:13], s[10:11], 20
	s_add_u32 s12, s80, s12
	s_addc_u32 s13, s81, s13
	s_and_b64 s[14:15], vcc, exec
	s_cselect_b32 s11, s13, s17
	s_cselect_b32 s41, s12, s16
	s_ashr_i32 s9, s8, 31
	s_lshl_b64 s[14:15], s[8:9], 20
	s_add_u32 s14, s22, s14
	s_addc_u32 s15, s23, s15
	s_and_b64 s[20:21], vcc, exec
	s_cselect_b32 s9, s15, s19
	s_cselect_b32 s44, s14, s18
	s_add_u32 s16, s16, 0x80080
	s_addc_u32 s17, s17, 0
	s_add_u32 s45, s18, 0x100
	v_mov_b32_e32 v0, 0
	s_addc_u32 s46, s19, 0
	s_mov_b32 s47, -2
	v_mov_b32_e32 v1, v0
	v_mov_b32_e32 v2, v0
	v_mov_b32_e32 v3, v0
	v_mov_b32_e32 v4, v0
	v_mov_b32_e32 v5, v0
	v_mov_b32_e32 v6, v0
	v_mov_b32_e32 v7, v0
	v_mov_b32_e32 v16, v0
	v_mov_b32_e32 v17, v0
	s_waitcnt vmcnt(0)
	v_mov_b32_e32 v18, v0
	v_mov_b32_e32 v19, v0
	v_mov_b32_e32 v20, v0
	v_mov_b32_e32 v21, v0
	v_mov_b32_e32 v22, v0
	v_mov_b32_e32 v23, v0
	v_mov_b32_e32 v32, v0
	v_mov_b32_e32 v33, v0
	v_mov_b32_e32 v34, v0
	v_mov_b32_e32 v35, v0
	v_mov_b32_e32 v36, v0
	v_mov_b32_e32 v37, v0
	v_mov_b32_e32 v38, v0
	v_mov_b32_e32 v39, v0
	v_mov_b32_e32 v48, v0
	v_mov_b32_e32 v49, v0
	v_mov_b32_e32 v50, v0
	v_mov_b32_e32 v51, v0
	v_mov_b32_e32 v52, v0
	v_mov_b32_e32 v53, v0
	v_mov_b32_e32 v54, v0
	v_mov_b32_e32 v55, v0
	v_mov_b32_e32 v8, v0
	v_mov_b32_e32 v9, v0
	v_mov_b32_e32 v10, v0
	v_mov_b32_e32 v11, v0
	v_mov_b32_e32 v12, v0
	v_mov_b32_e32 v13, v0
	v_mov_b32_e32 v14, v0
	v_mov_b32_e32 v15, v0
	v_mov_b32_e32 v24, v0
	v_mov_b32_e32 v25, v0
	v_mov_b32_e32 v26, v0
	v_mov_b32_e32 v27, v0
	v_mov_b32_e32 v28, v0
	v_mov_b32_e32 v29, v0
	v_mov_b32_e32 v30, v0
	v_mov_b32_e32 v31, v0
	v_mov_b32_e32 v40, v0
	v_mov_b32_e32 v41, v0
	v_mov_b32_e32 v42, v0
	v_mov_b32_e32 v43, v0
	v_mov_b32_e32 v44, v0
	v_mov_b32_e32 v45, v0
	v_mov_b32_e32 v46, v0
	v_mov_b32_e32 v47, v0
	v_mov_b32_e32 v56, v0
	v_mov_b32_e32 v57, v0
	v_mov_b32_e32 v58, v0
	v_mov_b32_e32 v59, v0
	v_mov_b32_e32 v60, v0
	v_mov_b32_e32 v61, v0
	v_mov_b32_e32 v62, v0
	v_mov_b32_e32 v63, v0
	v_mov_b32_e32 v64, v0
	v_mov_b32_e32 v65, v0
	v_mov_b32_e32 v66, v0
	v_mov_b32_e32 v67, v0
	v_mov_b32_e32 v68, v0
	v_mov_b32_e32 v69, v0
	v_mov_b32_e32 v70, v0
	v_mov_b32_e32 v71, v0
	v_mov_b32_e32 v80, v0
	v_mov_b32_e32 v81, v0
	v_mov_b32_e32 v82, v0
	v_mov_b32_e32 v83, v0
	v_mov_b32_e32 v84, v0
	v_mov_b32_e32 v85, v0
	v_mov_b32_e32 v86, v0
	v_mov_b32_e32 v87, v0
	v_mov_b32_e32 v96, v0
	v_mov_b32_e32 v97, v0
	v_mov_b32_e32 v98, v0
	v_mov_b32_e32 v99, v0
	v_mov_b32_e32 v100, v0
	v_mov_b32_e32 v101, v0
	v_mov_b32_e32 v102, v0
	v_mov_b32_e32 v103, v0
	v_mov_b32_e32 v112, v0
	v_mov_b32_e32 v113, v0
	v_mov_b32_e32 v114, v0
	v_mov_b32_e32 v115, v0
	v_mov_b32_e32 v116, v0
	v_mov_b32_e32 v117, v0
	v_mov_b32_e32 v118, v0
	v_mov_b32_e32 v119, v0
	v_mov_b32_e32 v72, v0
	v_mov_b32_e32 v73, v0
	v_mov_b32_e32 v74, v0
	v_mov_b32_e32 v75, v0
	v_mov_b32_e32 v76, v0
	v_mov_b32_e32 v77, v0
	v_mov_b32_e32 v78, v0
	v_mov_b32_e32 v79, v0
	v_mov_b32_e32 v88, v0
	v_mov_b32_e32 v89, v0
	v_mov_b32_e32 v90, v0
	v_mov_b32_e32 v91, v0
	v_mov_b32_e32 v92, v0
	v_mov_b32_e32 v93, v0
	v_mov_b32_e32 v94, v0
	v_mov_b32_e32 v95, v0
	v_mov_b32_e32 v104, v0
	v_mov_b32_e32 v105, v0
	v_mov_b32_e32 v106, v0
	v_mov_b32_e32 v107, v0
	v_mov_b32_e32 v108, v0
	v_mov_b32_e32 v109, v0
	v_mov_b32_e32 v110, v0
	v_mov_b32_e32 v111, v0
	v_mov_b32_e32 v120, v0
	v_mov_b32_e32 v121, v0
	v_mov_b32_e32 v122, v0
	v_mov_b32_e32 v123, v0
	v_mov_b32_e32 v124, v0
	v_mov_b32_e32 v125, v0
	v_mov_b32_e32 v126, v0
	v_mov_b32_e32 v127, v0
	v_and_b32_e32 v144, 63, v222
	v_lshrrev_b32_e32 v145, 6, v222
	v_lshrrev_b32_e32 v146, 3, v144
	v_lshl_add_u32 v147, v145, 3, v146
	v_and_b32_e32 v148, 7, v144
	v_and_b32_e32 v149, 6, v146
	v_xor_b32_e32 v148, v148, v149
	v_lshlrev_b32_e32 v148, 4, v148
	v_mul_u32_u24_e32 v149, 0x1000, v147
	v_add_u32_e32 v169, v149, v148
	v_and_b32_e32 v149, 31, v147
	v_and_b32_e32 v146, 12, v149
	v_lshlrev_b32_e32 v146, 1, v146
	v_lshrrev_b32_e32 v220, 4, v149
	v_lshlrev_b32_e32 v220, 2, v220
	v_and_b32_e32 v149, 3, v149
	v_or3_b32 v149, v146, v220, v149
	v_and_b32_e32 v146, 0x60, v147
	v_add_u32_e32 v149, v149, v146
	v_mul_u32_u24_e32 v149, 0x1000, v149
	v_add_u32_e32 v220, v149, v148
	v_and_b32_e32 v146, 15, v144
	v_lshrrev_b32_e32 v147, 4, v144
	v_and_b32_e32 v148, 6, v146
	v_xor_b32_e32 v147, v147, v148
	v_lshlrev_b32_e32 v147, 4, v147
	v_lshl_or_b32 v147, v146, 7, v147
	v_lshrrev_b32_e32 v148, 2, v145
	v_lshl_add_u32 v221, v148, 13, v147
	v_xor_b32_e32 v234, 64, v221
	v_and_b32_e32 v148, 3, v145
	v_lshl_add_u32 v235, v148, 12, v147
	v_add_u32_e32 v235, 0x10000, v235
	v_xor_b32_e32 v236, 64, v235
	v_readfirstlane_b32 s52, v222
	s_nop 3
	s_lshr_b32 s52, s52, 6
	s_lshl_b32 s52, s52, 10
	s_mul_i32 s20, s98, s94
	s_add_i32 s20, s20, s2
	s_and_b32 s21, s20, 7
	s_lshr_b32 s20, s20, 3
	s_mul_i32 s21, s21, 0xc0
	s_add_i32 s20, s20, s21
	s_mul_i32 s21, s20, 0x2aaab
	s_lshr_b32 s21, s21, 24
	s_mul_i32 s100, s21, 0x60
	s_sub_i32 s20, s20, s100
	s_and_b32 s45, s20, 3
	s_lshl_b32 s21, s21, 2
	s_add_i32 s45, s45, s21
	s_lshr_b32 s100, s20, 2
	s_mul_i32 s99, s45, 0x100000
	s_add_u32 s16, s92, 0xbd00100
	s_addc_u32 s17, s93, 0
	s_add_u32 s16, s16, s99
	s_addc_u32 s17, s17, 0
	s_mul_i32 s99, s100, 0x100000
	s_add_u32 s18, s92, 0x100100
	s_addc_u32 s19, s93, 0
	s_add_u32 s18, s18, s99
	s_addc_u32 s19, s19, 0
	s_add_i32 s98, s98, 1
	s_mul_i32 s46, s98, s94
	s_add_i32 s46, s46, s2
	s_cmp_lt_u32 s46, 0x600
	s_cbranch_scc0 .Ls1_nonext
	s_mul_i32 s20, s98, s94
	s_add_i32 s20, s20, s2
	s_and_b32 s21, s20, 7
	s_lshr_b32 s20, s20, 3
	s_mul_i32 s21, s21, 0xc0
	s_add_i32 s20, s20, s21
	s_mul_i32 s21, s20, 0x2aaab
	s_lshr_b32 s21, s21, 24
	s_mul_i32 s100, s21, 0x60
	s_sub_i32 s20, s20, s100
	s_and_b32 s45, s20, 3
	s_lshl_b32 s21, s21, 2
	s_add_i32 s45, s45, s21
	s_lshr_b32 s100, s20, 2
.Ls1_nonext:
	s_mul_i32 s99, s45, 0x100000
	s_add_u32 s20, s92, 0xbd00000
	s_addc_u32 s21, s93, 0
	s_add_u32 s20, s20, s99
	s_addc_u32 s21, s21, 0
	s_mul_i32 s99, s100, 0x100000
	s_add_u32 s46, s92, 0x100000
	s_addc_u32 s47, s93, 0
	s_add_u32 s46, s46, s99
	s_addc_u32 s47, s47, 0
	s_waitcnt vmcnt(0)
	s_barrier
	ds_read_b128 v[144:147], v221
	ds_read_b128 v[148:151], v221 offset:2048
	ds_read_b128 v[194:197], v235
	ds_read_b128 v[198:201], v235 offset:2048
	ds_read_b128 v[202:205], v235 offset:16384
	ds_read_b128 v[206:209], v235 offset:18432
	ds_read_b128 v[170:173], v221 offset:4096
	ds_read_b128 v[174:177], v221 offset:6144
	ds_read_b128 v[178:181], v221 offset:16384
	ds_read_b128 v[182:185], v221 offset:18432
	ds_read_b128 v[186:189], v221 offset:20480
	ds_read_b128 v[190:193], v221 offset:22528
	s_mov_b32 s45, 0
.Ls1_loop:
	s_cmp_eq_u32 s45, 15
	s_cselect_b32 s16, s20, s16
	s_cselect_b32 s17, s21, s17
	s_cselect_b32 s18, s46, s18
	s_cselect_b32 s19, s47, s19
	s_waitcnt lgkmcnt(6)
	v_mfma_f32_16x16x32_bf16 v[124:127], v[194:197], v[144:147], v[124:127]
	v_mfma_f32_16x16x32_bf16 v[120:123], v[198:201], v[144:147], v[120:123]
	v_mfma_f32_16x16x32_bf16 v[116:119], v[202:205], v[144:147], v[116:119]
	v_mfma_f32_16x16x32_bf16 v[112:115], v[206:209], v[144:147], v[112:115]
	v_mfma_f32_16x16x32_bf16 v[108:111], v[194:197], v[148:151], v[108:111]
	v_mfma_f32_16x16x32_bf16 v[104:107], v[198:201], v[148:151], v[104:107]
	v_mfma_f32_16x16x32_bf16 v[100:103], v[202:205], v[148:151], v[100:103]
	v_mfma_f32_16x16x32_bf16 v[96:99], v[206:209], v[148:151], v[96:99]
	s_waitcnt lgkmcnt(0)
	ds_read_b128 v[144:147], v234
	ds_read_b128 v[148:151], v234 offset:2048
	ds_read_b128 v[210:213], v236
	ds_read_b128 v[214:217], v236 offset:2048
	ds_read_b128 v[226:229], v236 offset:16384
	ds_read_b128 v[230:233], v236 offset:18432
	v_mfma_f32_16x16x32_bf16 v[92:95], v[194:197], v[170:173], v[92:95]
	v_mfma_f32_16x16x32_bf16 v[88:91], v[198:201], v[170:173], v[88:91]
	v_mfma_f32_16x16x32_bf16 v[84:87], v[202:205], v[170:173], v[84:87]
	v_mfma_f32_16x16x32_bf16 v[80:83], v[206:209], v[170:173], v[80:83]
	ds_read_b128 v[170:173], v234 offset:4096
	v_mfma_f32_16x16x32_bf16 v[76:79], v[194:197], v[174:177], v[76:79]
	v_mfma_f32_16x16x32_bf16 v[72:75], v[198:201], v[174:177], v[72:75]
	v_mfma_f32_16x16x32_bf16 v[68:71], v[202:205], v[174:177], v[68:71]
	v_mfma_f32_16x16x32_bf16 v[64:67], v[206:209], v[174:177], v[64:67]
	ds_read_b128 v[174:177], v234 offset:6144
	s_waitcnt lgkmcnt(0)
	s_barrier
	s_add_i32 m0, s52, 0x10000
	v_mfma_f32_16x16x32_bf16 v[60:63], v[194:197], v[178:181], v[60:63]
	v_mfma_f32_16x16x32_bf16 v[56:59], v[198:201], v[178:181], v[56:59]
	v_mfma_f32_16x16x32_bf16 v[52:55], v[202:205], v[178:181], v[52:55]
	v_mfma_f32_16x16x32_bf16 v[48:51], v[206:209], v[178:181], v[48:51]
	ds_read_b128 v[178:181], v234 offset:16384
	global_load_lds_dwordx4 v220, s[18:19]
	s_add_i32 m0, s52, 0x12000
	s_add_u32 s48, s18, 0x40000
	s_addc_u32 s49, s19, 0
	v_mfma_f32_16x16x32_bf16 v[44:47], v[194:197], v[182:185], v[44:47]
	v_mfma_f32_16x16x32_bf16 v[40:43], v[198:201], v[182:185], v[40:43]
	v_mfma_f32_16x16x32_bf16 v[36:39], v[202:205], v[182:185], v[36:39]
	v_mfma_f32_16x16x32_bf16 v[32:35], v[206:209], v[182:185], v[32:35]
	ds_read_b128 v[182:185], v234 offset:18432
	global_load_lds_dwordx4 v220, s[48:49]
	s_add_i32 m0, s52, 0x14000
	s_add_u32 s48, s18, 0x80000
	s_addc_u32 s49, s19, 0
	v_mfma_f32_16x16x32_bf16 v[28:31], v[194:197], v[186:189], v[28:31]
	v_mfma_f32_16x16x32_bf16 v[24:27], v[198:201], v[186:189], v[24:27]
	v_mfma_f32_16x16x32_bf16 v[20:23], v[202:205], v[186:189], v[20:23]
	v_mfma_f32_16x16x32_bf16 v[16:19], v[206:209], v[186:189], v[16:19]
	ds_read_b128 v[186:189], v234 offset:20480
	global_load_lds_dwordx4 v220, s[48:49]
	s_add_i32 m0, s52, 0x16000
	s_add_u32 s48, s18, 0xc0000
	s_addc_u32 s49, s19, 0
	v_mfma_f32_16x16x32_bf16 v[12:15], v[194:197], v[190:193], v[12:15]
	v_mfma_f32_16x16x32_bf16 v[8:11], v[198:201], v[190:193], v[8:11]
	v_mfma_f32_16x16x32_bf16 v[4:7], v[202:205], v[190:193], v[4:7]
	v_mfma_f32_16x16x32_bf16 v[0:3], v[206:209], v[190:193], v[0:3]
	ds_read_b128 v[190:193], v234 offset:22528
	global_load_lds_dwordx4 v220, s[48:49]
	s_waitcnt lgkmcnt(6)
	s_add_i32 m0, s52, 0x0
	v_mfma_f32_16x16x32_bf16 v[124:127], v[210:213], v[144:147], v[124:127]
	v_mfma_f32_16x16x32_bf16 v[120:123], v[214:217], v[144:147], v[120:123]
	v_mfma_f32_16x16x32_bf16 v[116:119], v[226:229], v[144:147], v[116:119]
	v_mfma_f32_16x16x32_bf16 v[112:115], v[230:233], v[144:147], v[112:115]
	global_load_lds_dwordx4 v169, s[16:17]
	s_add_i32 m0, s52, 0x2000
	s_add_u32 s48, s16, 0x40000
	s_addc_u32 s49, s17, 0
	v_mfma_f32_16x16x32_bf16 v[108:111], v[210:213], v[148:151], v[108:111]
	v_mfma_f32_16x16x32_bf16 v[104:107], v[214:217], v[148:151], v[104:107]
	v_mfma_f32_16x16x32_bf16 v[100:103], v[226:229], v[148:151], v[100:103]
	v_mfma_f32_16x16x32_bf16 v[96:99], v[230:233], v[148:151], v[96:99]
	global_load_lds_dwordx4 v169, s[48:49]
	s_waitcnt lgkmcnt(0)
	s_waitcnt vmcnt(6)
	s_barrier
	ds_read_b128 v[144:147], v221 offset:32768
	ds_read_b128 v[148:151], v221 offset:34816
	ds_read_b128 v[194:197], v235 offset:32768
	ds_read_b128 v[198:201], v235 offset:34816
	ds_read_b128 v[202:205], v235 offset:49152
	ds_read_b128 v[206:209], v235 offset:51200
	s_add_i32 m0, s52, 0x4000
	s_add_u32 s48, s16, 0x80000
	s_addc_u32 s49, s17, 0
	v_mfma_f32_16x16x32_bf16 v[92:95], v[210:213], v[170:173], v[92:95]
	v_mfma_f32_16x16x32_bf16 v[88:91], v[214:217], v[170:173], v[88:91]
	v_mfma_f32_16x16x32_bf16 v[84:87], v[226:229], v[170:173], v[84:87]
	v_mfma_f32_16x16x32_bf16 v[80:83], v[230:233], v[170:173], v[80:83]
	ds_read_b128 v[170:173], v221 offset:36864
	global_load_lds_dwordx4 v169, s[48:49]
	s_add_i32 m0, s52, 0x6000
	s_add_u32 s48, s16, 0xc0000
	s_addc_u32 s49, s17, 0
	v_mfma_f32_16x16x32_bf16 v[76:79], v[210:213], v[174:177], v[76:79]
	v_mfma_f32_16x16x32_bf16 v[72:75], v[214:217], v[174:177], v[72:75]
	v_mfma_f32_16x16x32_bf16 v[68:71], v[226:229], v[174:177], v[68:71]
	v_mfma_f32_16x16x32_bf16 v[64:67], v[230:233], v[174:177], v[64:67]
	ds_read_b128 v[174:177], v221 offset:38912
	global_load_lds_dwordx4 v169, s[48:49]
	v_mfma_f32_16x16x32_bf16 v[60:63], v[210:213], v[178:181], v[60:63]
	v_mfma_f32_16x16x32_bf16 v[56:59], v[214:217], v[178:181], v[56:59]
	v_mfma_f32_16x16x32_bf16 v[52:55], v[226:229], v[178:181], v[52:55]
	v_mfma_f32_16x16x32_bf16 v[48:51], v[230:233], v[178:181], v[48:51]
	ds_read_b128 v[178:181], v221 offset:49152
	v_mfma_f32_16x16x32_bf16 v[44:47], v[210:213], v[182:185], v[44:47]
	v_mfma_f32_16x16x32_bf16 v[40:43], v[214:217], v[182:185], v[40:43]
	v_mfma_f32_16x16x32_bf16 v[36:39], v[226:229], v[182:185], v[36:39]
	v_mfma_f32_16x16x32_bf16 v[32:35], v[230:233], v[182:185], v[32:35]
	ds_read_b128 v[182:185], v221 offset:51200
	v_mfma_f32_16x16x32_bf16 v[28:31], v[210:213], v[186:189], v[28:31]
	v_mfma_f32_16x16x32_bf16 v[24:27], v[214:217], v[186:189], v[24:27]
	v_mfma_f32_16x16x32_bf16 v[20:23], v[226:229], v[186:189], v[20:23]
	v_mfma_f32_16x16x32_bf16 v[16:19], v[230:233], v[186:189], v[16:19]
	ds_read_b128 v[186:189], v221 offset:53248
	v_mfma_f32_16x16x32_bf16 v[12:15], v[210:213], v[190:193], v[12:15]
	v_mfma_f32_16x16x32_bf16 v[8:11], v[214:217], v[190:193], v[8:11]
	v_mfma_f32_16x16x32_bf16 v[4:7], v[226:229], v[190:193], v[4:7]
	v_mfma_f32_16x16x32_bf16 v[0:3], v[230:233], v[190:193], v[0:3]
	ds_read_b128 v[190:193], v221 offset:55296
	s_add_u32 s16, s16, 128
	s_addc_u32 s17, s17, 0
	s_add_u32 s18, s18, 128
	s_addc_u32 s19, s19, 0
	s_waitcnt lgkmcnt(6)
	v_mfma_f32_16x16x32_bf16 v[124:127], v[194:197], v[144:147], v[124:127]
	v_mfma_f32_16x16x32_bf16 v[120:123], v[198:201], v[144:147], v[120:123]
	v_mfma_f32_16x16x32_bf16 v[116:119], v[202:205], v[144:147], v[116:119]
	v_mfma_f32_16x16x32_bf16 v[112:115], v[206:209], v[144:147], v[112:115]
	v_mfma_f32_16x16x32_bf16 v[108:111], v[194:197], v[148:151], v[108:111]
	v_mfma_f32_16x16x32_bf16 v[104:107], v[198:201], v[148:151], v[104:107]
	v_mfma_f32_16x16x32_bf16 v[100:103], v[202:205], v[148:151], v[100:103]
	v_mfma_f32_16x16x32_bf16 v[96:99], v[206:209], v[148:151], v[96:99]
	s_waitcnt lgkmcnt(0)
	ds_read_b128 v[144:147], v234 offset:32768
	ds_read_b128 v[148:151], v234 offset:34816
	ds_read_b128 v[210:213], v236 offset:32768
	ds_read_b128 v[214:217], v236 offset:34816
	ds_read_b128 v[226:229], v236 offset:49152
	ds_read_b128 v[230:233], v236 offset:51200
	v_mfma_f32_16x16x32_bf16 v[92:95], v[194:197], v[170:173], v[92:95]
	v_mfma_f32_16x16x32_bf16 v[88:91], v[198:201], v[170:173], v[88:91]
	v_mfma_f32_16x16x32_bf16 v[84:87], v[202:205], v[170:173], v[84:87]
	v_mfma_f32_16x16x32_bf16 v[80:83], v[206:209], v[170:173], v[80:83]
	ds_read_b128 v[170:173], v234 offset:36864
	v_mfma_f32_16x16x32_bf16 v[76:79], v[194:197], v[174:177], v[76:79]
	v_mfma_f32_16x16x32_bf16 v[72:75], v[198:201], v[174:177], v[72:75]
	v_mfma_f32_16x16x32_bf16 v[68:71], v[202:205], v[174:177], v[68:71]
	v_mfma_f32_16x16x32_bf16 v[64:67], v[206:209], v[174:177], v[64:67]
	ds_read_b128 v[174:177], v234 offset:38912
	s_waitcnt lgkmcnt(0)
	s_barrier
	s_add_i32 m0, s52, 0x18000
	v_mfma_f32_16x16x32_bf16 v[60:63], v[194:197], v[178:181], v[60:63]
	v_mfma_f32_16x16x32_bf16 v[56:59], v[198:201], v[178:181], v[56:59]
	v_mfma_f32_16x16x32_bf16 v[52:55], v[202:205], v[178:181], v[52:55]
	v_mfma_f32_16x16x32_bf16 v[48:51], v[206:209], v[178:181], v[48:51]
	ds_read_b128 v[178:181], v234 offset:49152
	global_load_lds_dwordx4 v220, s[18:19]
	s_add_i32 m0, s52, 0x1a000
	s_add_u32 s48, s18, 0x40000
	s_addc_u32 s49, s19, 0
	v_mfma_f32_16x16x32_bf16 v[44:47], v[194:197], v[182:185], v[44:47]
	v_mfma_f32_16x16x32_bf16 v[40:43], v[198:201], v[182:185], v[40:43]
	v_mfma_f32_16x16x32_bf16 v[36:39], v[202:205], v[182:185], v[36:39]
	v_mfma_f32_16x16x32_bf16 v[32:35], v[206:209], v[182:185], v[32:35]
	ds_read_b128 v[182:185], v234 offset:51200
	global_load_lds_dwordx4 v220, s[48:49]
	s_add_i32 m0, s52, 0x1c000
	s_add_u32 s48, s18, 0x80000
	s_addc_u32 s49, s19, 0
	v_mfma_f32_16x16x32_bf16 v[28:31], v[194:197], v[186:189], v[28:31]
	v_mfma_f32_16x16x32_bf16 v[24:27], v[198:201], v[186:189], v[24:27]
	v_mfma_f32_16x16x32_bf16 v[20:23], v[202:205], v[186:189], v[20:23]
	v_mfma_f32_16x16x32_bf16 v[16:19], v[206:209], v[186:189], v[16:19]
	ds_read_b128 v[186:189], v234 offset:53248
	global_load_lds_dwordx4 v220, s[48:49]
	s_add_i32 m0, s52, 0x1e000
	s_add_u32 s48, s18, 0xc0000
	s_addc_u32 s49, s19, 0
	v_mfma_f32_16x16x32_bf16 v[12:15], v[194:197], v[190:193], v[12:15]
	v_mfma_f32_16x16x32_bf16 v[8:11], v[198:201], v[190:193], v[8:11]
	v_mfma_f32_16x16x32_bf16 v[4:7], v[202:205], v[190:193], v[4:7]
	v_mfma_f32_16x16x32_bf16 v[0:3], v[206:209], v[190:193], v[0:3]
	ds_read_b128 v[190:193], v234 offset:55296
	global_load_lds_dwordx4 v220, s[48:49]
	s_waitcnt lgkmcnt(6)
	s_add_i32 m0, s52, 0x8000
	v_mfma_f32_16x16x32_bf16 v[124:127], v[210:213], v[144:147], v[124:127]
	v_mfma_f32_16x16x32_bf16 v[120:123], v[214:217], v[144:147], v[120:123]
	v_mfma_f32_16x16x32_bf16 v[116:119], v[226:229], v[144:147], v[116:119]
	v_mfma_f32_16x16x32_bf16 v[112:115], v[230:233], v[144:147], v[112:115]
	global_load_lds_dwordx4 v169, s[16:17]
	s_add_i32 m0, s52, 0xa000
	s_add_u32 s48, s16, 0x40000
	s_addc_u32 s49, s17, 0
	v_mfma_f32_16x16x32_bf16 v[108:111], v[210:213], v[148:151], v[108:111]
	v_mfma_f32_16x16x32_bf16 v[104:107], v[214:217], v[148:151], v[104:107]
	v_mfma_f32_16x16x32_bf16 v[100:103], v[226:229], v[148:151], v[100:103]
	v_mfma_f32_16x16x32_bf16 v[96:99], v[230:233], v[148:151], v[96:99]
	global_load_lds_dwordx4 v169, s[48:49]
	s_waitcnt lgkmcnt(0)
	s_waitcnt vmcnt(6)
	s_barrier
	ds_read_b128 v[144:147], v221
	ds_read_b128 v[148:151], v221 offset:2048
	ds_read_b128 v[194:197], v235
	ds_read_b128 v[198:201], v235 offset:2048
	ds_read_b128 v[202:205], v235 offset:16384
	ds_read_b128 v[206:209], v235 offset:18432
	s_add_i32 m0, s52, 0xc000
	s_add_u32 s48, s16, 0x80000
	s_addc_u32 s49, s17, 0
	v_mfma_f32_16x16x32_bf16 v[92:95], v[210:213], v[170:173], v[92:95]
	v_mfma_f32_16x16x32_bf16 v[88:91], v[214:217], v[170:173], v[88:91]
	v_mfma_f32_16x16x32_bf16 v[84:87], v[226:229], v[170:173], v[84:87]
	v_mfma_f32_16x16x32_bf16 v[80:83], v[230:233], v[170:173], v[80:83]
	ds_read_b128 v[170:173], v221 offset:4096
	global_load_lds_dwordx4 v169, s[48:49]
	s_add_i32 m0, s52, 0xe000
	s_add_u32 s48, s16, 0xc0000
	s_addc_u32 s49, s17, 0
	v_mfma_f32_16x16x32_bf16 v[76:79], v[210:213], v[174:177], v[76:79]
	v_mfma_f32_16x16x32_bf16 v[72:75], v[214:217], v[174:177], v[72:75]
	v_mfma_f32_16x16x32_bf16 v[68:71], v[226:229], v[174:177], v[68:71]
	v_mfma_f32_16x16x32_bf16 v[64:67], v[230:233], v[174:177], v[64:67]
	ds_read_b128 v[174:177], v221 offset:6144
	global_load_lds_dwordx4 v169, s[48:49]
	v_mfma_f32_16x16x32_bf16 v[60:63], v[210:213], v[178:181], v[60:63]
	v_mfma_f32_16x16x32_bf16 v[56:59], v[214:217], v[178:181], v[56:59]
	v_mfma_f32_16x16x32_bf16 v[52:55], v[226:229], v[178:181], v[52:55]
	v_mfma_f32_16x16x32_bf16 v[48:51], v[230:233], v[178:181], v[48:51]
	ds_read_b128 v[178:181], v221 offset:16384
	v_mfma_f32_16x16x32_bf16 v[44:47], v[210:213], v[182:185], v[44:47]
	v_mfma_f32_16x16x32_bf16 v[40:43], v[214:217], v[182:185], v[40:43]
	v_mfma_f32_16x16x32_bf16 v[36:39], v[226:229], v[182:185], v[36:39]
	v_mfma_f32_16x16x32_bf16 v[32:35], v[230:233], v[182:185], v[32:35]
	ds_read_b128 v[182:185], v221 offset:18432
	v_mfma_f32_16x16x32_bf16 v[28:31], v[210:213], v[186:189], v[28:31]
	v_mfma_f32_16x16x32_bf16 v[24:27], v[214:217], v[186:189], v[24:27]
	v_mfma_f32_16x16x32_bf16 v[20:23], v[226:229], v[186:189], v[20:23]
	v_mfma_f32_16x16x32_bf16 v[16:19], v[230:233], v[186:189], v[16:19]
	ds_read_b128 v[186:189], v221 offset:20480
	v_mfma_f32_16x16x32_bf16 v[12:15], v[210:213], v[190:193], v[12:15]
	v_mfma_f32_16x16x32_bf16 v[8:11], v[214:217], v[190:193], v[8:11]
	v_mfma_f32_16x16x32_bf16 v[4:7], v[226:229], v[190:193], v[4:7]
	v_mfma_f32_16x16x32_bf16 v[0:3], v[230:233], v[190:193], v[0:3]
	ds_read_b128 v[190:193], v221 offset:22528
	s_add_u32 s16, s16, 128
	s_addc_u32 s17, s17, 0
	s_add_u32 s18, s18, 128
	s_addc_u32 s19, s19, 0
	s_add_i32 s45, s45, 1
	s_cmp_lt_u32 s45, 16
	s_cbranch_scc1 .Ls1_loop
	s_waitcnt lgkmcnt(0)
	s_nop 7
	s_nop 3
	v_lshl_add_u32 v144, s0, 8, v160
	v_ashrrev_i32_e32 v145, 31, v144
	v_lshl_add_u64 v[150:151], v[144:145], 2, s[92:93]
	global_load_dword v176, v[150:151], off
	global_load_dword v177, v[150:151], off offset:64
	global_load_dword v178, v[150:151], off offset:128
	global_load_dword v179, v[150:151], off offset:192
	global_load_dword v180, v[150:151], off offset:512
	global_load_dword v181, v[150:151], off offset:576
	global_load_dword v182, v[150:151], off offset:640
	global_load_dword v183, v[150:151], off offset:704
	v_lshl_or_b32 v148, s40, 8, v164
	v_mov_b64_e32 v[146:147], s[96:97]
	v_ashrrev_i32_e32 v149, 31, v148
	v_mad_i64_i32 v[172:173], s[16:17], v144, s39, v[146:147]
	v_lshlrev_b64 v[148:149], 1, v[148:149]
	v_lshl_add_u64 v[172:173], v[172:173], 0, v[148:149]
	s_and_b64 vcc, exec, s[4:5]
	s_mov_b32 s40, s8
	s_mov_b32 s0, s10
	s_mov_b64 s[18:19], s[14:15]
	s_waitcnt vmcnt(0)
	v_fmamk_f32 v145, v176, 0x3a000000, v168
	v_rsq_f32_e32 v170, v145
	s_nop 0
	v_pk_mul_f32 v[126:127], v[126:127], v[170:171] op_sel_hi:[1,0]
	v_pk_mul_f32 v[124:125], v[124:125], v[170:171] op_sel_hi:[1,0]
	v_pk_mul_f32 v[122:123], v[122:123], v[170:171] op_sel_hi:[1,0]
	v_pk_mul_f32 v[120:121], v[120:121], v[170:171] op_sel_hi:[1,0]
	v_pk_mul_f32 v[118:119], v[118:119], v[170:171] op_sel_hi:[1,0]
	v_pk_mul_f32 v[116:117], v[116:117], v[170:171] op_sel_hi:[1,0]
	v_pk_mul_f32 v[174:175], v[114:115], v[170:171] op_sel_hi:[1,0]
	v_pk_mul_f32 v[170:171], v[112:113], v[170:171] op_sel_hi:[1,0]
	v_cvt_pk_bf16_f32 v112, v124, v125
	v_cvt_pk_bf16_f32 v113, v126, v127
	v_cvt_pk_bf16_f32 v114, v120, v121
	v_cvt_pk_bf16_f32 v115, v122, v123
	global_store_dwordx4 v[172:173], v[112:115], off
	s_nop 1
	v_cvt_pk_bf16_f32 v112, v116, v117
	v_cvt_pk_bf16_f32 v113, v118, v119
	v_cvt_pk_bf16_f32 v114, v170, v171
	v_cvt_pk_bf16_f32 v115, v174, v175
	global_store_dwordx4 v[172:173], v[112:115], off offset:256
	s_nop 0
	s_nop 0
	v_or_b32_e32 v113, 16, v144
	v_mad_i64_i32 v[114:115], s[16:17], v113, s39, v[146:147]
	v_lshl_add_u64 v[114:115], v[114:115], 0, v[148:149]
	s_nop 0
	v_fmamk_f32 v112, v177, 0x3a000000, v168
	v_rsq_f32_e32 v112, v112
	s_nop 0
	v_pk_mul_f32 v[110:111], v[110:111], v[112:113] op_sel_hi:[1,0]
	v_pk_mul_f32 v[108:109], v[108:109], v[112:113] op_sel_hi:[1,0]
	v_pk_mul_f32 v[106:107], v[106:107], v[112:113] op_sel_hi:[1,0]
	v_pk_mul_f32 v[104:105], v[104:105], v[112:113] op_sel_hi:[1,0]
	v_pk_mul_f32 v[102:103], v[102:103], v[112:113] op_sel_hi:[1,0]
	v_pk_mul_f32 v[100:101], v[100:101], v[112:113] op_sel_hi:[1,0]
	v_pk_mul_f32 v[116:117], v[98:99], v[112:113] op_sel_hi:[1,0]
	v_pk_mul_f32 v[112:113], v[96:97], v[112:113] op_sel_hi:[1,0]
	v_cvt_pk_bf16_f32 v96, v108, v109
	v_cvt_pk_bf16_f32 v97, v110, v111
	v_cvt_pk_bf16_f32 v98, v104, v105
	v_cvt_pk_bf16_f32 v99, v106, v107
	global_store_dwordx4 v[114:115], v[96:99], off
	s_nop 1
	v_cvt_pk_bf16_f32 v96, v100, v101
	v_cvt_pk_bf16_f32 v97, v102, v103
	v_cvt_pk_bf16_f32 v98, v112, v113
	v_cvt_pk_bf16_f32 v99, v116, v117
	global_store_dwordx4 v[114:115], v[96:99], off offset:256
	s_nop 0
	s_nop 0
	v_or_b32_e32 v97, 32, v144
	v_mad_i64_i32 v[98:99], s[16:17], v97, s39, v[146:147]
	v_lshl_add_u64 v[98:99], v[98:99], 0, v[148:149]
	s_nop 0
	v_fmamk_f32 v96, v178, 0x3a000000, v168
	v_rsq_f32_e32 v96, v96
	s_nop 0
	v_pk_mul_f32 v[94:95], v[94:95], v[96:97] op_sel_hi:[1,0]
	v_pk_mul_f32 v[92:93], v[92:93], v[96:97] op_sel_hi:[1,0]
	v_pk_mul_f32 v[90:91], v[90:91], v[96:97] op_sel_hi:[1,0]
	v_pk_mul_f32 v[88:89], v[88:89], v[96:97] op_sel_hi:[1,0]
	v_pk_mul_f32 v[86:87], v[86:87], v[96:97] op_sel_hi:[1,0]
	v_pk_mul_f32 v[84:85], v[84:85], v[96:97] op_sel_hi:[1,0]
	v_pk_mul_f32 v[100:101], v[82:83], v[96:97] op_sel_hi:[1,0]
	v_pk_mul_f32 v[96:97], v[80:81], v[96:97] op_sel_hi:[1,0]
	v_cvt_pk_bf16_f32 v80, v92, v93
	v_cvt_pk_bf16_f32 v81, v94, v95
	v_cvt_pk_bf16_f32 v82, v88, v89
	v_cvt_pk_bf16_f32 v83, v90, v91
	global_store_dwordx4 v[98:99], v[80:83], off
	s_nop 1
	v_cvt_pk_bf16_f32 v80, v84, v85
	v_cvt_pk_bf16_f32 v81, v86, v87
	v_cvt_pk_bf16_f32 v82, v96, v97
	v_cvt_pk_bf16_f32 v83, v100, v101
	global_store_dwordx4 v[98:99], v[80:83], off offset:256
	s_nop 0
	s_nop 0
	v_or_b32_e32 v81, 48, v144
	v_mad_i64_i32 v[82:83], s[16:17], v81, s39, v[146:147]
	v_lshl_add_u64 v[82:83], v[82:83], 0, v[148:149]
	s_nop 0
	v_fmamk_f32 v80, v179, 0x3a000000, v168
	v_rsq_f32_e32 v80, v80
	s_nop 0
	v_pk_mul_f32 v[78:79], v[78:79], v[80:81] op_sel_hi:[1,0]
	v_pk_mul_f32 v[76:77], v[76:77], v[80:81] op_sel_hi:[1,0]
	v_pk_mul_f32 v[74:75], v[74:75], v[80:81] op_sel_hi:[1,0]
	v_pk_mul_f32 v[72:73], v[72:73], v[80:81] op_sel_hi:[1,0]
	v_pk_mul_f32 v[70:71], v[70:71], v[80:81] op_sel_hi:[1,0]
	v_pk_mul_f32 v[68:69], v[68:69], v[80:81] op_sel_hi:[1,0]
	v_pk_mul_f32 v[84:85], v[66:67], v[80:81] op_sel_hi:[1,0]
	v_pk_mul_f32 v[80:81], v[64:65], v[80:81] op_sel_hi:[1,0]
	v_cvt_pk_bf16_f32 v64, v76, v77
	v_cvt_pk_bf16_f32 v65, v78, v79
	v_cvt_pk_bf16_f32 v66, v72, v73
	v_cvt_pk_bf16_f32 v67, v74, v75
	global_store_dwordx4 v[82:83], v[64:67], off
	s_nop 1
	v_cvt_pk_bf16_f32 v64, v68, v69
	v_cvt_pk_bf16_f32 v65, v70, v71
	v_cvt_pk_bf16_f32 v66, v80, v81
	v_cvt_pk_bf16_f32 v67, v84, v85
	global_store_dwordx4 v[82:83], v[64:67], off offset:256
	s_nop 0
	s_nop 0
	v_add_u32_e32 v65, 0x80, v144
	v_mad_i64_i32 v[66:67], s[16:17], v65, s39, v[146:147]
	v_lshl_add_u64 v[66:67], v[66:67], 0, v[148:149]
	s_nop 0
	v_fmamk_f32 v64, v180, 0x3a000000, v168
	v_rsq_f32_e32 v64, v64
	s_nop 0
	v_pk_mul_f32 v[62:63], v[62:63], v[64:65] op_sel_hi:[1,0]
	v_pk_mul_f32 v[60:61], v[60:61], v[64:65] op_sel_hi:[1,0]
	v_pk_mul_f32 v[58:59], v[58:59], v[64:65] op_sel_hi:[1,0]
	v_pk_mul_f32 v[56:57], v[56:57], v[64:65] op_sel_hi:[1,0]
	v_pk_mul_f32 v[54:55], v[54:55], v[64:65] op_sel_hi:[1,0]
	v_pk_mul_f32 v[52:53], v[52:53], v[64:65] op_sel_hi:[1,0]
	v_pk_mul_f32 v[68:69], v[50:51], v[64:65] op_sel_hi:[1,0]
	v_pk_mul_f32 v[64:65], v[48:49], v[64:65] op_sel_hi:[1,0]
	v_cvt_pk_bf16_f32 v48, v60, v61
	v_cvt_pk_bf16_f32 v49, v62, v63
	v_cvt_pk_bf16_f32 v50, v56, v57
	v_cvt_pk_bf16_f32 v51, v58, v59
	global_store_dwordx4 v[66:67], v[48:51], off
	s_nop 1
	v_cvt_pk_bf16_f32 v48, v52, v53
	v_cvt_pk_bf16_f32 v49, v54, v55
	v_cvt_pk_bf16_f32 v50, v64, v65
	v_cvt_pk_bf16_f32 v51, v68, v69
	global_store_dwordx4 v[66:67], v[48:51], off offset:256
	s_nop 0
	s_nop 0
	v_add_u32_e32 v49, 0x90, v144
	v_mad_i64_i32 v[50:51], s[16:17], v49, s39, v[146:147]
	v_lshl_add_u64 v[50:51], v[50:51], 0, v[148:149]
	s_nop 0
	v_fmamk_f32 v48, v181, 0x3a000000, v168
	v_rsq_f32_e32 v48, v48
	s_nop 0
	v_pk_mul_f32 v[46:47], v[46:47], v[48:49] op_sel_hi:[1,0]
	v_pk_mul_f32 v[44:45], v[44:45], v[48:49] op_sel_hi:[1,0]
	v_pk_mul_f32 v[42:43], v[42:43], v[48:49] op_sel_hi:[1,0]
	v_pk_mul_f32 v[40:41], v[40:41], v[48:49] op_sel_hi:[1,0]
	v_pk_mul_f32 v[38:39], v[38:39], v[48:49] op_sel_hi:[1,0]
	v_pk_mul_f32 v[36:37], v[36:37], v[48:49] op_sel_hi:[1,0]
	v_pk_mul_f32 v[52:53], v[34:35], v[48:49] op_sel_hi:[1,0]
	v_pk_mul_f32 v[48:49], v[32:33], v[48:49] op_sel_hi:[1,0]
	v_cvt_pk_bf16_f32 v32, v44, v45
	v_cvt_pk_bf16_f32 v33, v46, v47
	v_cvt_pk_bf16_f32 v34, v40, v41
	v_cvt_pk_bf16_f32 v35, v42, v43
	global_store_dwordx4 v[50:51], v[32:35], off
	s_nop 1
	v_cvt_pk_bf16_f32 v32, v36, v37
	v_cvt_pk_bf16_f32 v33, v38, v39
	v_cvt_pk_bf16_f32 v34, v48, v49
	v_cvt_pk_bf16_f32 v35, v52, v53
	global_store_dwordx4 v[50:51], v[32:35], off offset:256
	s_nop 0
	s_nop 0
	v_add_u32_e32 v33, 0xa0, v144
	v_mad_i64_i32 v[34:35], s[16:17], v33, s39, v[146:147]
	v_lshl_add_u64 v[34:35], v[34:35], 0, v[148:149]
	s_mov_b64 s[16:17], s[12:13]
	s_nop 0
	v_fmamk_f32 v32, v182, 0x3a000000, v168
	v_rsq_f32_e32 v32, v32
	s_nop 0
	v_pk_mul_f32 v[30:31], v[30:31], v[32:33] op_sel_hi:[1,0]
	v_pk_mul_f32 v[28:29], v[28:29], v[32:33] op_sel_hi:[1,0]
	v_pk_mul_f32 v[26:27], v[26:27], v[32:33] op_sel_hi:[1,0]
	v_pk_mul_f32 v[24:25], v[24:25], v[32:33] op_sel_hi:[1,0]
	v_pk_mul_f32 v[22:23], v[22:23], v[32:33] op_sel_hi:[1,0]
	v_pk_mul_f32 v[20:21], v[20:21], v[32:33] op_sel_hi:[1,0]
	v_pk_mul_f32 v[36:37], v[18:19], v[32:33] op_sel_hi:[1,0]
	v_pk_mul_f32 v[32:33], v[16:17], v[32:33] op_sel_hi:[1,0]
	v_cvt_pk_bf16_f32 v16, v28, v29
	v_cvt_pk_bf16_f32 v17, v30, v31
	v_cvt_pk_bf16_f32 v18, v24, v25
	v_cvt_pk_bf16_f32 v19, v26, v27
	global_store_dwordx4 v[34:35], v[16:19], off
	s_nop 1
	v_cvt_pk_bf16_f32 v16, v20, v21
	v_cvt_pk_bf16_f32 v17, v22, v23
	v_cvt_pk_bf16_f32 v18, v32, v33
	v_cvt_pk_bf16_f32 v19, v36, v37
	global_store_dwordx4 v[34:35], v[16:19], off offset:256
	s_nop 0
	s_nop 0
	v_add_u32_e32 v17, 0xb0, v144
	v_mad_i64_i32 v[18:19], s[4:5], v17, s39, v[146:147]
	v_lshl_add_u64 v[18:19], v[18:19], 0, v[148:149]
	s_nop 0
	v_fmamk_f32 v16, v183, 0x3a000000, v168
	v_rsq_f32_e32 v16, v16
	s_nop 0
	v_pk_mul_f32 v[14:15], v[14:15], v[16:17] op_sel_hi:[1,0]
	v_pk_mul_f32 v[12:13], v[12:13], v[16:17] op_sel_hi:[1,0]
	v_pk_mul_f32 v[10:11], v[10:11], v[16:17] op_sel_hi:[1,0]
	v_pk_mul_f32 v[8:9], v[8:9], v[16:17] op_sel_hi:[1,0]
	v_pk_mul_f32 v[6:7], v[6:7], v[16:17] op_sel_hi:[1,0]
	v_pk_mul_f32 v[4:5], v[4:5], v[16:17] op_sel_hi:[1,0]
	v_pk_mul_f32 v[20:21], v[2:3], v[16:17] op_sel_hi:[1,0]
	v_pk_mul_f32 v[16:17], v[0:1], v[16:17] op_sel_hi:[1,0]
	v_cvt_pk_bf16_f32 v0, v12, v13
	v_cvt_pk_bf16_f32 v1, v14, v15
	v_cvt_pk_bf16_f32 v2, v8, v9
	v_cvt_pk_bf16_f32 v3, v10, v11
	global_store_dwordx4 v[18:19], v[0:3], off
	s_nop 1
	v_cvt_pk_bf16_f32 v0, v4, v5
	v_cvt_pk_bf16_f32 v1, v6, v7
	v_cvt_pk_bf16_f32 v2, v16, v17
	v_cvt_pk_bf16_f32 v3, v20, v21
	global_store_dwordx4 v[18:19], v[0:3], off offset:256
	s_cbranch_vccz .LBB0_144
	s_waitcnt vmcnt(0)
	s_cmpk_gt_u32 s3, 0xff
	s_cbranch_scc1 .LBB0_151
	s_nop 0

.LBB0_269:
	v_and_b32_e32 v0, 24, v158
	v_and_b32_e32 v1, 4, v238
	s_movk_i32 s1, 0x70
	v_or3_b32 v0, v1, v157, v0
	v_and_or_b32 v236, v153, s1, v218
	s_movk_i32 s1, 0x60
	v_add_u32_e32 v233, 0x2000, v156
	v_and_or_b32 v232, v153, s1, v0
	v_lshrrev_b32_e32 v144, 7, v233
	s_movk_i32 s1, 0xf0
	v_and_or_b32 v237, v144, s1, v218
	s_movk_i32 s1, 0xe0
	v_and_or_b32 v240, v144, s1, v0
	v_cndmask_b32_e64 v0, 0, 1, s[4:5]
	v_bitop3_b32 v226, v156, v159, 48 bitop3:0x6c
	v_bfe_u32 v225, v222, 4, 2
	v_cmp_ne_u32_e64 s[6:7], 1, v0
	v_or_b32_e32 v219, v226, v224
	v_lshlrev_b32_e32 v227, 4, v225
	s_add_u32 s12, s92, 0x10000
	v_writelane_b32 v255, s6, 8
	v_lshl_or_b32 v164, v232, 12, v219
	v_lshl_or_b32 v166, v240, 12, v219
	s_addc_u32 s13, s93, 0
	v_writelane_b32 v255, s7, 9
	s_andn2_b64 vcc, exec, s[4:5]
	v_bitop3_b32 v228, v227, v152, v155 bitop3:0x36
	s_cbranch_vccnz .LBB0_303
	s_add_u32 s22, s92, 0x1900000
	s_addc_u32 s23, s93, 0
	s_lshr_b32 s5, s3, 6
	s_ashr_i32 s1, s0, 31
	s_lshr_b32 s4, s3, 8
	s_lshl_b32 s24, s5, 10
	s_lshl_b64 s[6:7], s[0:1], 20
	s_add_u32 s18, s22, s6
	s_addc_u32 s19, s23, s7
	s_add_i32 s25, s24, 0
	s_add_i32 m0, s25, 0x10000
	s_mul_i32 s9, s42, 0x300000
	v_and_b32_e32 v140, 63, v222
	v_lshrrev_b32_e32 v141, 3, v140
	v_lshrrev_b32_e32 v142, 6, v222
	v_lshl_add_u32 v143, v142, 3, v141
	v_and_b32_e32 v150, 7, v140
	v_and_b32_e32 v151, 6, v141
	v_xor_b32_e32 v150, v150, v151
	v_lshlrev_b32_e32 v150, 4, v150
	v_mul_u32_u24_e32 v151, 0x3000, v143
	v_add_u32_e32 v151, v151, v150
	v_mov_b32_e32 v132, v151
	v_mov_b32_e32 v128, v151
	v_add_u32_e32 v134, 0xc0000, v151
	v_add_u32_e32 v130, 0xc0000, v151
	v_add_u32_e32 v134, 0xc0000, v151
	v_add_u32_e32 v130, 0xc0000, v151
	v_and_b32_e32 v151, 31, v143
	v_and_b32_e32 v154, 12, v151
	v_lshlrev_b32_e32 v154, 1, v154
	v_lshrrev_b32_e32 v155, 4, v151
	v_lshlrev_b32_e32 v155, 2, v155
	v_and_b32_e32 v151, 3, v151
	v_or3_b32 v151, v154, v155, v151
	v_and_b32_e32 v154, 0x60, v143
	v_add_u32_e32 v151, v151, v154
	v_mul_u32_u24_e32 v151, 0x1000, v151
	v_add_u32_e32 v151, v151, v150
	v_mov_b32_e32 v164, v151
	v_add_u32_e32 v166, 0x40000, v151
	v_add_u32_e32 v166, 0x40000, v151
	v_and_b32_e32 v151, 15, v140
	v_lshrrev_b32_e32 v154, 4, v140
	v_and_b32_e32 v155, 6, v151
	v_xor_b32_e32 v154, v154, v155
	v_lshlrev_b32_e32 v154, 4, v154
	v_lshl_or_b32 v154, v151, 7, v154
	v_lshrrev_b32_e32 v155, 2, v142
	v_lshl_add_u32 v155, v155, 13, v154
	v_add_u32_e32 v147, 0x0, v155
	v_and_b32_e32 v151, 3, v142
	v_lshl_add_u32 v151, v151, 12, v154
	v_add_u32_e32 v145, 0x0, v151
	v_add_u32_e32 v146, 0x10000, v151
	v_add_u32_e32 v148, 0x14000, v151
	s_add_i32 m0, s25, 0x12000
	v_mul_u32_u24_e32 v9, 0x3000, v236
	s_mul_hi_i32 s8, s42, 0x300000
	s_add_u32 s20, s96, s9
	v_mul_u32_u24_e32 v8, 0x3000, v237
	s_addc_u32 s21, s97, s8
	s_mov_b32 m0, s25
	s_add_i32 s26, s25, 0x2000
	s_mov_b32 m0, s26
	s_add_u32 s6, s18, 0x80000
	s_addc_u32 s7, s19, 0
	s_add_i32 m0, s25, 0x14000
	v_mov_b32_e32 v165, 0
	s_add_i32 m0, s25, 0x16000
	v_mov_b32_e32 v167, v165
	s_add_u32 s6, s20, 0x180000
	s_addc_u32 s7, s21, 0
	s_add_i32 s27, s25, 0x4000
	s_mov_b32 m0, s27
	s_add_i32 s28, s25, 0x6000
	s_mov_b32 m0, s28
	v_mov_b32_e32 v129, v165
	v_mov_b32_e32 v131, v165
	s_mov_b32 s29, 0
	v_lshl_add_u64 v[6:7], s[18:19], 0, v[164:165]
	v_lshl_add_u64 v[4:5], s[18:19], 0, v[166:167]
	v_lshl_add_u64 v[2:3], s[20:21], 0, v[128:129]
	s_cmp_lg_u32 s4, 1
	v_lshl_add_u64 v[0:1], s[20:21], 0, v[130:131]
	s_cbranch_scc1 .LBB0_272
.LBB0_272:
	s_mov_b64 s[8:9], 0x80
	s_lshl_b32 s30, s4, 6
	s_lshl_b32 s1, s4, 13
	s_lshl_b32 s4, s5, 5
	s_add_i32 m0, s25, 0x18000
	v_lshl_add_u64 v[6:7], v[6:7], 0, s[8:9]
	s_and_b32 s31, s4, 0x60
	v_lshl_add_u64 v[4:5], v[4:5], 0, s[8:9]
	s_add_i32 m0, s25, 0x1a000
	s_add_i32 s33, s25, 0x8000
	s_add_i32 s34, s25, 0xa000
	v_lshl_add_u64 v[2:3], v[2:3], 0, s[8:9]
	s_mov_b32 m0, s33
	s_add_u32 s4, s18, 0x80080
	v_lshl_add_u64 v[0:1], v[0:1], 0, s[8:9]
	s_mov_b32 m0, s34
	s_addc_u32 s5, s19, 0
	s_add_i32 m0, s25, 0x1c000
	v_lshl_add_u64 v[0:1], s[4:5], 0, v[164:165]
	v_lshl_add_u64 v[0:1], s[4:5], 0, v[166:167]
	s_add_i32 m0, s25, 0x1e000
	v_lshlrev_b32_e32 v1, 2, v163
	v_lshl_or_b32 v0, v163, 6, v227
	v_and_b32_e32 v1, 32, v1
	v_bitop3_b32 v0, v0, s1, v1 bitop3:0xde
	s_add_i32 s39, 0, 0x10000
	s_add_i32 s40, 0, 0x14000
	v_mbcnt_lo_u32_b32 v0, -1, 0
	s_ashr_i32 s35, s94, 31
	s_mov_b32 s38, s94
	v_mov_b32_e32 v133, v165
	v_mov_b32_e32 v135, v165
	v_mov_b64_e32 v[136:137], 0x200
	v_mov_b64_e32 v[138:139], 0x1ff
	v_mbcnt_hi_u32_b32 v149, -1, v0
	v_and_b32_e32 v140, 63, v222
	v_lshrrev_b32_e32 v141, 6, v222
	v_lshrrev_b32_e32 v142, 3, v140
	v_lshl_add_u32 v143, v141, 3, v142
	v_and_b32_e32 v154, 7, v140
	v_and_b32_e32 v155, 6, v142
	v_xor_b32_e32 v154, v154, v155
	v_lshlrev_b32_e32 v154, 4, v154
	v_mul_u32_u24_e32 v155, 0x3000, v143
	v_add_u32_e32 v150, v155, v154
	v_and_b32_e32 v155, 31, v143
	v_and_b32_e32 v142, 12, v155
	v_lshlrev_b32_e32 v142, 1, v142
	v_lshrrev_b32_e32 v151, 4, v155
	v_lshlrev_b32_e32 v151, 2, v151
	v_and_b32_e32 v155, 3, v155
	v_or3_b32 v155, v142, v151, v155
	v_and_b32_e32 v142, 0x60, v143
	v_add_u32_e32 v155, v155, v142
	v_mul_u32_u24_e32 v155, 0x1000, v155
	v_add_u32_e32 v151, v155, v154
	v_and_b32_e32 v142, 15, v140
	v_lshrrev_b32_e32 v143, 4, v140
	v_and_b32_e32 v154, 6, v142
	v_xor_b32_e32 v143, v143, v154
	v_lshlrev_b32_e32 v143, 4, v143
	v_lshl_or_b32 v143, v142, 7, v143
	v_lshrrev_b32_e32 v154, 2, v141
	v_lshl_add_u32 v216, v154, 13, v143
	v_xor_b32_e32 v217, 64, v216
	v_and_b32_e32 v154, 3, v141
	v_lshl_add_u32 v220, v154, 12, v143
	v_add_u32_e32 v220, 0x10000, v220
	v_xor_b32_e32 v221, 64, v220
	v_readfirstlane_b32 s48, v222
	s_nop 3
	s_lshr_b32 s48, s48, 6
	s_lshl_b32 s48, s48, 10
	s_mov_b32 s98, 0
	s_mul_i32 s20, s98, s94
	s_add_i32 s20, s20, s2
	s_and_b32 s21, s20, 7
	s_lshr_b32 s20, s20, 3
	s_mul_i32 s21, s21, 0x40
	s_add_i32 s20, s20, s21
	s_mul_i32 s21, s20, 0x80000
	s_lshr_b32 s21, s21, 24
	s_mul_i32 s45, s21, 0x20
	s_sub_i32 s20, s20, s45
	s_and_b32 s44, s20, 3
	s_lshl_b32 s21, s21, 2
	s_add_i32 s44, s44, s21
	s_lshr_b32 s45, s20, 2
	s_mul_i32 s100, s44, 0x300000
	s_add_u32 s6, s92, 0xfd00000
	s_addc_u32 s7, s93, 0
	s_add_u32 s6, s6, s100
	s_addc_u32 s7, s7, 0
	s_mul_i32 s100, s45, 0x100000
	s_add_u32 s18, s92, 0x1900000
	s_addc_u32 s19, s93, 0
	s_add_u32 s18, s18, s100
	s_addc_u32 s19, s19, 0
	s_add_i32 m0, s48, 0x0
	s_nop 0
	global_load_lds_dwordx4 v150, s[6:7]
	s_add_i32 m0, s48, 0x2000
	s_add_u32 s46, s6, 0xc0000
	s_addc_u32 s47, s7, 0
	s_nop 0
	global_load_lds_dwordx4 v150, s[46:47]
	s_add_i32 m0, s48, 0x4000
	s_add_u32 s46, s6, 0x180000
	s_addc_u32 s47, s7, 0
	s_nop 0
	global_load_lds_dwordx4 v150, s[46:47]
	s_add_i32 m0, s48, 0x6000
	s_add_u32 s46, s6, 0x240000
	s_addc_u32 s47, s7, 0
	s_nop 0
	global_load_lds_dwordx4 v150, s[46:47]
	s_add_i32 m0, s48, 0x10000
	s_nop 0
	global_load_lds_dwordx4 v151, s[18:19]
	s_add_i32 m0, s48, 0x12000
	s_add_u32 s46, s18, 0x40000
	s_addc_u32 s47, s19, 0
	s_nop 0
	global_load_lds_dwordx4 v151, s[46:47]
	s_add_i32 m0, s48, 0x14000
	s_add_u32 s46, s18, 0x80000
	s_addc_u32 s47, s19, 0
	s_nop 0
	global_load_lds_dwordx4 v151, s[46:47]
	s_add_i32 m0, s48, 0x16000
	s_add_u32 s46, s18, 0xc0000
	s_addc_u32 s47, s19, 0
	s_nop 0
	global_load_lds_dwordx4 v151, s[46:47]
	s_add_u32 s6, s6, 128
	s_addc_u32 s7, s7, 0
	s_add_u32 s18, s18, 128
	s_addc_u32 s19, s19, 0
	s_add_i32 m0, s48, 0x8000
	s_nop 0
	global_load_lds_dwordx4 v150, s[6:7]
	s_add_i32 m0, s48, 0xa000
	s_add_u32 s46, s6, 0xc0000
	s_addc_u32 s47, s7, 0
	s_nop 0
	global_load_lds_dwordx4 v150, s[46:47]
	s_add_i32 m0, s48, 0xc000
	s_add_u32 s46, s6, 0x180000
	s_addc_u32 s47, s7, 0
	s_nop 0
	global_load_lds_dwordx4 v150, s[46:47]
	s_add_i32 m0, s48, 0xe000
	s_add_u32 s46, s6, 0x240000
	s_addc_u32 s47, s7, 0
	s_nop 0
	global_load_lds_dwordx4 v150, s[46:47]
	s_add_i32 m0, s48, 0x18000
	s_nop 0
	global_load_lds_dwordx4 v151, s[18:19]
	s_add_i32 m0, s48, 0x1a000
	s_add_u32 s46, s18, 0x40000
	s_addc_u32 s47, s19, 0
	s_nop 0
	global_load_lds_dwordx4 v151, s[46:47]
	s_add_i32 m0, s48, 0x1c000
	s_add_u32 s46, s18, 0x80000
	s_addc_u32 s47, s19, 0
	s_nop 0
	global_load_lds_dwordx4 v151, s[46:47]
	s_add_i32 m0, s48, 0x1e000
	s_add_u32 s46, s18, 0xc0000
	s_addc_u32 s47, s19, 0
	s_nop 0
	global_load_lds_dwordx4 v151, s[46:47]
	s_branch .LBB0_274

.LBB0_282:
	s_ashr_i32 s11, s10, 31
	s_lshl_b64 s[16:17], s[10:11], 20
	s_add_u32 s16, s22, s16
	s_addc_u32 s17, s23, s17
	s_and_b64 s[6:7], s[6:7], exec
	s_cselect_b32 s1, s17, s19
	s_cselect_b32 s11, s16, s18
	s_add_u32 s6, s20, 0x180080
	s_addc_u32 s7, s21, 0
	s_add_u32 s43, s18, 0x100
	v_mov_b32_e32 v0, 0
	s_addc_u32 s44, s19, 0
	s_mov_b32 s45, -2
	s_waitcnt lgkmcnt(0)
	v_mov_b32_e32 v1, v0
	v_mov_b32_e32 v2, v0
	v_mov_b32_e32 v3, v0
	v_mov_b32_e32 v4, v0
	v_mov_b32_e32 v5, v0
	v_mov_b32_e32 v6, v0
	v_mov_b32_e32 v7, v0
	s_waitcnt vmcnt(0)
	v_mov_b32_e32 v16, v0
	v_mov_b32_e32 v17, v0
	v_mov_b32_e32 v18, v0
	v_mov_b32_e32 v19, v0
	v_mov_b32_e32 v20, v0
	v_mov_b32_e32 v21, v0
	v_mov_b32_e32 v22, v0
	v_mov_b32_e32 v23, v0
	v_mov_b32_e32 v32, v0
	v_mov_b32_e32 v33, v0
	v_mov_b32_e32 v34, v0
	v_mov_b32_e32 v35, v0
	v_mov_b32_e32 v36, v0
	v_mov_b32_e32 v37, v0
	v_mov_b32_e32 v38, v0
	v_mov_b32_e32 v39, v0
	v_mov_b32_e32 v48, v0
	v_mov_b32_e32 v49, v0
	v_mov_b32_e32 v50, v0
	v_mov_b32_e32 v51, v0
	v_mov_b32_e32 v52, v0
	v_mov_b32_e32 v53, v0
	v_mov_b32_e32 v54, v0
	v_mov_b32_e32 v55, v0
	v_mov_b32_e32 v8, v0
	v_mov_b32_e32 v9, v0
	v_mov_b32_e32 v10, v0
	v_mov_b32_e32 v11, v0
	v_mov_b32_e32 v12, v0
	v_mov_b32_e32 v13, v0
	v_mov_b32_e32 v14, v0
	v_mov_b32_e32 v15, v0
	v_mov_b32_e32 v24, v0
	v_mov_b32_e32 v25, v0
	v_mov_b32_e32 v26, v0
	v_mov_b32_e32 v27, v0
	v_mov_b32_e32 v28, v0
	v_mov_b32_e32 v29, v0
	v_mov_b32_e32 v30, v0
	v_mov_b32_e32 v31, v0
	v_mov_b32_e32 v40, v0
	v_mov_b32_e32 v41, v0
	v_mov_b32_e32 v42, v0
	v_mov_b32_e32 v43, v0
	v_mov_b32_e32 v44, v0
	v_mov_b32_e32 v45, v0
	v_mov_b32_e32 v46, v0
	v_mov_b32_e32 v47, v0
	v_mov_b32_e32 v56, v0
	v_mov_b32_e32 v57, v0
	v_mov_b32_e32 v58, v0
	v_mov_b32_e32 v59, v0
	v_mov_b32_e32 v60, v0
	v_mov_b32_e32 v61, v0
	v_mov_b32_e32 v62, v0
	v_mov_b32_e32 v63, v0
	v_mov_b32_e32 v64, v0
	v_mov_b32_e32 v65, v0
	v_mov_b32_e32 v66, v0
	v_mov_b32_e32 v67, v0
	v_mov_b32_e32 v68, v0
	v_mov_b32_e32 v69, v0
	v_mov_b32_e32 v70, v0
	v_mov_b32_e32 v71, v0
	v_mov_b32_e32 v80, v0
	v_mov_b32_e32 v81, v0
	v_mov_b32_e32 v82, v0
	v_mov_b32_e32 v83, v0
	v_mov_b32_e32 v84, v0
	v_mov_b32_e32 v85, v0
	v_mov_b32_e32 v86, v0
	v_mov_b32_e32 v87, v0
	v_mov_b32_e32 v96, v0
	v_mov_b32_e32 v97, v0
	v_mov_b32_e32 v98, v0
	v_mov_b32_e32 v99, v0
	v_mov_b32_e32 v100, v0
	v_mov_b32_e32 v101, v0
	v_mov_b32_e32 v102, v0
	v_mov_b32_e32 v103, v0
	v_mov_b32_e32 v112, v0
	v_mov_b32_e32 v113, v0
	v_mov_b32_e32 v114, v0
	v_mov_b32_e32 v115, v0
	v_mov_b32_e32 v116, v0
	v_mov_b32_e32 v117, v0
	v_mov_b32_e32 v118, v0
	v_mov_b32_e32 v119, v0
	v_mov_b32_e32 v72, v0
	v_mov_b32_e32 v73, v0
	v_mov_b32_e32 v74, v0
	v_mov_b32_e32 v75, v0
	v_mov_b32_e32 v76, v0
	v_mov_b32_e32 v77, v0
	v_mov_b32_e32 v78, v0
	v_mov_b32_e32 v79, v0
	v_mov_b32_e32 v88, v0
	v_mov_b32_e32 v89, v0
	v_mov_b32_e32 v90, v0
	v_mov_b32_e32 v91, v0
	v_mov_b32_e32 v92, v0
	v_mov_b32_e32 v93, v0
	v_mov_b32_e32 v94, v0
	v_mov_b32_e32 v95, v0
	v_mov_b32_e32 v104, v0
	v_mov_b32_e32 v105, v0
	v_mov_b32_e32 v106, v0
	v_mov_b32_e32 v107, v0
	v_mov_b32_e32 v108, v0
	v_mov_b32_e32 v109, v0
	v_mov_b32_e32 v110, v0
	v_mov_b32_e32 v111, v0
	v_mov_b32_e32 v120, v0
	v_mov_b32_e32 v121, v0
	v_mov_b32_e32 v122, v0
	v_mov_b32_e32 v123, v0
	v_mov_b32_e32 v124, v0
	v_mov_b32_e32 v125, v0
	v_mov_b32_e32 v126, v0
	v_mov_b32_e32 v127, v0
	v_and_b32_e32 v140, 63, v222
	v_lshrrev_b32_e32 v141, 6, v222
	v_lshrrev_b32_e32 v142, 3, v140
	v_lshl_add_u32 v143, v141, 3, v142
	v_and_b32_e32 v154, 7, v140
	v_and_b32_e32 v155, 6, v142
	v_xor_b32_e32 v154, v154, v155
	v_lshlrev_b32_e32 v154, 4, v154
	v_mul_u32_u24_e32 v155, 0x3000, v143
	v_add_u32_e32 v150, v155, v154
	v_and_b32_e32 v155, 31, v143
	v_and_b32_e32 v142, 12, v155
	v_lshlrev_b32_e32 v142, 1, v142
	v_lshrrev_b32_e32 v151, 4, v155
	v_lshlrev_b32_e32 v151, 2, v151
	v_and_b32_e32 v155, 3, v155
	v_or3_b32 v155, v142, v151, v155
	v_and_b32_e32 v142, 0x60, v143
	v_add_u32_e32 v155, v155, v142
	v_mul_u32_u24_e32 v155, 0x1000, v155
	v_add_u32_e32 v151, v155, v154
	v_and_b32_e32 v142, 15, v140
	v_lshrrev_b32_e32 v143, 4, v140
	v_and_b32_e32 v154, 6, v142
	v_xor_b32_e32 v143, v143, v154
	v_lshlrev_b32_e32 v143, 4, v143
	v_lshl_or_b32 v143, v142, 7, v143
	v_lshrrev_b32_e32 v154, 2, v141
	v_lshl_add_u32 v216, v154, 13, v143
	v_xor_b32_e32 v217, 64, v216
	v_and_b32_e32 v154, 3, v141
	v_lshl_add_u32 v220, v154, 12, v143
	v_add_u32_e32 v220, 0x10000, v220
	v_xor_b32_e32 v221, 64, v220
	v_readfirstlane_b32 s48, v222
	s_nop 3
	s_lshr_b32 s48, s48, 6
	s_lshl_b32 s48, s48, 10
	s_mul_i32 s20, s98, s94
	s_add_i32 s20, s20, s2
	s_and_b32 s21, s20, 7
	s_lshr_b32 s20, s20, 3
	s_mul_i32 s21, s21, 0x40
	s_add_i32 s20, s20, s21
	s_mul_i32 s21, s20, 0x80000
	s_lshr_b32 s21, s21, 24
	s_mul_i32 s100, s21, 0x20
	s_sub_i32 s20, s20, s100
	s_and_b32 s43, s20, 3
	s_lshl_b32 s21, s21, 2
	s_add_i32 s43, s43, s21
	s_lshr_b32 s100, s20, 2
	s_mul_i32 s99, s43, 0x300000
	s_add_u32 s6, s92, 0xfd00100
	s_addc_u32 s7, s93, 0
	s_add_u32 s6, s6, s99
	s_addc_u32 s7, s7, 0
	s_mul_i32 s99, s100, 0x100000
	s_add_u32 s18, s92, 0x1900100
	s_addc_u32 s19, s93, 0
	s_add_u32 s18, s18, s99
	s_addc_u32 s19, s19, 0
	s_add_i32 s98, s98, 1
	s_mul_i32 s44, s98, s94
	s_add_i32 s44, s44, s2
	s_cmp_lt_u32 s44, 0x200
	s_cbranch_scc0 .Ls2_nonext
	s_mul_i32 s20, s98, s94
	s_add_i32 s20, s20, s2
	s_and_b32 s21, s20, 7
	s_lshr_b32 s20, s20, 3
	s_mul_i32 s21, s21, 0x40
	s_add_i32 s20, s20, s21
	s_mul_i32 s21, s20, 0x80000
	s_lshr_b32 s21, s21, 24
	s_mul_i32 s100, s21, 0x20
	s_sub_i32 s20, s20, s100
	s_and_b32 s43, s20, 3
	s_lshl_b32 s21, s21, 2
	s_add_i32 s43, s43, s21
	s_lshr_b32 s100, s20, 2
.Ls2_nonext:
	s_mul_i32 s99, s43, 0x300000
	s_add_u32 s20, s92, 0xfd00000
	s_addc_u32 s21, s93, 0
	s_add_u32 s20, s20, s99
	s_addc_u32 s21, s21, 0
	s_mul_i32 s99, s100, 0x100000
	s_add_u32 s44, s92, 0x1900000
	s_addc_u32 s45, s93, 0
	s_add_u32 s44, s44, s99
	s_addc_u32 s45, s45, 0
	s_waitcnt vmcnt(0)
	s_barrier
	ds_read_b128 v[140:143], v216
	ds_read_b128 v[154:157], v216 offset:2048
	ds_read_b128 v[188:191], v220
	ds_read_b128 v[192:195], v220 offset:2048
	ds_read_b128 v[196:199], v220 offset:16384
	ds_read_b128 v[200:203], v220 offset:18432
	ds_read_b128 v[158:161], v216 offset:4096
	ds_read_b128 v[168:171], v216 offset:6144
	ds_read_b128 v[172:175], v216 offset:16384
	ds_read_b128 v[176:179], v216 offset:18432
	ds_read_b128 v[180:183], v216 offset:20480
	ds_read_b128 v[184:187], v216 offset:22528
	s_mov_b32 s43, 0
.Ls2_loop:
	s_cmp_eq_u32 s43, 15
	s_cselect_b32 s6, s20, s6
	s_cselect_b32 s7, s21, s7
	s_cselect_b32 s18, s44, s18
	s_cselect_b32 s19, s45, s19
	s_waitcnt lgkmcnt(6)
	v_mfma_f32_16x16x32_bf16 v[124:127], v[188:191], v[140:143], v[124:127]
	v_mfma_f32_16x16x32_bf16 v[120:123], v[192:195], v[140:143], v[120:123]
	v_mfma_f32_16x16x32_bf16 v[116:119], v[196:199], v[140:143], v[116:119]
	v_mfma_f32_16x16x32_bf16 v[112:115], v[200:203], v[140:143], v[112:115]
	v_mfma_f32_16x16x32_bf16 v[108:111], v[188:191], v[154:157], v[108:111]
	v_mfma_f32_16x16x32_bf16 v[104:107], v[192:195], v[154:157], v[104:107]
	v_mfma_f32_16x16x32_bf16 v[100:103], v[196:199], v[154:157], v[100:103]
	v_mfma_f32_16x16x32_bf16 v[96:99], v[200:203], v[154:157], v[96:99]
	s_waitcnt lgkmcnt(0)
	ds_read_b128 v[140:143], v217
	ds_read_b128 v[154:157], v217 offset:2048
	ds_read_b128 v[204:207], v221
	ds_read_b128 v[208:211], v221 offset:2048
	ds_read_b128 v[212:215], v221 offset:16384
	ds_read_b128 v[242:245], v221 offset:18432
	v_mfma_f32_16x16x32_bf16 v[92:95], v[188:191], v[158:161], v[92:95]
	v_mfma_f32_16x16x32_bf16 v[88:91], v[192:195], v[158:161], v[88:91]
	v_mfma_f32_16x16x32_bf16 v[84:87], v[196:199], v[158:161], v[84:87]
	v_mfma_f32_16x16x32_bf16 v[80:83], v[200:203], v[158:161], v[80:83]
	ds_read_b128 v[158:161], v217 offset:4096
	v_mfma_f32_16x16x32_bf16 v[76:79], v[188:191], v[168:171], v[76:79]
	v_mfma_f32_16x16x32_bf16 v[72:75], v[192:195], v[168:171], v[72:75]
	v_mfma_f32_16x16x32_bf16 v[68:71], v[196:199], v[168:171], v[68:71]
	v_mfma_f32_16x16x32_bf16 v[64:67], v[200:203], v[168:171], v[64:67]
	ds_read_b128 v[168:171], v217 offset:6144
	s_waitcnt lgkmcnt(0)
	s_barrier
	s_add_i32 m0, s48, 0x10000
	v_mfma_f32_16x16x32_bf16 v[60:63], v[188:191], v[172:175], v[60:63]
	v_mfma_f32_16x16x32_bf16 v[56:59], v[192:195], v[172:175], v[56:59]
	v_mfma_f32_16x16x32_bf16 v[52:55], v[196:199], v[172:175], v[52:55]
	v_mfma_f32_16x16x32_bf16 v[48:51], v[200:203], v[172:175], v[48:51]
	ds_read_b128 v[172:175], v217 offset:16384
	global_load_lds_dwordx4 v151, s[18:19]
	s_add_i32 m0, s48, 0x12000
	s_add_u32 s46, s18, 0x40000
	s_addc_u32 s47, s19, 0
	v_mfma_f32_16x16x32_bf16 v[44:47], v[188:191], v[176:179], v[44:47]
	v_mfma_f32_16x16x32_bf16 v[40:43], v[192:195], v[176:179], v[40:43]
	v_mfma_f32_16x16x32_bf16 v[36:39], v[196:199], v[176:179], v[36:39]
	v_mfma_f32_16x16x32_bf16 v[32:35], v[200:203], v[176:179], v[32:35]
	ds_read_b128 v[176:179], v217 offset:18432
	global_load_lds_dwordx4 v151, s[46:47]
	s_add_i32 m0, s48, 0x14000
	s_add_u32 s46, s18, 0x80000
	s_addc_u32 s47, s19, 0
	v_mfma_f32_16x16x32_bf16 v[28:31], v[188:191], v[180:183], v[28:31]
	v_mfma_f32_16x16x32_bf16 v[24:27], v[192:195], v[180:183], v[24:27]
	v_mfma_f32_16x16x32_bf16 v[20:23], v[196:199], v[180:183], v[20:23]
	v_mfma_f32_16x16x32_bf16 v[16:19], v[200:203], v[180:183], v[16:19]
	ds_read_b128 v[180:183], v217 offset:20480
	global_load_lds_dwordx4 v151, s[46:47]
	s_add_i32 m0, s48, 0x16000
	s_add_u32 s46, s18, 0xc0000
	s_addc_u32 s47, s19, 0
	v_mfma_f32_16x16x32_bf16 v[12:15], v[188:191], v[184:187], v[12:15]
	v_mfma_f32_16x16x32_bf16 v[8:11], v[192:195], v[184:187], v[8:11]
	v_mfma_f32_16x16x32_bf16 v[4:7], v[196:199], v[184:187], v[4:7]
	v_mfma_f32_16x16x32_bf16 v[0:3], v[200:203], v[184:187], v[0:3]
	ds_read_b128 v[184:187], v217 offset:22528
	global_load_lds_dwordx4 v151, s[46:47]
	s_waitcnt lgkmcnt(6)
	s_add_i32 m0, s48, 0x0
	v_mfma_f32_16x16x32_bf16 v[124:127], v[204:207], v[140:143], v[124:127]
	v_mfma_f32_16x16x32_bf16 v[120:123], v[208:211], v[140:143], v[120:123]
	v_mfma_f32_16x16x32_bf16 v[116:119], v[212:215], v[140:143], v[116:119]
	v_mfma_f32_16x16x32_bf16 v[112:115], v[242:245], v[140:143], v[112:115]
	global_load_lds_dwordx4 v150, s[6:7]
	s_add_i32 m0, s48, 0x2000
	s_add_u32 s46, s6, 0xc0000
	s_addc_u32 s47, s7, 0
	v_mfma_f32_16x16x32_bf16 v[108:111], v[204:207], v[154:157], v[108:111]
	v_mfma_f32_16x16x32_bf16 v[104:107], v[208:211], v[154:157], v[104:107]
	v_mfma_f32_16x16x32_bf16 v[100:103], v[212:215], v[154:157], v[100:103]
	v_mfma_f32_16x16x32_bf16 v[96:99], v[242:245], v[154:157], v[96:99]
	global_load_lds_dwordx4 v150, s[46:47]
	s_waitcnt lgkmcnt(0)
	s_waitcnt vmcnt(6)
	s_barrier
	ds_read_b128 v[140:143], v216 offset:32768
	ds_read_b128 v[154:157], v216 offset:34816
	ds_read_b128 v[188:191], v220 offset:32768
	ds_read_b128 v[192:195], v220 offset:34816
	ds_read_b128 v[196:199], v220 offset:49152
	ds_read_b128 v[200:203], v220 offset:51200
	s_add_i32 m0, s48, 0x4000
	s_add_u32 s46, s6, 0x180000
	s_addc_u32 s47, s7, 0
	v_mfma_f32_16x16x32_bf16 v[92:95], v[204:207], v[158:161], v[92:95]
	v_mfma_f32_16x16x32_bf16 v[88:91], v[208:211], v[158:161], v[88:91]
	v_mfma_f32_16x16x32_bf16 v[84:87], v[212:215], v[158:161], v[84:87]
	v_mfma_f32_16x16x32_bf16 v[80:83], v[242:245], v[158:161], v[80:83]
	ds_read_b128 v[158:161], v216 offset:36864
	global_load_lds_dwordx4 v150, s[46:47]
	s_add_i32 m0, s48, 0x6000
	s_add_u32 s46, s6, 0x240000
	s_addc_u32 s47, s7, 0
	v_mfma_f32_16x16x32_bf16 v[76:79], v[204:207], v[168:171], v[76:79]
	v_mfma_f32_16x16x32_bf16 v[72:75], v[208:211], v[168:171], v[72:75]
	v_mfma_f32_16x16x32_bf16 v[68:71], v[212:215], v[168:171], v[68:71]
	v_mfma_f32_16x16x32_bf16 v[64:67], v[242:245], v[168:171], v[64:67]
	ds_read_b128 v[168:171], v216 offset:38912
	global_load_lds_dwordx4 v150, s[46:47]
	v_mfma_f32_16x16x32_bf16 v[60:63], v[204:207], v[172:175], v[60:63]
	v_mfma_f32_16x16x32_bf16 v[56:59], v[208:211], v[172:175], v[56:59]
	v_mfma_f32_16x16x32_bf16 v[52:55], v[212:215], v[172:175], v[52:55]
	v_mfma_f32_16x16x32_bf16 v[48:51], v[242:245], v[172:175], v[48:51]
	ds_read_b128 v[172:175], v216 offset:49152
	v_mfma_f32_16x16x32_bf16 v[44:47], v[204:207], v[176:179], v[44:47]
	v_mfma_f32_16x16x32_bf16 v[40:43], v[208:211], v[176:179], v[40:43]
	v_mfma_f32_16x16x32_bf16 v[36:39], v[212:215], v[176:179], v[36:39]
	v_mfma_f32_16x16x32_bf16 v[32:35], v[242:245], v[176:179], v[32:35]
	ds_read_b128 v[176:179], v216 offset:51200
	v_mfma_f32_16x16x32_bf16 v[28:31], v[204:207], v[180:183], v[28:31]
	v_mfma_f32_16x16x32_bf16 v[24:27], v[208:211], v[180:183], v[24:27]
	v_mfma_f32_16x16x32_bf16 v[20:23], v[212:215], v[180:183], v[20:23]
	v_mfma_f32_16x16x32_bf16 v[16:19], v[242:245], v[180:183], v[16:19]
	ds_read_b128 v[180:183], v216 offset:53248
	v_mfma_f32_16x16x32_bf16 v[12:15], v[204:207], v[184:187], v[12:15]
	v_mfma_f32_16x16x32_bf16 v[8:11], v[208:211], v[184:187], v[8:11]
	v_mfma_f32_16x16x32_bf16 v[4:7], v[212:215], v[184:187], v[4:7]
	v_mfma_f32_16x16x32_bf16 v[0:3], v[242:245], v[184:187], v[0:3]
	ds_read_b128 v[184:187], v216 offset:55296
	s_add_u32 s6, s6, 128
	s_addc_u32 s7, s7, 0
	s_add_u32 s18, s18, 128
	s_addc_u32 s19, s19, 0
	s_waitcnt lgkmcnt(6)
	v_mfma_f32_16x16x32_bf16 v[124:127], v[188:191], v[140:143], v[124:127]
	v_mfma_f32_16x16x32_bf16 v[120:123], v[192:195], v[140:143], v[120:123]
	v_mfma_f32_16x16x32_bf16 v[116:119], v[196:199], v[140:143], v[116:119]
	v_mfma_f32_16x16x32_bf16 v[112:115], v[200:203], v[140:143], v[112:115]
	v_mfma_f32_16x16x32_bf16 v[108:111], v[188:191], v[154:157], v[108:111]
	v_mfma_f32_16x16x32_bf16 v[104:107], v[192:195], v[154:157], v[104:107]
	v_mfma_f32_16x16x32_bf16 v[100:103], v[196:199], v[154:157], v[100:103]
	v_mfma_f32_16x16x32_bf16 v[96:99], v[200:203], v[154:157], v[96:99]
	s_waitcnt lgkmcnt(0)
	ds_read_b128 v[140:143], v217 offset:32768
	ds_read_b128 v[154:157], v217 offset:34816
	ds_read_b128 v[204:207], v221 offset:32768
	ds_read_b128 v[208:211], v221 offset:34816
	ds_read_b128 v[212:215], v221 offset:49152
	ds_read_b128 v[242:245], v221 offset:51200
	v_mfma_f32_16x16x32_bf16 v[92:95], v[188:191], v[158:161], v[92:95]
	v_mfma_f32_16x16x32_bf16 v[88:91], v[192:195], v[158:161], v[88:91]
	v_mfma_f32_16x16x32_bf16 v[84:87], v[196:199], v[158:161], v[84:87]
	v_mfma_f32_16x16x32_bf16 v[80:83], v[200:203], v[158:161], v[80:83]
	ds_read_b128 v[158:161], v217 offset:36864
	v_mfma_f32_16x16x32_bf16 v[76:79], v[188:191], v[168:171], v[76:79]
	v_mfma_f32_16x16x32_bf16 v[72:75], v[192:195], v[168:171], v[72:75]
	v_mfma_f32_16x16x32_bf16 v[68:71], v[196:199], v[168:171], v[68:71]
	v_mfma_f32_16x16x32_bf16 v[64:67], v[200:203], v[168:171], v[64:67]
	ds_read_b128 v[168:171], v217 offset:38912
	s_waitcnt lgkmcnt(0)
	s_barrier
	s_add_i32 m0, s48, 0x18000
	v_mfma_f32_16x16x32_bf16 v[60:63], v[188:191], v[172:175], v[60:63]
	v_mfma_f32_16x16x32_bf16 v[56:59], v[192:195], v[172:175], v[56:59]
	v_mfma_f32_16x16x32_bf16 v[52:55], v[196:199], v[172:175], v[52:55]
	v_mfma_f32_16x16x32_bf16 v[48:51], v[200:203], v[172:175], v[48:51]
	ds_read_b128 v[172:175], v217 offset:49152
	global_load_lds_dwordx4 v151, s[18:19]
	s_add_i32 m0, s48, 0x1a000
	s_add_u32 s46, s18, 0x40000
	s_addc_u32 s47, s19, 0
	v_mfma_f32_16x16x32_bf16 v[44:47], v[188:191], v[176:179], v[44:47]
	v_mfma_f32_16x16x32_bf16 v[40:43], v[192:195], v[176:179], v[40:43]
	v_mfma_f32_16x16x32_bf16 v[36:39], v[196:199], v[176:179], v[36:39]
	v_mfma_f32_16x16x32_bf16 v[32:35], v[200:203], v[176:179], v[32:35]
	ds_read_b128 v[176:179], v217 offset:51200
	global_load_lds_dwordx4 v151, s[46:47]
	s_add_i32 m0, s48, 0x1c000
	s_add_u32 s46, s18, 0x80000
	s_addc_u32 s47, s19, 0
	v_mfma_f32_16x16x32_bf16 v[28:31], v[188:191], v[180:183], v[28:31]
	v_mfma_f32_16x16x32_bf16 v[24:27], v[192:195], v[180:183], v[24:27]
	v_mfma_f32_16x16x32_bf16 v[20:23], v[196:199], v[180:183], v[20:23]
	v_mfma_f32_16x16x32_bf16 v[16:19], v[200:203], v[180:183], v[16:19]
	ds_read_b128 v[180:183], v217 offset:53248
	global_load_lds_dwordx4 v151, s[46:47]
	s_add_i32 m0, s48, 0x1e000
	s_add_u32 s46, s18, 0xc0000
	s_addc_u32 s47, s19, 0
	v_mfma_f32_16x16x32_bf16 v[12:15], v[188:191], v[184:187], v[12:15]
	v_mfma_f32_16x16x32_bf16 v[8:11], v[192:195], v[184:187], v[8:11]
	v_mfma_f32_16x16x32_bf16 v[4:7], v[196:199], v[184:187], v[4:7]
	v_mfma_f32_16x16x32_bf16 v[0:3], v[200:203], v[184:187], v[0:3]
	ds_read_b128 v[184:187], v217 offset:55296
	global_load_lds_dwordx4 v151, s[46:47]
	s_waitcnt lgkmcnt(6)
	s_add_i32 m0, s48, 0x8000
	v_mfma_f32_16x16x32_bf16 v[124:127], v[204:207], v[140:143], v[124:127]
	v_mfma_f32_16x16x32_bf16 v[120:123], v[208:211], v[140:143], v[120:123]
	v_mfma_f32_16x16x32_bf16 v[116:119], v[212:215], v[140:143], v[116:119]
	v_mfma_f32_16x16x32_bf16 v[112:115], v[242:245], v[140:143], v[112:115]
	global_load_lds_dwordx4 v150, s[6:7]
	s_add_i32 m0, s48, 0xa000
	s_add_u32 s46, s6, 0xc0000
	s_addc_u32 s47, s7, 0
	v_mfma_f32_16x16x32_bf16 v[108:111], v[204:207], v[154:157], v[108:111]
	v_mfma_f32_16x16x32_bf16 v[104:107], v[208:211], v[154:157], v[104:107]
	v_mfma_f32_16x16x32_bf16 v[100:103], v[212:215], v[154:157], v[100:103]
	v_mfma_f32_16x16x32_bf16 v[96:99], v[242:245], v[154:157], v[96:99]
	global_load_lds_dwordx4 v150, s[46:47]
	s_waitcnt lgkmcnt(0)
	s_waitcnt vmcnt(6)
	s_barrier
	ds_read_b128 v[140:143], v216
	ds_read_b128 v[154:157], v216 offset:2048
	ds_read_b128 v[188:191], v220
	ds_read_b128 v[192:195], v220 offset:2048
	ds_read_b128 v[196:199], v220 offset:16384
	ds_read_b128 v[200:203], v220 offset:18432
	s_add_i32 m0, s48, 0xc000
	s_add_u32 s46, s6, 0x180000
	s_addc_u32 s47, s7, 0
	v_mfma_f32_16x16x32_bf16 v[92:95], v[204:207], v[158:161], v[92:95]
	v_mfma_f32_16x16x32_bf16 v[88:91], v[208:211], v[158:161], v[88:91]
	v_mfma_f32_16x16x32_bf16 v[84:87], v[212:215], v[158:161], v[84:87]
	v_mfma_f32_16x16x32_bf16 v[80:83], v[242:245], v[158:161], v[80:83]
	ds_read_b128 v[158:161], v216 offset:4096
	global_load_lds_dwordx4 v150, s[46:47]
	s_add_i32 m0, s48, 0xe000
	s_add_u32 s46, s6, 0x240000
	s_addc_u32 s47, s7, 0
	v_mfma_f32_16x16x32_bf16 v[76:79], v[204:207], v[168:171], v[76:79]
	v_mfma_f32_16x16x32_bf16 v[72:75], v[208:211], v[168:171], v[72:75]
	v_mfma_f32_16x16x32_bf16 v[68:71], v[212:215], v[168:171], v[68:71]
	v_mfma_f32_16x16x32_bf16 v[64:67], v[242:245], v[168:171], v[64:67]
	ds_read_b128 v[168:171], v216 offset:6144
	global_load_lds_dwordx4 v150, s[46:47]
	v_mfma_f32_16x16x32_bf16 v[60:63], v[204:207], v[172:175], v[60:63]
	v_mfma_f32_16x16x32_bf16 v[56:59], v[208:211], v[172:175], v[56:59]
	v_mfma_f32_16x16x32_bf16 v[52:55], v[212:215], v[172:175], v[52:55]
	v_mfma_f32_16x16x32_bf16 v[48:51], v[242:245], v[172:175], v[48:51]
	ds_read_b128 v[172:175], v216 offset:16384
	v_mfma_f32_16x16x32_bf16 v[44:47], v[204:207], v[176:179], v[44:47]
	v_mfma_f32_16x16x32_bf16 v[40:43], v[208:211], v[176:179], v[40:43]
	v_mfma_f32_16x16x32_bf16 v[36:39], v[212:215], v[176:179], v[36:39]
	v_mfma_f32_16x16x32_bf16 v[32:35], v[242:245], v[176:179], v[32:35]
	ds_read_b128 v[176:179], v216 offset:18432
	v_mfma_f32_16x16x32_bf16 v[28:31], v[204:207], v[180:183], v[28:31]
	v_mfma_f32_16x16x32_bf16 v[24:27], v[208:211], v[180:183], v[24:27]
	v_mfma_f32_16x16x32_bf16 v[20:23], v[212:215], v[180:183], v[20:23]
	v_mfma_f32_16x16x32_bf16 v[16:19], v[242:245], v[180:183], v[16:19]
	ds_read_b128 v[180:183], v216 offset:20480
	v_mfma_f32_16x16x32_bf16 v[12:15], v[204:207], v[184:187], v[12:15]
	v_mfma_f32_16x16x32_bf16 v[8:11], v[208:211], v[184:187], v[8:11]
	v_mfma_f32_16x16x32_bf16 v[4:7], v[212:215], v[184:187], v[4:7]
	v_mfma_f32_16x16x32_bf16 v[0:3], v[242:245], v[184:187], v[0:3]
	ds_read_b128 v[184:187], v216 offset:22528
	s_add_u32 s6, s6, 128
	s_addc_u32 s7, s7, 0
	s_add_u32 s18, s18, 128
	s_addc_u32 s19, s19, 0
	s_add_i32 s43, s43, 1
	s_cmp_lt_u32 s43, 16
	s_cbranch_scc1 .Ls2_loop
	s_waitcnt lgkmcnt(0)
	s_nop 7
	s_nop 3
	v_lshl_add_u32 v217, s42, 8, v163
	v_add_u32_e32 v217, s30, v217
	v_lshlrev_b32_e32 v208, 2, v217
	v_lshl_add_u32 v214, v225, 3, s31
	v_lshl_add_u32 v214, s0, 8, v214
	v_lshl_add_u32 v209, v217, 11, v214
	v_lshlrev_b32_e32 v209, 1, v209
	v_lshlrev_b32_e32 v210, 1, v209
	v_lshl_add_u32 v217, v225, 4, v163
	v_xor_b32_e32 v215, 16, v217
	v_lshlrev_b32_e32 v215, 2, v215
	v_xor_b32_e32 v216, 32, v217
	v_lshlrev_b32_e32 v216, 2, v216
	v_add_u32_e32 v212, 0x0, v210
	global_load_dwordx4 v[176:179], v212, s[36:37]
	global_load_dwordx4 v[180:183], v212, s[36:37] offset:16
	global_load_dwordx4 v[184:187], v212, s[36:37] offset:512
	global_load_dwordx4 v[188:191], v212, s[36:37] offset:528
	v_add_u32_e32 v212, 0x20000, v210
	global_load_dwordx4 v[192:195], v212, s[36:37]
	global_load_dwordx4 v[196:199], v212, s[36:37] offset:16
	global_load_dwordx4 v[200:203], v212, s[36:37] offset:512
	global_load_dwordx4 v[204:207], v212, s[36:37] offset:528
	s_waitcnt vmcnt(4)
	v_pk_add_f32 v[124:125], v[124:125], v[176:177]
	v_pk_add_f32 v[126:127], v[126:127], v[178:179]
	v_pk_add_f32 v[120:121], v[120:121], v[180:181]
	v_pk_add_f32 v[122:123], v[122:123], v[182:183]
	v_mul_f32_e32 v213, v124, v124
	v_fmac_f32_e32 v213, v125, v125
	v_fmac_f32_e32 v213, v126, v126
	v_fmac_f32_e32 v213, v127, v127
	v_fmac_f32_e32 v213, v120, v120
	v_fmac_f32_e32 v213, v121, v121
	v_fmac_f32_e32 v213, v122, v122
	v_fmac_f32_e32 v213, v123, v123
	v_cvt_pk_bf16_f32 v176, v124, v125
	v_cvt_pk_bf16_f32 v177, v126, v127
	v_cvt_pk_bf16_f32 v178, v120, v121
	v_cvt_pk_bf16_f32 v179, v122, v123
	v_add_u32_e32 v217, 0x0, v209
	global_store_dwordx4 v217, v[176:179], s[80:81]
	v_pk_add_f32 v[116:117], v[116:117], v[184:185]
	v_pk_add_f32 v[118:119], v[118:119], v[186:187]
	v_pk_add_f32 v[112:113], v[112:113], v[188:189]
	v_pk_add_f32 v[114:115], v[114:115], v[190:191]
	v_fmac_f32_e32 v213, v116, v116
	v_fmac_f32_e32 v213, v117, v117
	v_fmac_f32_e32 v213, v118, v118
	v_fmac_f32_e32 v213, v119, v119
	v_fmac_f32_e32 v213, v112, v112
	v_fmac_f32_e32 v213, v113, v113
	v_fmac_f32_e32 v213, v114, v114
	v_fmac_f32_e32 v213, v115, v115
	v_cvt_pk_bf16_f32 v184, v116, v117
	v_cvt_pk_bf16_f32 v185, v118, v119
	v_cvt_pk_bf16_f32 v186, v112, v113
	v_cvt_pk_bf16_f32 v187, v114, v115
	global_store_dwordx4 v217, v[184:187], s[80:81] offset:256
	ds_bpermute_b32 v214, v215, v213
	s_waitcnt lgkmcnt(0)
	v_add_f32_e32 v213, v213, v214
	ds_bpermute_b32 v214, v216, v213
	s_waitcnt lgkmcnt(0)
	v_add_f32_e32 v213, v213, v214
	s_mov_b64 exec, 0xffff
	global_atomic_add_f32 v208, v213, s[12:13]
	s_mov_b64 exec, -1
	v_add_u32_e32 v212, 0x40000, v210
	global_load_dwordx4 v[176:179], v212, s[36:37]
	global_load_dwordx4 v[180:183], v212, s[36:37] offset:16
	global_load_dwordx4 v[184:187], v212, s[36:37] offset:512
	global_load_dwordx4 v[188:191], v212, s[36:37] offset:528
	s_waitcnt vmcnt(7)
	v_pk_add_f32 v[108:109], v[108:109], v[192:193]
	v_pk_add_f32 v[110:111], v[110:111], v[194:195]
	v_pk_add_f32 v[104:105], v[104:105], v[196:197]
	v_pk_add_f32 v[106:107], v[106:107], v[198:199]
	v_mul_f32_e32 v213, v108, v108
	v_fmac_f32_e32 v213, v109, v109
	v_fmac_f32_e32 v213, v110, v110
	v_fmac_f32_e32 v213, v111, v111
	v_fmac_f32_e32 v213, v104, v104
	v_fmac_f32_e32 v213, v105, v105
	v_fmac_f32_e32 v213, v106, v106
	v_fmac_f32_e32 v213, v107, v107
	v_cvt_pk_bf16_f32 v192, v108, v109
	v_cvt_pk_bf16_f32 v193, v110, v111
	v_cvt_pk_bf16_f32 v194, v104, v105
	v_cvt_pk_bf16_f32 v195, v106, v107
	v_add_u32_e32 v217, 0x10000, v209
	global_store_dwordx4 v217, v[192:195], s[80:81]
	v_pk_add_f32 v[100:101], v[100:101], v[200:201]
	v_pk_add_f32 v[102:103], v[102:103], v[202:203]
	v_pk_add_f32 v[96:97], v[96:97], v[204:205]
	v_pk_add_f32 v[98:99], v[98:99], v[206:207]
	v_fmac_f32_e32 v213, v100, v100
	v_fmac_f32_e32 v213, v101, v101
	v_fmac_f32_e32 v213, v102, v102
	v_fmac_f32_e32 v213, v103, v103
	v_fmac_f32_e32 v213, v96, v96
	v_fmac_f32_e32 v213, v97, v97
	v_fmac_f32_e32 v213, v98, v98
	v_fmac_f32_e32 v213, v99, v99
	v_cvt_pk_bf16_f32 v200, v100, v101
	v_cvt_pk_bf16_f32 v201, v102, v103
	v_cvt_pk_bf16_f32 v202, v96, v97
	v_cvt_pk_bf16_f32 v203, v98, v99
	global_store_dwordx4 v217, v[200:203], s[80:81] offset:256
	ds_bpermute_b32 v214, v215, v213
	s_waitcnt lgkmcnt(0)
	v_add_f32_e32 v213, v213, v214
	ds_bpermute_b32 v214, v216, v213
	s_waitcnt lgkmcnt(0)
	v_add_f32_e32 v213, v213, v214
	s_mov_b64 exec, 0xffff
	global_atomic_add_f32 v208, v213, s[12:13] offset:64
	s_mov_b64 exec, -1
	v_add_u32_e32 v212, 0x60000, v210
	global_load_dwordx4 v[192:195], v212, s[36:37]
	global_load_dwordx4 v[196:199], v212, s[36:37] offset:16
	global_load_dwordx4 v[200:203], v212, s[36:37] offset:512
	global_load_dwordx4 v[204:207], v212, s[36:37] offset:528
	s_waitcnt vmcnt(7)
	v_pk_add_f32 v[92:93], v[92:93], v[176:177]
	v_pk_add_f32 v[94:95], v[94:95], v[178:179]
	v_pk_add_f32 v[88:89], v[88:89], v[180:181]
	v_pk_add_f32 v[90:91], v[90:91], v[182:183]
	v_mul_f32_e32 v213, v92, v92
	v_fmac_f32_e32 v213, v93, v93
	v_fmac_f32_e32 v213, v94, v94
	v_fmac_f32_e32 v213, v95, v95
	v_fmac_f32_e32 v213, v88, v88
	v_fmac_f32_e32 v213, v89, v89
	v_fmac_f32_e32 v213, v90, v90
	v_fmac_f32_e32 v213, v91, v91
	v_cvt_pk_bf16_f32 v176, v92, v93
	v_cvt_pk_bf16_f32 v177, v94, v95
	v_cvt_pk_bf16_f32 v178, v88, v89
	v_cvt_pk_bf16_f32 v179, v90, v91
	v_add_u32_e32 v217, 0x20000, v209
	global_store_dwordx4 v217, v[176:179], s[80:81]
	v_pk_add_f32 v[84:85], v[84:85], v[184:185]
	v_pk_add_f32 v[86:87], v[86:87], v[186:187]
	v_pk_add_f32 v[80:81], v[80:81], v[188:189]
	v_pk_add_f32 v[82:83], v[82:83], v[190:191]
	v_fmac_f32_e32 v213, v84, v84
	v_fmac_f32_e32 v213, v85, v85
	v_fmac_f32_e32 v213, v86, v86
	v_fmac_f32_e32 v213, v87, v87
	v_fmac_f32_e32 v213, v80, v80
	v_fmac_f32_e32 v213, v81, v81
	v_fmac_f32_e32 v213, v82, v82
	v_fmac_f32_e32 v213, v83, v83
	v_cvt_pk_bf16_f32 v184, v84, v85
	v_cvt_pk_bf16_f32 v185, v86, v87
	v_cvt_pk_bf16_f32 v186, v80, v81
	v_cvt_pk_bf16_f32 v187, v82, v83
	global_store_dwordx4 v217, v[184:187], s[80:81] offset:256
	ds_bpermute_b32 v214, v215, v213
	s_waitcnt lgkmcnt(0)
	v_add_f32_e32 v213, v213, v214
	ds_bpermute_b32 v214, v216, v213
	s_waitcnt lgkmcnt(0)
	v_add_f32_e32 v213, v213, v214
	s_mov_b64 exec, 0xffff
	global_atomic_add_f32 v208, v213, s[12:13] offset:128
	s_mov_b64 exec, -1
	v_add_u32_e32 v212, 0x100000, v210
	global_load_dwordx4 v[176:179], v212, s[36:37]
	global_load_dwordx4 v[180:183], v212, s[36:37] offset:16
	global_load_dwordx4 v[184:187], v212, s[36:37] offset:512
	global_load_dwordx4 v[188:191], v212, s[36:37] offset:528
	s_waitcnt vmcnt(7)
	v_pk_add_f32 v[76:77], v[76:77], v[192:193]
	v_pk_add_f32 v[78:79], v[78:79], v[194:195]
	v_pk_add_f32 v[72:73], v[72:73], v[196:197]
	v_pk_add_f32 v[74:75], v[74:75], v[198:199]
	v_mul_f32_e32 v213, v76, v76
	v_fmac_f32_e32 v213, v77, v77
	v_fmac_f32_e32 v213, v78, v78
	v_fmac_f32_e32 v213, v79, v79
	v_fmac_f32_e32 v213, v72, v72
	v_fmac_f32_e32 v213, v73, v73
	v_fmac_f32_e32 v213, v74, v74
	v_fmac_f32_e32 v213, v75, v75
	v_cvt_pk_bf16_f32 v192, v76, v77
	v_cvt_pk_bf16_f32 v193, v78, v79
	v_cvt_pk_bf16_f32 v194, v72, v73
	v_cvt_pk_bf16_f32 v195, v74, v75
	v_add_u32_e32 v217, 0x30000, v209
	global_store_dwordx4 v217, v[192:195], s[80:81]
	v_pk_add_f32 v[68:69], v[68:69], v[200:201]
	v_pk_add_f32 v[70:71], v[70:71], v[202:203]
	v_pk_add_f32 v[64:65], v[64:65], v[204:205]
	v_pk_add_f32 v[66:67], v[66:67], v[206:207]
	v_fmac_f32_e32 v213, v68, v68
	v_fmac_f32_e32 v213, v69, v69
	v_fmac_f32_e32 v213, v70, v70
	v_fmac_f32_e32 v213, v71, v71
	v_fmac_f32_e32 v213, v64, v64
	v_fmac_f32_e32 v213, v65, v65
	v_fmac_f32_e32 v213, v66, v66
	v_fmac_f32_e32 v213, v67, v67
	v_cvt_pk_bf16_f32 v200, v68, v69
	v_cvt_pk_bf16_f32 v201, v70, v71
	v_cvt_pk_bf16_f32 v202, v64, v65
	v_cvt_pk_bf16_f32 v203, v66, v67
	global_store_dwordx4 v217, v[200:203], s[80:81] offset:256
	ds_bpermute_b32 v214, v215, v213
	s_waitcnt lgkmcnt(0)
	v_add_f32_e32 v213, v213, v214
	ds_bpermute_b32 v214, v216, v213
	s_waitcnt lgkmcnt(0)
	v_add_f32_e32 v213, v213, v214
	s_mov_b64 exec, 0xffff
	global_atomic_add_f32 v208, v213, s[12:13] offset:192
	s_mov_b64 exec, -1
	v_add_u32_e32 v212, 0x120000, v210
	global_load_dwordx4 v[192:195], v212, s[36:37]
	global_load_dwordx4 v[196:199], v212, s[36:37] offset:16
	global_load_dwordx4 v[200:203], v212, s[36:37] offset:512
	global_load_dwordx4 v[204:207], v212, s[36:37] offset:528
	s_waitcnt vmcnt(7)
	v_pk_add_f32 v[60:61], v[60:61], v[176:177]
	v_pk_add_f32 v[62:63], v[62:63], v[178:179]
	v_pk_add_f32 v[56:57], v[56:57], v[180:181]
	v_pk_add_f32 v[58:59], v[58:59], v[182:183]
	v_mul_f32_e32 v213, v60, v60
	v_fmac_f32_e32 v213, v61, v61
	v_fmac_f32_e32 v213, v62, v62
	v_fmac_f32_e32 v213, v63, v63
	v_fmac_f32_e32 v213, v56, v56
	v_fmac_f32_e32 v213, v57, v57
	v_fmac_f32_e32 v213, v58, v58
	v_fmac_f32_e32 v213, v59, v59
	v_cvt_pk_bf16_f32 v176, v60, v61
	v_cvt_pk_bf16_f32 v177, v62, v63
	v_cvt_pk_bf16_f32 v178, v56, v57
	v_cvt_pk_bf16_f32 v179, v58, v59
	v_add_u32_e32 v217, 0x80000, v209
	global_store_dwordx4 v217, v[176:179], s[80:81]
	v_pk_add_f32 v[52:53], v[52:53], v[184:185]
	v_pk_add_f32 v[54:55], v[54:55], v[186:187]
	v_pk_add_f32 v[48:49], v[48:49], v[188:189]
	v_pk_add_f32 v[50:51], v[50:51], v[190:191]
	v_fmac_f32_e32 v213, v52, v52
	v_fmac_f32_e32 v213, v53, v53
	v_fmac_f32_e32 v213, v54, v54
	v_fmac_f32_e32 v213, v55, v55
	v_fmac_f32_e32 v213, v48, v48
	v_fmac_f32_e32 v213, v49, v49
	v_fmac_f32_e32 v213, v50, v50
	v_fmac_f32_e32 v213, v51, v51
	v_cvt_pk_bf16_f32 v184, v52, v53
	v_cvt_pk_bf16_f32 v185, v54, v55
	v_cvt_pk_bf16_f32 v186, v48, v49
	v_cvt_pk_bf16_f32 v187, v50, v51
	global_store_dwordx4 v217, v[184:187], s[80:81] offset:256
	ds_bpermute_b32 v214, v215, v213
	s_waitcnt lgkmcnt(0)
	v_add_f32_e32 v213, v213, v214
	ds_bpermute_b32 v214, v216, v213
	s_waitcnt lgkmcnt(0)
	v_add_f32_e32 v213, v213, v214
	s_mov_b64 exec, 0xffff
	global_atomic_add_f32 v208, v213, s[12:13] offset:512
	s_mov_b64 exec, -1
	v_add_u32_e32 v212, 0x140000, v210
	global_load_dwordx4 v[176:179], v212, s[36:37]
	global_load_dwordx4 v[180:183], v212, s[36:37] offset:16
	global_load_dwordx4 v[184:187], v212, s[36:37] offset:512
	global_load_dwordx4 v[188:191], v212, s[36:37] offset:528
	s_waitcnt vmcnt(7)
	v_pk_add_f32 v[44:45], v[44:45], v[192:193]
	v_pk_add_f32 v[46:47], v[46:47], v[194:195]
	v_pk_add_f32 v[40:41], v[40:41], v[196:197]
	v_pk_add_f32 v[42:43], v[42:43], v[198:199]
	v_mul_f32_e32 v213, v44, v44
	v_fmac_f32_e32 v213, v45, v45
	v_fmac_f32_e32 v213, v46, v46
	v_fmac_f32_e32 v213, v47, v47
	v_fmac_f32_e32 v213, v40, v40
	v_fmac_f32_e32 v213, v41, v41
	v_fmac_f32_e32 v213, v42, v42
	v_fmac_f32_e32 v213, v43, v43
	v_cvt_pk_bf16_f32 v192, v44, v45
	v_cvt_pk_bf16_f32 v193, v46, v47
	v_cvt_pk_bf16_f32 v194, v40, v41
	v_cvt_pk_bf16_f32 v195, v42, v43
	v_add_u32_e32 v217, 0x90000, v209
	global_store_dwordx4 v217, v[192:195], s[80:81]
	v_pk_add_f32 v[36:37], v[36:37], v[200:201]
	v_pk_add_f32 v[38:39], v[38:39], v[202:203]
	v_pk_add_f32 v[32:33], v[32:33], v[204:205]
	v_pk_add_f32 v[34:35], v[34:35], v[206:207]
	v_fmac_f32_e32 v213, v36, v36
	v_fmac_f32_e32 v213, v37, v37
	v_fmac_f32_e32 v213, v38, v38
	v_fmac_f32_e32 v213, v39, v39
	v_fmac_f32_e32 v213, v32, v32
	v_fmac_f32_e32 v213, v33, v33
	v_fmac_f32_e32 v213, v34, v34
	v_fmac_f32_e32 v213, v35, v35
	v_cvt_pk_bf16_f32 v200, v36, v37
	v_cvt_pk_bf16_f32 v201, v38, v39
	v_cvt_pk_bf16_f32 v202, v32, v33
	v_cvt_pk_bf16_f32 v203, v34, v35
	global_store_dwordx4 v217, v[200:203], s[80:81] offset:256
	ds_bpermute_b32 v214, v215, v213
	s_waitcnt lgkmcnt(0)
	v_add_f32_e32 v213, v213, v214
	ds_bpermute_b32 v214, v216, v213
	s_waitcnt lgkmcnt(0)
	v_add_f32_e32 v213, v213, v214
	s_mov_b64 exec, 0xffff
	global_atomic_add_f32 v208, v213, s[12:13] offset:576
	s_mov_b64 exec, -1
	v_add_u32_e32 v212, 0x160000, v210
	global_load_dwordx4 v[192:195], v212, s[36:37]
	global_load_dwordx4 v[196:199], v212, s[36:37] offset:16
	global_load_dwordx4 v[200:203], v212, s[36:37] offset:512
	global_load_dwordx4 v[204:207], v212, s[36:37] offset:528
	s_waitcnt vmcnt(7)
	v_pk_add_f32 v[28:29], v[28:29], v[176:177]
	v_pk_add_f32 v[30:31], v[30:31], v[178:179]
	v_pk_add_f32 v[24:25], v[24:25], v[180:181]
	v_pk_add_f32 v[26:27], v[26:27], v[182:183]
	v_mul_f32_e32 v213, v28, v28
	v_fmac_f32_e32 v213, v29, v29
	v_fmac_f32_e32 v213, v30, v30
	v_fmac_f32_e32 v213, v31, v31
	v_fmac_f32_e32 v213, v24, v24
	v_fmac_f32_e32 v213, v25, v25
	v_fmac_f32_e32 v213, v26, v26
	v_fmac_f32_e32 v213, v27, v27
	v_cvt_pk_bf16_f32 v176, v28, v29
	v_cvt_pk_bf16_f32 v177, v30, v31
	v_cvt_pk_bf16_f32 v178, v24, v25
	v_cvt_pk_bf16_f32 v179, v26, v27
	v_add_u32_e32 v217, 0xa0000, v209
	global_store_dwordx4 v217, v[176:179], s[80:81]
	v_pk_add_f32 v[20:21], v[20:21], v[184:185]
	v_pk_add_f32 v[22:23], v[22:23], v[186:187]
	v_pk_add_f32 v[16:17], v[16:17], v[188:189]
	v_pk_add_f32 v[18:19], v[18:19], v[190:191]
	v_fmac_f32_e32 v213, v20, v20
	v_fmac_f32_e32 v213, v21, v21
	v_fmac_f32_e32 v213, v22, v22
	v_fmac_f32_e32 v213, v23, v23
	v_fmac_f32_e32 v213, v16, v16
	v_fmac_f32_e32 v213, v17, v17
	v_fmac_f32_e32 v213, v18, v18
	v_fmac_f32_e32 v213, v19, v19
	v_cvt_pk_bf16_f32 v184, v20, v21
	v_cvt_pk_bf16_f32 v185, v22, v23
	v_cvt_pk_bf16_f32 v186, v16, v17
	v_cvt_pk_bf16_f32 v187, v18, v19
	global_store_dwordx4 v217, v[184:187], s[80:81] offset:256
	ds_bpermute_b32 v214, v215, v213
	s_waitcnt lgkmcnt(0)
	v_add_f32_e32 v213, v213, v214
	ds_bpermute_b32 v214, v216, v213
	s_waitcnt lgkmcnt(0)
	v_add_f32_e32 v213, v213, v214
	s_mov_b64 exec, 0xffff
	global_atomic_add_f32 v208, v213, s[12:13] offset:640
	s_mov_b64 exec, -1
	s_waitcnt vmcnt(3)
	v_pk_add_f32 v[12:13], v[12:13], v[192:193]
	v_pk_add_f32 v[14:15], v[14:15], v[194:195]
	v_pk_add_f32 v[8:9], v[8:9], v[196:197]
	v_pk_add_f32 v[10:11], v[10:11], v[198:199]
	v_mul_f32_e32 v213, v12, v12
	v_fmac_f32_e32 v213, v13, v13
	v_fmac_f32_e32 v213, v14, v14
	v_fmac_f32_e32 v213, v15, v15
	v_fmac_f32_e32 v213, v8, v8
	v_fmac_f32_e32 v213, v9, v9
	v_fmac_f32_e32 v213, v10, v10
	v_fmac_f32_e32 v213, v11, v11
	v_cvt_pk_bf16_f32 v192, v12, v13
	v_cvt_pk_bf16_f32 v193, v14, v15
	v_cvt_pk_bf16_f32 v194, v8, v9
	v_cvt_pk_bf16_f32 v195, v10, v11
	v_add_u32_e32 v217, 0xb0000, v209
	global_store_dwordx4 v217, v[192:195], s[80:81]
	v_pk_add_f32 v[4:5], v[4:5], v[200:201]
	v_pk_add_f32 v[6:7], v[6:7], v[202:203]
	v_pk_add_f32 v[0:1], v[0:1], v[204:205]
	v_pk_add_f32 v[2:3], v[2:3], v[206:207]
	v_fmac_f32_e32 v213, v4, v4
	v_fmac_f32_e32 v213, v5, v5
	v_fmac_f32_e32 v213, v6, v6
	v_fmac_f32_e32 v213, v7, v7
	v_fmac_f32_e32 v213, v0, v0
	v_fmac_f32_e32 v213, v1, v1
	v_fmac_f32_e32 v213, v2, v2
	v_fmac_f32_e32 v213, v3, v3
	v_cvt_pk_bf16_f32 v200, v4, v5
	v_cvt_pk_bf16_f32 v201, v6, v7
	v_cvt_pk_bf16_f32 v202, v0, v1
	v_cvt_pk_bf16_f32 v203, v2, v3
	global_store_dwordx4 v217, v[200:203], s[80:81] offset:256
	ds_bpermute_b32 v214, v215, v213
	s_waitcnt lgkmcnt(0)
	v_add_f32_e32 v213, v213, v214
	ds_bpermute_b32 v214, v216, v213
	s_waitcnt lgkmcnt(0)
	v_add_f32_e32 v213, v213, v214
	s_mov_b64 exec, 0xffff
	global_atomic_add_f32 v208, v213, s[12:13] offset:704
	s_mov_b64 exec, -1
	s_branch .LBB0_273
.LBB0_300:
	s_waitcnt vmcnt(0)
	s_cmpk_gt_u32 s3, 0xff
	s_cbranch_scc1 .LBB0_302
	s_nop 0

.LBB0_355:
	s_or_b64 exec, exec, s[0:1]
	s_add_u32 s70, s92, 0x1bd00000
	s_addc_u32 s71, s93, 0
	s_cmpk_lt_i32 s2, 0xb00
	s_cselect_b64 s[0:1], -1, 0
	s_waitcnt lgkmcnt(0)
	v_lshlrev_b32_e32 v0, 6, v163
	v_writelane_b32 v255, s0, 10
	v_readfirstlane_b32 s3, v222
	v_bitop3_b32 v230, v227, v152, v0 bitop3:0x36
	v_writelane_b32 v255, s1, 11
	s_cmpk_gt_i32 s2, 0xaff
	v_and_b32_e32 v220, 48, v144
	v_lshlrev_b32_e32 v223, 1, v144
	v_and_b32_e32 v221, 48, v153
	v_lshlrev_b32_e32 v254, 1, v153
	s_barrier
	s_cbranch_scc1 .LBB0_377
	s_add_u32 s40, s92, 0x2100000
	s_addc_u32 s41, s93, 0
	s_lshr_b32 s0, s77, 29
	s_add_i32 s0, s2, s0
	s_lshr_b32 s10, s3, 6
	s_ashr_i32 s1, s0, 3
	s_and_b32 s0, s0, -8
	s_lshr_b32 s5, s3, 8
	s_lshl_b32 s42, s10, 10
	s_sub_i32 s0, s2, s0
	s_cmp_lt_i32 s0, 0
	s_movk_i32 s43, 0x161
	s_cselect_b32 s4, s43, 0x160
	s_mul_i32 s0, s4, s0
	s_add_i32 s0, s0, s1
	s_mul_hi_i32 s1, s0, 0x2e8ba2e9
	s_lshr_b32 s4, s1, 31
	s_ashr_i32 s1, s1, 5
	s_add_i32 s1, s1, s4
	s_lshl_b32 s6, s1, 2
	s_mulk_i32 s1, 0xb0
	s_sub_i32 s0, s0, s1
	s_sext_i32_i16 s1, s0
	s_bfe_u32 s1, s1, 0x2001d
	s_add_i32 s1, s0, s1
	s_sext_i32_i16 s4, s1
	s_and_b32 s1, s1, 0xfffc
	s_sub_i32 s0, s0, s1
	s_sext_i32_i16 s0, s0
	s_lshr_b32 s4, s4, 2
	s_add_i32 s0, s6, s0
	s_ashr_i32 s1, s0, 31
	s_bfe_i64 s[8:9], s[4:5], 0x100000
	s_lshl_b64 s[6:7], s[0:1], 20
	s_lshl_b64 s[8:9], s[8:9], 19
	s_add_u32 s8, s40, s8
	s_addc_u32 s9, s41, s9
	s_add_i32 s44, s42, 0
	v_and_b32_e32 v8, 0x180, v223
	s_add_i32 m0, s44, 0x10000
	v_or3_b32 v0, v220, v8, v218
	v_and_b32_e32 v9, 0x80, v254
	v_and_b32_e32 v183, 63, v222
	v_lshrrev_b32_e32 v184, 3, v183
	v_lshrrev_b32_e32 v185, 6, v222
	v_lshl_add_u32 v186, v185, 3, v184
	v_and_b32_e32 v187, 7, v183
	v_and_b32_e32 v188, 6, v184
	v_xor_b32_e32 v187, v187, v188
	v_lshlrev_b32_e32 v187, 4, v187
	v_mul_u32_u24_e32 v188, 0x1000, v186
	v_add_u32_e32 v188, v188, v187
	v_add_u32_e32 v168, 0x80000, v188
	v_mov_b32_e32 v170, v188
	v_add_u32_e32 v172, 0x40080, v188
	v_add_u32_e32 v174, 0xc0080, v188
	v_add_u32_e32 v168, 0x80000, v188
	v_add_u32_e32 v174, 0xc0080, v188
	v_and_b32_e32 v188, 31, v186
	v_and_b32_e32 v189, 12, v188
	v_lshlrev_b32_e32 v189, 1, v189
	v_lshrrev_b32_e32 v190, 4, v188
	v_lshlrev_b32_e32 v190, 2, v190
	v_and_b32_e32 v188, 3, v188
	v_or3_b32 v188, v189, v190, v188
	v_and_b32_e32 v189, 0x60, v186
	v_add_u32_e32 v188, v188, v189
	v_mul_u32_u24_e32 v188, 0x1000, v188
	v_add_u32_e32 v188, v188, v187
	v_mov_b32_e32 v164, v188
	v_add_u32_e32 v166, 0x40000, v188
	v_add_u32_e32 v166, 0x40000, v188
	v_and_b32_e32 v188, 15, v183
	v_lshrrev_b32_e32 v189, 4, v183
	v_and_b32_e32 v190, 6, v188
	v_xor_b32_e32 v189, v189, v190
	v_lshlrev_b32_e32 v189, 4, v189
	v_lshl_or_b32 v189, v188, 7, v189
	v_lshrrev_b32_e32 v190, 2, v185
	v_lshl_add_u32 v190, v190, 13, v189
	v_add_u32_e32 v241, 0x0, v190
	v_and_b32_e32 v188, 3, v185
	v_lshl_add_u32 v188, v188, 12, v189
	v_add_u32_e32 v229, 0x0, v188
	v_add_u32_e32 v231, 0x10000, v188
	v_add_u32_e32 v242, 0x14000, v188
	v_mov_b32_e32 v173, 0x0
	v_mov_b32_e32 v175, 0x0
	s_add_i32 m0, s44, 0x12000
	v_or3_b32 v0, v221, v9, v218
	s_add_u32 s6, s80, s6
	s_addc_u32 s7, s81, s7
	s_mov_b32 m0, s44
	s_add_i32 s45, s44, 0x2000
	s_mov_b32 m0, s45
	s_add_u32 s14, s8, 0x1600000
	s_addc_u32 s15, s9, 0
	s_add_i32 m0, s44, 0x14000
	v_mov_b32_e32 v165, 0
	s_add_i32 m0, s44, 0x16000
	v_mov_b32_e32 v167, v165
	s_add_u32 s14, s6, 0x40000
	s_addc_u32 s15, s7, 0
	s_add_i32 s46, s44, 0x4000
	s_mov_b32 m0, s46
	s_add_i32 s47, s44, 0x6000
	s_mov_b32 m0, s47
	v_mov_b32_e32 v171, v165
	v_mov_b32_e32 v169, v165
	s_mov_b32 s48, 0
	v_lshl_add_u64 v[6:7], s[8:9], 0, v[164:165]
	v_lshl_add_u64 v[4:5], s[8:9], 0, v[166:167]
	v_lshl_add_u64 v[2:3], s[6:7], 0, v[170:171]
	s_cmp_lg_u32 s5, 1
	v_lshl_add_u64 v[0:1], s[6:7], 0, v[168:169]
	s_cbranch_scc1 .LBB0_358
.LBB0_358:
	s_mov_b64 s[14:15], 0x80
	s_lshl_b32 s1, s10, 5
	s_add_i32 m0, s44, 0x18000
	v_lshl_add_u64 v[6:7], v[6:7], 0, s[14:15]
	s_and_b32 s49, s1, 0x60
	v_lshl_add_u64 v[4:5], v[4:5], 0, s[14:15]
	s_add_i32 m0, s44, 0x1a000
	s_add_i32 s52, s44, 0x8000
	s_add_i32 s53, s44, 0xa000
	v_lshl_add_u64 v[2:3], v[2:3], 0, s[14:15]
	s_mov_b32 m0, s52
	s_add_u32 s10, s8, 0x1600080
	v_lshl_add_u64 v[0:1], v[0:1], 0, s[14:15]
	s_mov_b32 m0, s53
	s_addc_u32 s11, s9, 0
	s_add_i32 m0, s44, 0x1c000
	v_lshl_add_u64 v[0:1], s[10:11], 0, v[164:165]
	v_lshl_add_u64 v[0:1], s[10:11], 0, v[166:167]
	s_add_i32 m0, s44, 0x1e000
	s_ashr_i32 s54, s94, 31
	s_lshl_b32 s56, s5, 7
	s_lshl_b32 s57, s5, 2
	s_add_u32 s16, s82, 0xb000
	s_addc_u32 s17, s83, 0
	s_add_u32 s18, s82, 0x16000
	s_addc_u32 s19, s83, 0
	s_add_u32 s20, s82, 0x5800
	s_addc_u32 s21, s83, 0
	s_add_u32 s22, s82, 0x10800
	v_add3_u32 v0, v9, v221, v218
	s_addc_u32 s23, s83, 0
	v_lshl_or_b32 v0, v0, 12, v226
	s_sext_i32_i16 s1, s4
	v_lshl_or_b32 v2, s5, 13, v230
	s_add_u32 s24, s82, 0x1b800
	v_add_u32_e32 v0, v0, v224
	v_mov_b32_e32 v1, v165
	s_mov_b64 s[4:5], 0x40080
	s_addc_u32 s25, s83, 0
	v_add3_u32 v0, v8, v220, v218
	s_add_u32 s26, s84, 0x5800
	v_lshl_or_b32 v0, v0, 12, v226
	s_addc_u32 s27, s85, 0
	v_add_u32_e32 v0, v0, v224
	s_add_i32 s58, 0, 0x10000
	s_add_i32 s59, 0, 0x14000
	s_mov_b32 s55, s94
	v_mov_b64_e32 v[176:177], 0xb00
	v_mov_b64_e32 v[178:179], 0xaff
	v_mov_b32_e32 v243, 0x3727c5ac
	s_mov_b32 s60, 0xb000
	s_movk_i32 s61, 0x2c00
	v_and_b32_e32 v76, 63, v222
	v_lshrrev_b32_e32 v77, 6, v222
	v_lshrrev_b32_e32 v78, 3, v76
	v_lshl_add_u32 v79, v77, 3, v78
	v_and_b32_e32 v80, 7, v76
	v_and_b32_e32 v81, 6, v78
	v_xor_b32_e32 v80, v80, v81
	v_lshlrev_b32_e32 v80, 4, v80
	v_mul_u32_u24_e32 v81, 0x1000, v79
	v_add_u32_e32 v108, v81, v80
	v_and_b32_e32 v81, 31, v79
	v_and_b32_e32 v78, 12, v81
	v_lshlrev_b32_e32 v78, 1, v78
	v_lshrrev_b32_e32 v109, 4, v81
	v_lshlrev_b32_e32 v109, 2, v109
	v_and_b32_e32 v81, 3, v81
	v_or3_b32 v81, v78, v109, v81
	v_and_b32_e32 v78, 0x60, v79
	v_add_u32_e32 v81, v81, v78
	v_mul_u32_u24_e32 v81, 0x1000, v81
	v_add_u32_e32 v109, v81, v80
	v_and_b32_e32 v78, 15, v76
	v_lshrrev_b32_e32 v79, 4, v76
	v_and_b32_e32 v80, 6, v78
	v_xor_b32_e32 v79, v79, v80
	v_lshlrev_b32_e32 v79, 4, v79
	v_lshl_or_b32 v79, v78, 7, v79
	v_lshrrev_b32_e32 v80, 2, v77
	v_lshl_add_u32 v212, v80, 13, v79
	v_xor_b32_e32 v213, 64, v212
	v_and_b32_e32 v80, 3, v77
	v_lshl_add_u32 v214, v80, 12, v79
	v_add_u32_e32 v214, 0x10000, v214
	v_xor_b32_e32 v215, 64, v214
	v_readfirstlane_b32 s66, v222
	s_nop 3
	s_lshr_b32 s66, s66, 6
	s_lshl_b32 s66, s66, 10
	s_mov_b32 s98, 0
	s_mul_i32 s10, s98, s94
	s_add_i32 s10, s10, s2
	s_and_b32 s11, s10, 7
	s_lshr_b32 s10, s10, 3
	s_mul_i32 s11, s11, 0x160
	s_add_i32 s10, s10, s11
	s_mul_i32 s11, s10, 0x1745e
	s_lshr_b32 s11, s11, 24
	s_mul_i32 s39, s11, 0xb0
	s_sub_i32 s10, s10, s39
	s_and_b32 s38, s10, 3
	s_lshl_b32 s11, s11, 2
	s_add_i32 s38, s38, s11
	s_lshr_b32 s39, s10, 2
	s_mul_i32 s100, s38, 0x100000
	s_add_u32 s6, s92, 0xbd00000
	s_addc_u32 s7, s93, 0
	s_add_u32 s6, s6, s100
	s_addc_u32 s7, s7, 0
	s_mul_i32 s100, s39, 0x80000
	s_add_u32 s8, s92, 0x2100000
	s_addc_u32 s9, s93, 0
	s_add_u32 s8, s8, s100
	s_addc_u32 s9, s9, 0
	s_add_i32 m0, s66, 0x0
	s_nop 0
	global_load_lds_dwordx4 v108, s[6:7]
	s_add_i32 m0, s66, 0x2000
	s_add_u32 s64, s6, 0x80000
	s_addc_u32 s65, s7, 0
	s_nop 0
	global_load_lds_dwordx4 v108, s[64:65]
	s_add_i32 m0, s66, 0x4000
	s_add_u32 s64, s6, 0x40000
	s_addc_u32 s65, s7, 0
	s_nop 0
	global_load_lds_dwordx4 v108, s[64:65]
	s_add_i32 m0, s66, 0x6000
	s_add_u32 s64, s6, 0xc0000
	s_addc_u32 s65, s7, 0
	s_nop 0
	global_load_lds_dwordx4 v108, s[64:65]
	s_add_i32 m0, s66, 0x10000
	s_nop 0
	global_load_lds_dwordx4 v109, s[8:9]
	s_add_i32 m0, s66, 0x12000
	s_add_u32 s64, s8, 0x40000
	s_addc_u32 s65, s9, 0
	s_nop 0
	global_load_lds_dwordx4 v109, s[64:65]
	s_add_i32 m0, s66, 0x14000
	s_add_u32 s64, s8, 0x1600000
	s_addc_u32 s65, s9, 0
	s_nop 0
	global_load_lds_dwordx4 v109, s[64:65]
	s_add_i32 m0, s66, 0x16000
	s_add_u32 s64, s8, 0x1640000
	s_addc_u32 s65, s9, 0
	s_nop 0
	global_load_lds_dwordx4 v109, s[64:65]
	s_add_u32 s6, s6, 128
	s_addc_u32 s7, s7, 0
	s_add_u32 s8, s8, 128
	s_addc_u32 s9, s9, 0
	s_add_i32 m0, s66, 0x8000
	s_nop 0
	global_load_lds_dwordx4 v108, s[6:7]
	s_add_i32 m0, s66, 0xa000
	s_add_u32 s64, s6, 0x80000
	s_addc_u32 s65, s7, 0
	s_nop 0
	global_load_lds_dwordx4 v108, s[64:65]
	s_add_i32 m0, s66, 0xc000
	s_add_u32 s64, s6, 0x40000
	s_addc_u32 s65, s7, 0
	s_nop 0
	global_load_lds_dwordx4 v108, s[64:65]
	s_add_i32 m0, s66, 0xe000
	s_add_u32 s64, s6, 0xc0000
	s_addc_u32 s65, s7, 0
	s_nop 0
	global_load_lds_dwordx4 v108, s[64:65]
	s_add_i32 m0, s66, 0x18000
	s_nop 0
	global_load_lds_dwordx4 v109, s[8:9]
	s_add_i32 m0, s66, 0x1a000
	s_add_u32 s64, s8, 0x40000
	s_addc_u32 s65, s9, 0
	s_nop 0
	global_load_lds_dwordx4 v109, s[64:65]
	s_add_i32 m0, s66, 0x1c000
	s_add_u32 s64, s8, 0x1600000
	s_addc_u32 s65, s9, 0
	s_nop 0
	global_load_lds_dwordx4 v109, s[64:65]
	s_add_i32 m0, s66, 0x1e000
	s_add_u32 s64, s8, 0x1640000
	s_addc_u32 s65, s9, 0
	s_nop 0
	global_load_lds_dwordx4 v109, s[64:65]
	s_branch .LBB0_360

.LBB0_362:
	s_ashr_i32 s31, s30, 31
	v_cmp_lt_i64_e32 vcc, s[10:11], v[176:177]
	s_lshl_b64 s[10:11], s[30:31], 20
	s_add_u32 s34, s80, s10
	s_addc_u32 s35, s81, s11
	s_and_b64 s[10:11], vcc, exec
	s_cselect_b32 s31, s35, s7
	s_cselect_b32 s33, s34, s6
	s_ashr_i32 s29, s28, 31
	s_lshl_b64 s[10:11], s[28:29], 19
	s_add_u32 s36, s40, s10
	s_addc_u32 s37, s41, s11
	s_and_b64 s[10:11], vcc, exec
	s_cselect_b32 s29, s37, s9
	s_cselect_b32 s62, s36, s8
	s_add_u32 s63, s8, 0x100
	v_mov_b32_e32 v0, 0
	s_addc_u32 s64, s9, 0
	s_mov_b32 s65, -2
	v_mov_b32_e32 v1, v0
	v_mov_b32_e32 v2, v0
	v_mov_b32_e32 v3, v0
	v_mov_b32_e32 v64, v0
	v_mov_b32_e32 v65, v0
	v_mov_b32_e32 v66, v0
	v_mov_b32_e32 v67, v0
	v_mov_b32_e32 v8, v0
	v_mov_b32_e32 v9, v0
	s_waitcnt vmcnt(0)
	v_mov_b32_e32 v10, v0
	v_mov_b32_e32 v11, v0
	v_mov_b32_e32 v68, v0
	v_mov_b32_e32 v69, v0
	v_mov_b32_e32 v70, v0
	v_mov_b32_e32 v71, v0
	v_mov_b32_e32 v12, v0
	v_mov_b32_e32 v13, v0
	v_mov_b32_e32 v14, v0
	v_mov_b32_e32 v15, v0
	v_mov_b32_e32 v110, v0
	v_mov_b32_e32 v111, v0
	v_mov_b32_e32 v112, v0
	v_mov_b32_e32 v113, v0
	v_mov_b32_e32 v16, v0
	v_mov_b32_e32 v17, v0
	v_mov_b32_e32 v18, v0
	v_mov_b32_e32 v19, v0
	v_mov_b32_e32 v118, v0
	v_mov_b32_e32 v119, v0
	v_mov_b32_e32 v120, v0
	v_mov_b32_e32 v121, v0
	v_mov_b32_e32 v4, v0
	v_mov_b32_e32 v5, v0
	v_mov_b32_e32 v6, v0
	v_mov_b32_e32 v7, v0
	v_mov_b32_e32 v72, v0
	v_mov_b32_e32 v73, v0
	v_mov_b32_e32 v74, v0
	v_mov_b32_e32 v75, v0
	v_mov_b32_e32 v20, v0
	v_mov_b32_e32 v21, v0
	v_mov_b32_e32 v22, v0
	v_mov_b32_e32 v23, v0
	v_mov_b32_e32 v114, v0
	v_mov_b32_e32 v115, v0
	v_mov_b32_e32 v116, v0
	v_mov_b32_e32 v117, v0
	v_mov_b32_e32 v24, v0
	v_mov_b32_e32 v25, v0
	v_mov_b32_e32 v26, v0
	v_mov_b32_e32 v27, v0
	v_mov_b32_e32 v122, v0
	v_mov_b32_e32 v123, v0
	v_mov_b32_e32 v124, v0
	v_mov_b32_e32 v125, v0
	v_mov_b32_e32 v28, v0
	v_mov_b32_e32 v29, v0
	v_mov_b32_e32 v30, v0
	v_mov_b32_e32 v31, v0
	v_mov_b32_e32 v126, v0
	v_mov_b32_e32 v127, v0
	v_mov_b32_e32 v128, v0
	v_mov_b32_e32 v129, v0
	v_mov_b32_e32 v32, v0
	v_mov_b32_e32 v33, v0
	v_mov_b32_e32 v34, v0
	v_mov_b32_e32 v35, v0
	v_mov_b32_e32 v130, v0
	v_mov_b32_e32 v131, v0
	v_mov_b32_e32 v132, v0
	v_mov_b32_e32 v133, v0
	v_mov_b32_e32 v36, v0
	v_mov_b32_e32 v37, v0
	v_mov_b32_e32 v38, v0
	v_mov_b32_e32 v39, v0
	v_mov_b32_e32 v134, v0
	v_mov_b32_e32 v135, v0
	v_mov_b32_e32 v136, v0
	v_mov_b32_e32 v137, v0
	v_mov_b32_e32 v44, v0
	v_mov_b32_e32 v45, v0
	v_mov_b32_e32 v46, v0
	v_mov_b32_e32 v47, v0
	v_mov_b32_e32 v142, v0
	v_mov_b32_e32 v143, v0
	v_mov_b32_e32 v144, v0
	v_mov_b32_e32 v145, v0
	v_mov_b32_e32 v56, v0
	v_mov_b32_e32 v57, v0
	v_mov_b32_e32 v58, v0
	v_mov_b32_e32 v59, v0
	v_mov_b32_e32 v154, v0
	v_mov_b32_e32 v155, v0
	v_mov_b32_e32 v156, v0
	v_mov_b32_e32 v157, v0
	v_mov_b32_e32 v40, v0
	v_mov_b32_e32 v41, v0
	v_mov_b32_e32 v42, v0
	v_mov_b32_e32 v43, v0
	v_mov_b32_e32 v138, v0
	v_mov_b32_e32 v139, v0
	v_mov_b32_e32 v140, v0
	v_mov_b32_e32 v141, v0
	v_mov_b32_e32 v48, v0
	v_mov_b32_e32 v49, v0
	v_mov_b32_e32 v50, v0
	v_mov_b32_e32 v51, v0
	v_mov_b32_e32 v146, v0
	v_mov_b32_e32 v147, v0
	v_mov_b32_e32 v148, v0
	v_mov_b32_e32 v149, v0
	v_mov_b32_e32 v52, v0
	v_mov_b32_e32 v53, v0
	v_mov_b32_e32 v54, v0
	v_mov_b32_e32 v55, v0
	v_mov_b32_e32 v150, v0
	v_mov_b32_e32 v151, v0
	v_mov_b32_e32 v152, v0
	v_mov_b32_e32 v153, v0
	v_mov_b32_e32 v60, v0
	v_mov_b32_e32 v61, v0
	v_mov_b32_e32 v62, v0
	v_mov_b32_e32 v63, v0
	v_mov_b32_e32 v158, v0
	v_mov_b32_e32 v159, v0
	v_mov_b32_e32 v160, v0
	v_mov_b32_e32 v161, v0
	v_and_b32_e32 v76, 63, v222
	v_lshrrev_b32_e32 v77, 6, v222
	v_lshrrev_b32_e32 v78, 3, v76
	v_lshl_add_u32 v79, v77, 3, v78
	v_and_b32_e32 v80, 7, v76
	v_and_b32_e32 v81, 6, v78
	v_xor_b32_e32 v80, v80, v81
	v_lshlrev_b32_e32 v80, 4, v80
	v_mul_u32_u24_e32 v81, 0x1000, v79
	v_add_u32_e32 v108, v81, v80
	v_and_b32_e32 v81, 31, v79
	v_and_b32_e32 v78, 12, v81
	v_lshlrev_b32_e32 v78, 1, v78
	v_lshrrev_b32_e32 v109, 4, v81
	v_lshlrev_b32_e32 v109, 2, v109
	v_and_b32_e32 v81, 3, v81
	v_or3_b32 v81, v78, v109, v81
	v_and_b32_e32 v78, 0x60, v79
	v_add_u32_e32 v81, v81, v78
	v_mul_u32_u24_e32 v81, 0x1000, v81
	v_add_u32_e32 v109, v81, v80
	v_and_b32_e32 v78, 15, v76
	v_lshrrev_b32_e32 v79, 4, v76
	v_and_b32_e32 v80, 6, v78
	v_xor_b32_e32 v79, v79, v80
	v_lshlrev_b32_e32 v79, 4, v79
	v_lshl_or_b32 v79, v78, 7, v79
	v_lshrrev_b32_e32 v80, 2, v77
	v_lshl_add_u32 v212, v80, 13, v79
	v_xor_b32_e32 v213, 64, v212
	v_and_b32_e32 v80, 3, v77
	v_lshl_add_u32 v214, v80, 12, v79
	v_add_u32_e32 v214, 0x10000, v214
	v_xor_b32_e32 v215, 64, v214
	v_readfirstlane_b32 s66, v222
	s_nop 3
	s_lshr_b32 s66, s66, 6
	s_lshl_b32 s66, s66, 10
	s_mul_i32 s10, s98, s94
	s_add_i32 s10, s10, s2
	s_and_b32 s11, s10, 7
	s_lshr_b32 s10, s10, 3
	s_mul_i32 s11, s11, 0x160
	s_add_i32 s10, s10, s11
	s_mul_i32 s11, s10, 0x1745e
	s_lshr_b32 s11, s11, 24
	s_mul_i32 s100, s11, 0xb0
	s_sub_i32 s10, s10, s100
	s_and_b32 s63, s10, 3
	s_lshl_b32 s11, s11, 2
	s_add_i32 s63, s63, s11
	s_lshr_b32 s100, s10, 2
	s_mul_i32 s99, s63, 0x100000
	s_add_u32 s6, s92, 0xbd00100
	s_addc_u32 s7, s93, 0
	s_add_u32 s6, s6, s99
	s_addc_u32 s7, s7, 0
	s_mul_i32 s99, s100, 0x80000
	s_add_u32 s8, s92, 0x2100100
	s_addc_u32 s9, s93, 0
	s_add_u32 s8, s8, s99
	s_addc_u32 s9, s9, 0
	s_add_i32 s98, s98, 1
	s_mul_i32 s38, s98, s94
	s_add_i32 s38, s38, s2
	s_cmp_lt_u32 s38, 0xb00
	s_cbranch_scc0 .Ls3_nonext
	s_mul_i32 s10, s98, s94
	s_add_i32 s10, s10, s2
	s_and_b32 s11, s10, 7
	s_lshr_b32 s10, s10, 3
	s_mul_i32 s11, s11, 0x160
	s_add_i32 s10, s10, s11
	s_mul_i32 s11, s10, 0x1745e
	s_lshr_b32 s11, s11, 24
	s_mul_i32 s100, s11, 0xb0
	s_sub_i32 s10, s10, s100
	s_and_b32 s63, s10, 3
	s_lshl_b32 s11, s11, 2
	s_add_i32 s63, s63, s11
	s_lshr_b32 s100, s10, 2
.Ls3_nonext:
	s_mul_i32 s99, s63, 0x100000
	s_add_u32 s10, s92, 0xbd00000
	s_addc_u32 s11, s93, 0
	s_add_u32 s10, s10, s99
	s_addc_u32 s11, s11, 0
	s_mul_i32 s99, s100, 0x80000
	s_add_u32 s38, s92, 0x2100000
	s_addc_u32 s39, s93, 0
	s_add_u32 s38, s38, s99
	s_addc_u32 s39, s39, 0
	s_waitcnt vmcnt(0)
	s_barrier
	ds_read_b128 v[76:79], v212
	ds_read_b128 v[80:83], v212 offset:2048
	ds_read_b128 v[180:183], v214
	ds_read_b128 v[184:187], v214 offset:2048
	ds_read_b128 v[188:191], v214 offset:16384
	ds_read_b128 v[192:195], v214 offset:18432
	ds_read_b128 v[84:87], v212 offset:4096
	ds_read_b128 v[88:91], v212 offset:6144
	ds_read_b128 v[92:95], v212 offset:16384
	ds_read_b128 v[96:99], v212 offset:18432
	ds_read_b128 v[100:103], v212 offset:20480
	ds_read_b128 v[104:107], v212 offset:22528
	s_mov_b32 s63, 0
.Ls3_loop:
	s_cmp_eq_u32 s63, 15
	s_cselect_b32 s6, s10, s6
	s_cselect_b32 s7, s11, s7
	s_cselect_b32 s8, s38, s8
	s_cselect_b32 s9, s39, s9
	s_waitcnt lgkmcnt(6)
	v_mfma_f32_16x16x32_bf16 v[158:161], v[180:183], v[76:79], v[158:161]
	v_mfma_f32_16x16x32_bf16 v[60:63], v[184:187], v[76:79], v[60:63]
	v_mfma_f32_16x16x32_bf16 v[154:157], v[188:191], v[76:79], v[154:157]
	v_mfma_f32_16x16x32_bf16 v[56:59], v[192:195], v[76:79], v[56:59]
	v_mfma_f32_16x16x32_bf16 v[150:153], v[180:183], v[80:83], v[150:153]
	v_mfma_f32_16x16x32_bf16 v[52:55], v[184:187], v[80:83], v[52:55]
	v_mfma_f32_16x16x32_bf16 v[142:145], v[188:191], v[80:83], v[142:145]
	v_mfma_f32_16x16x32_bf16 v[44:47], v[192:195], v[80:83], v[44:47]
	s_waitcnt lgkmcnt(0)
	ds_read_b128 v[76:79], v213
	ds_read_b128 v[80:83], v213 offset:2048
	ds_read_b128 v[196:199], v215
	ds_read_b128 v[200:203], v215 offset:2048
	ds_read_b128 v[204:207], v215 offset:16384
	ds_read_b128 v[208:211], v215 offset:18432
	v_mfma_f32_16x16x32_bf16 v[146:149], v[180:183], v[84:87], v[146:149]
	v_mfma_f32_16x16x32_bf16 v[48:51], v[184:187], v[84:87], v[48:51]
	v_mfma_f32_16x16x32_bf16 v[134:137], v[188:191], v[84:87], v[134:137]
	v_mfma_f32_16x16x32_bf16 v[36:39], v[192:195], v[84:87], v[36:39]
	ds_read_b128 v[84:87], v213 offset:4096
	v_mfma_f32_16x16x32_bf16 v[138:141], v[180:183], v[88:91], v[138:141]
	v_mfma_f32_16x16x32_bf16 v[40:43], v[184:187], v[88:91], v[40:43]
	v_mfma_f32_16x16x32_bf16 v[130:133], v[188:191], v[88:91], v[130:133]
	v_mfma_f32_16x16x32_bf16 v[32:35], v[192:195], v[88:91], v[32:35]
	ds_read_b128 v[88:91], v213 offset:6144
	s_waitcnt lgkmcnt(0)
	s_barrier
	s_add_i32 m0, s66, 0x10000
	v_mfma_f32_16x16x32_bf16 v[126:129], v[180:183], v[92:95], v[126:129]
	v_mfma_f32_16x16x32_bf16 v[28:31], v[184:187], v[92:95], v[28:31]
	v_mfma_f32_16x16x32_bf16 v[118:121], v[188:191], v[92:95], v[118:121]
	v_mfma_f32_16x16x32_bf16 v[16:19], v[192:195], v[92:95], v[16:19]
	ds_read_b128 v[92:95], v213 offset:16384
	global_load_lds_dwordx4 v109, s[8:9]
	s_add_i32 m0, s66, 0x12000
	s_add_u32 s64, s8, 0x40000
	s_addc_u32 s65, s9, 0
	v_mfma_f32_16x16x32_bf16 v[122:125], v[180:183], v[96:99], v[122:125]
	v_mfma_f32_16x16x32_bf16 v[24:27], v[184:187], v[96:99], v[24:27]
	v_mfma_f32_16x16x32_bf16 v[110:113], v[188:191], v[96:99], v[110:113]
	v_mfma_f32_16x16x32_bf16 v[12:15], v[192:195], v[96:99], v[12:15]
	ds_read_b128 v[96:99], v213 offset:18432
	global_load_lds_dwordx4 v109, s[64:65]
	s_add_i32 m0, s66, 0x14000
	s_add_u32 s64, s8, 0x1600000
	s_addc_u32 s65, s9, 0
	v_mfma_f32_16x16x32_bf16 v[114:117], v[180:183], v[100:103], v[114:117]
	v_mfma_f32_16x16x32_bf16 v[20:23], v[184:187], v[100:103], v[20:23]
	v_mfma_f32_16x16x32_bf16 v[68:71], v[188:191], v[100:103], v[68:71]
	v_mfma_f32_16x16x32_bf16 v[8:11], v[192:195], v[100:103], v[8:11]
	ds_read_b128 v[100:103], v213 offset:20480
	global_load_lds_dwordx4 v109, s[64:65]
	s_add_i32 m0, s66, 0x16000
	s_add_u32 s64, s8, 0x1640000
	s_addc_u32 s65, s9, 0
	v_mfma_f32_16x16x32_bf16 v[72:75], v[180:183], v[104:107], v[72:75]
	v_mfma_f32_16x16x32_bf16 v[4:7], v[184:187], v[104:107], v[4:7]
	v_mfma_f32_16x16x32_bf16 v[64:67], v[188:191], v[104:107], v[64:67]
	v_mfma_f32_16x16x32_bf16 v[0:3], v[192:195], v[104:107], v[0:3]
	ds_read_b128 v[104:107], v213 offset:22528
	global_load_lds_dwordx4 v109, s[64:65]
	s_waitcnt lgkmcnt(6)
	s_add_i32 m0, s66, 0x0
	v_mfma_f32_16x16x32_bf16 v[158:161], v[196:199], v[76:79], v[158:161]
	v_mfma_f32_16x16x32_bf16 v[60:63], v[200:203], v[76:79], v[60:63]
	v_mfma_f32_16x16x32_bf16 v[154:157], v[204:207], v[76:79], v[154:157]
	v_mfma_f32_16x16x32_bf16 v[56:59], v[208:211], v[76:79], v[56:59]
	global_load_lds_dwordx4 v108, s[6:7]
	s_add_i32 m0, s66, 0x2000
	s_add_u32 s64, s6, 0x80000
	s_addc_u32 s65, s7, 0
	v_mfma_f32_16x16x32_bf16 v[150:153], v[196:199], v[80:83], v[150:153]
	v_mfma_f32_16x16x32_bf16 v[52:55], v[200:203], v[80:83], v[52:55]
	v_mfma_f32_16x16x32_bf16 v[142:145], v[204:207], v[80:83], v[142:145]
	v_mfma_f32_16x16x32_bf16 v[44:47], v[208:211], v[80:83], v[44:47]
	global_load_lds_dwordx4 v108, s[64:65]
	s_waitcnt lgkmcnt(0)
	s_waitcnt vmcnt(6)
	s_barrier
	ds_read_b128 v[76:79], v212 offset:32768
	ds_read_b128 v[80:83], v212 offset:34816
	ds_read_b128 v[180:183], v214 offset:32768
	ds_read_b128 v[184:187], v214 offset:34816
	ds_read_b128 v[188:191], v214 offset:49152
	ds_read_b128 v[192:195], v214 offset:51200
	s_add_i32 m0, s66, 0x4000
	s_add_u32 s64, s6, 0x40000
	s_addc_u32 s65, s7, 0
	v_mfma_f32_16x16x32_bf16 v[146:149], v[196:199], v[84:87], v[146:149]
	v_mfma_f32_16x16x32_bf16 v[48:51], v[200:203], v[84:87], v[48:51]
	v_mfma_f32_16x16x32_bf16 v[134:137], v[204:207], v[84:87], v[134:137]
	v_mfma_f32_16x16x32_bf16 v[36:39], v[208:211], v[84:87], v[36:39]
	ds_read_b128 v[84:87], v212 offset:36864
	global_load_lds_dwordx4 v108, s[64:65]
	s_add_i32 m0, s66, 0x6000
	s_add_u32 s64, s6, 0xc0000
	s_addc_u32 s65, s7, 0
	v_mfma_f32_16x16x32_bf16 v[138:141], v[196:199], v[88:91], v[138:141]
	v_mfma_f32_16x16x32_bf16 v[40:43], v[200:203], v[88:91], v[40:43]
	v_mfma_f32_16x16x32_bf16 v[130:133], v[204:207], v[88:91], v[130:133]
	v_mfma_f32_16x16x32_bf16 v[32:35], v[208:211], v[88:91], v[32:35]
	ds_read_b128 v[88:91], v212 offset:38912
	global_load_lds_dwordx4 v108, s[64:65]
	v_mfma_f32_16x16x32_bf16 v[126:129], v[196:199], v[92:95], v[126:129]
	v_mfma_f32_16x16x32_bf16 v[28:31], v[200:203], v[92:95], v[28:31]
	v_mfma_f32_16x16x32_bf16 v[118:121], v[204:207], v[92:95], v[118:121]
	v_mfma_f32_16x16x32_bf16 v[16:19], v[208:211], v[92:95], v[16:19]
	ds_read_b128 v[92:95], v212 offset:49152
	v_mfma_f32_16x16x32_bf16 v[122:125], v[196:199], v[96:99], v[122:125]
	v_mfma_f32_16x16x32_bf16 v[24:27], v[200:203], v[96:99], v[24:27]
	v_mfma_f32_16x16x32_bf16 v[110:113], v[204:207], v[96:99], v[110:113]
	v_mfma_f32_16x16x32_bf16 v[12:15], v[208:211], v[96:99], v[12:15]
	ds_read_b128 v[96:99], v212 offset:51200
	v_mfma_f32_16x16x32_bf16 v[114:117], v[196:199], v[100:103], v[114:117]
	v_mfma_f32_16x16x32_bf16 v[20:23], v[200:203], v[100:103], v[20:23]
	v_mfma_f32_16x16x32_bf16 v[68:71], v[204:207], v[100:103], v[68:71]
	v_mfma_f32_16x16x32_bf16 v[8:11], v[208:211], v[100:103], v[8:11]
	ds_read_b128 v[100:103], v212 offset:53248
	v_mfma_f32_16x16x32_bf16 v[72:75], v[196:199], v[104:107], v[72:75]
	v_mfma_f32_16x16x32_bf16 v[4:7], v[200:203], v[104:107], v[4:7]
	v_mfma_f32_16x16x32_bf16 v[64:67], v[204:207], v[104:107], v[64:67]
	v_mfma_f32_16x16x32_bf16 v[0:3], v[208:211], v[104:107], v[0:3]
	ds_read_b128 v[104:107], v212 offset:55296
	s_add_u32 s6, s6, 128
	s_addc_u32 s7, s7, 0
	s_add_u32 s8, s8, 128
	s_addc_u32 s9, s9, 0
	s_waitcnt lgkmcnt(6)
	v_mfma_f32_16x16x32_bf16 v[158:161], v[180:183], v[76:79], v[158:161]
	v_mfma_f32_16x16x32_bf16 v[60:63], v[184:187], v[76:79], v[60:63]
	v_mfma_f32_16x16x32_bf16 v[154:157], v[188:191], v[76:79], v[154:157]
	v_mfma_f32_16x16x32_bf16 v[56:59], v[192:195], v[76:79], v[56:59]
	v_mfma_f32_16x16x32_bf16 v[150:153], v[180:183], v[80:83], v[150:153]
	v_mfma_f32_16x16x32_bf16 v[52:55], v[184:187], v[80:83], v[52:55]
	v_mfma_f32_16x16x32_bf16 v[142:145], v[188:191], v[80:83], v[142:145]
	v_mfma_f32_16x16x32_bf16 v[44:47], v[192:195], v[80:83], v[44:47]
	s_waitcnt lgkmcnt(0)
	ds_read_b128 v[76:79], v213 offset:32768
	ds_read_b128 v[80:83], v213 offset:34816
	ds_read_b128 v[196:199], v215 offset:32768
	ds_read_b128 v[200:203], v215 offset:34816
	ds_read_b128 v[204:207], v215 offset:49152
	ds_read_b128 v[208:211], v215 offset:51200
	v_mfma_f32_16x16x32_bf16 v[146:149], v[180:183], v[84:87], v[146:149]
	v_mfma_f32_16x16x32_bf16 v[48:51], v[184:187], v[84:87], v[48:51]
	v_mfma_f32_16x16x32_bf16 v[134:137], v[188:191], v[84:87], v[134:137]
	v_mfma_f32_16x16x32_bf16 v[36:39], v[192:195], v[84:87], v[36:39]
	ds_read_b128 v[84:87], v213 offset:36864
	v_mfma_f32_16x16x32_bf16 v[138:141], v[180:183], v[88:91], v[138:141]
	v_mfma_f32_16x16x32_bf16 v[40:43], v[184:187], v[88:91], v[40:43]
	v_mfma_f32_16x16x32_bf16 v[130:133], v[188:191], v[88:91], v[130:133]
	v_mfma_f32_16x16x32_bf16 v[32:35], v[192:195], v[88:91], v[32:35]
	ds_read_b128 v[88:91], v213 offset:38912
	s_waitcnt lgkmcnt(0)
	s_barrier
	s_add_i32 m0, s66, 0x18000
	v_mfma_f32_16x16x32_bf16 v[126:129], v[180:183], v[92:95], v[126:129]
	v_mfma_f32_16x16x32_bf16 v[28:31], v[184:187], v[92:95], v[28:31]
	v_mfma_f32_16x16x32_bf16 v[118:121], v[188:191], v[92:95], v[118:121]
	v_mfma_f32_16x16x32_bf16 v[16:19], v[192:195], v[92:95], v[16:19]
	ds_read_b128 v[92:95], v213 offset:49152
	global_load_lds_dwordx4 v109, s[8:9]
	s_add_i32 m0, s66, 0x1a000
	s_add_u32 s64, s8, 0x40000
	s_addc_u32 s65, s9, 0
	v_mfma_f32_16x16x32_bf16 v[122:125], v[180:183], v[96:99], v[122:125]
	v_mfma_f32_16x16x32_bf16 v[24:27], v[184:187], v[96:99], v[24:27]
	v_mfma_f32_16x16x32_bf16 v[110:113], v[188:191], v[96:99], v[110:113]
	v_mfma_f32_16x16x32_bf16 v[12:15], v[192:195], v[96:99], v[12:15]
	ds_read_b128 v[96:99], v213 offset:51200
	global_load_lds_dwordx4 v109, s[64:65]
	s_add_i32 m0, s66, 0x1c000
	s_add_u32 s64, s8, 0x1600000
	s_addc_u32 s65, s9, 0
	v_mfma_f32_16x16x32_bf16 v[114:117], v[180:183], v[100:103], v[114:117]
	v_mfma_f32_16x16x32_bf16 v[20:23], v[184:187], v[100:103], v[20:23]
	v_mfma_f32_16x16x32_bf16 v[68:71], v[188:191], v[100:103], v[68:71]
	v_mfma_f32_16x16x32_bf16 v[8:11], v[192:195], v[100:103], v[8:11]
	ds_read_b128 v[100:103], v213 offset:53248
	global_load_lds_dwordx4 v109, s[64:65]
	s_add_i32 m0, s66, 0x1e000
	s_add_u32 s64, s8, 0x1640000
	s_addc_u32 s65, s9, 0
	v_mfma_f32_16x16x32_bf16 v[72:75], v[180:183], v[104:107], v[72:75]
	v_mfma_f32_16x16x32_bf16 v[4:7], v[184:187], v[104:107], v[4:7]
	v_mfma_f32_16x16x32_bf16 v[64:67], v[188:191], v[104:107], v[64:67]
	v_mfma_f32_16x16x32_bf16 v[0:3], v[192:195], v[104:107], v[0:3]
	ds_read_b128 v[104:107], v213 offset:55296
	global_load_lds_dwordx4 v109, s[64:65]
	s_waitcnt lgkmcnt(6)
	s_add_i32 m0, s66, 0x8000
	v_mfma_f32_16x16x32_bf16 v[158:161], v[196:199], v[76:79], v[158:161]
	v_mfma_f32_16x16x32_bf16 v[60:63], v[200:203], v[76:79], v[60:63]
	v_mfma_f32_16x16x32_bf16 v[154:157], v[204:207], v[76:79], v[154:157]
	v_mfma_f32_16x16x32_bf16 v[56:59], v[208:211], v[76:79], v[56:59]
	global_load_lds_dwordx4 v108, s[6:7]
	s_add_i32 m0, s66, 0xa000
	s_add_u32 s64, s6, 0x80000
	s_addc_u32 s65, s7, 0
	v_mfma_f32_16x16x32_bf16 v[150:153], v[196:199], v[80:83], v[150:153]
	v_mfma_f32_16x16x32_bf16 v[52:55], v[200:203], v[80:83], v[52:55]
	v_mfma_f32_16x16x32_bf16 v[142:145], v[204:207], v[80:83], v[142:145]
	v_mfma_f32_16x16x32_bf16 v[44:47], v[208:211], v[80:83], v[44:47]
	global_load_lds_dwordx4 v108, s[64:65]
	s_waitcnt lgkmcnt(0)
	s_waitcnt vmcnt(6)
	s_barrier
	ds_read_b128 v[76:79], v212
	ds_read_b128 v[80:83], v212 offset:2048
	ds_read_b128 v[180:183], v214
	ds_read_b128 v[184:187], v214 offset:2048
	ds_read_b128 v[188:191], v214 offset:16384
	ds_read_b128 v[192:195], v214 offset:18432
	s_add_i32 m0, s66, 0xc000
	s_add_u32 s64, s6, 0x40000
	s_addc_u32 s65, s7, 0
	v_mfma_f32_16x16x32_bf16 v[146:149], v[196:199], v[84:87], v[146:149]
	v_mfma_f32_16x16x32_bf16 v[48:51], v[200:203], v[84:87], v[48:51]
	v_mfma_f32_16x16x32_bf16 v[134:137], v[204:207], v[84:87], v[134:137]
	v_mfma_f32_16x16x32_bf16 v[36:39], v[208:211], v[84:87], v[36:39]
	ds_read_b128 v[84:87], v212 offset:4096
	global_load_lds_dwordx4 v108, s[64:65]
	s_add_i32 m0, s66, 0xe000
	s_add_u32 s64, s6, 0xc0000
	s_addc_u32 s65, s7, 0
	v_mfma_f32_16x16x32_bf16 v[138:141], v[196:199], v[88:91], v[138:141]
	v_mfma_f32_16x16x32_bf16 v[40:43], v[200:203], v[88:91], v[40:43]
	v_mfma_f32_16x16x32_bf16 v[130:133], v[204:207], v[88:91], v[130:133]
	v_mfma_f32_16x16x32_bf16 v[32:35], v[208:211], v[88:91], v[32:35]
	ds_read_b128 v[88:91], v212 offset:6144
	global_load_lds_dwordx4 v108, s[64:65]
	v_mfma_f32_16x16x32_bf16 v[126:129], v[196:199], v[92:95], v[126:129]
	v_mfma_f32_16x16x32_bf16 v[28:31], v[200:203], v[92:95], v[28:31]
	v_mfma_f32_16x16x32_bf16 v[118:121], v[204:207], v[92:95], v[118:121]
	v_mfma_f32_16x16x32_bf16 v[16:19], v[208:211], v[92:95], v[16:19]
	ds_read_b128 v[92:95], v212 offset:16384
	v_mfma_f32_16x16x32_bf16 v[122:125], v[196:199], v[96:99], v[122:125]
	v_mfma_f32_16x16x32_bf16 v[24:27], v[200:203], v[96:99], v[24:27]
	v_mfma_f32_16x16x32_bf16 v[110:113], v[204:207], v[96:99], v[110:113]
	v_mfma_f32_16x16x32_bf16 v[12:15], v[208:211], v[96:99], v[12:15]
	ds_read_b128 v[96:99], v212 offset:18432
	v_mfma_f32_16x16x32_bf16 v[114:117], v[196:199], v[100:103], v[114:117]
	v_mfma_f32_16x16x32_bf16 v[20:23], v[200:203], v[100:103], v[20:23]
	v_mfma_f32_16x16x32_bf16 v[68:71], v[204:207], v[100:103], v[68:71]
	v_mfma_f32_16x16x32_bf16 v[8:11], v[208:211], v[100:103], v[8:11]
	ds_read_b128 v[100:103], v212 offset:20480
	v_mfma_f32_16x16x32_bf16 v[72:75], v[196:199], v[104:107], v[72:75]
	v_mfma_f32_16x16x32_bf16 v[4:7], v[200:203], v[104:107], v[4:7]
	v_mfma_f32_16x16x32_bf16 v[64:67], v[204:207], v[104:107], v[64:67]
	v_mfma_f32_16x16x32_bf16 v[0:3], v[208:211], v[104:107], v[0:3]
	ds_read_b128 v[104:107], v212 offset:22528
	s_add_u32 s6, s6, 128
	s_addc_u32 s7, s7, 0
	s_add_u32 s8, s8, 128
	s_addc_u32 s9, s9, 0
	s_add_i32 s63, s63, 1
	s_cmp_lt_u32 s63, 16
	s_cbranch_scc1 .Ls3_loop
	s_waitcnt lgkmcnt(0)
	s_nop 7
	s_nop 3
	s_lshl_b32 s6, s0, 8
	s_lshl_b32 s1, s1, 7
	v_mov_b32_e32 v185, v163
	v_mov_b32_e32 v80, v225
	s_add_i32 s6, s6, s56
	s_or_b32 s1, s1, s49
	s_lshl_b32 s0, s0, 3
	v_add_u32_e32 v182, s6, v185
	v_lshl_add_u32 v180, v80, 3, s1
	v_ashrrev_i32_e32 v183, 31, v182
	v_ashrrev_i32_e32 v181, 31, v180
	v_lshl_add_u64 v[78:79], v[182:183], 2, s[12:13]
	v_lshlrev_b64 v[90:91], 2, v[180:181]
	global_load_dword v188, v[78:79], off
	global_load_dword v184, v[78:79], off offset:64
	global_load_dword v186, v[78:79], off offset:128
	global_load_dword v196, v[78:79], off offset:192
	global_load_dword v195, v[78:79], off offset:256
	global_load_dword v77, v[78:79], off offset:320
	global_load_dword v76, v[78:79], off offset:384
	global_load_dword v183, v[78:79], off offset:448
	v_lshl_add_u64 v[190:191], s[82:83], 0, v[90:91]
	v_lshl_add_u64 v[78:79], s[16:17], 0, v[90:91]
	v_lshl_add_u64 v[80:81], s[18:19], 0, v[90:91]
	global_load_dwordx4 v[94:97], v[190:191], off
	global_load_dwordx4 v[102:105], v[78:79], off
	global_load_dwordx4 v[98:101], v[80:81], off
	v_lshl_add_u64 v[192:193], s[84:85], 0, v[90:91]
	v_lshl_add_u64 v[78:79], s[20:21], 0, v[90:91]
	v_lshl_add_u64 v[80:81], s[22:23], 0, v[90:91]
	v_lshl_add_u64 v[82:83], s[24:25], 0, v[90:91]
	v_lshl_add_u64 v[90:91], s[26:27], 0, v[90:91]
	global_load_dwordx4 v[106:109], v[192:193], off
	global_load_dwordx4 v[86:89], v[78:79], off
	s_nop 0
	global_load_dwordx4 v[78:81], v[80:81], off
	s_add_i32 s0, s0, s57
	global_load_dwordx4 v[82:85], v[82:83], off
	v_add_u32_e32 v187, s0, v185
	global_load_dwordx4 v[90:93], v[90:91], off
	v_cmp_gt_i32_e64 s[10:11], 2, v185
	s_waitcnt vmcnt(0)
	v_fmamk_f32 v188, v188, 0x3a000000, v243
	v_rsq_f32_e32 v194, v188
	v_mad_i64_i32 v[188:189], s[0:1], v187, s60, 0
	v_lshl_add_u64 v[188:189], s[70:71], 0, v[188:189]
	v_pk_mul_f32 v[160:161], v[160:161], v[194:195] op_sel_hi:[1,0]
	v_pk_mul_f32 v[158:159], v[158:159], v[194:195] op_sel_hi:[1,0]
	v_pk_mul_f32 v[156:157], v[156:157], v[194:195] op_sel_hi:[1,0]
	v_pk_mul_f32 v[154:155], v[154:155], v[194:195] op_sel_hi:[1,0]
	v_lshl_add_u64 v[188:189], v[180:181], 2, v[188:189]
	s_and_saveexec_b64 s[0:1], s[10:11]
	s_cbranch_execz .LBB0_366
	v_add_co_u32_e32 v198, vcc, 0x5000, v188
	global_store_dwordx4 v[188:189], v[158:161], off
	s_nop 0
	v_addc_co_u32_e32 v199, vcc, 0, v189, vcc
	global_store_dwordx4 v[198:199], v[154:157], off offset:2048

.LBB0_492:
	v_lshrrev_b32_e32 v0, 1, v219
	v_mul_u32_u24_e32 v231, 0x1600, v236
	v_or_b32_e32 v1, v0, v231
	v_lshlrev_b32_e32 v168, 1, v1
	v_mul_u32_u24_e32 v1, 0x1600, v232
	v_or_b32_e32 v1, v1, v0
	v_mul_u32_u24_e32 v232, 0x1600, v237
	v_lshlrev_b32_e32 v170, 1, v1
	v_or_b32_e32 v1, v232, v0
	v_lshlrev_b32_e32 v172, 1, v1
	v_mul_u32_u24_e32 v1, 0x1600, v240
	v_readlane_b32 s0, v255, 8
	v_or_b32_e32 v0, v1, v0
	s_add_u32 s14, s92, 0x20000
	v_readlane_b32 s1, v255, 9
	s_addc_u32 s15, s93, 0
	s_and_b64 vcc, exec, s[0:1]
	v_lshlrev_b32_e32 v174, 1, v0
	s_cbranch_vccnz .LBB0_528
	s_add_u32 s18, s92, 0x4d00000
	s_addc_u32 s19, s93, 0
	s_lshr_b32 s4, s3, 6
	s_lshr_b32 s5, s3, 8
	s_lshl_b32 s20, s4, 10
	s_mul_i32 s7, s37, 0x2c0000
	s_mul_hi_i32 s6, s37, 0x2c0000
	s_add_u32 s16, s18, s7
	s_addc_u32 s17, s19, s6
	s_add_i32 s21, s20, 0
	s_add_i32 m0, s21, 0x10000
	s_mul_i32 s0, s38, 0x2c0000
	v_and_b32_e32 v136, 63, v222
	v_lshrrev_b32_e32 v137, 3, v136
	v_lshrrev_b32_e32 v138, 6, v222
	v_lshl_add_u32 v139, v138, 3, v137
	v_and_b32_e32 v146, 7, v136
	v_and_b32_e32 v147, 6, v137
	v_xor_b32_e32 v146, v146, v147
	v_lshlrev_b32_e32 v146, 4, v146
	v_mul_u32_u24_e32 v147, 0x2c00, v139
	v_add_u32_e32 v147, v147, v146
	v_mov_b32_e32 v128, v147
	v_add_u32_e32 v130, 0xb0000, v147
	v_mov_b32_e32 v168, v147
	v_add_u32_e32 v172, 0xb0000, v147
	v_add_u32_e32 v130, 0xb0000, v147
	v_add_u32_e32 v172, 0xb0000, v147
	v_and_b32_e32 v147, 31, v139
	v_and_b32_e32 v148, 12, v147
	v_lshlrev_b32_e32 v148, 1, v148
	v_lshrrev_b32_e32 v149, 4, v147
	v_lshlrev_b32_e32 v149, 2, v149
	v_and_b32_e32 v147, 3, v147
	v_or3_b32 v147, v148, v149, v147
	v_and_b32_e32 v148, 0x60, v139
	v_add_u32_e32 v147, v147, v148
	v_mul_u32_u24_e32 v147, 0x2c00, v147
	v_add_u32_e32 v147, v147, v146
	v_mov_b32_e32 v170, v147
	v_add_u32_e32 v174, 0xb0000, v147
	v_add_u32_e32 v174, 0xb0000, v147
	v_and_b32_e32 v147, 15, v136
	v_lshrrev_b32_e32 v148, 4, v136
	v_and_b32_e32 v149, 6, v147
	v_xor_b32_e32 v148, v148, v149
	v_lshlrev_b32_e32 v148, 4, v148
	v_lshl_or_b32 v148, v147, 7, v148
	v_lshrrev_b32_e32 v149, 2, v138
	v_lshl_add_u32 v149, v149, 13, v148
	v_add_u32_e32 v142, 0x0, v149
	v_and_b32_e32 v147, 3, v138
	v_lshl_add_u32 v147, v147, 12, v148
	v_add_u32_e32 v140, 0x0, v147
	v_add_u32_e32 v141, 0x10000, v147
	v_add_u32_e32 v143, 0x14000, v147
	v_add_u32_e32 v145, 0x0, v147
	s_add_i32 m0, s21, 0x12000
	s_mul_hi_i32 s1, s38, 0x2c0000
	s_add_u32 s0, s96, s0
	s_addc_u32 s1, s97, s1
	s_mov_b32 m0, s21
	s_add_i32 s22, s21, 0x2000
	s_mov_b32 m0, s22
	s_add_u32 s6, s16, 0x160000
	s_addc_u32 s7, s17, 0
	s_add_i32 m0, s21, 0x14000
	v_mov_b32_e32 v171, 0
	s_add_i32 m0, s21, 0x16000
	v_mov_b32_e32 v175, v171
	s_add_u32 s6, s0, 0x160000
	s_addc_u32 s7, s1, 0
	s_add_i32 s23, s21, 0x4000
	s_mov_b32 m0, s23
	s_add_i32 s24, s21, 0x6000
	s_mov_b32 m0, s24
	v_mov_b32_e32 v169, v171
	v_mov_b32_e32 v173, v171
	s_mov_b32 s25, 0
	v_lshl_add_u64 v[6:7], s[16:17], 0, v[170:171]
	v_lshl_add_u64 v[4:5], s[16:17], 0, v[174:175]
	v_lshl_add_u64 v[2:3], s[0:1], 0, v[168:169]
	s_cmp_lg_u32 s5, 1
	v_lshl_add_u64 v[0:1], s[0:1], 0, v[172:173]
	s_cbranch_scc1 .LBB0_495
.LBB0_495:
	s_lshl_b32 s4, s4, 5
	s_lshl_b32 s26, s5, 6
	s_lshl_b32 s8, s5, 13
	s_and_b32 s27, s4, 0x60
	s_mov_b64 s[4:5], 0x80
	s_add_i32 m0, s21, 0x18000
	v_lshl_add_u64 v[6:7], v[6:7], 0, s[4:5]
	v_lshl_add_u64 v[4:5], v[4:5], 0, s[4:5]
	s_add_i32 m0, s21, 0x1a000
	s_add_i32 s28, s21, 0x8000
	s_add_i32 s29, s21, 0xa000
	v_lshl_add_u64 v[2:3], v[2:3], 0, s[4:5]
	s_mov_b32 m0, s28
	s_add_u32 s6, s16, 0x160080
	v_lshl_add_u64 v[0:1], v[0:1], 0, s[4:5]
	s_mov_b32 m0, s29
	s_addc_u32 s7, s17, 0
	s_add_i32 m0, s21, 0x1c000
	v_lshl_add_u64 v[0:1], s[6:7], 0, v[170:171]
	v_lshl_add_u64 v[0:1], s[6:7], 0, v[174:175]
	s_add_i32 m0, s21, 0x1e000
	v_lshlrev_b32_e32 v1, 2, v163
	v_lshl_or_b32 v0, v163, 6, v227
	v_and_b32_e32 v1, 32, v1
	v_bitop3_b32 v0, v0, s8, v1 bitop3:0xde
	v_add_u16_e32 v1, v226, v224
	v_lshrrev_b16_e32 v1, 1, v1
	s_add_i32 s33, 0, 0x10000
	s_add_i32 s34, 0, 0x14000
	v_mbcnt_lo_u32_b32 v0, -1, 0
	s_ashr_i32 s30, s94, 31
	s_mov_b32 s31, s94
	v_mov_b32_e32 v129, v171
	v_mov_b32_e32 v131, v171
	v_mov_b64_e32 v[132:133], 0x200
	v_mov_b64_e32 v[134:135], 0x1ff
	v_mbcnt_hi_u32_b32 v144, -1, v0
	v_and_b32_e32 v136, 63, v222
	v_lshrrev_b32_e32 v137, 6, v222
	v_lshrrev_b32_e32 v138, 3, v136
	v_lshl_add_u32 v139, v137, 3, v138
	v_and_b32_e32 v146, 7, v136
	v_and_b32_e32 v147, 6, v138
	v_xor_b32_e32 v146, v146, v147
	v_lshlrev_b32_e32 v146, 4, v146
	v_mul_u32_u24_e32 v147, 0x2c00, v139
	v_add_u32_e32 v145, v147, v146
	v_and_b32_e32 v147, 31, v139
	v_and_b32_e32 v138, 12, v147
	v_lshlrev_b32_e32 v138, 1, v138
	v_lshrrev_b32_e32 v216, 4, v147
	v_lshlrev_b32_e32 v216, 2, v216
	v_and_b32_e32 v147, 3, v147
	v_or3_b32 v147, v138, v216, v147
	v_and_b32_e32 v138, 0x60, v139
	v_add_u32_e32 v147, v147, v138
	v_mul_u32_u24_e32 v147, 0x2c00, v147
	v_add_u32_e32 v216, v147, v146
	v_and_b32_e32 v138, 15, v136
	v_lshrrev_b32_e32 v139, 4, v136
	v_and_b32_e32 v146, 6, v138
	v_xor_b32_e32 v139, v139, v146
	v_lshlrev_b32_e32 v139, 4, v139
	v_lshl_or_b32 v139, v138, 7, v139
	v_lshrrev_b32_e32 v146, 2, v137
	v_lshl_add_u32 v217, v146, 13, v139
	v_xor_b32_e32 v244, 64, v217
	v_and_b32_e32 v146, 3, v137
	v_lshl_add_u32 v245, v146, 12, v139
	v_add_u32_e32 v245, 0x10000, v245
	v_xor_b32_e32 v246, 64, v245
	v_readfirstlane_b32 s44, v222
	s_nop 3
	s_lshr_b32 s44, s44, 6
	s_lshl_b32 s44, s44, 10
	s_mov_b32 s98, 0
	s_mul_i32 s16, s98, s94
	s_add_i32 s16, s16, s2
	s_and_b32 s17, s16, 7
	s_lshr_b32 s16, s16, 3
	s_mul_i32 s17, s17, 0x40
	s_add_i32 s16, s16, s17
	s_mul_i32 s17, s16, 0x80000
	s_lshr_b32 s17, s17, 24
	s_mul_i32 s41, s17, 0x20
	s_sub_i32 s16, s16, s41
	s_and_b32 s40, s16, 3
	s_lshl_b32 s17, s17, 2
	s_add_i32 s40, s40, s17
	s_lshr_b32 s41, s16, 2
	s_mul_i32 s100, s40, 0x2c0000
	s_add_u32 s0, s92, 0xfd00000
	s_addc_u32 s1, s93, 0
	s_add_u32 s0, s0, s100
	s_addc_u32 s1, s1, 0
	s_mul_i32 s100, s41, 0x2c0000
	s_add_u32 s8, s92, 0x4d00000
	s_addc_u32 s9, s93, 0
	s_add_u32 s8, s8, s100
	s_addc_u32 s9, s9, 0
	s_add_i32 m0, s44, 0x0
	s_nop 0
	global_load_lds_dwordx4 v145, s[0:1]
	s_add_i32 m0, s44, 0x2000
	s_add_u32 s42, s0, 0xb0000
	s_addc_u32 s43, s1, 0
	s_nop 0
	global_load_lds_dwordx4 v145, s[42:43]
	s_add_i32 m0, s44, 0x4000
	s_add_u32 s42, s0, 0x160000
	s_addc_u32 s43, s1, 0
	s_nop 0
	global_load_lds_dwordx4 v145, s[42:43]
	s_add_i32 m0, s44, 0x6000
	s_add_u32 s42, s0, 0x210000
	s_addc_u32 s43, s1, 0
	s_nop 0
	global_load_lds_dwordx4 v145, s[42:43]
	s_add_i32 m0, s44, 0x10000
	s_nop 0
	global_load_lds_dwordx4 v216, s[8:9]
	s_add_i32 m0, s44, 0x12000
	s_add_u32 s42, s8, 0xb0000
	s_addc_u32 s43, s9, 0
	s_nop 0
	global_load_lds_dwordx4 v216, s[42:43]
	s_add_i32 m0, s44, 0x14000
	s_add_u32 s42, s8, 0x160000
	s_addc_u32 s43, s9, 0
	s_nop 0
	global_load_lds_dwordx4 v216, s[42:43]
	s_add_i32 m0, s44, 0x16000
	s_add_u32 s42, s8, 0x210000
	s_addc_u32 s43, s9, 0
	s_nop 0
	global_load_lds_dwordx4 v216, s[42:43]
	s_add_u32 s0, s0, 128
	s_addc_u32 s1, s1, 0
	s_add_u32 s8, s8, 128
	s_addc_u32 s9, s9, 0
	s_add_i32 m0, s44, 0x8000
	s_nop 0
	global_load_lds_dwordx4 v145, s[0:1]
	s_add_i32 m0, s44, 0xa000
	s_add_u32 s42, s0, 0xb0000
	s_addc_u32 s43, s1, 0
	s_nop 0
	global_load_lds_dwordx4 v145, s[42:43]
	s_add_i32 m0, s44, 0xc000
	s_add_u32 s42, s0, 0x160000
	s_addc_u32 s43, s1, 0
	s_nop 0
	global_load_lds_dwordx4 v145, s[42:43]
	s_add_i32 m0, s44, 0xe000
	s_add_u32 s42, s0, 0x210000
	s_addc_u32 s43, s1, 0
	s_nop 0
	global_load_lds_dwordx4 v145, s[42:43]
	s_add_i32 m0, s44, 0x18000
	s_nop 0
	global_load_lds_dwordx4 v216, s[8:9]
	s_add_i32 m0, s44, 0x1a000
	s_add_u32 s42, s8, 0xb0000
	s_addc_u32 s43, s9, 0
	s_nop 0
	global_load_lds_dwordx4 v216, s[42:43]
	s_add_i32 m0, s44, 0x1c000
	s_add_u32 s42, s8, 0x160000
	s_addc_u32 s43, s9, 0
	s_nop 0
	global_load_lds_dwordx4 v216, s[42:43]
	s_add_i32 m0, s44, 0x1e000
	s_add_u32 s42, s8, 0x210000
	s_addc_u32 s43, s9, 0
	s_nop 0
	global_load_lds_dwordx4 v216, s[42:43]
	s_branch .LBB0_497

.LBB0_507:
	s_add_u32 s0, s0, 0x160080
	s_addc_u32 s1, s1, 0
	s_add_u32 s39, s16, 0x100
	v_mov_b32_e32 v0, 0
	s_addc_u32 s40, s17, 0
	s_mov_b32 s41, -2
	s_waitcnt lgkmcnt(0)
	v_mov_b32_e32 v1, v0
	v_mov_b32_e32 v2, v0
	v_mov_b32_e32 v3, v0
	v_mov_b32_e32 v4, v0
	v_mov_b32_e32 v5, v0
	v_mov_b32_e32 v6, v0
	v_mov_b32_e32 v7, v0
	s_waitcnt vmcnt(0)
	v_mov_b32_e32 v16, v0
	v_mov_b32_e32 v17, v0
	v_mov_b32_e32 v18, v0
	v_mov_b32_e32 v19, v0
	v_mov_b32_e32 v20, v0
	v_mov_b32_e32 v21, v0
	v_mov_b32_e32 v22, v0
	v_mov_b32_e32 v23, v0
	v_mov_b32_e32 v32, v0
	v_mov_b32_e32 v33, v0
	v_mov_b32_e32 v34, v0
	v_mov_b32_e32 v35, v0
	v_mov_b32_e32 v36, v0
	v_mov_b32_e32 v37, v0
	v_mov_b32_e32 v38, v0
	v_mov_b32_e32 v39, v0
	v_mov_b32_e32 v48, v0
	v_mov_b32_e32 v49, v0
	v_mov_b32_e32 v50, v0
	v_mov_b32_e32 v51, v0
	v_mov_b32_e32 v52, v0
	v_mov_b32_e32 v53, v0
	v_mov_b32_e32 v54, v0
	v_mov_b32_e32 v55, v0
	v_mov_b32_e32 v8, v0
	v_mov_b32_e32 v9, v0
	v_mov_b32_e32 v10, v0
	v_mov_b32_e32 v11, v0
	v_mov_b32_e32 v12, v0
	v_mov_b32_e32 v13, v0
	v_mov_b32_e32 v14, v0
	v_mov_b32_e32 v15, v0
	v_mov_b32_e32 v24, v0
	v_mov_b32_e32 v25, v0
	v_mov_b32_e32 v26, v0
	v_mov_b32_e32 v27, v0
	v_mov_b32_e32 v28, v0
	v_mov_b32_e32 v29, v0
	v_mov_b32_e32 v30, v0
	v_mov_b32_e32 v31, v0
	v_mov_b32_e32 v40, v0
	v_mov_b32_e32 v41, v0
	v_mov_b32_e32 v42, v0
	v_mov_b32_e32 v43, v0
	v_mov_b32_e32 v44, v0
	v_mov_b32_e32 v45, v0
	v_mov_b32_e32 v46, v0
	v_mov_b32_e32 v47, v0
	v_mov_b32_e32 v56, v0
	v_mov_b32_e32 v57, v0
	v_mov_b32_e32 v58, v0
	v_mov_b32_e32 v59, v0
	v_mov_b32_e32 v60, v0
	v_mov_b32_e32 v61, v0
	v_mov_b32_e32 v62, v0
	v_mov_b32_e32 v63, v0
	v_mov_b32_e32 v64, v0
	v_mov_b32_e32 v65, v0
	v_mov_b32_e32 v66, v0
	v_mov_b32_e32 v67, v0
	v_mov_b32_e32 v68, v0
	v_mov_b32_e32 v69, v0
	v_mov_b32_e32 v70, v0
	v_mov_b32_e32 v71, v0
	v_mov_b32_e32 v80, v0
	v_mov_b32_e32 v81, v0
	v_mov_b32_e32 v82, v0
	v_mov_b32_e32 v83, v0
	v_mov_b32_e32 v84, v0
	v_mov_b32_e32 v85, v0
	v_mov_b32_e32 v86, v0
	v_mov_b32_e32 v87, v0
	v_mov_b32_e32 v96, v0
	v_mov_b32_e32 v97, v0
	v_mov_b32_e32 v98, v0
	v_mov_b32_e32 v99, v0
	v_mov_b32_e32 v100, v0
	v_mov_b32_e32 v101, v0
	v_mov_b32_e32 v102, v0
	v_mov_b32_e32 v103, v0
	v_mov_b32_e32 v112, v0
	v_mov_b32_e32 v113, v0
	v_mov_b32_e32 v114, v0
	v_mov_b32_e32 v115, v0
	v_mov_b32_e32 v116, v0
	v_mov_b32_e32 v117, v0
	v_mov_b32_e32 v118, v0
	v_mov_b32_e32 v119, v0
	v_mov_b32_e32 v72, v0
	v_mov_b32_e32 v73, v0
	v_mov_b32_e32 v74, v0
	v_mov_b32_e32 v75, v0
	v_mov_b32_e32 v76, v0
	v_mov_b32_e32 v77, v0
	v_mov_b32_e32 v78, v0
	v_mov_b32_e32 v79, v0
	v_mov_b32_e32 v88, v0
	v_mov_b32_e32 v89, v0
	v_mov_b32_e32 v90, v0
	v_mov_b32_e32 v91, v0
	v_mov_b32_e32 v92, v0
	v_mov_b32_e32 v93, v0
	v_mov_b32_e32 v94, v0
	v_mov_b32_e32 v95, v0
	v_mov_b32_e32 v104, v0
	v_mov_b32_e32 v105, v0
	v_mov_b32_e32 v106, v0
	v_mov_b32_e32 v107, v0
	v_mov_b32_e32 v108, v0
	v_mov_b32_e32 v109, v0
	v_mov_b32_e32 v110, v0
	v_mov_b32_e32 v111, v0
	v_mov_b32_e32 v120, v0
	v_mov_b32_e32 v121, v0
	v_mov_b32_e32 v122, v0
	v_mov_b32_e32 v123, v0
	v_mov_b32_e32 v124, v0
	v_mov_b32_e32 v125, v0
	v_mov_b32_e32 v126, v0
	v_mov_b32_e32 v127, v0
	v_and_b32_e32 v136, 63, v222
	v_lshrrev_b32_e32 v137, 6, v222
	v_lshrrev_b32_e32 v138, 3, v136
	v_lshl_add_u32 v139, v137, 3, v138
	v_and_b32_e32 v146, 7, v136
	v_and_b32_e32 v147, 6, v138
	v_xor_b32_e32 v146, v146, v147
	v_lshlrev_b32_e32 v146, 4, v146
	v_mul_u32_u24_e32 v147, 0x2c00, v139
	v_add_u32_e32 v145, v147, v146
	v_and_b32_e32 v147, 31, v139
	v_and_b32_e32 v138, 12, v147
	v_lshlrev_b32_e32 v138, 1, v138
	v_lshrrev_b32_e32 v216, 4, v147
	v_lshlrev_b32_e32 v216, 2, v216
	v_and_b32_e32 v147, 3, v147
	v_or3_b32 v147, v138, v216, v147
	v_and_b32_e32 v138, 0x60, v139
	v_add_u32_e32 v147, v147, v138
	v_mul_u32_u24_e32 v147, 0x2c00, v147
	v_add_u32_e32 v216, v147, v146
	v_and_b32_e32 v138, 15, v136
	v_lshrrev_b32_e32 v139, 4, v136
	v_and_b32_e32 v146, 6, v138
	v_xor_b32_e32 v139, v139, v146
	v_lshlrev_b32_e32 v139, 4, v139
	v_lshl_or_b32 v139, v138, 7, v139
	v_lshrrev_b32_e32 v146, 2, v137
	v_lshl_add_u32 v217, v146, 13, v139
	v_xor_b32_e32 v244, 64, v217
	v_and_b32_e32 v146, 3, v137
	v_lshl_add_u32 v245, v146, 12, v139
	v_add_u32_e32 v245, 0x10000, v245
	v_xor_b32_e32 v246, 64, v245
	v_readfirstlane_b32 s44, v222
	s_nop 3
	s_lshr_b32 s44, s44, 6
	s_lshl_b32 s44, s44, 10
	s_mul_i32 s16, s98, s94
	s_add_i32 s16, s16, s2
	s_and_b32 s17, s16, 7
	s_lshr_b32 s16, s16, 3
	s_mul_i32 s17, s17, 0x40
	s_add_i32 s16, s16, s17
	s_mul_i32 s17, s16, 0x80000
	s_lshr_b32 s17, s17, 24
	s_mul_i32 s100, s17, 0x20
	s_sub_i32 s16, s16, s100
	s_and_b32 s39, s16, 3
	s_lshl_b32 s17, s17, 2
	s_add_i32 s39, s39, s17
	s_lshr_b32 s100, s16, 2
	s_mul_i32 s99, s39, 0x2c0000
	s_add_u32 s0, s92, 0xfd00100
	s_addc_u32 s1, s93, 0
	s_add_u32 s0, s0, s99
	s_addc_u32 s1, s1, 0
	s_mul_i32 s99, s100, 0x2c0000
	s_add_u32 s8, s92, 0x4d00100
	s_addc_u32 s9, s93, 0
	s_add_u32 s8, s8, s99
	s_addc_u32 s9, s9, 0
	s_add_i32 s98, s98, 1
	s_mul_i32 s40, s98, s94
	s_add_i32 s40, s40, s2
	s_cmp_lt_u32 s40, 0x200
	s_cbranch_scc0 .Ls4_nonext
	s_mul_i32 s16, s98, s94
	s_add_i32 s16, s16, s2
	s_and_b32 s17, s16, 7
	s_lshr_b32 s16, s16, 3
	s_mul_i32 s17, s17, 0x40
	s_add_i32 s16, s16, s17
	s_mul_i32 s17, s16, 0x80000
	s_lshr_b32 s17, s17, 24
	s_mul_i32 s100, s17, 0x20
	s_sub_i32 s16, s16, s100
	s_and_b32 s39, s16, 3
	s_lshl_b32 s17, s17, 2
	s_add_i32 s39, s39, s17
	s_lshr_b32 s100, s16, 2
.Ls4_nonext:
	s_mul_i32 s99, s39, 0x2c0000
	s_add_u32 s16, s92, 0xfd00000
	s_addc_u32 s17, s93, 0
	s_add_u32 s16, s16, s99
	s_addc_u32 s17, s17, 0
	s_mul_i32 s99, s100, 0x2c0000
	s_add_u32 s40, s92, 0x4d00000
	s_addc_u32 s41, s93, 0
	s_add_u32 s40, s40, s99
	s_addc_u32 s41, s41, 0
	s_waitcnt vmcnt(0)
	s_barrier
	ds_read_b128 v[136:139], v217
	ds_read_b128 v[146:149], v217 offset:2048
	ds_read_b128 v[188:191], v245
	ds_read_b128 v[192:195], v245 offset:2048
	ds_read_b128 v[196:199], v245 offset:16384
	ds_read_b128 v[200:203], v245 offset:18432
	ds_read_b128 v[150:153], v217 offset:4096
	ds_read_b128 v[154:157], v217 offset:6144
	ds_read_b128 v[158:161], v217 offset:16384
	ds_read_b128 v[176:179], v217 offset:18432
	ds_read_b128 v[180:183], v217 offset:20480
	ds_read_b128 v[184:187], v217 offset:22528
	s_mov_b32 s39, 0
.Ls4_loop:
	s_cmp_eq_u32 s39, 43
	s_cselect_b32 s0, s16, s0
	s_cselect_b32 s1, s17, s1
	s_cselect_b32 s8, s40, s8
	s_cselect_b32 s9, s41, s9
	s_waitcnt lgkmcnt(6)
	v_mfma_f32_16x16x32_bf16 v[124:127], v[188:191], v[136:139], v[124:127]
	v_mfma_f32_16x16x32_bf16 v[120:123], v[192:195], v[136:139], v[120:123]
	v_mfma_f32_16x16x32_bf16 v[116:119], v[196:199], v[136:139], v[116:119]
	v_mfma_f32_16x16x32_bf16 v[112:115], v[200:203], v[136:139], v[112:115]
	v_mfma_f32_16x16x32_bf16 v[108:111], v[188:191], v[146:149], v[108:111]
	v_mfma_f32_16x16x32_bf16 v[104:107], v[192:195], v[146:149], v[104:107]
	v_mfma_f32_16x16x32_bf16 v[100:103], v[196:199], v[146:149], v[100:103]
	v_mfma_f32_16x16x32_bf16 v[96:99], v[200:203], v[146:149], v[96:99]
	s_waitcnt lgkmcnt(0)
	ds_read_b128 v[136:139], v244
	ds_read_b128 v[146:149], v244 offset:2048
	ds_read_b128 v[204:207], v246
	ds_read_b128 v[208:211], v246 offset:2048
	ds_read_b128 v[212:215], v246 offset:16384
	ds_read_b128 v[240:243], v246 offset:18432
	v_mfma_f32_16x16x32_bf16 v[92:95], v[188:191], v[150:153], v[92:95]
	v_mfma_f32_16x16x32_bf16 v[88:91], v[192:195], v[150:153], v[88:91]
	v_mfma_f32_16x16x32_bf16 v[84:87], v[196:199], v[150:153], v[84:87]
	v_mfma_f32_16x16x32_bf16 v[80:83], v[200:203], v[150:153], v[80:83]
	ds_read_b128 v[150:153], v244 offset:4096
	v_mfma_f32_16x16x32_bf16 v[76:79], v[188:191], v[154:157], v[76:79]
	v_mfma_f32_16x16x32_bf16 v[72:75], v[192:195], v[154:157], v[72:75]
	v_mfma_f32_16x16x32_bf16 v[68:71], v[196:199], v[154:157], v[68:71]
	v_mfma_f32_16x16x32_bf16 v[64:67], v[200:203], v[154:157], v[64:67]
	ds_read_b128 v[154:157], v244 offset:6144
	s_waitcnt lgkmcnt(0)
	s_barrier
	s_add_i32 m0, s44, 0x10000
	v_mfma_f32_16x16x32_bf16 v[60:63], v[188:191], v[158:161], v[60:63]
	v_mfma_f32_16x16x32_bf16 v[56:59], v[192:195], v[158:161], v[56:59]
	v_mfma_f32_16x16x32_bf16 v[52:55], v[196:199], v[158:161], v[52:55]
	v_mfma_f32_16x16x32_bf16 v[48:51], v[200:203], v[158:161], v[48:51]
	ds_read_b128 v[158:161], v244 offset:16384
	global_load_lds_dwordx4 v216, s[8:9]
	s_add_i32 m0, s44, 0x12000
	s_add_u32 s42, s8, 0xb0000
	s_addc_u32 s43, s9, 0
	v_mfma_f32_16x16x32_bf16 v[44:47], v[188:191], v[176:179], v[44:47]
	v_mfma_f32_16x16x32_bf16 v[40:43], v[192:195], v[176:179], v[40:43]
	v_mfma_f32_16x16x32_bf16 v[36:39], v[196:199], v[176:179], v[36:39]
	v_mfma_f32_16x16x32_bf16 v[32:35], v[200:203], v[176:179], v[32:35]
	ds_read_b128 v[176:179], v244 offset:18432
	global_load_lds_dwordx4 v216, s[42:43]
	s_add_i32 m0, s44, 0x14000
	s_add_u32 s42, s8, 0x160000
	s_addc_u32 s43, s9, 0
	v_mfma_f32_16x16x32_bf16 v[28:31], v[188:191], v[180:183], v[28:31]
	v_mfma_f32_16x16x32_bf16 v[24:27], v[192:195], v[180:183], v[24:27]
	v_mfma_f32_16x16x32_bf16 v[20:23], v[196:199], v[180:183], v[20:23]
	v_mfma_f32_16x16x32_bf16 v[16:19], v[200:203], v[180:183], v[16:19]
	ds_read_b128 v[180:183], v244 offset:20480
	global_load_lds_dwordx4 v216, s[42:43]
	s_add_i32 m0, s44, 0x16000
	s_add_u32 s42, s8, 0x210000
	s_addc_u32 s43, s9, 0
	v_mfma_f32_16x16x32_bf16 v[12:15], v[188:191], v[184:187], v[12:15]
	v_mfma_f32_16x16x32_bf16 v[8:11], v[192:195], v[184:187], v[8:11]
	v_mfma_f32_16x16x32_bf16 v[4:7], v[196:199], v[184:187], v[4:7]
	v_mfma_f32_16x16x32_bf16 v[0:3], v[200:203], v[184:187], v[0:3]
	ds_read_b128 v[184:187], v244 offset:22528
	global_load_lds_dwordx4 v216, s[42:43]
	s_waitcnt lgkmcnt(6)
	s_add_i32 m0, s44, 0x0
	v_mfma_f32_16x16x32_bf16 v[124:127], v[204:207], v[136:139], v[124:127]
	v_mfma_f32_16x16x32_bf16 v[120:123], v[208:211], v[136:139], v[120:123]
	v_mfma_f32_16x16x32_bf16 v[116:119], v[212:215], v[136:139], v[116:119]
	v_mfma_f32_16x16x32_bf16 v[112:115], v[240:243], v[136:139], v[112:115]
	global_load_lds_dwordx4 v145, s[0:1]
	s_add_i32 m0, s44, 0x2000
	s_add_u32 s42, s0, 0xb0000
	s_addc_u32 s43, s1, 0
	v_mfma_f32_16x16x32_bf16 v[108:111], v[204:207], v[146:149], v[108:111]
	v_mfma_f32_16x16x32_bf16 v[104:107], v[208:211], v[146:149], v[104:107]
	v_mfma_f32_16x16x32_bf16 v[100:103], v[212:215], v[146:149], v[100:103]
	v_mfma_f32_16x16x32_bf16 v[96:99], v[240:243], v[146:149], v[96:99]
	global_load_lds_dwordx4 v145, s[42:43]
	s_waitcnt lgkmcnt(0)
	s_waitcnt vmcnt(6)
	s_barrier
	ds_read_b128 v[136:139], v217 offset:32768
	ds_read_b128 v[146:149], v217 offset:34816
	ds_read_b128 v[188:191], v245 offset:32768
	ds_read_b128 v[192:195], v245 offset:34816
	ds_read_b128 v[196:199], v245 offset:49152
	ds_read_b128 v[200:203], v245 offset:51200
	s_add_i32 m0, s44, 0x4000
	s_add_u32 s42, s0, 0x160000
	s_addc_u32 s43, s1, 0
	v_mfma_f32_16x16x32_bf16 v[92:95], v[204:207], v[150:153], v[92:95]
	v_mfma_f32_16x16x32_bf16 v[88:91], v[208:211], v[150:153], v[88:91]
	v_mfma_f32_16x16x32_bf16 v[84:87], v[212:215], v[150:153], v[84:87]
	v_mfma_f32_16x16x32_bf16 v[80:83], v[240:243], v[150:153], v[80:83]
	ds_read_b128 v[150:153], v217 offset:36864
	global_load_lds_dwordx4 v145, s[42:43]
	s_add_i32 m0, s44, 0x6000
	s_add_u32 s42, s0, 0x210000
	s_addc_u32 s43, s1, 0
	v_mfma_f32_16x16x32_bf16 v[76:79], v[204:207], v[154:157], v[76:79]
	v_mfma_f32_16x16x32_bf16 v[72:75], v[208:211], v[154:157], v[72:75]
	v_mfma_f32_16x16x32_bf16 v[68:71], v[212:215], v[154:157], v[68:71]
	v_mfma_f32_16x16x32_bf16 v[64:67], v[240:243], v[154:157], v[64:67]
	ds_read_b128 v[154:157], v217 offset:38912
	global_load_lds_dwordx4 v145, s[42:43]
	v_mfma_f32_16x16x32_bf16 v[60:63], v[204:207], v[158:161], v[60:63]
	v_mfma_f32_16x16x32_bf16 v[56:59], v[208:211], v[158:161], v[56:59]
	v_mfma_f32_16x16x32_bf16 v[52:55], v[212:215], v[158:161], v[52:55]
	v_mfma_f32_16x16x32_bf16 v[48:51], v[240:243], v[158:161], v[48:51]
	ds_read_b128 v[158:161], v217 offset:49152
	v_mfma_f32_16x16x32_bf16 v[44:47], v[204:207], v[176:179], v[44:47]
	v_mfma_f32_16x16x32_bf16 v[40:43], v[208:211], v[176:179], v[40:43]
	v_mfma_f32_16x16x32_bf16 v[36:39], v[212:215], v[176:179], v[36:39]
	v_mfma_f32_16x16x32_bf16 v[32:35], v[240:243], v[176:179], v[32:35]
	ds_read_b128 v[176:179], v217 offset:51200
	v_mfma_f32_16x16x32_bf16 v[28:31], v[204:207], v[180:183], v[28:31]
	v_mfma_f32_16x16x32_bf16 v[24:27], v[208:211], v[180:183], v[24:27]
	v_mfma_f32_16x16x32_bf16 v[20:23], v[212:215], v[180:183], v[20:23]
	v_mfma_f32_16x16x32_bf16 v[16:19], v[240:243], v[180:183], v[16:19]
	ds_read_b128 v[180:183], v217 offset:53248
	v_mfma_f32_16x16x32_bf16 v[12:15], v[204:207], v[184:187], v[12:15]
	v_mfma_f32_16x16x32_bf16 v[8:11], v[208:211], v[184:187], v[8:11]
	v_mfma_f32_16x16x32_bf16 v[4:7], v[212:215], v[184:187], v[4:7]
	v_mfma_f32_16x16x32_bf16 v[0:3], v[240:243], v[184:187], v[0:3]
	ds_read_b128 v[184:187], v217 offset:55296
	s_add_u32 s0, s0, 128
	s_addc_u32 s1, s1, 0
	s_add_u32 s8, s8, 128
	s_addc_u32 s9, s9, 0
	s_waitcnt lgkmcnt(6)
	v_mfma_f32_16x16x32_bf16 v[124:127], v[188:191], v[136:139], v[124:127]
	v_mfma_f32_16x16x32_bf16 v[120:123], v[192:195], v[136:139], v[120:123]
	v_mfma_f32_16x16x32_bf16 v[116:119], v[196:199], v[136:139], v[116:119]
	v_mfma_f32_16x16x32_bf16 v[112:115], v[200:203], v[136:139], v[112:115]
	v_mfma_f32_16x16x32_bf16 v[108:111], v[188:191], v[146:149], v[108:111]
	v_mfma_f32_16x16x32_bf16 v[104:107], v[192:195], v[146:149], v[104:107]
	v_mfma_f32_16x16x32_bf16 v[100:103], v[196:199], v[146:149], v[100:103]
	v_mfma_f32_16x16x32_bf16 v[96:99], v[200:203], v[146:149], v[96:99]
	s_waitcnt lgkmcnt(0)
	ds_read_b128 v[136:139], v244 offset:32768
	ds_read_b128 v[146:149], v244 offset:34816
	ds_read_b128 v[204:207], v246 offset:32768
	ds_read_b128 v[208:211], v246 offset:34816
	ds_read_b128 v[212:215], v246 offset:49152
	ds_read_b128 v[240:243], v246 offset:51200
	v_mfma_f32_16x16x32_bf16 v[92:95], v[188:191], v[150:153], v[92:95]
	v_mfma_f32_16x16x32_bf16 v[88:91], v[192:195], v[150:153], v[88:91]
	v_mfma_f32_16x16x32_bf16 v[84:87], v[196:199], v[150:153], v[84:87]
	v_mfma_f32_16x16x32_bf16 v[80:83], v[200:203], v[150:153], v[80:83]
	ds_read_b128 v[150:153], v244 offset:36864
	v_mfma_f32_16x16x32_bf16 v[76:79], v[188:191], v[154:157], v[76:79]
	v_mfma_f32_16x16x32_bf16 v[72:75], v[192:195], v[154:157], v[72:75]
	v_mfma_f32_16x16x32_bf16 v[68:71], v[196:199], v[154:157], v[68:71]
	v_mfma_f32_16x16x32_bf16 v[64:67], v[200:203], v[154:157], v[64:67]
	ds_read_b128 v[154:157], v244 offset:38912
	s_waitcnt lgkmcnt(0)
	s_barrier
	s_add_i32 m0, s44, 0x18000
	v_mfma_f32_16x16x32_bf16 v[60:63], v[188:191], v[158:161], v[60:63]
	v_mfma_f32_16x16x32_bf16 v[56:59], v[192:195], v[158:161], v[56:59]
	v_mfma_f32_16x16x32_bf16 v[52:55], v[196:199], v[158:161], v[52:55]
	v_mfma_f32_16x16x32_bf16 v[48:51], v[200:203], v[158:161], v[48:51]
	ds_read_b128 v[158:161], v244 offset:49152
	global_load_lds_dwordx4 v216, s[8:9]
	s_add_i32 m0, s44, 0x1a000
	s_add_u32 s42, s8, 0xb0000
	s_addc_u32 s43, s9, 0
	v_mfma_f32_16x16x32_bf16 v[44:47], v[188:191], v[176:179], v[44:47]
	v_mfma_f32_16x16x32_bf16 v[40:43], v[192:195], v[176:179], v[40:43]
	v_mfma_f32_16x16x32_bf16 v[36:39], v[196:199], v[176:179], v[36:39]
	v_mfma_f32_16x16x32_bf16 v[32:35], v[200:203], v[176:179], v[32:35]
	ds_read_b128 v[176:179], v244 offset:51200
	global_load_lds_dwordx4 v216, s[42:43]
	s_add_i32 m0, s44, 0x1c000
	s_add_u32 s42, s8, 0x160000
	s_addc_u32 s43, s9, 0
	v_mfma_f32_16x16x32_bf16 v[28:31], v[188:191], v[180:183], v[28:31]
	v_mfma_f32_16x16x32_bf16 v[24:27], v[192:195], v[180:183], v[24:27]
	v_mfma_f32_16x16x32_bf16 v[20:23], v[196:199], v[180:183], v[20:23]
	v_mfma_f32_16x16x32_bf16 v[16:19], v[200:203], v[180:183], v[16:19]
	ds_read_b128 v[180:183], v244 offset:53248
	global_load_lds_dwordx4 v216, s[42:43]
	s_add_i32 m0, s44, 0x1e000
	s_add_u32 s42, s8, 0x210000
	s_addc_u32 s43, s9, 0
	v_mfma_f32_16x16x32_bf16 v[12:15], v[188:191], v[184:187], v[12:15]
	v_mfma_f32_16x16x32_bf16 v[8:11], v[192:195], v[184:187], v[8:11]
	v_mfma_f32_16x16x32_bf16 v[4:7], v[196:199], v[184:187], v[4:7]
	v_mfma_f32_16x16x32_bf16 v[0:3], v[200:203], v[184:187], v[0:3]
	ds_read_b128 v[184:187], v244 offset:55296
	global_load_lds_dwordx4 v216, s[42:43]
	s_waitcnt lgkmcnt(6)
	s_add_i32 m0, s44, 0x8000
	v_mfma_f32_16x16x32_bf16 v[124:127], v[204:207], v[136:139], v[124:127]
	v_mfma_f32_16x16x32_bf16 v[120:123], v[208:211], v[136:139], v[120:123]
	v_mfma_f32_16x16x32_bf16 v[116:119], v[212:215], v[136:139], v[116:119]
	v_mfma_f32_16x16x32_bf16 v[112:115], v[240:243], v[136:139], v[112:115]
	global_load_lds_dwordx4 v145, s[0:1]
	s_add_i32 m0, s44, 0xa000
	s_add_u32 s42, s0, 0xb0000
	s_addc_u32 s43, s1, 0
	v_mfma_f32_16x16x32_bf16 v[108:111], v[204:207], v[146:149], v[108:111]
	v_mfma_f32_16x16x32_bf16 v[104:107], v[208:211], v[146:149], v[104:107]
	v_mfma_f32_16x16x32_bf16 v[100:103], v[212:215], v[146:149], v[100:103]
	v_mfma_f32_16x16x32_bf16 v[96:99], v[240:243], v[146:149], v[96:99]
	global_load_lds_dwordx4 v145, s[42:43]
	s_waitcnt lgkmcnt(0)
	s_waitcnt vmcnt(6)
	s_barrier
	ds_read_b128 v[136:139], v217
	ds_read_b128 v[146:149], v217 offset:2048
	ds_read_b128 v[188:191], v245
	ds_read_b128 v[192:195], v245 offset:2048
	ds_read_b128 v[196:199], v245 offset:16384
	ds_read_b128 v[200:203], v245 offset:18432
	s_add_i32 m0, s44, 0xc000
	s_add_u32 s42, s0, 0x160000
	s_addc_u32 s43, s1, 0
	v_mfma_f32_16x16x32_bf16 v[92:95], v[204:207], v[150:153], v[92:95]
	v_mfma_f32_16x16x32_bf16 v[88:91], v[208:211], v[150:153], v[88:91]
	v_mfma_f32_16x16x32_bf16 v[84:87], v[212:215], v[150:153], v[84:87]
	v_mfma_f32_16x16x32_bf16 v[80:83], v[240:243], v[150:153], v[80:83]
	ds_read_b128 v[150:153], v217 offset:4096
	global_load_lds_dwordx4 v145, s[42:43]
	s_add_i32 m0, s44, 0xe000
	s_add_u32 s42, s0, 0x210000
	s_addc_u32 s43, s1, 0
	v_mfma_f32_16x16x32_bf16 v[76:79], v[204:207], v[154:157], v[76:79]
	v_mfma_f32_16x16x32_bf16 v[72:75], v[208:211], v[154:157], v[72:75]
	v_mfma_f32_16x16x32_bf16 v[68:71], v[212:215], v[154:157], v[68:71]
	v_mfma_f32_16x16x32_bf16 v[64:67], v[240:243], v[154:157], v[64:67]
	ds_read_b128 v[154:157], v217 offset:6144
	global_load_lds_dwordx4 v145, s[42:43]
	v_mfma_f32_16x16x32_bf16 v[60:63], v[204:207], v[158:161], v[60:63]
	v_mfma_f32_16x16x32_bf16 v[56:59], v[208:211], v[158:161], v[56:59]
	v_mfma_f32_16x16x32_bf16 v[52:55], v[212:215], v[158:161], v[52:55]
	v_mfma_f32_16x16x32_bf16 v[48:51], v[240:243], v[158:161], v[48:51]
	ds_read_b128 v[158:161], v217 offset:16384
	v_mfma_f32_16x16x32_bf16 v[44:47], v[204:207], v[176:179], v[44:47]
	v_mfma_f32_16x16x32_bf16 v[40:43], v[208:211], v[176:179], v[40:43]
	v_mfma_f32_16x16x32_bf16 v[36:39], v[212:215], v[176:179], v[36:39]
	v_mfma_f32_16x16x32_bf16 v[32:35], v[240:243], v[176:179], v[32:35]
	ds_read_b128 v[176:179], v217 offset:18432
	v_mfma_f32_16x16x32_bf16 v[28:31], v[204:207], v[180:183], v[28:31]
	v_mfma_f32_16x16x32_bf16 v[24:27], v[208:211], v[180:183], v[24:27]
	v_mfma_f32_16x16x32_bf16 v[20:23], v[212:215], v[180:183], v[20:23]
	v_mfma_f32_16x16x32_bf16 v[16:19], v[240:243], v[180:183], v[16:19]
	ds_read_b128 v[180:183], v217 offset:20480
	v_mfma_f32_16x16x32_bf16 v[12:15], v[204:207], v[184:187], v[12:15]
	v_mfma_f32_16x16x32_bf16 v[8:11], v[208:211], v[184:187], v[8:11]
	v_mfma_f32_16x16x32_bf16 v[4:7], v[212:215], v[184:187], v[4:7]
	v_mfma_f32_16x16x32_bf16 v[0:3], v[240:243], v[184:187], v[0:3]
	ds_read_b128 v[184:187], v217 offset:22528
	s_add_u32 s0, s0, 128
	s_addc_u32 s1, s1, 0
	s_add_u32 s8, s8, 128
	s_addc_u32 s9, s9, 0
	s_add_i32 s39, s39, 1
	s_cmp_lt_u32 s39, 44
	s_cbranch_scc1 .Ls4_loop
	s_waitcnt lgkmcnt(0)
	s_nop 7
	s_nop 3
	v_lshl_add_u32 v217, s38, 8, v163
	v_add_u32_e32 v217, s26, v217
	v_lshlrev_b32_e32 v208, 2, v217
	v_lshl_add_u32 v214, v225, 3, s27
	v_lshl_add_u32 v214, s37, 8, v214
	v_lshl_add_u32 v209, v217, 11, v214
	v_lshlrev_b32_e32 v209, 1, v209
	v_lshlrev_b32_e32 v210, 1, v209
	v_lshl_add_u32 v217, v225, 4, v163
	v_xor_b32_e32 v215, 16, v217
	v_lshlrev_b32_e32 v215, 2, v215
	v_xor_b32_e32 v216, 32, v217
	v_lshlrev_b32_e32 v216, 2, v216
	v_add_u32_e32 v211, 0x0, v209
	global_load_dwordx4 v[176:179], v211, s[80:81]
	global_load_dwordx4 v[180:183], v211, s[80:81] offset:256
	v_add_u32_e32 v211, 0x10000, v209
	global_load_dwordx4 v[192:195], v211, s[80:81]
	global_load_dwordx4 v[196:199], v211, s[80:81] offset:256
	s_waitcnt vmcnt(2)
	v_lshlrev_b32_e32 v184, 16, v176
	v_and_b32_e32 v185, 0xffff0000, v176
	v_lshlrev_b32_e32 v186, 16, v177
	v_and_b32_e32 v187, 0xffff0000, v177
	v_lshlrev_b32_e32 v188, 16, v178
	v_and_b32_e32 v189, 0xffff0000, v178
	v_lshlrev_b32_e32 v190, 16, v179
	v_and_b32_e32 v191, 0xffff0000, v179
	v_pk_add_f32 v[124:125], v[124:125], v[184:185]
	v_pk_add_f32 v[126:127], v[126:127], v[186:187]
	v_pk_add_f32 v[120:121], v[120:121], v[188:189]
	v_pk_add_f32 v[122:123], v[122:123], v[190:191]
	v_mul_f32_e32 v213, v124, v124
	v_fmac_f32_e32 v213, v125, v125
	v_fmac_f32_e32 v213, v126, v126
	v_fmac_f32_e32 v213, v127, v127
	v_fmac_f32_e32 v213, v120, v120
	v_fmac_f32_e32 v213, v121, v121
	v_fmac_f32_e32 v213, v122, v122
	v_fmac_f32_e32 v213, v123, v123
	v_cvt_pk_bf16_f32 v176, v124, v125
	v_cvt_pk_bf16_f32 v177, v126, v127
	v_cvt_pk_bf16_f32 v178, v120, v121
	v_cvt_pk_bf16_f32 v179, v122, v123
	v_add_u32_e32 v217, 0x0, v209
	global_store_dwordx4 v217, v[176:179], s[80:81]
	v_lshlrev_b32_e32 v184, 16, v180
	v_and_b32_e32 v185, 0xffff0000, v180
	v_lshlrev_b32_e32 v186, 16, v181
	v_and_b32_e32 v187, 0xffff0000, v181
	v_lshlrev_b32_e32 v188, 16, v182
	v_and_b32_e32 v189, 0xffff0000, v182
	v_lshlrev_b32_e32 v190, 16, v183
	v_and_b32_e32 v191, 0xffff0000, v183
	v_pk_add_f32 v[116:117], v[116:117], v[184:185]
	v_pk_add_f32 v[118:119], v[118:119], v[186:187]
	v_pk_add_f32 v[112:113], v[112:113], v[188:189]
	v_pk_add_f32 v[114:115], v[114:115], v[190:191]
	v_fmac_f32_e32 v213, v116, v116
	v_fmac_f32_e32 v213, v117, v117
	v_fmac_f32_e32 v213, v118, v118
	v_fmac_f32_e32 v213, v119, v119
	v_fmac_f32_e32 v213, v112, v112
	v_fmac_f32_e32 v213, v113, v113
	v_fmac_f32_e32 v213, v114, v114
	v_fmac_f32_e32 v213, v115, v115
	v_cvt_pk_bf16_f32 v180, v116, v117
	v_cvt_pk_bf16_f32 v181, v118, v119
	v_cvt_pk_bf16_f32 v182, v112, v113
	v_cvt_pk_bf16_f32 v183, v114, v115
	global_store_dwordx4 v217, v[180:183], s[80:81] offset:256
	ds_bpermute_b32 v214, v215, v213
	s_waitcnt lgkmcnt(0)
	v_add_f32_e32 v213, v213, v214
	ds_bpermute_b32 v214, v216, v213
	s_waitcnt lgkmcnt(0)
	v_add_f32_e32 v213, v213, v214
	s_mov_b64 exec, 0xffff
	global_atomic_add_f32 v208, v213, s[14:15]
	s_mov_b64 exec, -1
	v_add_u32_e32 v211, 0x20000, v209
	global_load_dwordx4 v[176:179], v211, s[80:81]
	global_load_dwordx4 v[180:183], v211, s[80:81] offset:256
	s_waitcnt vmcnt(5)
	v_lshlrev_b32_e32 v200, 16, v192
	v_and_b32_e32 v201, 0xffff0000, v192
	v_lshlrev_b32_e32 v202, 16, v193
	v_and_b32_e32 v203, 0xffff0000, v193
	v_lshlrev_b32_e32 v204, 16, v194
	v_and_b32_e32 v205, 0xffff0000, v194
	v_lshlrev_b32_e32 v206, 16, v195
	v_and_b32_e32 v207, 0xffff0000, v195
	v_pk_add_f32 v[108:109], v[108:109], v[200:201]
	v_pk_add_f32 v[110:111], v[110:111], v[202:203]
	v_pk_add_f32 v[104:105], v[104:105], v[204:205]
	v_pk_add_f32 v[106:107], v[106:107], v[206:207]
	v_mul_f32_e32 v213, v108, v108
	v_fmac_f32_e32 v213, v109, v109
	v_fmac_f32_e32 v213, v110, v110
	v_fmac_f32_e32 v213, v111, v111
	v_fmac_f32_e32 v213, v104, v104
	v_fmac_f32_e32 v213, v105, v105
	v_fmac_f32_e32 v213, v106, v106
	v_fmac_f32_e32 v213, v107, v107
	v_cvt_pk_bf16_f32 v192, v108, v109
	v_cvt_pk_bf16_f32 v193, v110, v111
	v_cvt_pk_bf16_f32 v194, v104, v105
	v_cvt_pk_bf16_f32 v195, v106, v107
	v_add_u32_e32 v217, 0x10000, v209
	global_store_dwordx4 v217, v[192:195], s[80:81]
	v_lshlrev_b32_e32 v200, 16, v196
	v_and_b32_e32 v201, 0xffff0000, v196
	v_lshlrev_b32_e32 v202, 16, v197
	v_and_b32_e32 v203, 0xffff0000, v197
	v_lshlrev_b32_e32 v204, 16, v198
	v_and_b32_e32 v205, 0xffff0000, v198
	v_lshlrev_b32_e32 v206, 16, v199
	v_and_b32_e32 v207, 0xffff0000, v199
	v_pk_add_f32 v[100:101], v[100:101], v[200:201]
	v_pk_add_f32 v[102:103], v[102:103], v[202:203]
	v_pk_add_f32 v[96:97], v[96:97], v[204:205]
	v_pk_add_f32 v[98:99], v[98:99], v[206:207]
	v_fmac_f32_e32 v213, v100, v100
	v_fmac_f32_e32 v213, v101, v101
	v_fmac_f32_e32 v213, v102, v102
	v_fmac_f32_e32 v213, v103, v103
	v_fmac_f32_e32 v213, v96, v96
	v_fmac_f32_e32 v213, v97, v97
	v_fmac_f32_e32 v213, v98, v98
	v_fmac_f32_e32 v213, v99, v99
	v_cvt_pk_bf16_f32 v196, v100, v101
	v_cvt_pk_bf16_f32 v197, v102, v103
	v_cvt_pk_bf16_f32 v198, v96, v97
	v_cvt_pk_bf16_f32 v199, v98, v99
	global_store_dwordx4 v217, v[196:199], s[80:81] offset:256
	ds_bpermute_b32 v214, v215, v213
	s_waitcnt lgkmcnt(0)
	v_add_f32_e32 v213, v213, v214
	ds_bpermute_b32 v214, v216, v213
	s_waitcnt lgkmcnt(0)
	v_add_f32_e32 v213, v213, v214
	s_mov_b64 exec, 0xffff
	global_atomic_add_f32 v208, v213, s[14:15] offset:64
	s_mov_b64 exec, -1
	v_add_u32_e32 v211, 0x30000, v209
	global_load_dwordx4 v[192:195], v211, s[80:81]
	global_load_dwordx4 v[196:199], v211, s[80:81] offset:256
	s_waitcnt vmcnt(5)
	v_lshlrev_b32_e32 v184, 16, v176
	v_and_b32_e32 v185, 0xffff0000, v176
	v_lshlrev_b32_e32 v186, 16, v177
	v_and_b32_e32 v187, 0xffff0000, v177
	v_lshlrev_b32_e32 v188, 16, v178
	v_and_b32_e32 v189, 0xffff0000, v178
	v_lshlrev_b32_e32 v190, 16, v179
	v_and_b32_e32 v191, 0xffff0000, v179
	v_pk_add_f32 v[92:93], v[92:93], v[184:185]
	v_pk_add_f32 v[94:95], v[94:95], v[186:187]
	v_pk_add_f32 v[88:89], v[88:89], v[188:189]
	v_pk_add_f32 v[90:91], v[90:91], v[190:191]
	v_mul_f32_e32 v213, v92, v92
	v_fmac_f32_e32 v213, v93, v93
	v_fmac_f32_e32 v213, v94, v94
	v_fmac_f32_e32 v213, v95, v95
	v_fmac_f32_e32 v213, v88, v88
	v_fmac_f32_e32 v213, v89, v89
	v_fmac_f32_e32 v213, v90, v90
	v_fmac_f32_e32 v213, v91, v91
	v_cvt_pk_bf16_f32 v176, v92, v93
	v_cvt_pk_bf16_f32 v177, v94, v95
	v_cvt_pk_bf16_f32 v178, v88, v89
	v_cvt_pk_bf16_f32 v179, v90, v91
	v_add_u32_e32 v217, 0x20000, v209
	global_store_dwordx4 v217, v[176:179], s[80:81]
	v_lshlrev_b32_e32 v184, 16, v180
	v_and_b32_e32 v185, 0xffff0000, v180
	v_lshlrev_b32_e32 v186, 16, v181
	v_and_b32_e32 v187, 0xffff0000, v181
	v_lshlrev_b32_e32 v188, 16, v182
	v_and_b32_e32 v189, 0xffff0000, v182
	v_lshlrev_b32_e32 v190, 16, v183
	v_and_b32_e32 v191, 0xffff0000, v183
	v_pk_add_f32 v[84:85], v[84:85], v[184:185]
	v_pk_add_f32 v[86:87], v[86:87], v[186:187]
	v_pk_add_f32 v[80:81], v[80:81], v[188:189]
	v_pk_add_f32 v[82:83], v[82:83], v[190:191]
	v_fmac_f32_e32 v213, v84, v84
	v_fmac_f32_e32 v213, v85, v85
	v_fmac_f32_e32 v213, v86, v86
	v_fmac_f32_e32 v213, v87, v87
	v_fmac_f32_e32 v213, v80, v80
	v_fmac_f32_e32 v213, v81, v81
	v_fmac_f32_e32 v213, v82, v82
	v_fmac_f32_e32 v213, v83, v83
	v_cvt_pk_bf16_f32 v180, v84, v85
	v_cvt_pk_bf16_f32 v181, v86, v87
	v_cvt_pk_bf16_f32 v182, v80, v81
	v_cvt_pk_bf16_f32 v183, v82, v83
	global_store_dwordx4 v217, v[180:183], s[80:81] offset:256
	ds_bpermute_b32 v214, v215, v213
	s_waitcnt lgkmcnt(0)
	v_add_f32_e32 v213, v213, v214
	ds_bpermute_b32 v214, v216, v213
	s_waitcnt lgkmcnt(0)
	v_add_f32_e32 v213, v213, v214
	s_mov_b64 exec, 0xffff
	global_atomic_add_f32 v208, v213, s[14:15] offset:128
	s_mov_b64 exec, -1
	v_add_u32_e32 v211, 0x80000, v209
	global_load_dwordx4 v[176:179], v211, s[80:81]
	global_load_dwordx4 v[180:183], v211, s[80:81] offset:256
	s_waitcnt vmcnt(5)
	v_lshlrev_b32_e32 v200, 16, v192
	v_and_b32_e32 v201, 0xffff0000, v192
	v_lshlrev_b32_e32 v202, 16, v193
	v_and_b32_e32 v203, 0xffff0000, v193
	v_lshlrev_b32_e32 v204, 16, v194
	v_and_b32_e32 v205, 0xffff0000, v194
	v_lshlrev_b32_e32 v206, 16, v195
	v_and_b32_e32 v207, 0xffff0000, v195
	v_pk_add_f32 v[76:77], v[76:77], v[200:201]
	v_pk_add_f32 v[78:79], v[78:79], v[202:203]
	v_pk_add_f32 v[72:73], v[72:73], v[204:205]
	v_pk_add_f32 v[74:75], v[74:75], v[206:207]
	v_mul_f32_e32 v213, v76, v76
	v_fmac_f32_e32 v213, v77, v77
	v_fmac_f32_e32 v213, v78, v78
	v_fmac_f32_e32 v213, v79, v79
	v_fmac_f32_e32 v213, v72, v72
	v_fmac_f32_e32 v213, v73, v73
	v_fmac_f32_e32 v213, v74, v74
	v_fmac_f32_e32 v213, v75, v75
	v_cvt_pk_bf16_f32 v192, v76, v77
	v_cvt_pk_bf16_f32 v193, v78, v79
	v_cvt_pk_bf16_f32 v194, v72, v73
	v_cvt_pk_bf16_f32 v195, v74, v75
	v_add_u32_e32 v217, 0x30000, v209
	global_store_dwordx4 v217, v[192:195], s[80:81]
	v_lshlrev_b32_e32 v200, 16, v196
	v_and_b32_e32 v201, 0xffff0000, v196
	v_lshlrev_b32_e32 v202, 16, v197
	v_and_b32_e32 v203, 0xffff0000, v197
	v_lshlrev_b32_e32 v204, 16, v198
	v_and_b32_e32 v205, 0xffff0000, v198
	v_lshlrev_b32_e32 v206, 16, v199
	v_and_b32_e32 v207, 0xffff0000, v199
	v_pk_add_f32 v[68:69], v[68:69], v[200:201]
	v_pk_add_f32 v[70:71], v[70:71], v[202:203]
	v_pk_add_f32 v[64:65], v[64:65], v[204:205]
	v_pk_add_f32 v[66:67], v[66:67], v[206:207]
	v_fmac_f32_e32 v213, v68, v68
	v_fmac_f32_e32 v213, v69, v69
	v_fmac_f32_e32 v213, v70, v70
	v_fmac_f32_e32 v213, v71, v71
	v_fmac_f32_e32 v213, v64, v64
	v_fmac_f32_e32 v213, v65, v65
	v_fmac_f32_e32 v213, v66, v66
	v_fmac_f32_e32 v213, v67, v67
	v_cvt_pk_bf16_f32 v196, v68, v69
	v_cvt_pk_bf16_f32 v197, v70, v71
	v_cvt_pk_bf16_f32 v198, v64, v65
	v_cvt_pk_bf16_f32 v199, v66, v67
	global_store_dwordx4 v217, v[196:199], s[80:81] offset:256
	ds_bpermute_b32 v214, v215, v213
	s_waitcnt lgkmcnt(0)
	v_add_f32_e32 v213, v213, v214
	ds_bpermute_b32 v214, v216, v213
	s_waitcnt lgkmcnt(0)
	v_add_f32_e32 v213, v213, v214
	s_mov_b64 exec, 0xffff
	global_atomic_add_f32 v208, v213, s[14:15] offset:192
	s_mov_b64 exec, -1
	v_add_u32_e32 v211, 0x90000, v209
	global_load_dwordx4 v[192:195], v211, s[80:81]
	global_load_dwordx4 v[196:199], v211, s[80:81] offset:256
	s_waitcnt vmcnt(5)
	v_lshlrev_b32_e32 v184, 16, v176
	v_and_b32_e32 v185, 0xffff0000, v176
	v_lshlrev_b32_e32 v186, 16, v177
	v_and_b32_e32 v187, 0xffff0000, v177
	v_lshlrev_b32_e32 v188, 16, v178
	v_and_b32_e32 v189, 0xffff0000, v178
	v_lshlrev_b32_e32 v190, 16, v179
	v_and_b32_e32 v191, 0xffff0000, v179
	v_pk_add_f32 v[60:61], v[60:61], v[184:185]
	v_pk_add_f32 v[62:63], v[62:63], v[186:187]
	v_pk_add_f32 v[56:57], v[56:57], v[188:189]
	v_pk_add_f32 v[58:59], v[58:59], v[190:191]
	v_mul_f32_e32 v213, v60, v60
	v_fmac_f32_e32 v213, v61, v61
	v_fmac_f32_e32 v213, v62, v62
	v_fmac_f32_e32 v213, v63, v63
	v_fmac_f32_e32 v213, v56, v56
	v_fmac_f32_e32 v213, v57, v57
	v_fmac_f32_e32 v213, v58, v58
	v_fmac_f32_e32 v213, v59, v59
	v_cvt_pk_bf16_f32 v176, v60, v61
	v_cvt_pk_bf16_f32 v177, v62, v63
	v_cvt_pk_bf16_f32 v178, v56, v57
	v_cvt_pk_bf16_f32 v179, v58, v59
	v_add_u32_e32 v217, 0x80000, v209
	global_store_dwordx4 v217, v[176:179], s[80:81]
	v_lshlrev_b32_e32 v184, 16, v180
	v_and_b32_e32 v185, 0xffff0000, v180
	v_lshlrev_b32_e32 v186, 16, v181
	v_and_b32_e32 v187, 0xffff0000, v181
	v_lshlrev_b32_e32 v188, 16, v182
	v_and_b32_e32 v189, 0xffff0000, v182
	v_lshlrev_b32_e32 v190, 16, v183
	v_and_b32_e32 v191, 0xffff0000, v183
	v_pk_add_f32 v[52:53], v[52:53], v[184:185]
	v_pk_add_f32 v[54:55], v[54:55], v[186:187]
	v_pk_add_f32 v[48:49], v[48:49], v[188:189]
	v_pk_add_f32 v[50:51], v[50:51], v[190:191]
	v_fmac_f32_e32 v213, v52, v52
	v_fmac_f32_e32 v213, v53, v53
	v_fmac_f32_e32 v213, v54, v54
	v_fmac_f32_e32 v213, v55, v55
	v_fmac_f32_e32 v213, v48, v48
	v_fmac_f32_e32 v213, v49, v49
	v_fmac_f32_e32 v213, v50, v50
	v_fmac_f32_e32 v213, v51, v51
	v_cvt_pk_bf16_f32 v180, v52, v53
	v_cvt_pk_bf16_f32 v181, v54, v55
	v_cvt_pk_bf16_f32 v182, v48, v49
	v_cvt_pk_bf16_f32 v183, v50, v51
	global_store_dwordx4 v217, v[180:183], s[80:81] offset:256
	ds_bpermute_b32 v214, v215, v213
	s_waitcnt lgkmcnt(0)
	v_add_f32_e32 v213, v213, v214
	ds_bpermute_b32 v214, v216, v213
	s_waitcnt lgkmcnt(0)
	v_add_f32_e32 v213, v213, v214
	s_mov_b64 exec, 0xffff
	global_atomic_add_f32 v208, v213, s[14:15] offset:512
	s_mov_b64 exec, -1
	v_add_u32_e32 v211, 0xa0000, v209
	global_load_dwordx4 v[176:179], v211, s[80:81]
	global_load_dwordx4 v[180:183], v211, s[80:81] offset:256
	s_waitcnt vmcnt(5)
	v_lshlrev_b32_e32 v200, 16, v192
	v_and_b32_e32 v201, 0xffff0000, v192
	v_lshlrev_b32_e32 v202, 16, v193
	v_and_b32_e32 v203, 0xffff0000, v193
	v_lshlrev_b32_e32 v204, 16, v194
	v_and_b32_e32 v205, 0xffff0000, v194
	v_lshlrev_b32_e32 v206, 16, v195
	v_and_b32_e32 v207, 0xffff0000, v195
	v_pk_add_f32 v[44:45], v[44:45], v[200:201]
	v_pk_add_f32 v[46:47], v[46:47], v[202:203]
	v_pk_add_f32 v[40:41], v[40:41], v[204:205]
	v_pk_add_f32 v[42:43], v[42:43], v[206:207]
	v_mul_f32_e32 v213, v44, v44
	v_fmac_f32_e32 v213, v45, v45
	v_fmac_f32_e32 v213, v46, v46
	v_fmac_f32_e32 v213, v47, v47
	v_fmac_f32_e32 v213, v40, v40
	v_fmac_f32_e32 v213, v41, v41
	v_fmac_f32_e32 v213, v42, v42
	v_fmac_f32_e32 v213, v43, v43
	v_cvt_pk_bf16_f32 v192, v44, v45
	v_cvt_pk_bf16_f32 v193, v46, v47
	v_cvt_pk_bf16_f32 v194, v40, v41
	v_cvt_pk_bf16_f32 v195, v42, v43
	v_add_u32_e32 v217, 0x90000, v209
	global_store_dwordx4 v217, v[192:195], s[80:81]
	v_lshlrev_b32_e32 v200, 16, v196
	v_and_b32_e32 v201, 0xffff0000, v196
	v_lshlrev_b32_e32 v202, 16, v197
	v_and_b32_e32 v203, 0xffff0000, v197
	v_lshlrev_b32_e32 v204, 16, v198
	v_and_b32_e32 v205, 0xffff0000, v198
	v_lshlrev_b32_e32 v206, 16, v199
	v_and_b32_e32 v207, 0xffff0000, v199
	v_pk_add_f32 v[36:37], v[36:37], v[200:201]
	v_pk_add_f32 v[38:39], v[38:39], v[202:203]
	v_pk_add_f32 v[32:33], v[32:33], v[204:205]
	v_pk_add_f32 v[34:35], v[34:35], v[206:207]
	v_fmac_f32_e32 v213, v36, v36
	v_fmac_f32_e32 v213, v37, v37
	v_fmac_f32_e32 v213, v38, v38
	v_fmac_f32_e32 v213, v39, v39
	v_fmac_f32_e32 v213, v32, v32
	v_fmac_f32_e32 v213, v33, v33
	v_fmac_f32_e32 v213, v34, v34
	v_fmac_f32_e32 v213, v35, v35
	v_cvt_pk_bf16_f32 v196, v36, v37
	v_cvt_pk_bf16_f32 v197, v38, v39
	v_cvt_pk_bf16_f32 v198, v32, v33
	v_cvt_pk_bf16_f32 v199, v34, v35
	global_store_dwordx4 v217, v[196:199], s[80:81] offset:256
	ds_bpermute_b32 v214, v215, v213
	s_waitcnt lgkmcnt(0)
	v_add_f32_e32 v213, v213, v214
	ds_bpermute_b32 v214, v216, v213
	s_waitcnt lgkmcnt(0)
	v_add_f32_e32 v213, v213, v214
	s_mov_b64 exec, 0xffff
	global_atomic_add_f32 v208, v213, s[14:15] offset:576
	s_mov_b64 exec, -1
	v_add_u32_e32 v211, 0xb0000, v209
	global_load_dwordx4 v[192:195], v211, s[80:81]
	global_load_dwordx4 v[196:199], v211, s[80:81] offset:256
	s_waitcnt vmcnt(5)
	v_lshlrev_b32_e32 v184, 16, v176
	v_and_b32_e32 v185, 0xffff0000, v176
	v_lshlrev_b32_e32 v186, 16, v177
	v_and_b32_e32 v187, 0xffff0000, v177
	v_lshlrev_b32_e32 v188, 16, v178
	v_and_b32_e32 v189, 0xffff0000, v178
	v_lshlrev_b32_e32 v190, 16, v179
	v_and_b32_e32 v191, 0xffff0000, v179
	v_pk_add_f32 v[28:29], v[28:29], v[184:185]
	v_pk_add_f32 v[30:31], v[30:31], v[186:187]
	v_pk_add_f32 v[24:25], v[24:25], v[188:189]
	v_pk_add_f32 v[26:27], v[26:27], v[190:191]
	v_mul_f32_e32 v213, v28, v28
	v_fmac_f32_e32 v213, v29, v29
	v_fmac_f32_e32 v213, v30, v30
	v_fmac_f32_e32 v213, v31, v31
	v_fmac_f32_e32 v213, v24, v24
	v_fmac_f32_e32 v213, v25, v25
	v_fmac_f32_e32 v213, v26, v26
	v_fmac_f32_e32 v213, v27, v27
	v_cvt_pk_bf16_f32 v176, v28, v29
	v_cvt_pk_bf16_f32 v177, v30, v31
	v_cvt_pk_bf16_f32 v178, v24, v25
	v_cvt_pk_bf16_f32 v179, v26, v27
	v_add_u32_e32 v217, 0xa0000, v209
	global_store_dwordx4 v217, v[176:179], s[80:81]
	v_lshlrev_b32_e32 v184, 16, v180
	v_and_b32_e32 v185, 0xffff0000, v180
	v_lshlrev_b32_e32 v186, 16, v181
	v_and_b32_e32 v187, 0xffff0000, v181
	v_lshlrev_b32_e32 v188, 16, v182
	v_and_b32_e32 v189, 0xffff0000, v182
	v_lshlrev_b32_e32 v190, 16, v183
	v_and_b32_e32 v191, 0xffff0000, v183
	v_pk_add_f32 v[20:21], v[20:21], v[184:185]
	v_pk_add_f32 v[22:23], v[22:23], v[186:187]
	v_pk_add_f32 v[16:17], v[16:17], v[188:189]
	v_pk_add_f32 v[18:19], v[18:19], v[190:191]
	v_fmac_f32_e32 v213, v20, v20
	v_fmac_f32_e32 v213, v21, v21
	v_fmac_f32_e32 v213, v22, v22
	v_fmac_f32_e32 v213, v23, v23
	v_fmac_f32_e32 v213, v16, v16
	v_fmac_f32_e32 v213, v17, v17
	v_fmac_f32_e32 v213, v18, v18
	v_fmac_f32_e32 v213, v19, v19
	v_cvt_pk_bf16_f32 v180, v20, v21
	v_cvt_pk_bf16_f32 v181, v22, v23
	v_cvt_pk_bf16_f32 v182, v16, v17
	v_cvt_pk_bf16_f32 v183, v18, v19
	global_store_dwordx4 v217, v[180:183], s[80:81] offset:256
	ds_bpermute_b32 v214, v215, v213
	s_waitcnt lgkmcnt(0)
	v_add_f32_e32 v213, v213, v214
	ds_bpermute_b32 v214, v216, v213
	s_waitcnt lgkmcnt(0)
	v_add_f32_e32 v213, v213, v214
	s_mov_b64 exec, 0xffff
	global_atomic_add_f32 v208, v213, s[14:15] offset:640
	s_mov_b64 exec, -1
	s_waitcnt vmcnt(3)
	v_lshlrev_b32_e32 v200, 16, v192
	v_and_b32_e32 v201, 0xffff0000, v192
	v_lshlrev_b32_e32 v202, 16, v193
	v_and_b32_e32 v203, 0xffff0000, v193
	v_lshlrev_b32_e32 v204, 16, v194
	v_and_b32_e32 v205, 0xffff0000, v194
	v_lshlrev_b32_e32 v206, 16, v195
	v_and_b32_e32 v207, 0xffff0000, v195
	v_pk_add_f32 v[12:13], v[12:13], v[200:201]
	v_pk_add_f32 v[14:15], v[14:15], v[202:203]
	v_pk_add_f32 v[8:9], v[8:9], v[204:205]
	v_pk_add_f32 v[10:11], v[10:11], v[206:207]
	v_mul_f32_e32 v213, v12, v12
	v_fmac_f32_e32 v213, v13, v13
	v_fmac_f32_e32 v213, v14, v14
	v_fmac_f32_e32 v213, v15, v15
	v_fmac_f32_e32 v213, v8, v8
	v_fmac_f32_e32 v213, v9, v9
	v_fmac_f32_e32 v213, v10, v10
	v_fmac_f32_e32 v213, v11, v11
	v_cvt_pk_bf16_f32 v192, v12, v13
	v_cvt_pk_bf16_f32 v193, v14, v15
	v_cvt_pk_bf16_f32 v194, v8, v9
	v_cvt_pk_bf16_f32 v195, v10, v11
	v_add_u32_e32 v217, 0xb0000, v209
	global_store_dwordx4 v217, v[192:195], s[80:81]
	v_lshlrev_b32_e32 v200, 16, v196
	v_and_b32_e32 v201, 0xffff0000, v196
	v_lshlrev_b32_e32 v202, 16, v197
	v_and_b32_e32 v203, 0xffff0000, v197
	v_lshlrev_b32_e32 v204, 16, v198
	v_and_b32_e32 v205, 0xffff0000, v198
	v_lshlrev_b32_e32 v206, 16, v199
	v_and_b32_e32 v207, 0xffff0000, v199
	v_pk_add_f32 v[4:5], v[4:5], v[200:201]
	v_pk_add_f32 v[6:7], v[6:7], v[202:203]
	v_pk_add_f32 v[0:1], v[0:1], v[204:205]
	v_pk_add_f32 v[2:3], v[2:3], v[206:207]
	v_fmac_f32_e32 v213, v4, v4
	v_fmac_f32_e32 v213, v5, v5
	v_fmac_f32_e32 v213, v6, v6
	v_fmac_f32_e32 v213, v7, v7
	v_fmac_f32_e32 v213, v0, v0
	v_fmac_f32_e32 v213, v1, v1
	v_fmac_f32_e32 v213, v2, v2
	v_fmac_f32_e32 v213, v3, v3
	v_cvt_pk_bf16_f32 v196, v4, v5
	v_cvt_pk_bf16_f32 v197, v6, v7
	v_cvt_pk_bf16_f32 v198, v0, v1
	v_cvt_pk_bf16_f32 v199, v2, v3
	global_store_dwordx4 v217, v[196:199], s[80:81] offset:256
	ds_bpermute_b32 v214, v215, v213
	s_waitcnt lgkmcnt(0)
	v_add_f32_e32 v213, v213, v214
	ds_bpermute_b32 v214, v216, v213
	s_waitcnt lgkmcnt(0)
	v_add_f32_e32 v213, v213, v214
	s_mov_b64 exec, 0xffff
	global_atomic_add_f32 v208, v213, s[14:15] offset:704
	s_mov_b64 exec, -1
	s_branch .LBB0_496

.LBB0_586:
	s_add_u32 s4, s92, 0x30000
	v_cndmask_b32_e64 v0, 0, 1, s[8:9]
	s_addc_u32 s5, s93, 0
	v_cmp_ne_u32_e64 s[6:7], 1, v0
	s_andn2_b64 vcc, exec, s[8:9]
	s_cbranch_vccnz .LBB0_634
	s_add_u32 s34, s92, 0x6300000
	s_addc_u32 s35, s93, 0
	s_lshr_b32 s9, s3, 6
	s_ashr_i32 s13, s12, 31
	s_ashr_i32 s1, s0, 31
	s_lshr_b32 s8, s3, 8
	s_lshl_b32 s36, s9, 10
	s_lshl_b64 s[10:11], s[12:13], 20
	s_lshl_b64 s[16:17], s[0:1], 20
	s_add_u32 s28, s34, s16
	s_addc_u32 s29, s35, s17
	s_add_i32 s37, s36, 0
	s_add_i32 m0, s37, 0x10000
	v_lshl_or_b32 v128, v236, 12, v219
	v_and_b32_e32 v140, 63, v222
	v_lshrrev_b32_e32 v141, 3, v140
	v_lshrrev_b32_e32 v142, 6, v222
	v_lshl_add_u32 v143, v142, 3, v141
	v_and_b32_e32 v144, 7, v140
	v_and_b32_e32 v145, 6, v141
	v_xor_b32_e32 v144, v144, v145
	v_lshlrev_b32_e32 v144, 4, v144
	v_mul_u32_u24_e32 v145, 0x1000, v143
	v_add_u32_e32 v145, v145, v144
	v_mov_b32_e32 v132, v145
	v_mov_b32_e32 v128, v145
	v_add_u32_e32 v134, 0x40000, v145
	v_add_u32_e32 v130, 0x40000, v145
	v_add_u32_e32 v134, 0x40000, v145
	v_add_u32_e32 v130, 0x40000, v145
	v_and_b32_e32 v145, 31, v143
	v_and_b32_e32 v154, 12, v145
	v_lshlrev_b32_e32 v154, 1, v154
	v_lshrrev_b32_e32 v155, 4, v145
	v_lshlrev_b32_e32 v155, 2, v155
	v_and_b32_e32 v145, 3, v145
	v_or3_b32 v145, v154, v155, v145
	v_and_b32_e32 v154, 0x60, v143
	v_add_u32_e32 v145, v145, v154
	v_mul_u32_u24_e32 v145, 0x1000, v145
	v_add_u32_e32 v145, v145, v144
	v_mov_b32_e32 v164, v145
	v_add_u32_e32 v166, 0x40000, v145
	v_add_u32_e32 v166, 0x40000, v145
	v_and_b32_e32 v145, 15, v140
	v_lshrrev_b32_e32 v154, 4, v140
	v_and_b32_e32 v155, 6, v145
	v_xor_b32_e32 v154, v154, v155
	v_lshlrev_b32_e32 v154, 4, v154
	v_lshl_or_b32 v154, v145, 7, v154
	v_lshrrev_b32_e32 v155, 2, v142
	v_lshl_add_u32 v155, v155, 13, v154
	v_add_u32_e32 v150, 0x0, v155
	v_and_b32_e32 v145, 3, v142
	v_lshl_add_u32 v145, v145, 12, v154
	v_add_u32_e32 v147, 0x0, v145
	v_add_u32_e32 v149, 0x10000, v145
	v_add_u32_e32 v151, 0x14000, v145
	s_add_i32 m0, s37, 0x12000
	s_add_u32 s26, s80, s10
	s_addc_u32 s27, s81, s11
	s_mov_b32 m0, s37
	s_add_i32 s38, s37, 0x2000
	s_mov_b32 m0, s38
	s_add_u32 s10, s28, 0x80000
	s_addc_u32 s11, s29, 0
	s_add_i32 m0, s37, 0x14000
	v_mov_b32_e32 v165, 0
	s_add_i32 m0, s37, 0x16000
	v_mov_b32_e32 v167, v165
	s_add_u32 s10, s26, 0x80000
	s_addc_u32 s11, s27, 0
	s_add_i32 s39, s37, 0x4000
	s_mov_b32 m0, s39
	s_add_i32 s40, s37, 0x6000
	s_mov_b32 m0, s40
	v_mov_b32_e32 v129, v165
	v_mov_b32_e32 v131, v165
	s_mov_b32 s41, 0
	v_lshl_add_u64 v[6:7], s[28:29], 0, v[164:165]
	v_lshl_add_u64 v[4:5], s[28:29], 0, v[166:167]
	v_lshl_add_u64 v[2:3], s[26:27], 0, v[128:129]
	s_cmp_lg_u32 s8, 1
	v_lshl_add_u64 v[0:1], s[26:27], 0, v[130:131]
	s_cbranch_scc1 .LBB0_589
.LBB0_589:
	s_mov_b64 s[16:17], 0x80
	s_lshl_b32 s9, s9, 5
	s_add_i32 m0, s37, 0x18000
	v_lshl_add_u64 v[6:7], v[6:7], 0, s[16:17]
	s_lshl_b32 s1, s8, 13
	s_and_b32 s13, s9, 0x60
	v_lshl_add_u64 v[4:5], v[4:5], 0, s[16:17]
	s_add_i32 m0, s37, 0x1a000
	s_add_i32 s42, s37, 0x8000
	s_add_i32 s43, s37, 0xa000
	v_lshl_add_u64 v[2:3], v[2:3], 0, s[16:17]
	s_mov_b32 m0, s42
	s_add_u32 s10, s28, 0x80080
	v_lshl_add_u64 v[0:1], v[0:1], 0, s[16:17]
	s_mov_b32 m0, s43
	s_addc_u32 s11, s29, 0
	s_add_i32 m0, s37, 0x1c000
	v_lshl_add_u64 v[0:1], s[10:11], 0, v[164:165]
	v_lshl_add_u64 v[0:1], s[10:11], 0, v[166:167]
	s_add_i32 m0, s37, 0x1e000
	v_lshlrev_b32_e32 v2, 12, v218
	v_lshlrev_b32_e32 v1, 2, v163
	v_lshl_or_b32 v0, v163, 6, v227
	v_and_b32_e32 v1, 32, v1
	v_bitop3_b32 v0, v0, s1, v1 bitop3:0xde
	v_lshlrev_b32_e32 v1, 9, v222
	v_and_b32_e32 v1, 0x70000, v1
	v_or3_b32 v1, v226, v1, v2
	v_lshlrev_b32_e32 v1, 5, v233
	v_and_b32_e32 v1, 0xf0000, v1
	v_or3_b32 v1, v226, v1, v2
	s_add_i32 s46, 0, 0x10000
	s_add_i32 s47, 0, 0x14000
	v_mbcnt_lo_u32_b32 v0, -1, 0
	v_lshl_or_b32 v146, s8, 6, v163
	s_ashr_i32 s44, s94, 31
	s_mov_b32 s45, s94
	v_cmp_eq_u32_e64 s[8:9], 0, v225
	v_lshl_or_b32 v148, v225, 3, s13
	v_mov_b32_e32 v133, v165
	v_mov_b32_e32 v135, v165
	v_mov_b64_e32 v[136:137], 0x400
	v_mov_b64_e32 v[138:139], 0x3ff
	v_mov_b32_e32 v152, 0x3727c5ac
	v_mbcnt_hi_u32_b32 v153, -1, v0
	v_and_b32_e32 v140, 63, v222
	v_lshrrev_b32_e32 v141, 6, v222
	v_lshrrev_b32_e32 v142, 3, v140
	v_lshl_add_u32 v143, v141, 3, v142
	v_and_b32_e32 v154, 7, v140
	v_and_b32_e32 v155, 6, v142
	v_xor_b32_e32 v154, v154, v155
	v_lshlrev_b32_e32 v154, 4, v154
	v_mul_u32_u24_e32 v155, 0x1000, v143
	v_add_u32_e32 v144, v155, v154
	v_and_b32_e32 v155, 31, v143
	v_and_b32_e32 v142, 12, v155
	v_lshlrev_b32_e32 v142, 1, v142
	v_lshrrev_b32_e32 v145, 4, v155
	v_lshlrev_b32_e32 v145, 2, v145
	v_and_b32_e32 v155, 3, v155
	v_or3_b32 v155, v142, v145, v155
	v_and_b32_e32 v142, 0x60, v143
	v_add_u32_e32 v155, v155, v142
	v_mul_u32_u24_e32 v155, 0x1000, v155
	v_add_u32_e32 v145, v155, v154
	v_and_b32_e32 v142, 15, v140
	v_lshrrev_b32_e32 v143, 4, v140
	v_and_b32_e32 v154, 6, v142
	v_xor_b32_e32 v143, v143, v154
	v_lshlrev_b32_e32 v143, 4, v143
	v_lshl_or_b32 v143, v142, 7, v143
	v_lshrrev_b32_e32 v154, 2, v141
	v_lshl_add_u32 v169, v154, 13, v143
	v_xor_b32_e32 v216, 64, v169
	v_and_b32_e32 v154, 3, v141
	v_lshl_add_u32 v217, v154, 12, v143
	v_add_u32_e32 v217, 0x10000, v217
	v_xor_b32_e32 v234, 64, v217
	v_readfirstlane_b32 s54, v222
	s_nop 3
	s_lshr_b32 s54, s54, 6
	s_lshl_b32 s54, s54, 10
	s_mov_b32 s98, 0
	s_mul_i32 s30, s98, s94
	s_add_i32 s30, s30, s2
	s_and_b32 s31, s30, 7
	s_lshr_b32 s30, s30, 3
	s_mul_i32 s31, s31, 0x80
	s_add_i32 s30, s30, s31
	s_mul_i32 s31, s30, 0x40000
	s_lshr_b32 s31, s31, 24
	s_mul_i32 s49, s31, 0x40
	s_sub_i32 s30, s30, s49
	s_and_b32 s48, s30, 3
	s_lshl_b32 s31, s31, 2
	s_add_i32 s48, s48, s31
	s_lshr_b32 s49, s30, 2
	s_mul_i32 s100, s48, 0x100000
	s_add_u32 s26, s92, 0xbd00000
	s_addc_u32 s27, s93, 0
	s_add_u32 s26, s26, s100
	s_addc_u32 s27, s27, 0
	s_mul_i32 s100, s49, 0x100000
	s_add_u32 s28, s92, 0x6300000
	s_addc_u32 s29, s93, 0
	s_add_u32 s28, s28, s100
	s_addc_u32 s29, s29, 0
	s_add_i32 m0, s54, 0x0
	s_nop 0
	global_load_lds_dwordx4 v144, s[26:27]
	s_add_i32 m0, s54, 0x2000
	s_add_u32 s52, s26, 0x40000
	s_addc_u32 s53, s27, 0
	s_nop 0
	global_load_lds_dwordx4 v144, s[52:53]
	s_add_i32 m0, s54, 0x4000
	s_add_u32 s52, s26, 0x80000
	s_addc_u32 s53, s27, 0
	s_nop 0
	global_load_lds_dwordx4 v144, s[52:53]
	s_add_i32 m0, s54, 0x6000
	s_add_u32 s52, s26, 0xc0000
	s_addc_u32 s53, s27, 0
	s_nop 0
	global_load_lds_dwordx4 v144, s[52:53]
	s_add_i32 m0, s54, 0x10000
	s_nop 0
	global_load_lds_dwordx4 v145, s[28:29]
	s_add_i32 m0, s54, 0x12000
	s_add_u32 s52, s28, 0x40000
	s_addc_u32 s53, s29, 0
	s_nop 0
	global_load_lds_dwordx4 v145, s[52:53]
	s_add_i32 m0, s54, 0x14000
	s_add_u32 s52, s28, 0x80000
	s_addc_u32 s53, s29, 0
	s_nop 0
	global_load_lds_dwordx4 v145, s[52:53]
	s_add_i32 m0, s54, 0x16000
	s_add_u32 s52, s28, 0xc0000
	s_addc_u32 s53, s29, 0
	s_nop 0
	global_load_lds_dwordx4 v145, s[52:53]
	s_add_u32 s26, s26, 128
	s_addc_u32 s27, s27, 0
	s_add_u32 s28, s28, 128
	s_addc_u32 s29, s29, 0
	s_add_i32 m0, s54, 0x8000
	s_nop 0
	global_load_lds_dwordx4 v144, s[26:27]
	s_add_i32 m0, s54, 0xa000
	s_add_u32 s52, s26, 0x40000
	s_addc_u32 s53, s27, 0
	s_nop 0
	global_load_lds_dwordx4 v144, s[52:53]
	s_add_i32 m0, s54, 0xc000
	s_add_u32 s52, s26, 0x80000
	s_addc_u32 s53, s27, 0
	s_nop 0
	global_load_lds_dwordx4 v144, s[52:53]
	s_add_i32 m0, s54, 0xe000
	s_add_u32 s52, s26, 0xc0000
	s_addc_u32 s53, s27, 0
	s_nop 0
	global_load_lds_dwordx4 v144, s[52:53]
	s_add_i32 m0, s54, 0x18000
	s_nop 0
	global_load_lds_dwordx4 v145, s[28:29]
	s_add_i32 m0, s54, 0x1a000
	s_add_u32 s52, s28, 0x40000
	s_addc_u32 s53, s29, 0
	s_nop 0
	global_load_lds_dwordx4 v145, s[52:53]
	s_add_i32 m0, s54, 0x1c000
	s_add_u32 s52, s28, 0x80000
	s_addc_u32 s53, s29, 0
	s_nop 0
	global_load_lds_dwordx4 v145, s[52:53]
	s_add_i32 m0, s54, 0x1e000
	s_add_u32 s52, s28, 0xc0000
	s_addc_u32 s53, s29, 0
	s_nop 0
	global_load_lds_dwordx4 v145, s[52:53]
	s_branch .LBB0_592

.LBB0_598:
	s_ashr_i32 s21, s20, 31
	v_cmp_lt_i64_e32 vcc, s[22:23], v[136:137]
	s_lshl_b64 s[22:23], s[20:21], 20
	s_add_u32 s22, s80, s22
	s_addc_u32 s23, s81, s23
	s_and_b64 s[24:25], vcc, exec
	s_cselect_b32 s1, s23, s27
	s_cselect_b32 s13, s22, s26
	s_ashr_i32 s19, s18, 31
	s_lshl_b64 s[24:25], s[18:19], 20
	s_add_u32 s24, s34, s24
	s_addc_u32 s25, s35, s25
	s_and_b64 s[30:31], vcc, exec
	s_cselect_b32 s19, s25, s29
	s_cselect_b32 s21, s24, s28
	s_add_u32 s26, s26, 0x80080
	s_addc_u32 s27, s27, 0
	s_add_u32 s33, s28, 0x100
	v_mov_b32_e32 v0, 0
	s_addc_u32 s48, s29, 0
	s_mov_b32 s49, -2
	s_waitcnt lgkmcnt(0)
	v_mov_b32_e32 v1, v0
	v_mov_b32_e32 v2, v0
	v_mov_b32_e32 v3, v0
	v_mov_b32_e32 v4, v0
	v_mov_b32_e32 v5, v0
	v_mov_b32_e32 v6, v0
	v_mov_b32_e32 v7, v0
	s_waitcnt vmcnt(0)
	v_mov_b32_e32 v16, v0
	v_mov_b32_e32 v17, v0
	v_mov_b32_e32 v18, v0
	v_mov_b32_e32 v19, v0
	v_mov_b32_e32 v20, v0
	v_mov_b32_e32 v21, v0
	v_mov_b32_e32 v22, v0
	v_mov_b32_e32 v23, v0
	v_mov_b32_e32 v32, v0
	v_mov_b32_e32 v33, v0
	v_mov_b32_e32 v34, v0
	v_mov_b32_e32 v35, v0
	v_mov_b32_e32 v36, v0
	v_mov_b32_e32 v37, v0
	v_mov_b32_e32 v38, v0
	v_mov_b32_e32 v39, v0
	v_mov_b32_e32 v48, v0
	v_mov_b32_e32 v49, v0
	v_mov_b32_e32 v50, v0
	v_mov_b32_e32 v51, v0
	v_mov_b32_e32 v52, v0
	v_mov_b32_e32 v53, v0
	v_mov_b32_e32 v54, v0
	v_mov_b32_e32 v55, v0
	v_mov_b32_e32 v8, v0
	v_mov_b32_e32 v9, v0
	v_mov_b32_e32 v10, v0
	v_mov_b32_e32 v11, v0
	v_mov_b32_e32 v12, v0
	v_mov_b32_e32 v13, v0
	v_mov_b32_e32 v14, v0
	v_mov_b32_e32 v15, v0
	v_mov_b32_e32 v24, v0
	v_mov_b32_e32 v25, v0
	v_mov_b32_e32 v26, v0
	v_mov_b32_e32 v27, v0
	v_mov_b32_e32 v28, v0
	v_mov_b32_e32 v29, v0
	v_mov_b32_e32 v30, v0
	v_mov_b32_e32 v31, v0
	v_mov_b32_e32 v40, v0
	v_mov_b32_e32 v41, v0
	v_mov_b32_e32 v42, v0
	v_mov_b32_e32 v43, v0
	v_mov_b32_e32 v44, v0
	v_mov_b32_e32 v45, v0
	v_mov_b32_e32 v46, v0
	v_mov_b32_e32 v47, v0
	v_mov_b32_e32 v56, v0
	v_mov_b32_e32 v57, v0
	v_mov_b32_e32 v58, v0
	v_mov_b32_e32 v59, v0
	v_mov_b32_e32 v60, v0
	v_mov_b32_e32 v61, v0
	v_mov_b32_e32 v62, v0
	v_mov_b32_e32 v63, v0
	v_mov_b32_e32 v64, v0
	v_mov_b32_e32 v65, v0
	v_mov_b32_e32 v66, v0
	v_mov_b32_e32 v67, v0
	v_mov_b32_e32 v68, v0
	v_mov_b32_e32 v69, v0
	v_mov_b32_e32 v70, v0
	v_mov_b32_e32 v71, v0
	v_mov_b32_e32 v80, v0
	v_mov_b32_e32 v81, v0
	v_mov_b32_e32 v82, v0
	v_mov_b32_e32 v83, v0
	v_mov_b32_e32 v84, v0
	v_mov_b32_e32 v85, v0
	v_mov_b32_e32 v86, v0
	v_mov_b32_e32 v87, v0
	v_mov_b32_e32 v96, v0
	v_mov_b32_e32 v97, v0
	v_mov_b32_e32 v98, v0
	v_mov_b32_e32 v99, v0
	v_mov_b32_e32 v100, v0
	v_mov_b32_e32 v101, v0
	v_mov_b32_e32 v102, v0
	v_mov_b32_e32 v103, v0
	v_mov_b32_e32 v112, v0
	v_mov_b32_e32 v113, v0
	v_mov_b32_e32 v114, v0
	v_mov_b32_e32 v115, v0
	v_mov_b32_e32 v116, v0
	v_mov_b32_e32 v117, v0
	v_mov_b32_e32 v118, v0
	v_mov_b32_e32 v119, v0
	v_mov_b32_e32 v72, v0
	v_mov_b32_e32 v73, v0
	v_mov_b32_e32 v74, v0
	v_mov_b32_e32 v75, v0
	v_mov_b32_e32 v76, v0
	v_mov_b32_e32 v77, v0
	v_mov_b32_e32 v78, v0
	v_mov_b32_e32 v79, v0
	v_mov_b32_e32 v88, v0
	v_mov_b32_e32 v89, v0
	v_mov_b32_e32 v90, v0
	v_mov_b32_e32 v91, v0
	v_mov_b32_e32 v92, v0
	v_mov_b32_e32 v93, v0
	v_mov_b32_e32 v94, v0
	v_mov_b32_e32 v95, v0
	v_mov_b32_e32 v104, v0
	v_mov_b32_e32 v105, v0
	v_mov_b32_e32 v106, v0
	v_mov_b32_e32 v107, v0
	v_mov_b32_e32 v108, v0
	v_mov_b32_e32 v109, v0
	v_mov_b32_e32 v110, v0
	v_mov_b32_e32 v111, v0
	v_mov_b32_e32 v120, v0
	v_mov_b32_e32 v121, v0
	v_mov_b32_e32 v122, v0
	v_mov_b32_e32 v123, v0
	v_mov_b32_e32 v124, v0
	v_mov_b32_e32 v125, v0
	v_mov_b32_e32 v126, v0
	v_mov_b32_e32 v127, v0
	v_and_b32_e32 v140, 63, v222
	v_lshrrev_b32_e32 v141, 6, v222
	v_lshrrev_b32_e32 v142, 3, v140
	v_lshl_add_u32 v143, v141, 3, v142
	v_and_b32_e32 v154, 7, v140
	v_and_b32_e32 v155, 6, v142
	v_xor_b32_e32 v154, v154, v155
	v_lshlrev_b32_e32 v154, 4, v154
	v_mul_u32_u24_e32 v155, 0x1000, v143
	v_add_u32_e32 v144, v155, v154
	v_and_b32_e32 v155, 31, v143
	v_and_b32_e32 v142, 12, v155
	v_lshlrev_b32_e32 v142, 1, v142
	v_lshrrev_b32_e32 v145, 4, v155
	v_lshlrev_b32_e32 v145, 2, v145
	v_and_b32_e32 v155, 3, v155
	v_or3_b32 v155, v142, v145, v155
	v_and_b32_e32 v142, 0x60, v143
	v_add_u32_e32 v155, v155, v142
	v_mul_u32_u24_e32 v155, 0x1000, v155
	v_add_u32_e32 v145, v155, v154
	v_and_b32_e32 v142, 15, v140
	v_lshrrev_b32_e32 v143, 4, v140
	v_and_b32_e32 v154, 6, v142
	v_xor_b32_e32 v143, v143, v154
	v_lshlrev_b32_e32 v143, 4, v143
	v_lshl_or_b32 v143, v142, 7, v143
	v_lshrrev_b32_e32 v154, 2, v141
	v_lshl_add_u32 v169, v154, 13, v143
	v_xor_b32_e32 v216, 64, v169
	v_and_b32_e32 v154, 3, v141
	v_lshl_add_u32 v217, v154, 12, v143
	v_add_u32_e32 v217, 0x10000, v217
	v_xor_b32_e32 v234, 64, v217
	v_readfirstlane_b32 s54, v222
	s_nop 3
	s_lshr_b32 s54, s54, 6
	s_lshl_b32 s54, s54, 10
	s_mul_i32 s30, s98, s94
	s_add_i32 s30, s30, s2
	s_and_b32 s31, s30, 7
	s_lshr_b32 s30, s30, 3
	s_mul_i32 s31, s31, 0x80
	s_add_i32 s30, s30, s31
	s_mul_i32 s31, s30, 0x40000
	s_lshr_b32 s31, s31, 24
	s_mul_i32 s100, s31, 0x40
	s_sub_i32 s30, s30, s100
	s_and_b32 s33, s30, 3
	s_lshl_b32 s31, s31, 2
	s_add_i32 s33, s33, s31
	s_lshr_b32 s100, s30, 2
	s_mul_i32 s99, s33, 0x100000
	s_add_u32 s26, s92, 0xbd00100
	s_addc_u32 s27, s93, 0
	s_add_u32 s26, s26, s99
	s_addc_u32 s27, s27, 0
	s_mul_i32 s99, s100, 0x100000
	s_add_u32 s28, s92, 0x6300100
	s_addc_u32 s29, s93, 0
	s_add_u32 s28, s28, s99
	s_addc_u32 s29, s29, 0
	s_add_i32 s98, s98, 1
	s_mul_i32 s48, s98, s94
	s_add_i32 s48, s48, s2
	s_cmp_lt_u32 s48, 0x400
	s_cbranch_scc0 .Ls5_nonext
	s_mul_i32 s30, s98, s94
	s_add_i32 s30, s30, s2
	s_and_b32 s31, s30, 7
	s_lshr_b32 s30, s30, 3
	s_mul_i32 s31, s31, 0x80
	s_add_i32 s30, s30, s31
	s_mul_i32 s31, s30, 0x40000
	s_lshr_b32 s31, s31, 24
	s_mul_i32 s100, s31, 0x40
	s_sub_i32 s30, s30, s100
	s_and_b32 s33, s30, 3
	s_lshl_b32 s31, s31, 2
	s_add_i32 s33, s33, s31
	s_lshr_b32 s100, s30, 2
.Ls5_nonext:
	s_mul_i32 s99, s33, 0x100000
	s_add_u32 s30, s92, 0xbd00000
	s_addc_u32 s31, s93, 0
	s_add_u32 s30, s30, s99
	s_addc_u32 s31, s31, 0
	s_mul_i32 s99, s100, 0x100000
	s_add_u32 s48, s92, 0x6300000
	s_addc_u32 s49, s93, 0
	s_add_u32 s48, s48, s99
	s_addc_u32 s49, s49, 0
	s_waitcnt vmcnt(0)
	s_barrier
	ds_read_b128 v[140:143], v169
	ds_read_b128 v[154:157], v169 offset:2048
	ds_read_b128 v[196:199], v217
	ds_read_b128 v[200:203], v217 offset:2048
	ds_read_b128 v[204:207], v217 offset:16384
	ds_read_b128 v[208:211], v217 offset:18432
	ds_read_b128 v[158:161], v169 offset:4096
	ds_read_b128 v[176:179], v169 offset:6144
	ds_read_b128 v[180:183], v169 offset:16384
	ds_read_b128 v[184:187], v169 offset:18432
	ds_read_b128 v[188:191], v169 offset:20480
	ds_read_b128 v[192:195], v169 offset:22528
	s_mov_b32 s33, 0
.Ls5_loop:
	s_cmp_eq_u32 s33, 15
	s_cselect_b32 s26, s30, s26
	s_cselect_b32 s27, s31, s27
	s_cselect_b32 s28, s48, s28
	s_cselect_b32 s29, s49, s29
	s_waitcnt lgkmcnt(6)
	v_mfma_f32_16x16x32_bf16 v[124:127], v[196:199], v[140:143], v[124:127]
	v_mfma_f32_16x16x32_bf16 v[120:123], v[200:203], v[140:143], v[120:123]
	v_mfma_f32_16x16x32_bf16 v[116:119], v[204:207], v[140:143], v[116:119]
	v_mfma_f32_16x16x32_bf16 v[112:115], v[208:211], v[140:143], v[112:115]
	v_mfma_f32_16x16x32_bf16 v[108:111], v[196:199], v[154:157], v[108:111]
	v_mfma_f32_16x16x32_bf16 v[104:107], v[200:203], v[154:157], v[104:107]
	v_mfma_f32_16x16x32_bf16 v[100:103], v[204:207], v[154:157], v[100:103]
	v_mfma_f32_16x16x32_bf16 v[96:99], v[208:211], v[154:157], v[96:99]
	s_waitcnt lgkmcnt(0)
	ds_read_b128 v[140:143], v216
	ds_read_b128 v[154:157], v216 offset:2048
	ds_read_b128 v[212:215], v234
	ds_read_b128 v[240:243], v234 offset:2048
	ds_read_b128 v[244:247], v234 offset:16384
	ds_read_b128 v[248:251], v234 offset:18432
	v_mfma_f32_16x16x32_bf16 v[92:95], v[196:199], v[158:161], v[92:95]
	v_mfma_f32_16x16x32_bf16 v[88:91], v[200:203], v[158:161], v[88:91]
	v_mfma_f32_16x16x32_bf16 v[84:87], v[204:207], v[158:161], v[84:87]
	v_mfma_f32_16x16x32_bf16 v[80:83], v[208:211], v[158:161], v[80:83]
	ds_read_b128 v[158:161], v216 offset:4096
	v_mfma_f32_16x16x32_bf16 v[76:79], v[196:199], v[176:179], v[76:79]
	v_mfma_f32_16x16x32_bf16 v[72:75], v[200:203], v[176:179], v[72:75]
	v_mfma_f32_16x16x32_bf16 v[68:71], v[204:207], v[176:179], v[68:71]
	v_mfma_f32_16x16x32_bf16 v[64:67], v[208:211], v[176:179], v[64:67]
	ds_read_b128 v[176:179], v216 offset:6144
	s_waitcnt lgkmcnt(0)
	s_barrier
	s_add_i32 m0, s54, 0x10000
	v_mfma_f32_16x16x32_bf16 v[60:63], v[196:199], v[180:183], v[60:63]
	v_mfma_f32_16x16x32_bf16 v[56:59], v[200:203], v[180:183], v[56:59]
	v_mfma_f32_16x16x32_bf16 v[52:55], v[204:207], v[180:183], v[52:55]
	v_mfma_f32_16x16x32_bf16 v[48:51], v[208:211], v[180:183], v[48:51]
	ds_read_b128 v[180:183], v216 offset:16384
	global_load_lds_dwordx4 v145, s[28:29]
	s_add_i32 m0, s54, 0x12000
	s_add_u32 s52, s28, 0x40000
	s_addc_u32 s53, s29, 0
	v_mfma_f32_16x16x32_bf16 v[44:47], v[196:199], v[184:187], v[44:47]
	v_mfma_f32_16x16x32_bf16 v[40:43], v[200:203], v[184:187], v[40:43]
	v_mfma_f32_16x16x32_bf16 v[36:39], v[204:207], v[184:187], v[36:39]
	v_mfma_f32_16x16x32_bf16 v[32:35], v[208:211], v[184:187], v[32:35]
	ds_read_b128 v[184:187], v216 offset:18432
	global_load_lds_dwordx4 v145, s[52:53]
	s_add_i32 m0, s54, 0x14000
	s_add_u32 s52, s28, 0x80000
	s_addc_u32 s53, s29, 0
	v_mfma_f32_16x16x32_bf16 v[28:31], v[196:199], v[188:191], v[28:31]
	v_mfma_f32_16x16x32_bf16 v[24:27], v[200:203], v[188:191], v[24:27]
	v_mfma_f32_16x16x32_bf16 v[20:23], v[204:207], v[188:191], v[20:23]
	v_mfma_f32_16x16x32_bf16 v[16:19], v[208:211], v[188:191], v[16:19]
	ds_read_b128 v[188:191], v216 offset:20480
	global_load_lds_dwordx4 v145, s[52:53]
	s_add_i32 m0, s54, 0x16000
	s_add_u32 s52, s28, 0xc0000
	s_addc_u32 s53, s29, 0
	v_mfma_f32_16x16x32_bf16 v[12:15], v[196:199], v[192:195], v[12:15]
	v_mfma_f32_16x16x32_bf16 v[8:11], v[200:203], v[192:195], v[8:11]
	v_mfma_f32_16x16x32_bf16 v[4:7], v[204:207], v[192:195], v[4:7]
	v_mfma_f32_16x16x32_bf16 v[0:3], v[208:211], v[192:195], v[0:3]
	ds_read_b128 v[192:195], v216 offset:22528
	global_load_lds_dwordx4 v145, s[52:53]
	s_waitcnt lgkmcnt(6)
	s_add_i32 m0, s54, 0x0
	v_mfma_f32_16x16x32_bf16 v[124:127], v[212:215], v[140:143], v[124:127]
	v_mfma_f32_16x16x32_bf16 v[120:123], v[240:243], v[140:143], v[120:123]
	v_mfma_f32_16x16x32_bf16 v[116:119], v[244:247], v[140:143], v[116:119]
	v_mfma_f32_16x16x32_bf16 v[112:115], v[248:251], v[140:143], v[112:115]
	global_load_lds_dwordx4 v144, s[26:27]
	s_add_i32 m0, s54, 0x2000
	s_add_u32 s52, s26, 0x40000
	s_addc_u32 s53, s27, 0
	v_mfma_f32_16x16x32_bf16 v[108:111], v[212:215], v[154:157], v[108:111]
	v_mfma_f32_16x16x32_bf16 v[104:107], v[240:243], v[154:157], v[104:107]
	v_mfma_f32_16x16x32_bf16 v[100:103], v[244:247], v[154:157], v[100:103]
	v_mfma_f32_16x16x32_bf16 v[96:99], v[248:251], v[154:157], v[96:99]
	global_load_lds_dwordx4 v144, s[52:53]
	s_waitcnt lgkmcnt(0)
	s_waitcnt vmcnt(6)
	s_barrier
	ds_read_b128 v[140:143], v169 offset:32768
	ds_read_b128 v[154:157], v169 offset:34816
	ds_read_b128 v[196:199], v217 offset:32768
	ds_read_b128 v[200:203], v217 offset:34816
	ds_read_b128 v[204:207], v217 offset:49152
	ds_read_b128 v[208:211], v217 offset:51200
	s_add_i32 m0, s54, 0x4000
	s_add_u32 s52, s26, 0x80000
	s_addc_u32 s53, s27, 0
	v_mfma_f32_16x16x32_bf16 v[92:95], v[212:215], v[158:161], v[92:95]
	v_mfma_f32_16x16x32_bf16 v[88:91], v[240:243], v[158:161], v[88:91]
	v_mfma_f32_16x16x32_bf16 v[84:87], v[244:247], v[158:161], v[84:87]
	v_mfma_f32_16x16x32_bf16 v[80:83], v[248:251], v[158:161], v[80:83]
	ds_read_b128 v[158:161], v169 offset:36864
	global_load_lds_dwordx4 v144, s[52:53]
	s_add_i32 m0, s54, 0x6000
	s_add_u32 s52, s26, 0xc0000
	s_addc_u32 s53, s27, 0
	v_mfma_f32_16x16x32_bf16 v[76:79], v[212:215], v[176:179], v[76:79]
	v_mfma_f32_16x16x32_bf16 v[72:75], v[240:243], v[176:179], v[72:75]
	v_mfma_f32_16x16x32_bf16 v[68:71], v[244:247], v[176:179], v[68:71]
	v_mfma_f32_16x16x32_bf16 v[64:67], v[248:251], v[176:179], v[64:67]
	ds_read_b128 v[176:179], v169 offset:38912
	global_load_lds_dwordx4 v144, s[52:53]
	v_mfma_f32_16x16x32_bf16 v[60:63], v[212:215], v[180:183], v[60:63]
	v_mfma_f32_16x16x32_bf16 v[56:59], v[240:243], v[180:183], v[56:59]
	v_mfma_f32_16x16x32_bf16 v[52:55], v[244:247], v[180:183], v[52:55]
	v_mfma_f32_16x16x32_bf16 v[48:51], v[248:251], v[180:183], v[48:51]
	ds_read_b128 v[180:183], v169 offset:49152
	v_mfma_f32_16x16x32_bf16 v[44:47], v[212:215], v[184:187], v[44:47]
	v_mfma_f32_16x16x32_bf16 v[40:43], v[240:243], v[184:187], v[40:43]
	v_mfma_f32_16x16x32_bf16 v[36:39], v[244:247], v[184:187], v[36:39]
	v_mfma_f32_16x16x32_bf16 v[32:35], v[248:251], v[184:187], v[32:35]
	ds_read_b128 v[184:187], v169 offset:51200
	v_mfma_f32_16x16x32_bf16 v[28:31], v[212:215], v[188:191], v[28:31]
	v_mfma_f32_16x16x32_bf16 v[24:27], v[240:243], v[188:191], v[24:27]
	v_mfma_f32_16x16x32_bf16 v[20:23], v[244:247], v[188:191], v[20:23]
	v_mfma_f32_16x16x32_bf16 v[16:19], v[248:251], v[188:191], v[16:19]
	ds_read_b128 v[188:191], v169 offset:53248
	v_mfma_f32_16x16x32_bf16 v[12:15], v[212:215], v[192:195], v[12:15]
	v_mfma_f32_16x16x32_bf16 v[8:11], v[240:243], v[192:195], v[8:11]
	v_mfma_f32_16x16x32_bf16 v[4:7], v[244:247], v[192:195], v[4:7]
	v_mfma_f32_16x16x32_bf16 v[0:3], v[248:251], v[192:195], v[0:3]
	ds_read_b128 v[192:195], v169 offset:55296
	s_add_u32 s26, s26, 128
	s_addc_u32 s27, s27, 0
	s_add_u32 s28, s28, 128
	s_addc_u32 s29, s29, 0
	s_waitcnt lgkmcnt(6)
	v_mfma_f32_16x16x32_bf16 v[124:127], v[196:199], v[140:143], v[124:127]
	v_mfma_f32_16x16x32_bf16 v[120:123], v[200:203], v[140:143], v[120:123]
	v_mfma_f32_16x16x32_bf16 v[116:119], v[204:207], v[140:143], v[116:119]
	v_mfma_f32_16x16x32_bf16 v[112:115], v[208:211], v[140:143], v[112:115]
	v_mfma_f32_16x16x32_bf16 v[108:111], v[196:199], v[154:157], v[108:111]
	v_mfma_f32_16x16x32_bf16 v[104:107], v[200:203], v[154:157], v[104:107]
	v_mfma_f32_16x16x32_bf16 v[100:103], v[204:207], v[154:157], v[100:103]
	v_mfma_f32_16x16x32_bf16 v[96:99], v[208:211], v[154:157], v[96:99]
	s_waitcnt lgkmcnt(0)
	ds_read_b128 v[140:143], v216 offset:32768
	ds_read_b128 v[154:157], v216 offset:34816
	ds_read_b128 v[212:215], v234 offset:32768
	ds_read_b128 v[240:243], v234 offset:34816
	ds_read_b128 v[244:247], v234 offset:49152
	ds_read_b128 v[248:251], v234 offset:51200
	v_mfma_f32_16x16x32_bf16 v[92:95], v[196:199], v[158:161], v[92:95]
	v_mfma_f32_16x16x32_bf16 v[88:91], v[200:203], v[158:161], v[88:91]
	v_mfma_f32_16x16x32_bf16 v[84:87], v[204:207], v[158:161], v[84:87]
	v_mfma_f32_16x16x32_bf16 v[80:83], v[208:211], v[158:161], v[80:83]
	ds_read_b128 v[158:161], v216 offset:36864
	v_mfma_f32_16x16x32_bf16 v[76:79], v[196:199], v[176:179], v[76:79]
	v_mfma_f32_16x16x32_bf16 v[72:75], v[200:203], v[176:179], v[72:75]
	v_mfma_f32_16x16x32_bf16 v[68:71], v[204:207], v[176:179], v[68:71]
	v_mfma_f32_16x16x32_bf16 v[64:67], v[208:211], v[176:179], v[64:67]
	ds_read_b128 v[176:179], v216 offset:38912
	s_waitcnt lgkmcnt(0)
	s_barrier
	s_add_i32 m0, s54, 0x18000
	v_mfma_f32_16x16x32_bf16 v[60:63], v[196:199], v[180:183], v[60:63]
	v_mfma_f32_16x16x32_bf16 v[56:59], v[200:203], v[180:183], v[56:59]
	v_mfma_f32_16x16x32_bf16 v[52:55], v[204:207], v[180:183], v[52:55]
	v_mfma_f32_16x16x32_bf16 v[48:51], v[208:211], v[180:183], v[48:51]
	ds_read_b128 v[180:183], v216 offset:49152
	global_load_lds_dwordx4 v145, s[28:29]
	s_add_i32 m0, s54, 0x1a000
	s_add_u32 s52, s28, 0x40000
	s_addc_u32 s53, s29, 0
	v_mfma_f32_16x16x32_bf16 v[44:47], v[196:199], v[184:187], v[44:47]
	v_mfma_f32_16x16x32_bf16 v[40:43], v[200:203], v[184:187], v[40:43]
	v_mfma_f32_16x16x32_bf16 v[36:39], v[204:207], v[184:187], v[36:39]
	v_mfma_f32_16x16x32_bf16 v[32:35], v[208:211], v[184:187], v[32:35]
	ds_read_b128 v[184:187], v216 offset:51200
	global_load_lds_dwordx4 v145, s[52:53]
	s_add_i32 m0, s54, 0x1c000
	s_add_u32 s52, s28, 0x80000
	s_addc_u32 s53, s29, 0
	v_mfma_f32_16x16x32_bf16 v[28:31], v[196:199], v[188:191], v[28:31]
	v_mfma_f32_16x16x32_bf16 v[24:27], v[200:203], v[188:191], v[24:27]
	v_mfma_f32_16x16x32_bf16 v[20:23], v[204:207], v[188:191], v[20:23]
	v_mfma_f32_16x16x32_bf16 v[16:19], v[208:211], v[188:191], v[16:19]
	ds_read_b128 v[188:191], v216 offset:53248
	global_load_lds_dwordx4 v145, s[52:53]
	s_add_i32 m0, s54, 0x1e000
	s_add_u32 s52, s28, 0xc0000
	s_addc_u32 s53, s29, 0
	v_mfma_f32_16x16x32_bf16 v[12:15], v[196:199], v[192:195], v[12:15]
	v_mfma_f32_16x16x32_bf16 v[8:11], v[200:203], v[192:195], v[8:11]
	v_mfma_f32_16x16x32_bf16 v[4:7], v[204:207], v[192:195], v[4:7]
	v_mfma_f32_16x16x32_bf16 v[0:3], v[208:211], v[192:195], v[0:3]
	ds_read_b128 v[192:195], v216 offset:55296
	global_load_lds_dwordx4 v145, s[52:53]
	s_waitcnt lgkmcnt(6)
	s_add_i32 m0, s54, 0x8000
	v_mfma_f32_16x16x32_bf16 v[124:127], v[212:215], v[140:143], v[124:127]
	v_mfma_f32_16x16x32_bf16 v[120:123], v[240:243], v[140:143], v[120:123]
	v_mfma_f32_16x16x32_bf16 v[116:119], v[244:247], v[140:143], v[116:119]
	v_mfma_f32_16x16x32_bf16 v[112:115], v[248:251], v[140:143], v[112:115]
	global_load_lds_dwordx4 v144, s[26:27]
	s_add_i32 m0, s54, 0xa000
	s_add_u32 s52, s26, 0x40000
	s_addc_u32 s53, s27, 0
	v_mfma_f32_16x16x32_bf16 v[108:111], v[212:215], v[154:157], v[108:111]
	v_mfma_f32_16x16x32_bf16 v[104:107], v[240:243], v[154:157], v[104:107]
	v_mfma_f32_16x16x32_bf16 v[100:103], v[244:247], v[154:157], v[100:103]
	v_mfma_f32_16x16x32_bf16 v[96:99], v[248:251], v[154:157], v[96:99]
	global_load_lds_dwordx4 v144, s[52:53]
	s_waitcnt lgkmcnt(0)
	s_waitcnt vmcnt(6)
	s_barrier
	ds_read_b128 v[140:143], v169
	ds_read_b128 v[154:157], v169 offset:2048
	ds_read_b128 v[196:199], v217
	ds_read_b128 v[200:203], v217 offset:2048
	ds_read_b128 v[204:207], v217 offset:16384
	ds_read_b128 v[208:211], v217 offset:18432
	s_add_i32 m0, s54, 0xc000
	s_add_u32 s52, s26, 0x80000
	s_addc_u32 s53, s27, 0
	v_mfma_f32_16x16x32_bf16 v[92:95], v[212:215], v[158:161], v[92:95]
	v_mfma_f32_16x16x32_bf16 v[88:91], v[240:243], v[158:161], v[88:91]
	v_mfma_f32_16x16x32_bf16 v[84:87], v[244:247], v[158:161], v[84:87]
	v_mfma_f32_16x16x32_bf16 v[80:83], v[248:251], v[158:161], v[80:83]
	ds_read_b128 v[158:161], v169 offset:4096
	global_load_lds_dwordx4 v144, s[52:53]
	s_add_i32 m0, s54, 0xe000
	s_add_u32 s52, s26, 0xc0000
	s_addc_u32 s53, s27, 0
	v_mfma_f32_16x16x32_bf16 v[76:79], v[212:215], v[176:179], v[76:79]
	v_mfma_f32_16x16x32_bf16 v[72:75], v[240:243], v[176:179], v[72:75]
	v_mfma_f32_16x16x32_bf16 v[68:71], v[244:247], v[176:179], v[68:71]
	v_mfma_f32_16x16x32_bf16 v[64:67], v[248:251], v[176:179], v[64:67]
	ds_read_b128 v[176:179], v169 offset:6144
	global_load_lds_dwordx4 v144, s[52:53]
	v_mfma_f32_16x16x32_bf16 v[60:63], v[212:215], v[180:183], v[60:63]
	v_mfma_f32_16x16x32_bf16 v[56:59], v[240:243], v[180:183], v[56:59]
	v_mfma_f32_16x16x32_bf16 v[52:55], v[244:247], v[180:183], v[52:55]
	v_mfma_f32_16x16x32_bf16 v[48:51], v[248:251], v[180:183], v[48:51]
	ds_read_b128 v[180:183], v169 offset:16384
	v_mfma_f32_16x16x32_bf16 v[44:47], v[212:215], v[184:187], v[44:47]
	v_mfma_f32_16x16x32_bf16 v[40:43], v[240:243], v[184:187], v[40:43]
	v_mfma_f32_16x16x32_bf16 v[36:39], v[244:247], v[184:187], v[36:39]
	v_mfma_f32_16x16x32_bf16 v[32:35], v[248:251], v[184:187], v[32:35]
	ds_read_b128 v[184:187], v169 offset:18432
	v_mfma_f32_16x16x32_bf16 v[28:31], v[212:215], v[188:191], v[28:31]
	v_mfma_f32_16x16x32_bf16 v[24:27], v[240:243], v[188:191], v[24:27]
	v_mfma_f32_16x16x32_bf16 v[20:23], v[244:247], v[188:191], v[20:23]
	v_mfma_f32_16x16x32_bf16 v[16:19], v[248:251], v[188:191], v[16:19]
	ds_read_b128 v[188:191], v169 offset:20480
	v_mfma_f32_16x16x32_bf16 v[12:15], v[212:215], v[192:195], v[12:15]
	v_mfma_f32_16x16x32_bf16 v[8:11], v[240:243], v[192:195], v[8:11]
	v_mfma_f32_16x16x32_bf16 v[4:7], v[244:247], v[192:195], v[4:7]
	v_mfma_f32_16x16x32_bf16 v[0:3], v[248:251], v[192:195], v[0:3]
	ds_read_b128 v[192:195], v169 offset:22528
	s_add_u32 s26, s26, 128
	s_addc_u32 s27, s27, 0
	s_add_u32 s28, s28, 128
	s_addc_u32 s29, s29, 0
	s_add_i32 s33, s33, 1
	s_cmp_lt_u32 s33, 16
	s_cbranch_scc1 .Ls5_loop
	s_waitcnt lgkmcnt(0)
	s_nop 7
	s_nop 3
	v_lshl_add_u32 v142, s12, 8, v146
	v_ashrrev_i32_e32 v143, 31, v142
	v_lshl_add_u64 v[144:145], v[142:143], 2, s[14:15]
	global_load_dword v179, v[144:145], off
	global_load_dword v180, v[144:145], off offset:64
	global_load_dword v181, v[144:145], off offset:128
	global_load_dword v182, v[144:145], off offset:192
	global_load_dword v183, v[144:145], off offset:512
	global_load_dword v184, v[144:145], off offset:576
	global_load_dword v185, v[144:145], off offset:640
	global_load_dword v186, v[144:145], off offset:704
	v_lshl_or_b32 v140, s0, 8, v148
	v_lshlrev_b64 v[156:157], 13, v[142:143]
	v_ashrrev_i32_e32 v141, 31, v140
	v_lshl_add_u64 v[156:157], s[96:97], 0, v[156:157]
	v_lshl_add_u64 v[158:159], v[140:141], 1, v[156:157]
	s_cmp_gt_i32 s0, 7
	s_cselect_b64 s[26:27], -1, 0
	s_cmp_lt_i32 s0, 8
	s_waitcnt vmcnt(0)
	v_fmamk_f32 v154, v179, 0x3a000000, v152
	v_rsq_f32_e32 v154, v154
	s_nop 0
	v_pk_mul_f32 v[126:127], v[126:127], v[154:155] op_sel_hi:[1,0]
	v_pk_mul_f32 v[124:125], v[124:125], v[154:155] op_sel_hi:[1,0]
	v_pk_mul_f32 v[120:121], v[120:121], v[154:155] op_sel_hi:[1,0]
	v_pk_mul_f32 v[122:123], v[122:123], v[154:155] op_sel_hi:[1,0]
	v_pk_mul_f32 v[156:157], v[118:119], v[154:155] op_sel_hi:[1,0]
	v_pk_mul_f32 v[160:161], v[116:117], v[154:155] op_sel_hi:[1,0]
	v_pk_mul_f32 v[176:177], v[114:115], v[154:155] op_sel_hi:[1,0]
	v_pk_mul_f32 v[154:155], v[112:113], v[154:155] op_sel_hi:[1,0]
	v_mul_f32_e32 v112, 0x3d372713, v124
	v_mul_f32_e32 v113, 0x3d372713, v120
	v_mul_f32_e32 v114, 0x3d372713, v125
	v_mul_f32_e32 v115, 0x3d372713, v121
	v_mul_f32_e32 v116, 0x3d372713, v126
	v_mul_f32_e32 v118, 0x3d372713, v127
	v_mul_f32_e32 v117, 0x3d372713, v122
	v_mul_f32_e32 v119, 0x3d372713, v123
	v_mul_f32_e32 v112, v124, v112
	v_mul_f32_e32 v113, v120, v113
	v_mul_f32_e32 v114, v125, v114
	v_mul_f32_e32 v115, v121, v115
	v_mul_f32_e32 v116, v126, v116
	v_mul_f32_e32 v118, v127, v118
	v_mul_f32_e32 v117, v122, v117
	v_mul_f32_e32 v119, v123, v119
	v_fma_f32 v112, v124, v112, v124
	v_fma_f32 v113, v120, v113, v120
	v_fma_f32 v114, v125, v114, v125
	v_fma_f32 v115, v121, v115, v121
	v_fma_f32 v116, v126, v116, v126
	v_fma_f32 v118, v127, v118, v127
	v_fma_f32 v117, v122, v117, v122
	v_fma_f32 v119, v123, v119, v123
	v_mul_f32_e32 v112, 0x3f4c422a, v112
	v_mul_f32_e32 v113, 0x3f4c422a, v113
	v_mul_f32_e32 v114, 0x3f4c422a, v114
	v_mul_f32_e32 v115, 0x3f4c422a, v115
	v_mul_f32_e32 v116, 0x3f4c422a, v116
	v_mul_f32_e32 v118, 0x3f4c422a, v118
	v_mul_f32_e32 v117, 0x3f4c422a, v117
	v_mul_f32_e32 v119, 0x3f4c422a, v119
	v_mul_f32_e32 v112, 0xc038aa3b, v112
	v_mul_f32_e32 v113, 0xc038aa3b, v113
	v_mul_f32_e32 v114, 0xc038aa3b, v114
	v_mul_f32_e32 v115, 0xc038aa3b, v115
	v_mul_f32_e32 v116, 0xc038aa3b, v116
	v_mul_f32_e32 v118, 0xc038aa3b, v118
	v_mul_f32_e32 v117, 0xc038aa3b, v117
	v_mul_f32_e32 v119, 0xc038aa3b, v119
	v_exp_f32_e32 v112, v112
	v_exp_f32_e32 v113, v113
	v_exp_f32_e32 v114, v114
	v_exp_f32_e32 v115, v115
	v_exp_f32_e32 v116, v116
	v_exp_f32_e32 v118, v118
	v_exp_f32_e32 v117, v117
	v_exp_f32_e32 v119, v119
	v_add_f32_e32 v112, 1.0, v112
	v_add_f32_e32 v113, 1.0, v113
	v_add_f32_e32 v114, 1.0, v114
	v_add_f32_e32 v115, 1.0, v115
	v_add_f32_e32 v116, 1.0, v116
	v_add_f32_e32 v118, 1.0, v118
	v_add_f32_e32 v117, 1.0, v117
	v_add_f32_e32 v119, 1.0, v119
	v_rcp_f32_e32 v112, v112
	v_rcp_f32_e32 v113, v113
	v_rcp_f32_e32 v114, v114
	v_rcp_f32_e32 v171, v115
	v_rcp_f32_e32 v173, v116
	v_rcp_f32_e32 v175, v118
	v_rcp_f32_e32 v117, v117
	v_rcp_f32_e32 v178, v119
	v_mul_f32_e32 v116, v124, v112
	v_mul_f32_e32 v119, v120, v113
	v_mul_f32_e32 v115, v125, v114
	v_mul_f32_e32 v118, v121, v171
	v_mul_f32_e32 v113, v126, v173
	v_mul_f32_e32 v112, v127, v175
	v_cvt_pk_bf16_f32 v120, v116, v115
	v_cvt_pk_bf16_f32 v121, v113, v112
	v_mul_f32_e32 v117, v122, v117
	v_mul_f32_e32 v114, v123, v178
	v_cvt_pk_bf16_f32 v122, v119, v118
	v_cvt_pk_bf16_f32 v123, v117, v114
	global_store_dwordx4 v[158:159], v[120:123], off
	v_mul_f32_e32 v169, 0x3d372713, v160
	v_mul_f32_e32 v169, v160, v169
	v_mul_f32_e32 v121, 0x3d372713, v161
	v_mul_f32_e32 v121, v161, v121
	v_fma_f32 v121, v161, v121, v161
	v_mul_f32_e32 v121, 0x3f4c422a, v121
	v_mul_f32_e32 v121, 0xc038aa3b, v121
	v_mul_f32_e32 v120, 0x3d372713, v154
	v_exp_f32_e32 v121, v121
	v_mul_f32_e32 v120, v154, v120
	v_fma_f32 v169, v160, v169, v160
	v_fma_f32 v120, v154, v120, v154
	v_mul_f32_e32 v169, 0x3f4c422a, v169
	v_mul_f32_e32 v120, 0x3f4c422a, v120
	v_mul_f32_e32 v169, 0xc038aa3b, v169
	v_mul_f32_e32 v120, 0xc038aa3b, v120
	v_add_f32_e32 v121, 1.0, v121
	v_exp_f32_e32 v169, v169
	v_exp_f32_e32 v120, v120
	v_rcp_f32_e32 v123, v121
	v_mul_f32_e32 v121, 0x3d372713, v155
	v_mul_f32_e32 v121, v155, v121
	v_fma_f32 v121, v155, v121, v155
	v_mul_f32_e32 v121, 0x3f4c422a, v121
	v_add_f32_e32 v169, 1.0, v169
	v_add_f32_e32 v120, 1.0, v120
	v_mul_f32_e32 v121, 0xc038aa3b, v121
	v_rcp_f32_e32 v122, v169
	v_rcp_f32_e32 v120, v120
	v_exp_f32_e32 v124, v121
	v_mul_f32_e32 v125, 0x3d372713, v176
	v_mul_f32_e32 v125, v176, v125
	v_mul_f32_e32 v126, 0x3d372713, v157
	v_mul_f32_e32 v121, v160, v122
	v_mul_f32_e32 v122, v154, v120
	v_mul_f32_e32 v120, v161, v123
	v_add_f32_e32 v123, 1.0, v124
	v_mul_f32_e32 v124, 0x3d372713, v156
	v_fma_f32 v125, v176, v125, v176
	v_mul_f32_e32 v126, v157, v126
	v_mul_f32_e32 v127, 0x3d372713, v177
	v_mul_f32_e32 v124, v156, v124
	v_mul_f32_e32 v125, 0x3f4c422a, v125
	v_fma_f32 v126, v157, v126, v157
	v_mul_f32_e32 v127, v177, v127
	v_fma_f32 v124, v156, v124, v156
	v_mul_f32_e32 v125, 0xc038aa3b, v125
	v_mul_f32_e32 v126, 0x3f4c422a, v126
	v_fma_f32 v127, v177, v127, v177
	v_mul_f32_e32 v124, 0x3f4c422a, v124
	v_exp_f32_e32 v125, v125
	v_mul_f32_e32 v126, 0xc038aa3b, v126
	v_mul_f32_e32 v127, 0x3f4c422a, v127
	v_mul_f32_e32 v124, 0xc038aa3b, v124
	v_exp_f32_e32 v126, v126
	v_mul_f32_e32 v127, 0xc038aa3b, v127
	v_exp_f32_e32 v124, v124
	v_exp_f32_e32 v127, v127
	v_rcp_f32_e32 v123, v123
	v_add_f32_e32 v125, 1.0, v125
	v_rcp_f32_e32 v154, v125
	v_add_f32_e32 v125, 1.0, v126
	v_add_f32_e32 v124, 1.0, v124
	v_rcp_f32_e32 v126, v125
	v_add_f32_e32 v125, 1.0, v127
	v_mul_f32_e32 v123, v155, v123
	v_rcp_f32_e32 v124, v124
	v_rcp_f32_e32 v155, v125
	v_mul_f32_e32 v127, v176, v154
	v_cvt_pk_bf16_f32 v154, v121, v120
	v_mul_f32_e32 v125, v156, v124
	v_mul_f32_e32 v124, v157, v126
	v_mul_f32_e32 v126, v177, v155
	v_cvt_pk_bf16_f32 v155, v125, v124
	v_cvt_pk_bf16_f32 v156, v122, v123
	v_cvt_pk_bf16_f32 v157, v127, v126
	global_store_dwordx4 v[158:159], v[154:157], off offset:256
	s_cbranch_scc1 .LBB0_604
	v_mul_f32_e32 v119, v119, v119
	v_fmac_f32_e32 v119, v116, v116
	v_mul_f32_e32 v116, v118, v118
	v_fmac_f32_e32 v116, v115, v115
	v_add_f32_e32 v115, v119, v116
	v_mul_f32_e32 v116, v117, v117
	v_fmac_f32_e32 v116, v113, v113
	v_mul_f32_e32 v114, v114, v114
	v_add_f32_e32 v113, v116, v115
	v_fmac_f32_e32 v114, v112, v112
	v_add_f32_e32 v112, v114, v113
	v_mul_f32_e32 v113, v122, v122
	v_fmac_f32_e32 v113, v121, v121
	v_add_f32_e32 v112, v113, v112
	v_mul_f32_e32 v113, v123, v123
	v_fmac_f32_e32 v113, v120, v120
	v_add_f32_e32 v112, v113, v112
	v_mul_f32_e32 v113, v127, v127
	v_fmac_f32_e32 v113, v125, v125
	v_add_f32_e32 v112, v113, v112
	v_mul_f32_e32 v113, v126, v126
	v_fmac_f32_e32 v113, v124, v124
	v_and_b32_e32 v114, 64, v153
	v_add_f32_e32 v112, v113, v112
	v_xor_b32_e32 v113, 16, v153
	v_add_u32_e32 v114, 64, v114
	v_cmp_lt_i32_e32 vcc, v113, v114
	s_nop 1
	v_cndmask_b32_e32 v113, v153, v113, vcc
	v_lshlrev_b32_e32 v113, 2, v113
	ds_bpermute_b32 v113, v113, v112
	s_waitcnt lgkmcnt(0)
	v_add_f32_e32 v112, v112, v113
	v_xor_b32_e32 v113, 32, v153
	v_cmp_lt_i32_e32 vcc, v113, v114
	s_nop 1
	v_cndmask_b32_e32 v113, v153, v113, vcc
	v_lshlrev_b32_e32 v113, 2, v113
	ds_bpermute_b32 v113, v113, v112
	s_and_saveexec_b64 s[0:1], s[8:9]
	s_cbranch_execz .LBB0_603
	v_lshl_add_u64 v[114:115], v[142:143], 2, s[4:5]
	s_waitcnt lgkmcnt(0)
	v_add_f32_e32 v112, v112, v113
	global_atomic_add_f32 v[114:115], v112, off

.LBB0_748:
	v_readlane_b32 s6, v255, 8
	s_add_u32 s4, s92, 0x40000
	v_readlane_b32 s7, v255, 9
	s_addc_u32 s5, s93, 0
	s_and_b64 vcc, exec, s[6:7]
	s_cbranch_vccnz .LBB0_780
	s_add_u32 s26, s92, 0x7300000
	s_addc_u32 s27, s93, 0
	s_lshr_b32 s6, s3, 6
	s_ashr_i32 s9, s8, 31
	s_ashr_i32 s1, s0, 31
	s_lshr_b32 s7, s3, 8
	s_lshl_b32 s28, s6, 10
	s_lshl_b64 s[10:11], s[8:9], 21
	s_lshl_b64 s[12:13], s[0:1], 20
	s_add_u32 s22, s26, s12
	s_addc_u32 s23, s27, s13
	s_add_i32 s29, s28, 0
	s_add_i32 m0, s29, 0x10000
	v_lshl_or_b32 v128, v236, 13, v219
	v_and_b32_e32 v140, 63, v222
	v_lshrrev_b32_e32 v141, 3, v140
	v_lshrrev_b32_e32 v142, 6, v222
	v_lshl_add_u32 v143, v142, 3, v141
	v_and_b32_e32 v150, 7, v140
	v_and_b32_e32 v151, 6, v141
	v_xor_b32_e32 v150, v150, v151
	v_lshlrev_b32_e32 v150, 4, v150
	v_mul_u32_u24_e32 v151, 0x2000, v143
	v_add_u32_e32 v151, v151, v150
	v_mov_b32_e32 v132, v151
	v_mov_b32_e32 v128, v151
	v_add_u32_e32 v134, 0x80000, v151
	v_add_u32_e32 v130, 0x80000, v151
	v_add_u32_e32 v134, 0x80000, v151
	v_add_u32_e32 v130, 0x80000, v151
	v_and_b32_e32 v151, 31, v143
	v_and_b32_e32 v152, 12, v151
	v_lshlrev_b32_e32 v152, 1, v152
	v_lshrrev_b32_e32 v153, 4, v151
	v_lshlrev_b32_e32 v153, 2, v153
	v_and_b32_e32 v151, 3, v151
	v_or3_b32 v151, v152, v153, v151
	v_and_b32_e32 v152, 0x60, v143
	v_add_u32_e32 v151, v151, v152
	v_mul_u32_u24_e32 v151, 0x1000, v151
	v_add_u32_e32 v151, v151, v150
	v_mov_b32_e32 v164, v151
	v_add_u32_e32 v166, 0x40000, v151
	v_add_u32_e32 v166, 0x40000, v151
	v_and_b32_e32 v151, 15, v140
	v_lshrrev_b32_e32 v152, 4, v140
	v_and_b32_e32 v153, 6, v151
	v_xor_b32_e32 v152, v152, v153
	v_lshlrev_b32_e32 v152, 4, v152
	v_lshl_or_b32 v152, v151, 7, v152
	v_lshrrev_b32_e32 v153, 2, v142
	v_lshl_add_u32 v153, v153, 13, v152
	v_add_u32_e32 v146, 0x0, v153
	v_and_b32_e32 v151, 3, v142
	v_lshl_add_u32 v151, v151, 12, v152
	v_add_u32_e32 v144, 0x0, v151
	v_add_u32_e32 v145, 0x10000, v151
	v_add_u32_e32 v147, 0x14000, v151
	v_add_u32_e32 v149, 0x10000, v151
	s_add_i32 m0, s29, 0x12000
	s_add_u32 s20, s96, s10
	s_addc_u32 s21, s97, s11
	s_mov_b32 m0, s29
	s_add_i32 s30, s29, 0x2000
	s_mov_b32 m0, s30
	s_add_u32 s10, s22, 0x80000
	s_addc_u32 s11, s23, 0
	s_add_i32 m0, s29, 0x14000
	v_mov_b32_e32 v165, 0
	s_add_i32 m0, s29, 0x16000
	v_mov_b32_e32 v167, v165
	s_add_u32 s10, s20, 0x100000
	s_addc_u32 s11, s21, 0
	s_add_i32 s31, s29, 0x4000
	s_mov_b32 m0, s31
	s_add_i32 s33, s29, 0x6000
	s_mov_b32 m0, s33
	v_mov_b32_e32 v129, v165
	v_mov_b32_e32 v131, v165
	s_mov_b32 s34, 0
	v_lshl_add_u64 v[6:7], s[22:23], 0, v[164:165]
	v_lshl_add_u64 v[4:5], s[22:23], 0, v[166:167]
	v_lshl_add_u64 v[2:3], s[20:21], 0, v[128:129]
	s_cmp_lg_u32 s7, 1
	v_lshl_add_u64 v[0:1], s[20:21], 0, v[130:131]
	s_cbranch_scc1 .LBB0_751
.LBB0_751:
	s_mov_b64 s[10:11], 0x80
	s_lshl_b32 s6, s6, 5
	s_add_i32 m0, s29, 0x18000
	v_lshl_add_u64 v[6:7], v[6:7], 0, s[10:11]
	s_lshl_b32 s35, s7, 6
	s_lshl_b32 s1, s7, 13
	s_and_b32 s36, s6, 0x60
	v_lshl_add_u64 v[4:5], v[4:5], 0, s[10:11]
	s_add_i32 m0, s29, 0x1a000
	s_add_i32 s37, s29, 0x8000
	s_add_i32 s38, s29, 0xa000
	v_lshl_add_u64 v[2:3], v[2:3], 0, s[10:11]
	s_mov_b32 m0, s37
	s_add_u32 s6, s22, 0x80080
	v_lshl_add_u64 v[0:1], v[0:1], 0, s[10:11]
	s_mov_b32 m0, s38
	s_addc_u32 s7, s23, 0
	s_add_i32 m0, s29, 0x1c000
	v_lshl_add_u64 v[0:1], s[6:7], 0, v[164:165]
	v_lshl_add_u64 v[0:1], s[6:7], 0, v[166:167]
	s_add_i32 m0, s29, 0x1e000
	v_lshlrev_b32_e32 v2, 13, v218
	v_lshlrev_b32_e32 v1, 2, v163
	v_lshl_or_b32 v0, v163, 6, v227
	v_and_b32_e32 v1, 32, v1
	v_bitop3_b32 v0, v0, s1, v1 bitop3:0xde
	v_lshlrev_b32_e32 v1, 10, v222
	v_and_b32_e32 v1, 0xe0000, v1
	v_or3_b32 v1, v226, v1, v2
	v_lshlrev_b32_e32 v1, 6, v233
	v_and_b32_e32 v1, 0x1e0000, v1
	v_or3_b32 v1, v226, v1, v2
	s_add_i32 s41, 0, 0x10000
	s_add_i32 s42, 0, 0x14000
	v_mbcnt_lo_u32_b32 v0, -1, 0
	s_ashr_i32 s39, s94, 31
	s_mov_b32 s40, s94
	v_mov_b32_e32 v133, v165
	v_mov_b32_e32 v135, v165
	v_mov_b64_e32 v[136:137], 0x200
	v_mov_b64_e32 v[138:139], 0x1ff
	v_mbcnt_hi_u32_b32 v148, -1, v0
	v_and_b32_e32 v140, 63, v222
	v_lshrrev_b32_e32 v141, 6, v222
	v_lshrrev_b32_e32 v142, 3, v140
	v_lshl_add_u32 v143, v141, 3, v142
	v_and_b32_e32 v150, 7, v140
	v_and_b32_e32 v151, 6, v142
	v_xor_b32_e32 v150, v150, v151
	v_lshlrev_b32_e32 v150, 4, v150
	v_mul_u32_u24_e32 v151, 0x2000, v143
	v_add_u32_e32 v149, v151, v150
	v_and_b32_e32 v151, 31, v143
	v_and_b32_e32 v142, 12, v151
	v_lshlrev_b32_e32 v142, 1, v142
	v_lshrrev_b32_e32 v216, 4, v151
	v_lshlrev_b32_e32 v216, 2, v216
	v_and_b32_e32 v151, 3, v151
	v_or3_b32 v151, v142, v216, v151
	v_and_b32_e32 v142, 0x60, v143
	v_add_u32_e32 v151, v151, v142
	v_mul_u32_u24_e32 v151, 0x1000, v151
	v_add_u32_e32 v216, v151, v150
	v_and_b32_e32 v142, 15, v140
	v_lshrrev_b32_e32 v143, 4, v140
	v_and_b32_e32 v150, 6, v142
	v_xor_b32_e32 v143, v143, v150
	v_lshlrev_b32_e32 v143, 4, v143
	v_lshl_or_b32 v143, v142, 7, v143
	v_lshrrev_b32_e32 v150, 2, v141
	v_lshl_add_u32 v217, v150, 13, v143
	v_xor_b32_e32 v242, 64, v217
	v_and_b32_e32 v150, 3, v141
	v_lshl_add_u32 v243, v150, 12, v143
	v_add_u32_e32 v243, 0x10000, v243
	v_xor_b32_e32 v244, 64, v243
	v_readfirstlane_b32 s48, v222
	s_nop 3
	s_lshr_b32 s48, s48, 6
	s_lshl_b32 s48, s48, 10
	s_mov_b32 s98, 0
	s_mul_i32 s24, s98, s94
	s_add_i32 s24, s24, s2
	s_and_b32 s25, s24, 7
	s_lshr_b32 s24, s24, 3
	s_mul_i32 s25, s25, 0x40
	s_add_i32 s24, s24, s25
	s_mul_i32 s25, s24, 0x80000
	s_lshr_b32 s25, s25, 24
	s_mul_i32 s45, s25, 0x20
	s_sub_i32 s24, s24, s45
	s_and_b32 s44, s24, 3
	s_lshl_b32 s25, s25, 2
	s_add_i32 s44, s44, s25
	s_lshr_b32 s45, s24, 2
	s_mul_i32 s100, s44, 0x200000
	s_add_u32 s20, s92, 0xfd00000
	s_addc_u32 s21, s93, 0
	s_add_u32 s20, s20, s100
	s_addc_u32 s21, s21, 0
	s_mul_i32 s100, s45, 0x100000
	s_add_u32 s22, s92, 0x7300000
	s_addc_u32 s23, s93, 0
	s_add_u32 s22, s22, s100
	s_addc_u32 s23, s23, 0
	s_add_i32 m0, s48, 0x0
	s_nop 0
	global_load_lds_dwordx4 v149, s[20:21]
	s_add_i32 m0, s48, 0x2000
	s_add_u32 s46, s20, 0x80000
	s_addc_u32 s47, s21, 0
	s_nop 0
	global_load_lds_dwordx4 v149, s[46:47]
	s_add_i32 m0, s48, 0x4000
	s_add_u32 s46, s20, 0x100000
	s_addc_u32 s47, s21, 0
	s_nop 0
	global_load_lds_dwordx4 v149, s[46:47]
	s_add_i32 m0, s48, 0x6000
	s_add_u32 s46, s20, 0x180000
	s_addc_u32 s47, s21, 0
	s_nop 0
	global_load_lds_dwordx4 v149, s[46:47]
	s_add_i32 m0, s48, 0x10000
	s_nop 0
	global_load_lds_dwordx4 v216, s[22:23]
	s_add_i32 m0, s48, 0x12000
	s_add_u32 s46, s22, 0x40000
	s_addc_u32 s47, s23, 0
	s_nop 0
	global_load_lds_dwordx4 v216, s[46:47]
	s_add_i32 m0, s48, 0x14000
	s_add_u32 s46, s22, 0x80000
	s_addc_u32 s47, s23, 0
	s_nop 0
	global_load_lds_dwordx4 v216, s[46:47]
	s_add_i32 m0, s48, 0x16000
	s_add_u32 s46, s22, 0xc0000
	s_addc_u32 s47, s23, 0
	s_nop 0
	global_load_lds_dwordx4 v216, s[46:47]
	s_add_u32 s20, s20, 128
	s_addc_u32 s21, s21, 0
	s_add_u32 s22, s22, 128
	s_addc_u32 s23, s23, 0
	s_add_i32 m0, s48, 0x8000
	s_nop 0
	global_load_lds_dwordx4 v149, s[20:21]
	s_add_i32 m0, s48, 0xa000
	s_add_u32 s46, s20, 0x80000
	s_addc_u32 s47, s21, 0
	s_nop 0
	global_load_lds_dwordx4 v149, s[46:47]
	s_add_i32 m0, s48, 0xc000
	s_add_u32 s46, s20, 0x100000
	s_addc_u32 s47, s21, 0
	s_nop 0
	global_load_lds_dwordx4 v149, s[46:47]
	s_add_i32 m0, s48, 0xe000
	s_add_u32 s46, s20, 0x180000
	s_addc_u32 s47, s21, 0
	s_nop 0
	global_load_lds_dwordx4 v149, s[46:47]
	s_add_i32 m0, s48, 0x18000
	s_nop 0
	global_load_lds_dwordx4 v216, s[22:23]
	s_add_i32 m0, s48, 0x1a000
	s_add_u32 s46, s22, 0x40000
	s_addc_u32 s47, s23, 0
	s_nop 0
	global_load_lds_dwordx4 v216, s[46:47]
	s_add_i32 m0, s48, 0x1c000
	s_add_u32 s46, s22, 0x80000
	s_addc_u32 s47, s23, 0
	s_nop 0
	global_load_lds_dwordx4 v216, s[46:47]
	s_add_i32 m0, s48, 0x1e000
	s_add_u32 s46, s22, 0xc0000
	s_addc_u32 s47, s23, 0
	s_nop 0
	global_load_lds_dwordx4 v216, s[46:47]
	s_branch .LBB0_753

.LBB0_759:
	s_ashr_i32 s15, s14, 31
	v_cmp_lt_i64_e32 vcc, s[16:17], v[136:137]
	s_lshl_b64 s[16:17], s[14:15], 21
	s_add_u32 s16, s96, s16
	s_addc_u32 s17, s97, s17
	s_and_b64 s[18:19], vcc, exec
	s_cselect_b32 s1, s17, s21
	s_cselect_b32 s9, s16, s20
	s_ashr_i32 s13, s12, 31
	s_lshl_b64 s[18:19], s[12:13], 20
	s_add_u32 s18, s26, s18
	s_addc_u32 s19, s27, s19
	s_and_b64 s[24:25], vcc, exec
	s_cselect_b32 s13, s19, s23
	s_cselect_b32 s15, s18, s22
	s_add_u32 s20, s20, 0x100080
	s_addc_u32 s21, s21, 0
	s_add_u32 s43, s22, 0x100
	v_mov_b32_e32 v0, 0
	s_addc_u32 s44, s23, 0
	s_mov_b32 s45, -2
	s_waitcnt lgkmcnt(0)
	v_mov_b32_e32 v1, v0
	v_mov_b32_e32 v2, v0
	v_mov_b32_e32 v3, v0
	v_mov_b32_e32 v4, v0
	v_mov_b32_e32 v5, v0
	v_mov_b32_e32 v6, v0
	v_mov_b32_e32 v7, v0
	s_waitcnt vmcnt(0)
	v_mov_b32_e32 v16, v0
	v_mov_b32_e32 v17, v0
	v_mov_b32_e32 v18, v0
	v_mov_b32_e32 v19, v0
	v_mov_b32_e32 v20, v0
	v_mov_b32_e32 v21, v0
	v_mov_b32_e32 v22, v0
	v_mov_b32_e32 v23, v0
	v_mov_b32_e32 v32, v0
	v_mov_b32_e32 v33, v0
	v_mov_b32_e32 v34, v0
	v_mov_b32_e32 v35, v0
	v_mov_b32_e32 v36, v0
	v_mov_b32_e32 v37, v0
	v_mov_b32_e32 v38, v0
	v_mov_b32_e32 v39, v0
	v_mov_b32_e32 v48, v0
	v_mov_b32_e32 v49, v0
	v_mov_b32_e32 v50, v0
	v_mov_b32_e32 v51, v0
	v_mov_b32_e32 v52, v0
	v_mov_b32_e32 v53, v0
	v_mov_b32_e32 v54, v0
	v_mov_b32_e32 v55, v0
	v_mov_b32_e32 v8, v0
	v_mov_b32_e32 v9, v0
	v_mov_b32_e32 v10, v0
	v_mov_b32_e32 v11, v0
	v_mov_b32_e32 v12, v0
	v_mov_b32_e32 v13, v0
	v_mov_b32_e32 v14, v0
	v_mov_b32_e32 v15, v0
	v_mov_b32_e32 v24, v0
	v_mov_b32_e32 v25, v0
	v_mov_b32_e32 v26, v0
	v_mov_b32_e32 v27, v0
	v_mov_b32_e32 v28, v0
	v_mov_b32_e32 v29, v0
	v_mov_b32_e32 v30, v0
	v_mov_b32_e32 v31, v0
	v_mov_b32_e32 v40, v0
	v_mov_b32_e32 v41, v0
	v_mov_b32_e32 v42, v0
	v_mov_b32_e32 v43, v0
	v_mov_b32_e32 v44, v0
	v_mov_b32_e32 v45, v0
	v_mov_b32_e32 v46, v0
	v_mov_b32_e32 v47, v0
	v_mov_b32_e32 v56, v0
	v_mov_b32_e32 v57, v0
	v_mov_b32_e32 v58, v0
	v_mov_b32_e32 v59, v0
	v_mov_b32_e32 v60, v0
	v_mov_b32_e32 v61, v0
	v_mov_b32_e32 v62, v0
	v_mov_b32_e32 v63, v0
	v_mov_b32_e32 v64, v0
	v_mov_b32_e32 v65, v0
	v_mov_b32_e32 v66, v0
	v_mov_b32_e32 v67, v0
	v_mov_b32_e32 v68, v0
	v_mov_b32_e32 v69, v0
	v_mov_b32_e32 v70, v0
	v_mov_b32_e32 v71, v0
	v_mov_b32_e32 v80, v0
	v_mov_b32_e32 v81, v0
	v_mov_b32_e32 v82, v0
	v_mov_b32_e32 v83, v0
	v_mov_b32_e32 v84, v0
	v_mov_b32_e32 v85, v0
	v_mov_b32_e32 v86, v0
	v_mov_b32_e32 v87, v0
	v_mov_b32_e32 v96, v0
	v_mov_b32_e32 v97, v0
	v_mov_b32_e32 v98, v0
	v_mov_b32_e32 v99, v0
	v_mov_b32_e32 v100, v0
	v_mov_b32_e32 v101, v0
	v_mov_b32_e32 v102, v0
	v_mov_b32_e32 v103, v0
	v_mov_b32_e32 v112, v0
	v_mov_b32_e32 v113, v0
	v_mov_b32_e32 v114, v0
	v_mov_b32_e32 v115, v0
	v_mov_b32_e32 v116, v0
	v_mov_b32_e32 v117, v0
	v_mov_b32_e32 v118, v0
	v_mov_b32_e32 v119, v0
	v_mov_b32_e32 v72, v0
	v_mov_b32_e32 v73, v0
	v_mov_b32_e32 v74, v0
	v_mov_b32_e32 v75, v0
	v_mov_b32_e32 v76, v0
	v_mov_b32_e32 v77, v0
	v_mov_b32_e32 v78, v0
	v_mov_b32_e32 v79, v0
	v_mov_b32_e32 v88, v0
	v_mov_b32_e32 v89, v0
	v_mov_b32_e32 v90, v0
	v_mov_b32_e32 v91, v0
	v_mov_b32_e32 v92, v0
	v_mov_b32_e32 v93, v0
	v_mov_b32_e32 v94, v0
	v_mov_b32_e32 v95, v0
	v_mov_b32_e32 v104, v0
	v_mov_b32_e32 v105, v0
	v_mov_b32_e32 v106, v0
	v_mov_b32_e32 v107, v0
	v_mov_b32_e32 v108, v0
	v_mov_b32_e32 v109, v0
	v_mov_b32_e32 v110, v0
	v_mov_b32_e32 v111, v0
	v_mov_b32_e32 v120, v0
	v_mov_b32_e32 v121, v0
	v_mov_b32_e32 v122, v0
	v_mov_b32_e32 v123, v0
	v_mov_b32_e32 v124, v0
	v_mov_b32_e32 v125, v0
	v_mov_b32_e32 v126, v0
	v_mov_b32_e32 v127, v0
	v_and_b32_e32 v140, 63, v222
	v_lshrrev_b32_e32 v141, 6, v222
	v_lshrrev_b32_e32 v142, 3, v140
	v_lshl_add_u32 v143, v141, 3, v142
	v_and_b32_e32 v150, 7, v140
	v_and_b32_e32 v151, 6, v142
	v_xor_b32_e32 v150, v150, v151
	v_lshlrev_b32_e32 v150, 4, v150
	v_mul_u32_u24_e32 v151, 0x2000, v143
	v_add_u32_e32 v149, v151, v150
	v_and_b32_e32 v151, 31, v143
	v_and_b32_e32 v142, 12, v151
	v_lshlrev_b32_e32 v142, 1, v142
	v_lshrrev_b32_e32 v216, 4, v151
	v_lshlrev_b32_e32 v216, 2, v216
	v_and_b32_e32 v151, 3, v151
	v_or3_b32 v151, v142, v216, v151
	v_and_b32_e32 v142, 0x60, v143
	v_add_u32_e32 v151, v151, v142
	v_mul_u32_u24_e32 v151, 0x1000, v151
	v_add_u32_e32 v216, v151, v150
	v_and_b32_e32 v142, 15, v140
	v_lshrrev_b32_e32 v143, 4, v140
	v_and_b32_e32 v150, 6, v142
	v_xor_b32_e32 v143, v143, v150
	v_lshlrev_b32_e32 v143, 4, v143
	v_lshl_or_b32 v143, v142, 7, v143
	v_lshrrev_b32_e32 v150, 2, v141
	v_lshl_add_u32 v217, v150, 13, v143
	v_xor_b32_e32 v242, 64, v217
	v_and_b32_e32 v150, 3, v141
	v_lshl_add_u32 v243, v150, 12, v143
	v_add_u32_e32 v243, 0x10000, v243
	v_xor_b32_e32 v244, 64, v243
	v_readfirstlane_b32 s48, v222
	s_nop 3
	s_lshr_b32 s48, s48, 6
	s_lshl_b32 s48, s48, 10
	s_mul_i32 s24, s98, s94
	s_add_i32 s24, s24, s2
	s_and_b32 s25, s24, 7
	s_lshr_b32 s24, s24, 3
	s_mul_i32 s25, s25, 0x40
	s_add_i32 s24, s24, s25
	s_mul_i32 s25, s24, 0x80000
	s_lshr_b32 s25, s25, 24
	s_mul_i32 s100, s25, 0x20
	s_sub_i32 s24, s24, s100
	s_and_b32 s43, s24, 3
	s_lshl_b32 s25, s25, 2
	s_add_i32 s43, s43, s25
	s_lshr_b32 s100, s24, 2
	s_mul_i32 s99, s43, 0x200000
	s_add_u32 s20, s92, 0xfd00100
	s_addc_u32 s21, s93, 0
	s_add_u32 s20, s20, s99
	s_addc_u32 s21, s21, 0
	s_mul_i32 s99, s100, 0x100000
	s_add_u32 s22, s92, 0x7300100
	s_addc_u32 s23, s93, 0
	s_add_u32 s22, s22, s99
	s_addc_u32 s23, s23, 0
	s_add_i32 s98, s98, 1
	s_mul_i32 s44, s98, s94
	s_add_i32 s44, s44, s2
	s_cmp_lt_u32 s44, 0x200
	s_cbranch_scc0 .Ls7_nonext
	s_mul_i32 s24, s98, s94
	s_add_i32 s24, s24, s2
	s_and_b32 s25, s24, 7
	s_lshr_b32 s24, s24, 3
	s_mul_i32 s25, s25, 0x40
	s_add_i32 s24, s24, s25
	s_mul_i32 s25, s24, 0x80000
	s_lshr_b32 s25, s25, 24
	s_mul_i32 s100, s25, 0x20
	s_sub_i32 s24, s24, s100
	s_and_b32 s43, s24, 3
	s_lshl_b32 s25, s25, 2
	s_add_i32 s43, s43, s25
	s_lshr_b32 s100, s24, 2
.Ls7_nonext:
	s_mul_i32 s99, s43, 0x200000
	s_add_u32 s24, s92, 0xfd00000
	s_addc_u32 s25, s93, 0
	s_add_u32 s24, s24, s99
	s_addc_u32 s25, s25, 0
	s_mul_i32 s99, s100, 0x100000
	s_add_u32 s44, s92, 0x7300000
	s_addc_u32 s45, s93, 0
	s_add_u32 s44, s44, s99
	s_addc_u32 s45, s45, 0
	s_waitcnt vmcnt(0)
	s_barrier
	ds_read_b128 v[140:143], v217
	ds_read_b128 v[150:153], v217 offset:2048
	ds_read_b128 v[192:195], v243
	ds_read_b128 v[196:199], v243 offset:2048
	ds_read_b128 v[200:203], v243 offset:16384
	ds_read_b128 v[204:207], v243 offset:18432
	ds_read_b128 v[154:157], v217 offset:4096
	ds_read_b128 v[158:161], v217 offset:6144
	ds_read_b128 v[176:179], v217 offset:16384
	ds_read_b128 v[180:183], v217 offset:18432
	ds_read_b128 v[184:187], v217 offset:20480
	ds_read_b128 v[188:191], v217 offset:22528
	s_mov_b32 s43, 0
.Ls7_loop:
	s_cmp_eq_u32 s43, 15
	s_cselect_b32 s20, s24, s20
	s_cselect_b32 s21, s25, s21
	s_cselect_b32 s22, s44, s22
	s_cselect_b32 s23, s45, s23
	s_waitcnt lgkmcnt(6)
	v_mfma_f32_16x16x32_bf16 v[124:127], v[192:195], v[140:143], v[124:127]
	v_mfma_f32_16x16x32_bf16 v[120:123], v[196:199], v[140:143], v[120:123]
	v_mfma_f32_16x16x32_bf16 v[116:119], v[200:203], v[140:143], v[116:119]
	v_mfma_f32_16x16x32_bf16 v[112:115], v[204:207], v[140:143], v[112:115]
	v_mfma_f32_16x16x32_bf16 v[108:111], v[192:195], v[150:153], v[108:111]
	v_mfma_f32_16x16x32_bf16 v[104:107], v[196:199], v[150:153], v[104:107]
	v_mfma_f32_16x16x32_bf16 v[100:103], v[200:203], v[150:153], v[100:103]
	v_mfma_f32_16x16x32_bf16 v[96:99], v[204:207], v[150:153], v[96:99]
	s_waitcnt lgkmcnt(0)
	ds_read_b128 v[140:143], v242
	ds_read_b128 v[150:153], v242 offset:2048
	ds_read_b128 v[208:211], v244
	ds_read_b128 v[212:215], v244 offset:2048
	ds_read_b128 v[234:237], v244 offset:16384
	ds_read_b128 v[238:241], v244 offset:18432
	v_mfma_f32_16x16x32_bf16 v[92:95], v[192:195], v[154:157], v[92:95]
	v_mfma_f32_16x16x32_bf16 v[88:91], v[196:199], v[154:157], v[88:91]
	v_mfma_f32_16x16x32_bf16 v[84:87], v[200:203], v[154:157], v[84:87]
	v_mfma_f32_16x16x32_bf16 v[80:83], v[204:207], v[154:157], v[80:83]
	ds_read_b128 v[154:157], v242 offset:4096
	v_mfma_f32_16x16x32_bf16 v[76:79], v[192:195], v[158:161], v[76:79]
	v_mfma_f32_16x16x32_bf16 v[72:75], v[196:199], v[158:161], v[72:75]
	v_mfma_f32_16x16x32_bf16 v[68:71], v[200:203], v[158:161], v[68:71]
	v_mfma_f32_16x16x32_bf16 v[64:67], v[204:207], v[158:161], v[64:67]
	ds_read_b128 v[158:161], v242 offset:6144
	s_waitcnt lgkmcnt(0)
	s_barrier
	s_add_i32 m0, s48, 0x10000
	v_mfma_f32_16x16x32_bf16 v[60:63], v[192:195], v[176:179], v[60:63]
	v_mfma_f32_16x16x32_bf16 v[56:59], v[196:199], v[176:179], v[56:59]
	v_mfma_f32_16x16x32_bf16 v[52:55], v[200:203], v[176:179], v[52:55]
	v_mfma_f32_16x16x32_bf16 v[48:51], v[204:207], v[176:179], v[48:51]
	ds_read_b128 v[176:179], v242 offset:16384
	global_load_lds_dwordx4 v216, s[22:23]
	s_add_i32 m0, s48, 0x12000
	s_add_u32 s46, s22, 0x40000
	s_addc_u32 s47, s23, 0
	v_mfma_f32_16x16x32_bf16 v[44:47], v[192:195], v[180:183], v[44:47]
	v_mfma_f32_16x16x32_bf16 v[40:43], v[196:199], v[180:183], v[40:43]
	v_mfma_f32_16x16x32_bf16 v[36:39], v[200:203], v[180:183], v[36:39]
	v_mfma_f32_16x16x32_bf16 v[32:35], v[204:207], v[180:183], v[32:35]
	ds_read_b128 v[180:183], v242 offset:18432
	global_load_lds_dwordx4 v216, s[46:47]
	s_add_i32 m0, s48, 0x14000
	s_add_u32 s46, s22, 0x80000
	s_addc_u32 s47, s23, 0
	v_mfma_f32_16x16x32_bf16 v[28:31], v[192:195], v[184:187], v[28:31]
	v_mfma_f32_16x16x32_bf16 v[24:27], v[196:199], v[184:187], v[24:27]
	v_mfma_f32_16x16x32_bf16 v[20:23], v[200:203], v[184:187], v[20:23]
	v_mfma_f32_16x16x32_bf16 v[16:19], v[204:207], v[184:187], v[16:19]
	ds_read_b128 v[184:187], v242 offset:20480
	global_load_lds_dwordx4 v216, s[46:47]
	s_add_i32 m0, s48, 0x16000
	s_add_u32 s46, s22, 0xc0000
	s_addc_u32 s47, s23, 0
	v_mfma_f32_16x16x32_bf16 v[12:15], v[192:195], v[188:191], v[12:15]
	v_mfma_f32_16x16x32_bf16 v[8:11], v[196:199], v[188:191], v[8:11]
	v_mfma_f32_16x16x32_bf16 v[4:7], v[200:203], v[188:191], v[4:7]
	v_mfma_f32_16x16x32_bf16 v[0:3], v[204:207], v[188:191], v[0:3]
	ds_read_b128 v[188:191], v242 offset:22528
	global_load_lds_dwordx4 v216, s[46:47]
	s_waitcnt lgkmcnt(6)
	s_add_i32 m0, s48, 0x0
	v_mfma_f32_16x16x32_bf16 v[124:127], v[208:211], v[140:143], v[124:127]
	v_mfma_f32_16x16x32_bf16 v[120:123], v[212:215], v[140:143], v[120:123]
	v_mfma_f32_16x16x32_bf16 v[116:119], v[234:237], v[140:143], v[116:119]
	v_mfma_f32_16x16x32_bf16 v[112:115], v[238:241], v[140:143], v[112:115]
	global_load_lds_dwordx4 v149, s[20:21]
	s_add_i32 m0, s48, 0x2000
	s_add_u32 s46, s20, 0x80000
	s_addc_u32 s47, s21, 0
	v_mfma_f32_16x16x32_bf16 v[108:111], v[208:211], v[150:153], v[108:111]
	v_mfma_f32_16x16x32_bf16 v[104:107], v[212:215], v[150:153], v[104:107]
	v_mfma_f32_16x16x32_bf16 v[100:103], v[234:237], v[150:153], v[100:103]
	v_mfma_f32_16x16x32_bf16 v[96:99], v[238:241], v[150:153], v[96:99]
	global_load_lds_dwordx4 v149, s[46:47]
	s_waitcnt lgkmcnt(0)
	s_waitcnt vmcnt(6)
	s_barrier
	ds_read_b128 v[140:143], v217 offset:32768
	ds_read_b128 v[150:153], v217 offset:34816
	ds_read_b128 v[192:195], v243 offset:32768
	ds_read_b128 v[196:199], v243 offset:34816
	ds_read_b128 v[200:203], v243 offset:49152
	ds_read_b128 v[204:207], v243 offset:51200
	s_add_i32 m0, s48, 0x4000
	s_add_u32 s46, s20, 0x100000
	s_addc_u32 s47, s21, 0
	v_mfma_f32_16x16x32_bf16 v[92:95], v[208:211], v[154:157], v[92:95]
	v_mfma_f32_16x16x32_bf16 v[88:91], v[212:215], v[154:157], v[88:91]
	v_mfma_f32_16x16x32_bf16 v[84:87], v[234:237], v[154:157], v[84:87]
	v_mfma_f32_16x16x32_bf16 v[80:83], v[238:241], v[154:157], v[80:83]
	ds_read_b128 v[154:157], v217 offset:36864
	global_load_lds_dwordx4 v149, s[46:47]
	s_add_i32 m0, s48, 0x6000
	s_add_u32 s46, s20, 0x180000
	s_addc_u32 s47, s21, 0
	v_mfma_f32_16x16x32_bf16 v[76:79], v[208:211], v[158:161], v[76:79]
	v_mfma_f32_16x16x32_bf16 v[72:75], v[212:215], v[158:161], v[72:75]
	v_mfma_f32_16x16x32_bf16 v[68:71], v[234:237], v[158:161], v[68:71]
	v_mfma_f32_16x16x32_bf16 v[64:67], v[238:241], v[158:161], v[64:67]
	ds_read_b128 v[158:161], v217 offset:38912
	global_load_lds_dwordx4 v149, s[46:47]
	v_mfma_f32_16x16x32_bf16 v[60:63], v[208:211], v[176:179], v[60:63]
	v_mfma_f32_16x16x32_bf16 v[56:59], v[212:215], v[176:179], v[56:59]
	v_mfma_f32_16x16x32_bf16 v[52:55], v[234:237], v[176:179], v[52:55]
	v_mfma_f32_16x16x32_bf16 v[48:51], v[238:241], v[176:179], v[48:51]
	ds_read_b128 v[176:179], v217 offset:49152
	v_mfma_f32_16x16x32_bf16 v[44:47], v[208:211], v[180:183], v[44:47]
	v_mfma_f32_16x16x32_bf16 v[40:43], v[212:215], v[180:183], v[40:43]
	v_mfma_f32_16x16x32_bf16 v[36:39], v[234:237], v[180:183], v[36:39]
	v_mfma_f32_16x16x32_bf16 v[32:35], v[238:241], v[180:183], v[32:35]
	ds_read_b128 v[180:183], v217 offset:51200
	v_mfma_f32_16x16x32_bf16 v[28:31], v[208:211], v[184:187], v[28:31]
	v_mfma_f32_16x16x32_bf16 v[24:27], v[212:215], v[184:187], v[24:27]
	v_mfma_f32_16x16x32_bf16 v[20:23], v[234:237], v[184:187], v[20:23]
	v_mfma_f32_16x16x32_bf16 v[16:19], v[238:241], v[184:187], v[16:19]
	ds_read_b128 v[184:187], v217 offset:53248
	v_mfma_f32_16x16x32_bf16 v[12:15], v[208:211], v[188:191], v[12:15]
	v_mfma_f32_16x16x32_bf16 v[8:11], v[212:215], v[188:191], v[8:11]
	v_mfma_f32_16x16x32_bf16 v[4:7], v[234:237], v[188:191], v[4:7]
	v_mfma_f32_16x16x32_bf16 v[0:3], v[238:241], v[188:191], v[0:3]
	ds_read_b128 v[188:191], v217 offset:55296
	s_add_u32 s20, s20, 128
	s_addc_u32 s21, s21, 0
	s_add_u32 s22, s22, 128
	s_addc_u32 s23, s23, 0
	s_waitcnt lgkmcnt(6)
	v_mfma_f32_16x16x32_bf16 v[124:127], v[192:195], v[140:143], v[124:127]
	v_mfma_f32_16x16x32_bf16 v[120:123], v[196:199], v[140:143], v[120:123]
	v_mfma_f32_16x16x32_bf16 v[116:119], v[200:203], v[140:143], v[116:119]
	v_mfma_f32_16x16x32_bf16 v[112:115], v[204:207], v[140:143], v[112:115]
	v_mfma_f32_16x16x32_bf16 v[108:111], v[192:195], v[150:153], v[108:111]
	v_mfma_f32_16x16x32_bf16 v[104:107], v[196:199], v[150:153], v[104:107]
	v_mfma_f32_16x16x32_bf16 v[100:103], v[200:203], v[150:153], v[100:103]
	v_mfma_f32_16x16x32_bf16 v[96:99], v[204:207], v[150:153], v[96:99]
	s_waitcnt lgkmcnt(0)
	ds_read_b128 v[140:143], v242 offset:32768
	ds_read_b128 v[150:153], v242 offset:34816
	ds_read_b128 v[208:211], v244 offset:32768
	ds_read_b128 v[212:215], v244 offset:34816
	ds_read_b128 v[234:237], v244 offset:49152
	ds_read_b128 v[238:241], v244 offset:51200
	v_mfma_f32_16x16x32_bf16 v[92:95], v[192:195], v[154:157], v[92:95]
	v_mfma_f32_16x16x32_bf16 v[88:91], v[196:199], v[154:157], v[88:91]
	v_mfma_f32_16x16x32_bf16 v[84:87], v[200:203], v[154:157], v[84:87]
	v_mfma_f32_16x16x32_bf16 v[80:83], v[204:207], v[154:157], v[80:83]
	ds_read_b128 v[154:157], v242 offset:36864
	v_mfma_f32_16x16x32_bf16 v[76:79], v[192:195], v[158:161], v[76:79]
	v_mfma_f32_16x16x32_bf16 v[72:75], v[196:199], v[158:161], v[72:75]
	v_mfma_f32_16x16x32_bf16 v[68:71], v[200:203], v[158:161], v[68:71]
	v_mfma_f32_16x16x32_bf16 v[64:67], v[204:207], v[158:161], v[64:67]
	ds_read_b128 v[158:161], v242 offset:38912
	s_waitcnt lgkmcnt(0)
	s_barrier
	s_add_i32 m0, s48, 0x18000
	v_mfma_f32_16x16x32_bf16 v[60:63], v[192:195], v[176:179], v[60:63]
	v_mfma_f32_16x16x32_bf16 v[56:59], v[196:199], v[176:179], v[56:59]
	v_mfma_f32_16x16x32_bf16 v[52:55], v[200:203], v[176:179], v[52:55]
	v_mfma_f32_16x16x32_bf16 v[48:51], v[204:207], v[176:179], v[48:51]
	ds_read_b128 v[176:179], v242 offset:49152
	global_load_lds_dwordx4 v216, s[22:23]
	s_add_i32 m0, s48, 0x1a000
	s_add_u32 s46, s22, 0x40000
	s_addc_u32 s47, s23, 0
	v_mfma_f32_16x16x32_bf16 v[44:47], v[192:195], v[180:183], v[44:47]
	v_mfma_f32_16x16x32_bf16 v[40:43], v[196:199], v[180:183], v[40:43]
	v_mfma_f32_16x16x32_bf16 v[36:39], v[200:203], v[180:183], v[36:39]
	v_mfma_f32_16x16x32_bf16 v[32:35], v[204:207], v[180:183], v[32:35]
	ds_read_b128 v[180:183], v242 offset:51200
	global_load_lds_dwordx4 v216, s[46:47]
	s_add_i32 m0, s48, 0x1c000
	s_add_u32 s46, s22, 0x80000
	s_addc_u32 s47, s23, 0
	v_mfma_f32_16x16x32_bf16 v[28:31], v[192:195], v[184:187], v[28:31]
	v_mfma_f32_16x16x32_bf16 v[24:27], v[196:199], v[184:187], v[24:27]
	v_mfma_f32_16x16x32_bf16 v[20:23], v[200:203], v[184:187], v[20:23]
	v_mfma_f32_16x16x32_bf16 v[16:19], v[204:207], v[184:187], v[16:19]
	ds_read_b128 v[184:187], v242 offset:53248
	global_load_lds_dwordx4 v216, s[46:47]
	s_add_i32 m0, s48, 0x1e000
	s_add_u32 s46, s22, 0xc0000
	s_addc_u32 s47, s23, 0
	v_mfma_f32_16x16x32_bf16 v[12:15], v[192:195], v[188:191], v[12:15]
	v_mfma_f32_16x16x32_bf16 v[8:11], v[196:199], v[188:191], v[8:11]
	v_mfma_f32_16x16x32_bf16 v[4:7], v[200:203], v[188:191], v[4:7]
	v_mfma_f32_16x16x32_bf16 v[0:3], v[204:207], v[188:191], v[0:3]
	ds_read_b128 v[188:191], v242 offset:55296
	global_load_lds_dwordx4 v216, s[46:47]
	s_waitcnt lgkmcnt(6)
	s_add_i32 m0, s48, 0x8000
	v_mfma_f32_16x16x32_bf16 v[124:127], v[208:211], v[140:143], v[124:127]
	v_mfma_f32_16x16x32_bf16 v[120:123], v[212:215], v[140:143], v[120:123]
	v_mfma_f32_16x16x32_bf16 v[116:119], v[234:237], v[140:143], v[116:119]
	v_mfma_f32_16x16x32_bf16 v[112:115], v[238:241], v[140:143], v[112:115]
	global_load_lds_dwordx4 v149, s[20:21]
	s_add_i32 m0, s48, 0xa000
	s_add_u32 s46, s20, 0x80000
	s_addc_u32 s47, s21, 0
	v_mfma_f32_16x16x32_bf16 v[108:111], v[208:211], v[150:153], v[108:111]
	v_mfma_f32_16x16x32_bf16 v[104:107], v[212:215], v[150:153], v[104:107]
	v_mfma_f32_16x16x32_bf16 v[100:103], v[234:237], v[150:153], v[100:103]
	v_mfma_f32_16x16x32_bf16 v[96:99], v[238:241], v[150:153], v[96:99]
	global_load_lds_dwordx4 v149, s[46:47]
	s_waitcnt lgkmcnt(0)
	s_waitcnt vmcnt(6)
	s_barrier
	ds_read_b128 v[140:143], v217
	ds_read_b128 v[150:153], v217 offset:2048
	ds_read_b128 v[192:195], v243
	ds_read_b128 v[196:199], v243 offset:2048
	ds_read_b128 v[200:203], v243 offset:16384
	ds_read_b128 v[204:207], v243 offset:18432
	s_add_i32 m0, s48, 0xc000
	s_add_u32 s46, s20, 0x100000
	s_addc_u32 s47, s21, 0
	v_mfma_f32_16x16x32_bf16 v[92:95], v[208:211], v[154:157], v[92:95]
	v_mfma_f32_16x16x32_bf16 v[88:91], v[212:215], v[154:157], v[88:91]
	v_mfma_f32_16x16x32_bf16 v[84:87], v[234:237], v[154:157], v[84:87]
	v_mfma_f32_16x16x32_bf16 v[80:83], v[238:241], v[154:157], v[80:83]
	ds_read_b128 v[154:157], v217 offset:4096
	global_load_lds_dwordx4 v149, s[46:47]
	s_add_i32 m0, s48, 0xe000
	s_add_u32 s46, s20, 0x180000
	s_addc_u32 s47, s21, 0
	v_mfma_f32_16x16x32_bf16 v[76:79], v[208:211], v[158:161], v[76:79]
	v_mfma_f32_16x16x32_bf16 v[72:75], v[212:215], v[158:161], v[72:75]
	v_mfma_f32_16x16x32_bf16 v[68:71], v[234:237], v[158:161], v[68:71]
	v_mfma_f32_16x16x32_bf16 v[64:67], v[238:241], v[158:161], v[64:67]
	ds_read_b128 v[158:161], v217 offset:6144
	global_load_lds_dwordx4 v149, s[46:47]
	v_mfma_f32_16x16x32_bf16 v[60:63], v[208:211], v[176:179], v[60:63]
	v_mfma_f32_16x16x32_bf16 v[56:59], v[212:215], v[176:179], v[56:59]
	v_mfma_f32_16x16x32_bf16 v[52:55], v[234:237], v[176:179], v[52:55]
	v_mfma_f32_16x16x32_bf16 v[48:51], v[238:241], v[176:179], v[48:51]
	ds_read_b128 v[176:179], v217 offset:16384
	v_mfma_f32_16x16x32_bf16 v[44:47], v[208:211], v[180:183], v[44:47]
	v_mfma_f32_16x16x32_bf16 v[40:43], v[212:215], v[180:183], v[40:43]
	v_mfma_f32_16x16x32_bf16 v[36:39], v[234:237], v[180:183], v[36:39]
	v_mfma_f32_16x16x32_bf16 v[32:35], v[238:241], v[180:183], v[32:35]
	ds_read_b128 v[180:183], v217 offset:18432
	v_mfma_f32_16x16x32_bf16 v[28:31], v[208:211], v[184:187], v[28:31]
	v_mfma_f32_16x16x32_bf16 v[24:27], v[212:215], v[184:187], v[24:27]
	v_mfma_f32_16x16x32_bf16 v[20:23], v[234:237], v[184:187], v[20:23]
	v_mfma_f32_16x16x32_bf16 v[16:19], v[238:241], v[184:187], v[16:19]
	ds_read_b128 v[184:187], v217 offset:20480
	v_mfma_f32_16x16x32_bf16 v[12:15], v[208:211], v[188:191], v[12:15]
	v_mfma_f32_16x16x32_bf16 v[8:11], v[212:215], v[188:191], v[8:11]
	v_mfma_f32_16x16x32_bf16 v[4:7], v[234:237], v[188:191], v[4:7]
	v_mfma_f32_16x16x32_bf16 v[0:3], v[238:241], v[188:191], v[0:3]
	ds_read_b128 v[188:191], v217 offset:22528
	s_add_u32 s20, s20, 128
	s_addc_u32 s21, s21, 0
	s_add_u32 s22, s22, 128
	s_addc_u32 s23, s23, 0
	s_add_i32 s43, s43, 1
	s_cmp_lt_u32 s43, 16
	s_cbranch_scc1 .Ls7_loop
	s_waitcnt lgkmcnt(0)
	s_nop 7
	s_nop 3
	v_lshl_add_u32 v217, s8, 8, v163
	v_add_u32_e32 v217, s35, v217
	v_lshlrev_b32_e32 v208, 2, v217
	v_lshl_add_u32 v214, v225, 3, s36
	v_lshl_add_u32 v214, s0, 8, v214
	v_lshl_add_u32 v209, v217, 11, v214
	v_lshlrev_b32_e32 v209, 1, v209
	v_lshlrev_b32_e32 v210, 1, v209
	v_lshl_add_u32 v217, v225, 4, v163
	v_xor_b32_e32 v215, 16, v217
	v_lshlrev_b32_e32 v215, 2, v215
	v_xor_b32_e32 v216, 32, v217
	v_lshlrev_b32_e32 v216, 2, v216
	v_add_u32_e32 v211, 0x0, v209
	global_load_dwordx4 v[176:179], v211, s[80:81]
	global_load_dwordx4 v[180:183], v211, s[80:81] offset:256
	v_add_u32_e32 v211, 0x10000, v209
	global_load_dwordx4 v[192:195], v211, s[80:81]
	global_load_dwordx4 v[196:199], v211, s[80:81] offset:256
	s_waitcnt vmcnt(2)
	v_lshlrev_b32_e32 v184, 16, v176
	v_and_b32_e32 v185, 0xffff0000, v176
	v_lshlrev_b32_e32 v186, 16, v177
	v_and_b32_e32 v187, 0xffff0000, v177
	v_lshlrev_b32_e32 v188, 16, v178
	v_and_b32_e32 v189, 0xffff0000, v178
	v_lshlrev_b32_e32 v190, 16, v179
	v_and_b32_e32 v191, 0xffff0000, v179
	v_pk_add_f32 v[124:125], v[124:125], v[184:185]
	v_pk_add_f32 v[126:127], v[126:127], v[186:187]
	v_pk_add_f32 v[120:121], v[120:121], v[188:189]
	v_pk_add_f32 v[122:123], v[122:123], v[190:191]
	v_mul_f32_e32 v213, v124, v124
	v_fmac_f32_e32 v213, v125, v125
	v_fmac_f32_e32 v213, v126, v126
	v_fmac_f32_e32 v213, v127, v127
	v_fmac_f32_e32 v213, v120, v120
	v_fmac_f32_e32 v213, v121, v121
	v_fmac_f32_e32 v213, v122, v122
	v_fmac_f32_e32 v213, v123, v123
	v_cvt_pk_bf16_f32 v176, v124, v125
	v_cvt_pk_bf16_f32 v177, v126, v127
	v_cvt_pk_bf16_f32 v178, v120, v121
	v_cvt_pk_bf16_f32 v179, v122, v123
	v_add_u32_e32 v217, 0x0, v209
	global_store_dwordx4 v217, v[176:179], s[80:81]
	v_lshlrev_b32_e32 v184, 16, v180
	v_and_b32_e32 v185, 0xffff0000, v180
	v_lshlrev_b32_e32 v186, 16, v181
	v_and_b32_e32 v187, 0xffff0000, v181
	v_lshlrev_b32_e32 v188, 16, v182
	v_and_b32_e32 v189, 0xffff0000, v182
	v_lshlrev_b32_e32 v190, 16, v183
	v_and_b32_e32 v191, 0xffff0000, v183
	v_pk_add_f32 v[116:117], v[116:117], v[184:185]
	v_pk_add_f32 v[118:119], v[118:119], v[186:187]
	v_pk_add_f32 v[112:113], v[112:113], v[188:189]
	v_pk_add_f32 v[114:115], v[114:115], v[190:191]
	v_fmac_f32_e32 v213, v116, v116
	v_fmac_f32_e32 v213, v117, v117
	v_fmac_f32_e32 v213, v118, v118
	v_fmac_f32_e32 v213, v119, v119
	v_fmac_f32_e32 v213, v112, v112
	v_fmac_f32_e32 v213, v113, v113
	v_fmac_f32_e32 v213, v114, v114
	v_fmac_f32_e32 v213, v115, v115
	v_cvt_pk_bf16_f32 v180, v116, v117
	v_cvt_pk_bf16_f32 v181, v118, v119
	v_cvt_pk_bf16_f32 v182, v112, v113
	v_cvt_pk_bf16_f32 v183, v114, v115
	global_store_dwordx4 v217, v[180:183], s[80:81] offset:256
	ds_bpermute_b32 v214, v215, v213
	s_waitcnt lgkmcnt(0)
	v_add_f32_e32 v213, v213, v214
	ds_bpermute_b32 v214, v216, v213
	s_waitcnt lgkmcnt(0)
	v_add_f32_e32 v213, v213, v214
	s_mov_b64 exec, 0xffff
	global_atomic_add_f32 v208, v213, s[4:5]
	s_mov_b64 exec, -1
	v_add_u32_e32 v211, 0x20000, v209
	global_load_dwordx4 v[176:179], v211, s[80:81]
	global_load_dwordx4 v[180:183], v211, s[80:81] offset:256
	s_waitcnt vmcnt(5)
	v_lshlrev_b32_e32 v200, 16, v192
	v_and_b32_e32 v201, 0xffff0000, v192
	v_lshlrev_b32_e32 v202, 16, v193
	v_and_b32_e32 v203, 0xffff0000, v193
	v_lshlrev_b32_e32 v204, 16, v194
	v_and_b32_e32 v205, 0xffff0000, v194
	v_lshlrev_b32_e32 v206, 16, v195
	v_and_b32_e32 v207, 0xffff0000, v195
	v_pk_add_f32 v[108:109], v[108:109], v[200:201]
	v_pk_add_f32 v[110:111], v[110:111], v[202:203]
	v_pk_add_f32 v[104:105], v[104:105], v[204:205]
	v_pk_add_f32 v[106:107], v[106:107], v[206:207]
	v_mul_f32_e32 v213, v108, v108
	v_fmac_f32_e32 v213, v109, v109
	v_fmac_f32_e32 v213, v110, v110
	v_fmac_f32_e32 v213, v111, v111
	v_fmac_f32_e32 v213, v104, v104
	v_fmac_f32_e32 v213, v105, v105
	v_fmac_f32_e32 v213, v106, v106
	v_fmac_f32_e32 v213, v107, v107
	v_cvt_pk_bf16_f32 v192, v108, v109
	v_cvt_pk_bf16_f32 v193, v110, v111
	v_cvt_pk_bf16_f32 v194, v104, v105
	v_cvt_pk_bf16_f32 v195, v106, v107
	v_add_u32_e32 v217, 0x10000, v209
	global_store_dwordx4 v217, v[192:195], s[80:81]
	v_lshlrev_b32_e32 v200, 16, v196
	v_and_b32_e32 v201, 0xffff0000, v196
	v_lshlrev_b32_e32 v202, 16, v197
	v_and_b32_e32 v203, 0xffff0000, v197
	v_lshlrev_b32_e32 v204, 16, v198
	v_and_b32_e32 v205, 0xffff0000, v198
	v_lshlrev_b32_e32 v206, 16, v199
	v_and_b32_e32 v207, 0xffff0000, v199
	v_pk_add_f32 v[100:101], v[100:101], v[200:201]
	v_pk_add_f32 v[102:103], v[102:103], v[202:203]
	v_pk_add_f32 v[96:97], v[96:97], v[204:205]
	v_pk_add_f32 v[98:99], v[98:99], v[206:207]
	v_fmac_f32_e32 v213, v100, v100
	v_fmac_f32_e32 v213, v101, v101
	v_fmac_f32_e32 v213, v102, v102
	v_fmac_f32_e32 v213, v103, v103
	v_fmac_f32_e32 v213, v96, v96
	v_fmac_f32_e32 v213, v97, v97
	v_fmac_f32_e32 v213, v98, v98
	v_fmac_f32_e32 v213, v99, v99
	v_cvt_pk_bf16_f32 v196, v100, v101
	v_cvt_pk_bf16_f32 v197, v102, v103
	v_cvt_pk_bf16_f32 v198, v96, v97
	v_cvt_pk_bf16_f32 v199, v98, v99
	global_store_dwordx4 v217, v[196:199], s[80:81] offset:256
	ds_bpermute_b32 v214, v215, v213
	s_waitcnt lgkmcnt(0)
	v_add_f32_e32 v213, v213, v214
	ds_bpermute_b32 v214, v216, v213
	s_waitcnt lgkmcnt(0)
	v_add_f32_e32 v213, v213, v214
	s_mov_b64 exec, 0xffff
	global_atomic_add_f32 v208, v213, s[4:5] offset:64
	s_mov_b64 exec, -1
	v_add_u32_e32 v211, 0x30000, v209
	global_load_dwordx4 v[192:195], v211, s[80:81]
	global_load_dwordx4 v[196:199], v211, s[80:81] offset:256
	s_waitcnt vmcnt(5)
	v_lshlrev_b32_e32 v184, 16, v176
	v_and_b32_e32 v185, 0xffff0000, v176
	v_lshlrev_b32_e32 v186, 16, v177
	v_and_b32_e32 v187, 0xffff0000, v177
	v_lshlrev_b32_e32 v188, 16, v178
	v_and_b32_e32 v189, 0xffff0000, v178
	v_lshlrev_b32_e32 v190, 16, v179
	v_and_b32_e32 v191, 0xffff0000, v179
	v_pk_add_f32 v[92:93], v[92:93], v[184:185]
	v_pk_add_f32 v[94:95], v[94:95], v[186:187]
	v_pk_add_f32 v[88:89], v[88:89], v[188:189]
	v_pk_add_f32 v[90:91], v[90:91], v[190:191]
	v_mul_f32_e32 v213, v92, v92
	v_fmac_f32_e32 v213, v93, v93
	v_fmac_f32_e32 v213, v94, v94
	v_fmac_f32_e32 v213, v95, v95
	v_fmac_f32_e32 v213, v88, v88
	v_fmac_f32_e32 v213, v89, v89
	v_fmac_f32_e32 v213, v90, v90
	v_fmac_f32_e32 v213, v91, v91
	v_cvt_pk_bf16_f32 v176, v92, v93
	v_cvt_pk_bf16_f32 v177, v94, v95
	v_cvt_pk_bf16_f32 v178, v88, v89
	v_cvt_pk_bf16_f32 v179, v90, v91
	v_add_u32_e32 v217, 0x20000, v209
	global_store_dwordx4 v217, v[176:179], s[80:81]
	v_lshlrev_b32_e32 v184, 16, v180
	v_and_b32_e32 v185, 0xffff0000, v180
	v_lshlrev_b32_e32 v186, 16, v181
	v_and_b32_e32 v187, 0xffff0000, v181
	v_lshlrev_b32_e32 v188, 16, v182
	v_and_b32_e32 v189, 0xffff0000, v182
	v_lshlrev_b32_e32 v190, 16, v183
	v_and_b32_e32 v191, 0xffff0000, v183
	v_pk_add_f32 v[84:85], v[84:85], v[184:185]
	v_pk_add_f32 v[86:87], v[86:87], v[186:187]
	v_pk_add_f32 v[80:81], v[80:81], v[188:189]
	v_pk_add_f32 v[82:83], v[82:83], v[190:191]
	v_fmac_f32_e32 v213, v84, v84
	v_fmac_f32_e32 v213, v85, v85
	v_fmac_f32_e32 v213, v86, v86
	v_fmac_f32_e32 v213, v87, v87
	v_fmac_f32_e32 v213, v80, v80
	v_fmac_f32_e32 v213, v81, v81
	v_fmac_f32_e32 v213, v82, v82
	v_fmac_f32_e32 v213, v83, v83
	v_cvt_pk_bf16_f32 v180, v84, v85
	v_cvt_pk_bf16_f32 v181, v86, v87
	v_cvt_pk_bf16_f32 v182, v80, v81
	v_cvt_pk_bf16_f32 v183, v82, v83
	global_store_dwordx4 v217, v[180:183], s[80:81] offset:256
	ds_bpermute_b32 v214, v215, v213
	s_waitcnt lgkmcnt(0)
	v_add_f32_e32 v213, v213, v214
	ds_bpermute_b32 v214, v216, v213
	s_waitcnt lgkmcnt(0)
	v_add_f32_e32 v213, v213, v214
	s_mov_b64 exec, 0xffff
	global_atomic_add_f32 v208, v213, s[4:5] offset:128
	s_mov_b64 exec, -1
	v_add_u32_e32 v211, 0x80000, v209
	global_load_dwordx4 v[176:179], v211, s[80:81]
	global_load_dwordx4 v[180:183], v211, s[80:81] offset:256
	s_waitcnt vmcnt(5)
	v_lshlrev_b32_e32 v200, 16, v192
	v_and_b32_e32 v201, 0xffff0000, v192
	v_lshlrev_b32_e32 v202, 16, v193
	v_and_b32_e32 v203, 0xffff0000, v193
	v_lshlrev_b32_e32 v204, 16, v194
	v_and_b32_e32 v205, 0xffff0000, v194
	v_lshlrev_b32_e32 v206, 16, v195
	v_and_b32_e32 v207, 0xffff0000, v195
	v_pk_add_f32 v[76:77], v[76:77], v[200:201]
	v_pk_add_f32 v[78:79], v[78:79], v[202:203]
	v_pk_add_f32 v[72:73], v[72:73], v[204:205]
	v_pk_add_f32 v[74:75], v[74:75], v[206:207]
	v_mul_f32_e32 v213, v76, v76
	v_fmac_f32_e32 v213, v77, v77
	v_fmac_f32_e32 v213, v78, v78
	v_fmac_f32_e32 v213, v79, v79
	v_fmac_f32_e32 v213, v72, v72
	v_fmac_f32_e32 v213, v73, v73
	v_fmac_f32_e32 v213, v74, v74
	v_fmac_f32_e32 v213, v75, v75
	v_cvt_pk_bf16_f32 v192, v76, v77
	v_cvt_pk_bf16_f32 v193, v78, v79
	v_cvt_pk_bf16_f32 v194, v72, v73
	v_cvt_pk_bf16_f32 v195, v74, v75
	v_add_u32_e32 v217, 0x30000, v209
	global_store_dwordx4 v217, v[192:195], s[80:81]
	v_lshlrev_b32_e32 v200, 16, v196
	v_and_b32_e32 v201, 0xffff0000, v196
	v_lshlrev_b32_e32 v202, 16, v197
	v_and_b32_e32 v203, 0xffff0000, v197
	v_lshlrev_b32_e32 v204, 16, v198
	v_and_b32_e32 v205, 0xffff0000, v198
	v_lshlrev_b32_e32 v206, 16, v199
	v_and_b32_e32 v207, 0xffff0000, v199
	v_pk_add_f32 v[68:69], v[68:69], v[200:201]
	v_pk_add_f32 v[70:71], v[70:71], v[202:203]
	v_pk_add_f32 v[64:65], v[64:65], v[204:205]
	v_pk_add_f32 v[66:67], v[66:67], v[206:207]
	v_fmac_f32_e32 v213, v68, v68
	v_fmac_f32_e32 v213, v69, v69
	v_fmac_f32_e32 v213, v70, v70
	v_fmac_f32_e32 v213, v71, v71
	v_fmac_f32_e32 v213, v64, v64
	v_fmac_f32_e32 v213, v65, v65
	v_fmac_f32_e32 v213, v66, v66
	v_fmac_f32_e32 v213, v67, v67
	v_cvt_pk_bf16_f32 v196, v68, v69
	v_cvt_pk_bf16_f32 v197, v70, v71
	v_cvt_pk_bf16_f32 v198, v64, v65
	v_cvt_pk_bf16_f32 v199, v66, v67
	global_store_dwordx4 v217, v[196:199], s[80:81] offset:256
	ds_bpermute_b32 v214, v215, v213
	s_waitcnt lgkmcnt(0)
	v_add_f32_e32 v213, v213, v214
	ds_bpermute_b32 v214, v216, v213
	s_waitcnt lgkmcnt(0)
	v_add_f32_e32 v213, v213, v214
	s_mov_b64 exec, 0xffff
	global_atomic_add_f32 v208, v213, s[4:5] offset:192
	s_mov_b64 exec, -1
	v_add_u32_e32 v211, 0x90000, v209
	global_load_dwordx4 v[192:195], v211, s[80:81]
	global_load_dwordx4 v[196:199], v211, s[80:81] offset:256
	s_waitcnt vmcnt(5)
	v_lshlrev_b32_e32 v184, 16, v176
	v_and_b32_e32 v185, 0xffff0000, v176
	v_lshlrev_b32_e32 v186, 16, v177
	v_and_b32_e32 v187, 0xffff0000, v177
	v_lshlrev_b32_e32 v188, 16, v178
	v_and_b32_e32 v189, 0xffff0000, v178
	v_lshlrev_b32_e32 v190, 16, v179
	v_and_b32_e32 v191, 0xffff0000, v179
	v_pk_add_f32 v[60:61], v[60:61], v[184:185]
	v_pk_add_f32 v[62:63], v[62:63], v[186:187]
	v_pk_add_f32 v[56:57], v[56:57], v[188:189]
	v_pk_add_f32 v[58:59], v[58:59], v[190:191]
	v_mul_f32_e32 v213, v60, v60
	v_fmac_f32_e32 v213, v61, v61
	v_fmac_f32_e32 v213, v62, v62
	v_fmac_f32_e32 v213, v63, v63
	v_fmac_f32_e32 v213, v56, v56
	v_fmac_f32_e32 v213, v57, v57
	v_fmac_f32_e32 v213, v58, v58
	v_fmac_f32_e32 v213, v59, v59
	v_cvt_pk_bf16_f32 v176, v60, v61
	v_cvt_pk_bf16_f32 v177, v62, v63
	v_cvt_pk_bf16_f32 v178, v56, v57
	v_cvt_pk_bf16_f32 v179, v58, v59
	v_add_u32_e32 v217, 0x80000, v209
	global_store_dwordx4 v217, v[176:179], s[80:81]
	v_lshlrev_b32_e32 v184, 16, v180
	v_and_b32_e32 v185, 0xffff0000, v180
	v_lshlrev_b32_e32 v186, 16, v181
	v_and_b32_e32 v187, 0xffff0000, v181
	v_lshlrev_b32_e32 v188, 16, v182
	v_and_b32_e32 v189, 0xffff0000, v182
	v_lshlrev_b32_e32 v190, 16, v183
	v_and_b32_e32 v191, 0xffff0000, v183
	v_pk_add_f32 v[52:53], v[52:53], v[184:185]
	v_pk_add_f32 v[54:55], v[54:55], v[186:187]
	v_pk_add_f32 v[48:49], v[48:49], v[188:189]
	v_pk_add_f32 v[50:51], v[50:51], v[190:191]
	v_fmac_f32_e32 v213, v52, v52
	v_fmac_f32_e32 v213, v53, v53
	v_fmac_f32_e32 v213, v54, v54
	v_fmac_f32_e32 v213, v55, v55
	v_fmac_f32_e32 v213, v48, v48
	v_fmac_f32_e32 v213, v49, v49
	v_fmac_f32_e32 v213, v50, v50
	v_fmac_f32_e32 v213, v51, v51
	v_cvt_pk_bf16_f32 v180, v52, v53
	v_cvt_pk_bf16_f32 v181, v54, v55
	v_cvt_pk_bf16_f32 v182, v48, v49
	v_cvt_pk_bf16_f32 v183, v50, v51
	global_store_dwordx4 v217, v[180:183], s[80:81] offset:256
	ds_bpermute_b32 v214, v215, v213
	s_waitcnt lgkmcnt(0)
	v_add_f32_e32 v213, v213, v214
	ds_bpermute_b32 v214, v216, v213
	s_waitcnt lgkmcnt(0)
	v_add_f32_e32 v213, v213, v214
	s_mov_b64 exec, 0xffff
	global_atomic_add_f32 v208, v213, s[4:5] offset:512
	s_mov_b64 exec, -1
	v_add_u32_e32 v211, 0xa0000, v209
	global_load_dwordx4 v[176:179], v211, s[80:81]
	global_load_dwordx4 v[180:183], v211, s[80:81] offset:256
	s_waitcnt vmcnt(5)
	v_lshlrev_b32_e32 v200, 16, v192
	v_and_b32_e32 v201, 0xffff0000, v192
	v_lshlrev_b32_e32 v202, 16, v193
	v_and_b32_e32 v203, 0xffff0000, v193
	v_lshlrev_b32_e32 v204, 16, v194
	v_and_b32_e32 v205, 0xffff0000, v194
	v_lshlrev_b32_e32 v206, 16, v195
	v_and_b32_e32 v207, 0xffff0000, v195
	v_pk_add_f32 v[44:45], v[44:45], v[200:201]
	v_pk_add_f32 v[46:47], v[46:47], v[202:203]
	v_pk_add_f32 v[40:41], v[40:41], v[204:205]
	v_pk_add_f32 v[42:43], v[42:43], v[206:207]
	v_mul_f32_e32 v213, v44, v44
	v_fmac_f32_e32 v213, v45, v45
	v_fmac_f32_e32 v213, v46, v46
	v_fmac_f32_e32 v213, v47, v47
	v_fmac_f32_e32 v213, v40, v40
	v_fmac_f32_e32 v213, v41, v41
	v_fmac_f32_e32 v213, v42, v42
	v_fmac_f32_e32 v213, v43, v43
	v_cvt_pk_bf16_f32 v192, v44, v45
	v_cvt_pk_bf16_f32 v193, v46, v47
	v_cvt_pk_bf16_f32 v194, v40, v41
	v_cvt_pk_bf16_f32 v195, v42, v43
	v_add_u32_e32 v217, 0x90000, v209
	global_store_dwordx4 v217, v[192:195], s[80:81]
	v_lshlrev_b32_e32 v200, 16, v196
	v_and_b32_e32 v201, 0xffff0000, v196
	v_lshlrev_b32_e32 v202, 16, v197
	v_and_b32_e32 v203, 0xffff0000, v197
	v_lshlrev_b32_e32 v204, 16, v198
	v_and_b32_e32 v205, 0xffff0000, v198
	v_lshlrev_b32_e32 v206, 16, v199
	v_and_b32_e32 v207, 0xffff0000, v199
	v_pk_add_f32 v[36:37], v[36:37], v[200:201]
	v_pk_add_f32 v[38:39], v[38:39], v[202:203]
	v_pk_add_f32 v[32:33], v[32:33], v[204:205]
	v_pk_add_f32 v[34:35], v[34:35], v[206:207]
	v_fmac_f32_e32 v213, v36, v36
	v_fmac_f32_e32 v213, v37, v37
	v_fmac_f32_e32 v213, v38, v38
	v_fmac_f32_e32 v213, v39, v39
	v_fmac_f32_e32 v213, v32, v32
	v_fmac_f32_e32 v213, v33, v33
	v_fmac_f32_e32 v213, v34, v34
	v_fmac_f32_e32 v213, v35, v35
	v_cvt_pk_bf16_f32 v196, v36, v37
	v_cvt_pk_bf16_f32 v197, v38, v39
	v_cvt_pk_bf16_f32 v198, v32, v33
	v_cvt_pk_bf16_f32 v199, v34, v35
	global_store_dwordx4 v217, v[196:199], s[80:81] offset:256
	ds_bpermute_b32 v214, v215, v213
	s_waitcnt lgkmcnt(0)
	v_add_f32_e32 v213, v213, v214
	ds_bpermute_b32 v214, v216, v213
	s_waitcnt lgkmcnt(0)
	v_add_f32_e32 v213, v213, v214
	s_mov_b64 exec, 0xffff
	global_atomic_add_f32 v208, v213, s[4:5] offset:576
	s_mov_b64 exec, -1
	v_add_u32_e32 v211, 0xb0000, v209
	global_load_dwordx4 v[192:195], v211, s[80:81]
	global_load_dwordx4 v[196:199], v211, s[80:81] offset:256
	s_waitcnt vmcnt(5)
	v_lshlrev_b32_e32 v184, 16, v176
	v_and_b32_e32 v185, 0xffff0000, v176
	v_lshlrev_b32_e32 v186, 16, v177
	v_and_b32_e32 v187, 0xffff0000, v177
	v_lshlrev_b32_e32 v188, 16, v178
	v_and_b32_e32 v189, 0xffff0000, v178
	v_lshlrev_b32_e32 v190, 16, v179
	v_and_b32_e32 v191, 0xffff0000, v179
	v_pk_add_f32 v[28:29], v[28:29], v[184:185]
	v_pk_add_f32 v[30:31], v[30:31], v[186:187]
	v_pk_add_f32 v[24:25], v[24:25], v[188:189]
	v_pk_add_f32 v[26:27], v[26:27], v[190:191]
	v_mul_f32_e32 v213, v28, v28
	v_fmac_f32_e32 v213, v29, v29
	v_fmac_f32_e32 v213, v30, v30
	v_fmac_f32_e32 v213, v31, v31
	v_fmac_f32_e32 v213, v24, v24
	v_fmac_f32_e32 v213, v25, v25
	v_fmac_f32_e32 v213, v26, v26
	v_fmac_f32_e32 v213, v27, v27
	v_cvt_pk_bf16_f32 v176, v28, v29
	v_cvt_pk_bf16_f32 v177, v30, v31
	v_cvt_pk_bf16_f32 v178, v24, v25
	v_cvt_pk_bf16_f32 v179, v26, v27
	v_add_u32_e32 v217, 0xa0000, v209
	global_store_dwordx4 v217, v[176:179], s[80:81]
	v_lshlrev_b32_e32 v184, 16, v180
	v_and_b32_e32 v185, 0xffff0000, v180
	v_lshlrev_b32_e32 v186, 16, v181
	v_and_b32_e32 v187, 0xffff0000, v181
	v_lshlrev_b32_e32 v188, 16, v182
	v_and_b32_e32 v189, 0xffff0000, v182
	v_lshlrev_b32_e32 v190, 16, v183
	v_and_b32_e32 v191, 0xffff0000, v183
	v_pk_add_f32 v[20:21], v[20:21], v[184:185]
	v_pk_add_f32 v[22:23], v[22:23], v[186:187]
	v_pk_add_f32 v[16:17], v[16:17], v[188:189]
	v_pk_add_f32 v[18:19], v[18:19], v[190:191]
	v_fmac_f32_e32 v213, v20, v20
	v_fmac_f32_e32 v213, v21, v21
	v_fmac_f32_e32 v213, v22, v22
	v_fmac_f32_e32 v213, v23, v23
	v_fmac_f32_e32 v213, v16, v16
	v_fmac_f32_e32 v213, v17, v17
	v_fmac_f32_e32 v213, v18, v18
	v_fmac_f32_e32 v213, v19, v19
	v_cvt_pk_bf16_f32 v180, v20, v21
	v_cvt_pk_bf16_f32 v181, v22, v23
	v_cvt_pk_bf16_f32 v182, v16, v17
	v_cvt_pk_bf16_f32 v183, v18, v19
	global_store_dwordx4 v217, v[180:183], s[80:81] offset:256
	ds_bpermute_b32 v214, v215, v213
	s_waitcnt lgkmcnt(0)
	v_add_f32_e32 v213, v213, v214
	ds_bpermute_b32 v214, v216, v213
	s_waitcnt lgkmcnt(0)
	v_add_f32_e32 v213, v213, v214
	s_mov_b64 exec, 0xffff
	global_atomic_add_f32 v208, v213, s[4:5] offset:640
	s_mov_b64 exec, -1
	s_waitcnt vmcnt(3)
	v_lshlrev_b32_e32 v200, 16, v192
	v_and_b32_e32 v201, 0xffff0000, v192
	v_lshlrev_b32_e32 v202, 16, v193
	v_and_b32_e32 v203, 0xffff0000, v193
	v_lshlrev_b32_e32 v204, 16, v194
	v_and_b32_e32 v205, 0xffff0000, v194
	v_lshlrev_b32_e32 v206, 16, v195
	v_and_b32_e32 v207, 0xffff0000, v195
	v_pk_add_f32 v[12:13], v[12:13], v[200:201]
	v_pk_add_f32 v[14:15], v[14:15], v[202:203]
	v_pk_add_f32 v[8:9], v[8:9], v[204:205]
	v_pk_add_f32 v[10:11], v[10:11], v[206:207]
	v_mul_f32_e32 v213, v12, v12
	v_fmac_f32_e32 v213, v13, v13
	v_fmac_f32_e32 v213, v14, v14
	v_fmac_f32_e32 v213, v15, v15
	v_fmac_f32_e32 v213, v8, v8
	v_fmac_f32_e32 v213, v9, v9
	v_fmac_f32_e32 v213, v10, v10
	v_fmac_f32_e32 v213, v11, v11
	v_cvt_pk_bf16_f32 v192, v12, v13
	v_cvt_pk_bf16_f32 v193, v14, v15
	v_cvt_pk_bf16_f32 v194, v8, v9
	v_cvt_pk_bf16_f32 v195, v10, v11
	v_add_u32_e32 v217, 0xb0000, v209
	global_store_dwordx4 v217, v[192:195], s[80:81]
	v_lshlrev_b32_e32 v200, 16, v196
	v_and_b32_e32 v201, 0xffff0000, v196
	v_lshlrev_b32_e32 v202, 16, v197
	v_and_b32_e32 v203, 0xffff0000, v197
	v_lshlrev_b32_e32 v204, 16, v198
	v_and_b32_e32 v205, 0xffff0000, v198
	v_lshlrev_b32_e32 v206, 16, v199
	v_and_b32_e32 v207, 0xffff0000, v199
	v_pk_add_f32 v[4:5], v[4:5], v[200:201]
	v_pk_add_f32 v[6:7], v[6:7], v[202:203]
	v_pk_add_f32 v[0:1], v[0:1], v[204:205]
	v_pk_add_f32 v[2:3], v[2:3], v[206:207]
	v_fmac_f32_e32 v213, v4, v4
	v_fmac_f32_e32 v213, v5, v5
	v_fmac_f32_e32 v213, v6, v6
	v_fmac_f32_e32 v213, v7, v7
	v_fmac_f32_e32 v213, v0, v0
	v_fmac_f32_e32 v213, v1, v1
	v_fmac_f32_e32 v213, v2, v2
	v_fmac_f32_e32 v213, v3, v3
	v_cvt_pk_bf16_f32 v196, v4, v5
	v_cvt_pk_bf16_f32 v197, v6, v7
	v_cvt_pk_bf16_f32 v198, v0, v1
	v_cvt_pk_bf16_f32 v199, v2, v3
	global_store_dwordx4 v217, v[196:199], s[80:81] offset:256
	ds_bpermute_b32 v214, v215, v213
	s_waitcnt lgkmcnt(0)
	v_add_f32_e32 v213, v213, v214
	ds_bpermute_b32 v214, v216, v213
	s_waitcnt lgkmcnt(0)
	v_add_f32_e32 v213, v213, v214
	s_mov_b64 exec, 0xffff
	global_atomic_add_f32 v208, v213, s[4:5] offset:704
	s_mov_b64 exec, -1
	s_branch .LBB0_752

.LBB0_832:
	s_or_b64 exec, exec, s[0:1]
	s_add_u32 s14, s82, 0x21000
	s_addc_u32 s15, s83, 0
	v_readlane_b32 s0, v255, 10
	s_add_u32 s16, s84, 0xb000
	v_readlane_b32 s1, v255, 11
	s_addc_u32 s17, s85, 0
	s_andn2_b64 vcc, exec, s[0:1]
	v_readfirstlane_b32 s3, v222
	s_waitcnt lgkmcnt(0)
	s_barrier
	s_cbranch_vccnz .LBB0_854
	s_add_u32 s44, s92, 0x7b00000
	s_addc_u32 s45, s93, 0
	s_lshr_b32 s0, s77, 29
	s_add_i32 s0, s2, s0
	s_lshr_b32 s12, s3, 6
	s_ashr_i32 s1, s0, 3
	s_and_b32 s0, s0, -8
	s_lshr_b32 s7, s3, 8
	s_lshl_b32 s46, s12, 10
	s_sub_i32 s0, s2, s0
	s_cmp_lt_i32 s0, 0
	s_movk_i32 s47, 0x161
	s_cselect_b32 s6, s47, 0x160
	s_mul_i32 s0, s6, s0
	s_add_i32 s0, s0, s1
	s_mul_hi_i32 s1, s0, 0x2e8ba2e9
	s_lshr_b32 s6, s1, 31
	s_ashr_i32 s1, s1, 5
	s_add_i32 s1, s1, s6
	s_lshl_b32 s8, s1, 2
	s_mulk_i32 s1, 0xb0
	s_sub_i32 s0, s0, s1
	s_sext_i32_i16 s1, s0
	s_bfe_u32 s1, s1, 0x2001d
	s_add_i32 s1, s0, s1
	s_sext_i32_i16 s6, s1
	s_and_b32 s1, s1, 0xfffc
	s_sub_i32 s0, s0, s1
	s_sext_i32_i16 s0, s0
	s_lshr_b32 s6, s6, 2
	s_add_i32 s0, s8, s0
	s_ashr_i32 s1, s0, 31
	s_bfe_i64 s[10:11], s[6:7], 0x100000
	s_lshl_b64 s[8:9], s[0:1], 20
	s_lshl_b64 s[10:11], s[10:11], 19
	s_add_u32 s10, s44, s10
	s_addc_u32 s11, s45, s11
	s_add_i32 s48, s46, 0
	v_and_b32_e32 v8, 0x180, v223
	s_add_i32 m0, s48, 0x10000
	v_or3_b32 v0, v220, v8, v218
	v_and_b32_e32 v9, 0x80, v254
	v_and_b32_e32 v191, 63, v222
	v_lshrrev_b32_e32 v192, 3, v191
	v_lshrrev_b32_e32 v193, 6, v222
	v_lshl_add_u32 v194, v193, 3, v192
	v_and_b32_e32 v195, 7, v191
	v_and_b32_e32 v196, 6, v192
	v_xor_b32_e32 v195, v195, v196
	v_lshlrev_b32_e32 v195, 4, v195
	v_mul_u32_u24_e32 v196, 0x1000, v194
	v_add_u32_e32 v196, v196, v195
	v_add_u32_e32 v176, 0x80000, v196
	v_mov_b32_e32 v178, v196
	v_add_u32_e32 v180, 0x40080, v196
	v_add_u32_e32 v182, 0xc0080, v196
	v_add_u32_e32 v176, 0x80000, v196
	v_add_u32_e32 v182, 0xc0080, v196
	v_and_b32_e32 v196, 31, v194
	v_and_b32_e32 v197, 12, v196
	v_lshlrev_b32_e32 v197, 1, v197
	v_lshrrev_b32_e32 v198, 4, v196
	v_lshlrev_b32_e32 v198, 2, v198
	v_and_b32_e32 v196, 3, v196
	v_or3_b32 v196, v197, v198, v196
	v_and_b32_e32 v197, 0x60, v194
	v_add_u32_e32 v196, v196, v197
	v_mul_u32_u24_e32 v196, 0x1000, v196
	v_add_u32_e32 v196, v196, v195
	v_mov_b32_e32 v164, v196
	v_add_u32_e32 v166, 0x40000, v196
	v_add_u32_e32 v166, 0x40000, v196
	v_and_b32_e32 v196, 15, v191
	v_lshrrev_b32_e32 v197, 4, v191
	v_and_b32_e32 v198, 6, v196
	v_xor_b32_e32 v197, v197, v198
	v_lshlrev_b32_e32 v197, 4, v197
	v_lshl_or_b32 v197, v196, 7, v197
	v_lshrrev_b32_e32 v198, 2, v193
	v_lshl_add_u32 v198, v198, 13, v197
	v_add_u32_e32 v173, 0x0, v198
	v_and_b32_e32 v196, 3, v193
	v_lshl_add_u32 v196, v196, 12, v197
	v_add_u32_e32 v171, 0x10000, v196
	v_add_u32_e32 v169, 0x0, v196
	v_add_u32_e32 v175, 0x14000, v196
	v_add_u32_e32 v242, 0x14000, v196
	v_mov_b32_e32 v181, 0x0
	v_mov_b32_e32 v183, 0x0
	s_add_i32 m0, s48, 0x12000
	v_or3_b32 v0, v221, v9, v218
	s_add_u32 s8, s80, s8
	s_addc_u32 s9, s81, s9
	s_mov_b32 m0, s48
	s_add_i32 s49, s48, 0x2000
	s_mov_b32 m0, s49
	s_add_u32 s18, s10, 0x1600000
	s_addc_u32 s19, s11, 0
	s_add_i32 m0, s48, 0x14000
	v_mov_b32_e32 v165, 0
	s_add_i32 m0, s48, 0x16000
	v_mov_b32_e32 v167, v165
	s_add_u32 s18, s8, 0x40000
	s_addc_u32 s19, s9, 0
	s_add_i32 s50, s48, 0x4000
	s_mov_b32 m0, s50
	s_add_i32 s51, s48, 0x6000
	s_mov_b32 m0, s51
	v_mov_b32_e32 v179, v165
	v_mov_b32_e32 v177, v165
	s_mov_b32 s52, 0
	v_lshl_add_u64 v[6:7], s[10:11], 0, v[164:165]
	v_lshl_add_u64 v[4:5], s[10:11], 0, v[166:167]
	v_lshl_add_u64 v[2:3], s[8:9], 0, v[178:179]
	s_cmp_lg_u32 s7, 1
	v_lshl_add_u64 v[0:1], s[8:9], 0, v[176:177]
	s_cbranch_scc1 .LBB0_835
.LBB0_835:
	s_mov_b64 s[18:19], 0x80
	s_lshl_b32 s1, s12, 5
	s_add_i32 m0, s48, 0x18000
	v_lshl_add_u64 v[6:7], v[6:7], 0, s[18:19]
	s_and_b32 s53, s1, 0x60
	v_lshl_add_u64 v[4:5], v[4:5], 0, s[18:19]
	s_add_i32 m0, s48, 0x1a000
	s_add_i32 s54, s48, 0x8000
	s_add_i32 s55, s48, 0xa000
	v_lshl_add_u64 v[2:3], v[2:3], 0, s[18:19]
	s_mov_b32 m0, s54
	s_add_u32 s12, s10, 0x1600080
	v_lshl_add_u64 v[0:1], v[0:1], 0, s[18:19]
	s_mov_b32 m0, s55
	s_addc_u32 s13, s11, 0
	s_add_i32 m0, s48, 0x1c000
	v_lshl_add_u64 v[0:1], s[12:13], 0, v[164:165]
	v_lshl_add_u64 v[0:1], s[12:13], 0, v[166:167]
	s_add_i32 m0, s48, 0x1e000
	s_ashr_i32 s56, s94, 31
	s_lshl_b32 s58, s7, 7
	s_lshl_b32 s59, s7, 2
	s_add_u32 s20, s82, 0x2c000
	s_addc_u32 s21, s83, 0
	s_add_u32 s22, s82, 0x37000
	s_addc_u32 s23, s83, 0
	s_add_u32 s24, s82, 0x26800
	s_addc_u32 s25, s83, 0
	s_add_u32 s26, s82, 0x31800
	v_add3_u32 v0, v9, v221, v218
	s_addc_u32 s27, s83, 0
	v_lshl_or_b32 v0, v0, 12, v226
	s_sext_i32_i16 s1, s6
	v_lshl_or_b32 v2, s7, 13, v230
	s_add_u32 s28, s82, 0x3c800
	v_add_u32_e32 v0, v0, v224
	v_mov_b32_e32 v1, v165
	s_mov_b64 s[6:7], 0x40080
	s_addc_u32 s29, s83, 0
	v_add3_u32 v0, v8, v220, v218
	s_add_u32 s30, s84, 0x10800
	v_lshl_or_b32 v0, v0, 12, v226
	s_addc_u32 s31, s85, 0
	v_add_u32_e32 v0, v0, v224
	s_add_i32 s60, 0, 0x10000
	s_add_i32 s61, 0, 0x14000
	s_mov_b32 s57, s94
	v_mov_b64_e32 v[184:185], 0xb00
	v_mov_b64_e32 v[186:187], 0xaff
	v_mov_b32_e32 v230, 0x3727c5ac
	s_mov_b32 s62, 0xb000
	s_movk_i32 s63, 0x2c00
	v_and_b32_e32 v76, 63, v222
	v_lshrrev_b32_e32 v77, 6, v222
	v_lshrrev_b32_e32 v78, 3, v76
	v_lshl_add_u32 v79, v77, 3, v78
	v_and_b32_e32 v80, 7, v76
	v_and_b32_e32 v81, 6, v78
	v_xor_b32_e32 v80, v80, v81
	v_lshlrev_b32_e32 v80, 4, v80
	v_mul_u32_u24_e32 v81, 0x1000, v79
	v_add_u32_e32 v108, v81, v80
	v_and_b32_e32 v81, 31, v79
	v_and_b32_e32 v78, 12, v81
	v_lshlrev_b32_e32 v78, 1, v78
	v_lshrrev_b32_e32 v109, 4, v81
	v_lshlrev_b32_e32 v109, 2, v109
	v_and_b32_e32 v81, 3, v81
	v_or3_b32 v81, v78, v109, v81
	v_and_b32_e32 v78, 0x60, v79
	v_add_u32_e32 v81, v81, v78
	v_mul_u32_u24_e32 v81, 0x1000, v81
	v_add_u32_e32 v109, v81, v80
	v_and_b32_e32 v78, 15, v76
	v_lshrrev_b32_e32 v79, 4, v76
	v_and_b32_e32 v80, 6, v78
	v_xor_b32_e32 v79, v79, v80
	v_lshlrev_b32_e32 v79, 4, v79
	v_lshl_or_b32 v79, v78, 7, v79
	v_lshrrev_b32_e32 v80, 2, v77
	v_lshl_add_u32 v220, v80, 13, v79
	v_xor_b32_e32 v221, 64, v220
	v_and_b32_e32 v80, 3, v77
	v_lshl_add_u32 v234, v80, 12, v79
	v_add_u32_e32 v234, 0x10000, v234
	v_xor_b32_e32 v235, 64, v234
	v_readfirstlane_b32 s68, v222
	s_nop 3
	s_lshr_b32 s68, s68, 6
	s_lshl_b32 s68, s68, 10
	s_mov_b32 s98, 0
	s_mul_i32 s12, s98, s94
	s_add_i32 s12, s12, s2
	s_and_b32 s13, s12, 7
	s_lshr_b32 s12, s12, 3
	s_mul_i32 s13, s13, 0x160
	s_add_i32 s12, s12, s13
	s_mul_i32 s13, s12, 0x1745e
	s_lshr_b32 s13, s13, 24
	s_mul_i32 s43, s13, 0xb0
	s_sub_i32 s12, s12, s43
	s_and_b32 s42, s12, 3
	s_lshl_b32 s13, s13, 2
	s_add_i32 s42, s42, s13
	s_lshr_b32 s43, s12, 2
	s_mul_i32 s100, s42, 0x100000
	s_add_u32 s8, s92, 0xbd00000
	s_addc_u32 s9, s93, 0
	s_add_u32 s8, s8, s100
	s_addc_u32 s9, s9, 0
	s_mul_i32 s100, s43, 0x80000
	s_add_u32 s10, s92, 0x7b00000
	s_addc_u32 s11, s93, 0
	s_add_u32 s10, s10, s100
	s_addc_u32 s11, s11, 0
	s_add_i32 m0, s68, 0x0
	s_nop 0
	global_load_lds_dwordx4 v108, s[8:9]
	s_add_i32 m0, s68, 0x2000
	s_add_u32 s66, s8, 0x80000
	s_addc_u32 s67, s9, 0
	s_nop 0
	global_load_lds_dwordx4 v108, s[66:67]
	s_add_i32 m0, s68, 0x4000
	s_add_u32 s66, s8, 0x40000
	s_addc_u32 s67, s9, 0
	s_nop 0
	global_load_lds_dwordx4 v108, s[66:67]
	s_add_i32 m0, s68, 0x6000
	s_add_u32 s66, s8, 0xc0000
	s_addc_u32 s67, s9, 0
	s_nop 0
	global_load_lds_dwordx4 v108, s[66:67]
	s_add_i32 m0, s68, 0x10000
	s_nop 0
	global_load_lds_dwordx4 v109, s[10:11]
	s_add_i32 m0, s68, 0x12000
	s_add_u32 s66, s10, 0x40000
	s_addc_u32 s67, s11, 0
	s_nop 0
	global_load_lds_dwordx4 v109, s[66:67]
	s_add_i32 m0, s68, 0x14000
	s_add_u32 s66, s10, 0x1600000
	s_addc_u32 s67, s11, 0
	s_nop 0
	global_load_lds_dwordx4 v109, s[66:67]
	s_add_i32 m0, s68, 0x16000
	s_add_u32 s66, s10, 0x1640000
	s_addc_u32 s67, s11, 0
	s_nop 0
	global_load_lds_dwordx4 v109, s[66:67]
	s_add_u32 s8, s8, 128
	s_addc_u32 s9, s9, 0
	s_add_u32 s10, s10, 128
	s_addc_u32 s11, s11, 0
	s_add_i32 m0, s68, 0x8000
	s_nop 0
	global_load_lds_dwordx4 v108, s[8:9]
	s_add_i32 m0, s68, 0xa000
	s_add_u32 s66, s8, 0x80000
	s_addc_u32 s67, s9, 0
	s_nop 0
	global_load_lds_dwordx4 v108, s[66:67]
	s_add_i32 m0, s68, 0xc000
	s_add_u32 s66, s8, 0x40000
	s_addc_u32 s67, s9, 0
	s_nop 0
	global_load_lds_dwordx4 v108, s[66:67]
	s_add_i32 m0, s68, 0xe000
	s_add_u32 s66, s8, 0xc0000
	s_addc_u32 s67, s9, 0
	s_nop 0
	global_load_lds_dwordx4 v108, s[66:67]
	s_add_i32 m0, s68, 0x18000
	s_nop 0
	global_load_lds_dwordx4 v109, s[10:11]
	s_add_i32 m0, s68, 0x1a000
	s_add_u32 s66, s10, 0x40000
	s_addc_u32 s67, s11, 0
	s_nop 0
	global_load_lds_dwordx4 v109, s[66:67]
	s_add_i32 m0, s68, 0x1c000
	s_add_u32 s66, s10, 0x1600000
	s_addc_u32 s67, s11, 0
	s_nop 0
	global_load_lds_dwordx4 v109, s[66:67]
	s_add_i32 m0, s68, 0x1e000
	s_add_u32 s66, s10, 0x1640000
	s_addc_u32 s67, s11, 0
	s_nop 0
	global_load_lds_dwordx4 v109, s[66:67]
	s_branch .LBB0_837

.LBB0_839:
	s_ashr_i32 s37, s36, 31
	v_cmp_lt_i64_e32 vcc, s[12:13], v[184:185]
	s_lshl_b64 s[12:13], s[36:37], 20
	s_add_u32 s38, s80, s12
	s_addc_u32 s39, s81, s13
	s_and_b64 s[12:13], vcc, exec
	s_cselect_b32 s33, s39, s9
	s_cselect_b32 s37, s38, s8
	s_ashr_i32 s35, s34, 31
	s_lshl_b64 s[12:13], s[34:35], 19
	s_add_u32 s40, s44, s12
	s_addc_u32 s41, s45, s13
	s_and_b64 s[12:13], vcc, exec
	s_cselect_b32 s35, s41, s11
	s_cselect_b32 s64, s40, s10
	s_add_u32 s65, s10, 0x100
	v_mov_b32_e32 v0, 0
	s_addc_u32 s66, s11, 0
	s_mov_b32 s67, -2
	v_mov_b32_e32 v1, v0
	v_mov_b32_e32 v2, v0
	v_mov_b32_e32 v3, v0
	v_mov_b32_e32 v64, v0
	v_mov_b32_e32 v65, v0
	v_mov_b32_e32 v66, v0
	v_mov_b32_e32 v67, v0
	v_mov_b32_e32 v8, v0
	v_mov_b32_e32 v9, v0
	s_waitcnt vmcnt(0)
	v_mov_b32_e32 v10, v0
	v_mov_b32_e32 v11, v0
	v_mov_b32_e32 v68, v0
	v_mov_b32_e32 v69, v0
	v_mov_b32_e32 v70, v0
	v_mov_b32_e32 v71, v0
	v_mov_b32_e32 v12, v0
	v_mov_b32_e32 v13, v0
	v_mov_b32_e32 v14, v0
	v_mov_b32_e32 v15, v0
	v_mov_b32_e32 v110, v0
	v_mov_b32_e32 v111, v0
	v_mov_b32_e32 v112, v0
	v_mov_b32_e32 v113, v0
	v_mov_b32_e32 v16, v0
	v_mov_b32_e32 v17, v0
	v_mov_b32_e32 v18, v0
	v_mov_b32_e32 v19, v0
	v_mov_b32_e32 v118, v0
	v_mov_b32_e32 v119, v0
	v_mov_b32_e32 v120, v0
	v_mov_b32_e32 v121, v0
	v_mov_b32_e32 v4, v0
	v_mov_b32_e32 v5, v0
	v_mov_b32_e32 v6, v0
	v_mov_b32_e32 v7, v0
	v_mov_b32_e32 v72, v0
	v_mov_b32_e32 v73, v0
	v_mov_b32_e32 v74, v0
	v_mov_b32_e32 v75, v0
	v_mov_b32_e32 v20, v0
	v_mov_b32_e32 v21, v0
	v_mov_b32_e32 v22, v0
	v_mov_b32_e32 v23, v0
	v_mov_b32_e32 v114, v0
	v_mov_b32_e32 v115, v0
	v_mov_b32_e32 v116, v0
	v_mov_b32_e32 v117, v0
	v_mov_b32_e32 v24, v0
	v_mov_b32_e32 v25, v0
	v_mov_b32_e32 v26, v0
	v_mov_b32_e32 v27, v0
	v_mov_b32_e32 v122, v0
	v_mov_b32_e32 v123, v0
	v_mov_b32_e32 v124, v0
	v_mov_b32_e32 v125, v0
	v_mov_b32_e32 v28, v0
	v_mov_b32_e32 v29, v0
	v_mov_b32_e32 v30, v0
	v_mov_b32_e32 v31, v0
	v_mov_b32_e32 v126, v0
	v_mov_b32_e32 v127, v0
	v_mov_b32_e32 v128, v0
	v_mov_b32_e32 v129, v0
	v_mov_b32_e32 v32, v0
	v_mov_b32_e32 v33, v0
	v_mov_b32_e32 v34, v0
	v_mov_b32_e32 v35, v0
	v_mov_b32_e32 v130, v0
	v_mov_b32_e32 v131, v0
	v_mov_b32_e32 v132, v0
	v_mov_b32_e32 v133, v0
	v_mov_b32_e32 v36, v0
	v_mov_b32_e32 v37, v0
	v_mov_b32_e32 v38, v0
	v_mov_b32_e32 v39, v0
	v_mov_b32_e32 v134, v0
	v_mov_b32_e32 v135, v0
	v_mov_b32_e32 v136, v0
	v_mov_b32_e32 v137, v0
	v_mov_b32_e32 v44, v0
	v_mov_b32_e32 v45, v0
	v_mov_b32_e32 v46, v0
	v_mov_b32_e32 v47, v0
	v_mov_b32_e32 v142, v0
	v_mov_b32_e32 v143, v0
	v_mov_b32_e32 v144, v0
	v_mov_b32_e32 v145, v0
	v_mov_b32_e32 v56, v0
	v_mov_b32_e32 v57, v0
	v_mov_b32_e32 v58, v0
	v_mov_b32_e32 v59, v0
	v_mov_b32_e32 v154, v0
	v_mov_b32_e32 v155, v0
	v_mov_b32_e32 v156, v0
	v_mov_b32_e32 v157, v0
	v_mov_b32_e32 v40, v0
	v_mov_b32_e32 v41, v0
	v_mov_b32_e32 v42, v0
	v_mov_b32_e32 v43, v0
	v_mov_b32_e32 v138, v0
	v_mov_b32_e32 v139, v0
	v_mov_b32_e32 v140, v0
	v_mov_b32_e32 v141, v0
	v_mov_b32_e32 v48, v0
	v_mov_b32_e32 v49, v0
	v_mov_b32_e32 v50, v0
	v_mov_b32_e32 v51, v0
	v_mov_b32_e32 v146, v0
	v_mov_b32_e32 v147, v0
	v_mov_b32_e32 v148, v0
	v_mov_b32_e32 v149, v0
	v_mov_b32_e32 v52, v0
	v_mov_b32_e32 v53, v0
	v_mov_b32_e32 v54, v0
	v_mov_b32_e32 v55, v0
	v_mov_b32_e32 v150, v0
	v_mov_b32_e32 v151, v0
	v_mov_b32_e32 v152, v0
	v_mov_b32_e32 v153, v0
	v_mov_b32_e32 v60, v0
	v_mov_b32_e32 v61, v0
	v_mov_b32_e32 v62, v0
	v_mov_b32_e32 v63, v0
	v_mov_b32_e32 v158, v0
	v_mov_b32_e32 v159, v0
	v_mov_b32_e32 v160, v0
	v_mov_b32_e32 v161, v0
	v_and_b32_e32 v76, 63, v222
	v_lshrrev_b32_e32 v77, 6, v222
	v_lshrrev_b32_e32 v78, 3, v76
	v_lshl_add_u32 v79, v77, 3, v78
	v_and_b32_e32 v80, 7, v76
	v_and_b32_e32 v81, 6, v78
	v_xor_b32_e32 v80, v80, v81
	v_lshlrev_b32_e32 v80, 4, v80
	v_mul_u32_u24_e32 v81, 0x1000, v79
	v_add_u32_e32 v108, v81, v80
	v_and_b32_e32 v81, 31, v79
	v_and_b32_e32 v78, 12, v81
	v_lshlrev_b32_e32 v78, 1, v78
	v_lshrrev_b32_e32 v109, 4, v81
	v_lshlrev_b32_e32 v109, 2, v109
	v_and_b32_e32 v81, 3, v81
	v_or3_b32 v81, v78, v109, v81
	v_and_b32_e32 v78, 0x60, v79
	v_add_u32_e32 v81, v81, v78
	v_mul_u32_u24_e32 v81, 0x1000, v81
	v_add_u32_e32 v109, v81, v80
	v_and_b32_e32 v78, 15, v76
	v_lshrrev_b32_e32 v79, 4, v76
	v_and_b32_e32 v80, 6, v78
	v_xor_b32_e32 v79, v79, v80
	v_lshlrev_b32_e32 v79, 4, v79
	v_lshl_or_b32 v79, v78, 7, v79
	v_lshrrev_b32_e32 v80, 2, v77
	v_lshl_add_u32 v220, v80, 13, v79
	v_xor_b32_e32 v221, 64, v220
	v_and_b32_e32 v80, 3, v77
	v_lshl_add_u32 v234, v80, 12, v79
	v_add_u32_e32 v234, 0x10000, v234
	v_xor_b32_e32 v235, 64, v234
	v_readfirstlane_b32 s68, v222
	s_nop 3
	s_lshr_b32 s68, s68, 6
	s_lshl_b32 s68, s68, 10
	s_mul_i32 s12, s98, s94
	s_add_i32 s12, s12, s2
	s_and_b32 s13, s12, 7
	s_lshr_b32 s12, s12, 3
	s_mul_i32 s13, s13, 0x160
	s_add_i32 s12, s12, s13
	s_mul_i32 s13, s12, 0x1745e
	s_lshr_b32 s13, s13, 24
	s_mul_i32 s100, s13, 0xb0
	s_sub_i32 s12, s12, s100
	s_and_b32 s65, s12, 3
	s_lshl_b32 s13, s13, 2
	s_add_i32 s65, s65, s13
	s_lshr_b32 s100, s12, 2
	s_mul_i32 s99, s65, 0x100000
	s_add_u32 s8, s92, 0xbd00100
	s_addc_u32 s9, s93, 0
	s_add_u32 s8, s8, s99
	s_addc_u32 s9, s9, 0
	s_mul_i32 s99, s100, 0x80000
	s_add_u32 s10, s92, 0x7b00100
	s_addc_u32 s11, s93, 0
	s_add_u32 s10, s10, s99
	s_addc_u32 s11, s11, 0
	s_add_i32 s98, s98, 1
	s_mul_i32 s42, s98, s94
	s_add_i32 s42, s42, s2
	s_cmp_lt_u32 s42, 0xb00
	s_cbranch_scc0 .Ls8_nonext
	s_mul_i32 s12, s98, s94
	s_add_i32 s12, s12, s2
	s_and_b32 s13, s12, 7
	s_lshr_b32 s12, s12, 3
	s_mul_i32 s13, s13, 0x160
	s_add_i32 s12, s12, s13
	s_mul_i32 s13, s12, 0x1745e
	s_lshr_b32 s13, s13, 24
	s_mul_i32 s100, s13, 0xb0
	s_sub_i32 s12, s12, s100
	s_and_b32 s65, s12, 3
	s_lshl_b32 s13, s13, 2
	s_add_i32 s65, s65, s13
	s_lshr_b32 s100, s12, 2
.Ls8_nonext:
	s_mul_i32 s99, s65, 0x100000
	s_add_u32 s12, s92, 0xbd00000
	s_addc_u32 s13, s93, 0
	s_add_u32 s12, s12, s99
	s_addc_u32 s13, s13, 0
	s_mul_i32 s99, s100, 0x80000
	s_add_u32 s42, s92, 0x7b00000
	s_addc_u32 s43, s93, 0
	s_add_u32 s42, s42, s99
	s_addc_u32 s43, s43, 0
	s_waitcnt vmcnt(0)
	s_barrier
	ds_read_b128 v[76:79], v220
	ds_read_b128 v[80:83], v220 offset:2048
	ds_read_b128 v[188:191], v234
	ds_read_b128 v[192:195], v234 offset:2048
	ds_read_b128 v[196:199], v234 offset:16384
	ds_read_b128 v[200:203], v234 offset:18432
	ds_read_b128 v[84:87], v220 offset:4096
	ds_read_b128 v[88:91], v220 offset:6144
	ds_read_b128 v[92:95], v220 offset:16384
	ds_read_b128 v[96:99], v220 offset:18432
	ds_read_b128 v[100:103], v220 offset:20480
	ds_read_b128 v[104:107], v220 offset:22528
	s_mov_b32 s65, 0
.Ls8_loop:
	s_cmp_eq_u32 s65, 15
	s_cselect_b32 s8, s12, s8
	s_cselect_b32 s9, s13, s9
	s_cselect_b32 s10, s42, s10
	s_cselect_b32 s11, s43, s11
	s_waitcnt lgkmcnt(6)
	v_mfma_f32_16x16x32_bf16 v[158:161], v[188:191], v[76:79], v[158:161]
	v_mfma_f32_16x16x32_bf16 v[60:63], v[192:195], v[76:79], v[60:63]
	v_mfma_f32_16x16x32_bf16 v[154:157], v[196:199], v[76:79], v[154:157]
	v_mfma_f32_16x16x32_bf16 v[56:59], v[200:203], v[76:79], v[56:59]
	v_mfma_f32_16x16x32_bf16 v[150:153], v[188:191], v[80:83], v[150:153]
	v_mfma_f32_16x16x32_bf16 v[52:55], v[192:195], v[80:83], v[52:55]
	v_mfma_f32_16x16x32_bf16 v[142:145], v[196:199], v[80:83], v[142:145]
	v_mfma_f32_16x16x32_bf16 v[44:47], v[200:203], v[80:83], v[44:47]
	s_waitcnt lgkmcnt(0)
	ds_read_b128 v[76:79], v221
	ds_read_b128 v[80:83], v221 offset:2048
	ds_read_b128 v[204:207], v235
	ds_read_b128 v[208:211], v235 offset:2048
	ds_read_b128 v[212:215], v235 offset:16384
	ds_read_b128 v[216:219], v235 offset:18432
	v_mfma_f32_16x16x32_bf16 v[146:149], v[188:191], v[84:87], v[146:149]
	v_mfma_f32_16x16x32_bf16 v[48:51], v[192:195], v[84:87], v[48:51]
	v_mfma_f32_16x16x32_bf16 v[134:137], v[196:199], v[84:87], v[134:137]
	v_mfma_f32_16x16x32_bf16 v[36:39], v[200:203], v[84:87], v[36:39]
	ds_read_b128 v[84:87], v221 offset:4096
	v_mfma_f32_16x16x32_bf16 v[138:141], v[188:191], v[88:91], v[138:141]
	v_mfma_f32_16x16x32_bf16 v[40:43], v[192:195], v[88:91], v[40:43]
	v_mfma_f32_16x16x32_bf16 v[130:133], v[196:199], v[88:91], v[130:133]
	v_mfma_f32_16x16x32_bf16 v[32:35], v[200:203], v[88:91], v[32:35]
	ds_read_b128 v[88:91], v221 offset:6144
	s_waitcnt lgkmcnt(0)
	s_barrier
	s_add_i32 m0, s68, 0x10000
	v_mfma_f32_16x16x32_bf16 v[126:129], v[188:191], v[92:95], v[126:129]
	v_mfma_f32_16x16x32_bf16 v[28:31], v[192:195], v[92:95], v[28:31]
	v_mfma_f32_16x16x32_bf16 v[118:121], v[196:199], v[92:95], v[118:121]
	v_mfma_f32_16x16x32_bf16 v[16:19], v[200:203], v[92:95], v[16:19]
	ds_read_b128 v[92:95], v221 offset:16384
	global_load_lds_dwordx4 v109, s[10:11]
	s_add_i32 m0, s68, 0x12000
	s_add_u32 s66, s10, 0x40000
	s_addc_u32 s67, s11, 0
	v_mfma_f32_16x16x32_bf16 v[122:125], v[188:191], v[96:99], v[122:125]
	v_mfma_f32_16x16x32_bf16 v[24:27], v[192:195], v[96:99], v[24:27]
	v_mfma_f32_16x16x32_bf16 v[110:113], v[196:199], v[96:99], v[110:113]
	v_mfma_f32_16x16x32_bf16 v[12:15], v[200:203], v[96:99], v[12:15]
	ds_read_b128 v[96:99], v221 offset:18432
	global_load_lds_dwordx4 v109, s[66:67]
	s_add_i32 m0, s68, 0x14000
	s_add_u32 s66, s10, 0x1600000
	s_addc_u32 s67, s11, 0
	v_mfma_f32_16x16x32_bf16 v[114:117], v[188:191], v[100:103], v[114:117]
	v_mfma_f32_16x16x32_bf16 v[20:23], v[192:195], v[100:103], v[20:23]
	v_mfma_f32_16x16x32_bf16 v[68:71], v[196:199], v[100:103], v[68:71]
	v_mfma_f32_16x16x32_bf16 v[8:11], v[200:203], v[100:103], v[8:11]
	ds_read_b128 v[100:103], v221 offset:20480
	global_load_lds_dwordx4 v109, s[66:67]
	s_add_i32 m0, s68, 0x16000
	s_add_u32 s66, s10, 0x1640000
	s_addc_u32 s67, s11, 0
	v_mfma_f32_16x16x32_bf16 v[72:75], v[188:191], v[104:107], v[72:75]
	v_mfma_f32_16x16x32_bf16 v[4:7], v[192:195], v[104:107], v[4:7]
	v_mfma_f32_16x16x32_bf16 v[64:67], v[196:199], v[104:107], v[64:67]
	v_mfma_f32_16x16x32_bf16 v[0:3], v[200:203], v[104:107], v[0:3]
	ds_read_b128 v[104:107], v221 offset:22528
	global_load_lds_dwordx4 v109, s[66:67]
	s_waitcnt lgkmcnt(6)
	s_add_i32 m0, s68, 0x0
	v_mfma_f32_16x16x32_bf16 v[158:161], v[204:207], v[76:79], v[158:161]
	v_mfma_f32_16x16x32_bf16 v[60:63], v[208:211], v[76:79], v[60:63]
	v_mfma_f32_16x16x32_bf16 v[154:157], v[212:215], v[76:79], v[154:157]
	v_mfma_f32_16x16x32_bf16 v[56:59], v[216:219], v[76:79], v[56:59]
	global_load_lds_dwordx4 v108, s[8:9]
	s_add_i32 m0, s68, 0x2000
	s_add_u32 s66, s8, 0x80000
	s_addc_u32 s67, s9, 0
	v_mfma_f32_16x16x32_bf16 v[150:153], v[204:207], v[80:83], v[150:153]
	v_mfma_f32_16x16x32_bf16 v[52:55], v[208:211], v[80:83], v[52:55]
	v_mfma_f32_16x16x32_bf16 v[142:145], v[212:215], v[80:83], v[142:145]
	v_mfma_f32_16x16x32_bf16 v[44:47], v[216:219], v[80:83], v[44:47]
	global_load_lds_dwordx4 v108, s[66:67]
	s_waitcnt lgkmcnt(0)
	s_waitcnt vmcnt(6)
	s_barrier
	ds_read_b128 v[76:79], v220 offset:32768
	ds_read_b128 v[80:83], v220 offset:34816
	ds_read_b128 v[188:191], v234 offset:32768
	ds_read_b128 v[192:195], v234 offset:34816
	ds_read_b128 v[196:199], v234 offset:49152
	ds_read_b128 v[200:203], v234 offset:51200
	s_add_i32 m0, s68, 0x4000
	s_add_u32 s66, s8, 0x40000
	s_addc_u32 s67, s9, 0
	v_mfma_f32_16x16x32_bf16 v[146:149], v[204:207], v[84:87], v[146:149]
	v_mfma_f32_16x16x32_bf16 v[48:51], v[208:211], v[84:87], v[48:51]
	v_mfma_f32_16x16x32_bf16 v[134:137], v[212:215], v[84:87], v[134:137]
	v_mfma_f32_16x16x32_bf16 v[36:39], v[216:219], v[84:87], v[36:39]
	ds_read_b128 v[84:87], v220 offset:36864
	global_load_lds_dwordx4 v108, s[66:67]
	s_add_i32 m0, s68, 0x6000
	s_add_u32 s66, s8, 0xc0000
	s_addc_u32 s67, s9, 0
	v_mfma_f32_16x16x32_bf16 v[138:141], v[204:207], v[88:91], v[138:141]
	v_mfma_f32_16x16x32_bf16 v[40:43], v[208:211], v[88:91], v[40:43]
	v_mfma_f32_16x16x32_bf16 v[130:133], v[212:215], v[88:91], v[130:133]
	v_mfma_f32_16x16x32_bf16 v[32:35], v[216:219], v[88:91], v[32:35]
	ds_read_b128 v[88:91], v220 offset:38912
	global_load_lds_dwordx4 v108, s[66:67]
	v_mfma_f32_16x16x32_bf16 v[126:129], v[204:207], v[92:95], v[126:129]
	v_mfma_f32_16x16x32_bf16 v[28:31], v[208:211], v[92:95], v[28:31]
	v_mfma_f32_16x16x32_bf16 v[118:121], v[212:215], v[92:95], v[118:121]
	v_mfma_f32_16x16x32_bf16 v[16:19], v[216:219], v[92:95], v[16:19]
	ds_read_b128 v[92:95], v220 offset:49152
	v_mfma_f32_16x16x32_bf16 v[122:125], v[204:207], v[96:99], v[122:125]
	v_mfma_f32_16x16x32_bf16 v[24:27], v[208:211], v[96:99], v[24:27]
	v_mfma_f32_16x16x32_bf16 v[110:113], v[212:215], v[96:99], v[110:113]
	v_mfma_f32_16x16x32_bf16 v[12:15], v[216:219], v[96:99], v[12:15]
	ds_read_b128 v[96:99], v220 offset:51200
	v_mfma_f32_16x16x32_bf16 v[114:117], v[204:207], v[100:103], v[114:117]
	v_mfma_f32_16x16x32_bf16 v[20:23], v[208:211], v[100:103], v[20:23]
	v_mfma_f32_16x16x32_bf16 v[68:71], v[212:215], v[100:103], v[68:71]
	v_mfma_f32_16x16x32_bf16 v[8:11], v[216:219], v[100:103], v[8:11]
	ds_read_b128 v[100:103], v220 offset:53248
	v_mfma_f32_16x16x32_bf16 v[72:75], v[204:207], v[104:107], v[72:75]
	v_mfma_f32_16x16x32_bf16 v[4:7], v[208:211], v[104:107], v[4:7]
	v_mfma_f32_16x16x32_bf16 v[64:67], v[212:215], v[104:107], v[64:67]
	v_mfma_f32_16x16x32_bf16 v[0:3], v[216:219], v[104:107], v[0:3]
	ds_read_b128 v[104:107], v220 offset:55296
	s_add_u32 s8, s8, 128
	s_addc_u32 s9, s9, 0
	s_add_u32 s10, s10, 128
	s_addc_u32 s11, s11, 0
	s_waitcnt lgkmcnt(6)
	v_mfma_f32_16x16x32_bf16 v[158:161], v[188:191], v[76:79], v[158:161]
	v_mfma_f32_16x16x32_bf16 v[60:63], v[192:195], v[76:79], v[60:63]
	v_mfma_f32_16x16x32_bf16 v[154:157], v[196:199], v[76:79], v[154:157]
	v_mfma_f32_16x16x32_bf16 v[56:59], v[200:203], v[76:79], v[56:59]
	v_mfma_f32_16x16x32_bf16 v[150:153], v[188:191], v[80:83], v[150:153]
	v_mfma_f32_16x16x32_bf16 v[52:55], v[192:195], v[80:83], v[52:55]
	v_mfma_f32_16x16x32_bf16 v[142:145], v[196:199], v[80:83], v[142:145]
	v_mfma_f32_16x16x32_bf16 v[44:47], v[200:203], v[80:83], v[44:47]
	s_waitcnt lgkmcnt(0)
	ds_read_b128 v[76:79], v221 offset:32768
	ds_read_b128 v[80:83], v221 offset:34816
	ds_read_b128 v[204:207], v235 offset:32768
	ds_read_b128 v[208:211], v235 offset:34816
	ds_read_b128 v[212:215], v235 offset:49152
	ds_read_b128 v[216:219], v235 offset:51200
	v_mfma_f32_16x16x32_bf16 v[146:149], v[188:191], v[84:87], v[146:149]
	v_mfma_f32_16x16x32_bf16 v[48:51], v[192:195], v[84:87], v[48:51]
	v_mfma_f32_16x16x32_bf16 v[134:137], v[196:199], v[84:87], v[134:137]
	v_mfma_f32_16x16x32_bf16 v[36:39], v[200:203], v[84:87], v[36:39]
	ds_read_b128 v[84:87], v221 offset:36864
	v_mfma_f32_16x16x32_bf16 v[138:141], v[188:191], v[88:91], v[138:141]
	v_mfma_f32_16x16x32_bf16 v[40:43], v[192:195], v[88:91], v[40:43]
	v_mfma_f32_16x16x32_bf16 v[130:133], v[196:199], v[88:91], v[130:133]
	v_mfma_f32_16x16x32_bf16 v[32:35], v[200:203], v[88:91], v[32:35]
	ds_read_b128 v[88:91], v221 offset:38912
	s_waitcnt lgkmcnt(0)
	s_barrier
	s_add_i32 m0, s68, 0x18000
	v_mfma_f32_16x16x32_bf16 v[126:129], v[188:191], v[92:95], v[126:129]
	v_mfma_f32_16x16x32_bf16 v[28:31], v[192:195], v[92:95], v[28:31]
	v_mfma_f32_16x16x32_bf16 v[118:121], v[196:199], v[92:95], v[118:121]
	v_mfma_f32_16x16x32_bf16 v[16:19], v[200:203], v[92:95], v[16:19]
	ds_read_b128 v[92:95], v221 offset:49152
	global_load_lds_dwordx4 v109, s[10:11]
	s_add_i32 m0, s68, 0x1a000
	s_add_u32 s66, s10, 0x40000
	s_addc_u32 s67, s11, 0
	v_mfma_f32_16x16x32_bf16 v[122:125], v[188:191], v[96:99], v[122:125]
	v_mfma_f32_16x16x32_bf16 v[24:27], v[192:195], v[96:99], v[24:27]
	v_mfma_f32_16x16x32_bf16 v[110:113], v[196:199], v[96:99], v[110:113]
	v_mfma_f32_16x16x32_bf16 v[12:15], v[200:203], v[96:99], v[12:15]
	ds_read_b128 v[96:99], v221 offset:51200
	global_load_lds_dwordx4 v109, s[66:67]
	s_add_i32 m0, s68, 0x1c000
	s_add_u32 s66, s10, 0x1600000
	s_addc_u32 s67, s11, 0
	v_mfma_f32_16x16x32_bf16 v[114:117], v[188:191], v[100:103], v[114:117]
	v_mfma_f32_16x16x32_bf16 v[20:23], v[192:195], v[100:103], v[20:23]
	v_mfma_f32_16x16x32_bf16 v[68:71], v[196:199], v[100:103], v[68:71]
	v_mfma_f32_16x16x32_bf16 v[8:11], v[200:203], v[100:103], v[8:11]
	ds_read_b128 v[100:103], v221 offset:53248
	global_load_lds_dwordx4 v109, s[66:67]
	s_add_i32 m0, s68, 0x1e000
	s_add_u32 s66, s10, 0x1640000
	s_addc_u32 s67, s11, 0
	v_mfma_f32_16x16x32_bf16 v[72:75], v[188:191], v[104:107], v[72:75]
	v_mfma_f32_16x16x32_bf16 v[4:7], v[192:195], v[104:107], v[4:7]
	v_mfma_f32_16x16x32_bf16 v[64:67], v[196:199], v[104:107], v[64:67]
	v_mfma_f32_16x16x32_bf16 v[0:3], v[200:203], v[104:107], v[0:3]
	ds_read_b128 v[104:107], v221 offset:55296
	global_load_lds_dwordx4 v109, s[66:67]
	s_waitcnt lgkmcnt(6)
	s_add_i32 m0, s68, 0x8000
	v_mfma_f32_16x16x32_bf16 v[158:161], v[204:207], v[76:79], v[158:161]
	v_mfma_f32_16x16x32_bf16 v[60:63], v[208:211], v[76:79], v[60:63]
	v_mfma_f32_16x16x32_bf16 v[154:157], v[212:215], v[76:79], v[154:157]
	v_mfma_f32_16x16x32_bf16 v[56:59], v[216:219], v[76:79], v[56:59]
	global_load_lds_dwordx4 v108, s[8:9]
	s_add_i32 m0, s68, 0xa000
	s_add_u32 s66, s8, 0x80000
	s_addc_u32 s67, s9, 0
	v_mfma_f32_16x16x32_bf16 v[150:153], v[204:207], v[80:83], v[150:153]
	v_mfma_f32_16x16x32_bf16 v[52:55], v[208:211], v[80:83], v[52:55]
	v_mfma_f32_16x16x32_bf16 v[142:145], v[212:215], v[80:83], v[142:145]
	v_mfma_f32_16x16x32_bf16 v[44:47], v[216:219], v[80:83], v[44:47]
	global_load_lds_dwordx4 v108, s[66:67]
	s_waitcnt lgkmcnt(0)
	s_waitcnt vmcnt(6)
	s_barrier
	ds_read_b128 v[76:79], v220
	ds_read_b128 v[80:83], v220 offset:2048
	ds_read_b128 v[188:191], v234
	ds_read_b128 v[192:195], v234 offset:2048
	ds_read_b128 v[196:199], v234 offset:16384
	ds_read_b128 v[200:203], v234 offset:18432
	s_add_i32 m0, s68, 0xc000
	s_add_u32 s66, s8, 0x40000
	s_addc_u32 s67, s9, 0
	v_mfma_f32_16x16x32_bf16 v[146:149], v[204:207], v[84:87], v[146:149]
	v_mfma_f32_16x16x32_bf16 v[48:51], v[208:211], v[84:87], v[48:51]
	v_mfma_f32_16x16x32_bf16 v[134:137], v[212:215], v[84:87], v[134:137]
	v_mfma_f32_16x16x32_bf16 v[36:39], v[216:219], v[84:87], v[36:39]
	ds_read_b128 v[84:87], v220 offset:4096
	global_load_lds_dwordx4 v108, s[66:67]
	s_add_i32 m0, s68, 0xe000
	s_add_u32 s66, s8, 0xc0000
	s_addc_u32 s67, s9, 0
	v_mfma_f32_16x16x32_bf16 v[138:141], v[204:207], v[88:91], v[138:141]
	v_mfma_f32_16x16x32_bf16 v[40:43], v[208:211], v[88:91], v[40:43]
	v_mfma_f32_16x16x32_bf16 v[130:133], v[212:215], v[88:91], v[130:133]
	v_mfma_f32_16x16x32_bf16 v[32:35], v[216:219], v[88:91], v[32:35]
	ds_read_b128 v[88:91], v220 offset:6144
	global_load_lds_dwordx4 v108, s[66:67]
	v_mfma_f32_16x16x32_bf16 v[126:129], v[204:207], v[92:95], v[126:129]
	v_mfma_f32_16x16x32_bf16 v[28:31], v[208:211], v[92:95], v[28:31]
	v_mfma_f32_16x16x32_bf16 v[118:121], v[212:215], v[92:95], v[118:121]
	v_mfma_f32_16x16x32_bf16 v[16:19], v[216:219], v[92:95], v[16:19]
	ds_read_b128 v[92:95], v220 offset:16384
	v_mfma_f32_16x16x32_bf16 v[122:125], v[204:207], v[96:99], v[122:125]
	v_mfma_f32_16x16x32_bf16 v[24:27], v[208:211], v[96:99], v[24:27]
	v_mfma_f32_16x16x32_bf16 v[110:113], v[212:215], v[96:99], v[110:113]
	v_mfma_f32_16x16x32_bf16 v[12:15], v[216:219], v[96:99], v[12:15]
	ds_read_b128 v[96:99], v220 offset:18432
	v_mfma_f32_16x16x32_bf16 v[114:117], v[204:207], v[100:103], v[114:117]
	v_mfma_f32_16x16x32_bf16 v[20:23], v[208:211], v[100:103], v[20:23]
	v_mfma_f32_16x16x32_bf16 v[68:71], v[212:215], v[100:103], v[68:71]
	v_mfma_f32_16x16x32_bf16 v[8:11], v[216:219], v[100:103], v[8:11]
	ds_read_b128 v[100:103], v220 offset:20480
	v_mfma_f32_16x16x32_bf16 v[72:75], v[204:207], v[104:107], v[72:75]
	v_mfma_f32_16x16x32_bf16 v[4:7], v[208:211], v[104:107], v[4:7]
	v_mfma_f32_16x16x32_bf16 v[64:67], v[212:215], v[104:107], v[64:67]
	v_mfma_f32_16x16x32_bf16 v[0:3], v[216:219], v[104:107], v[0:3]
	ds_read_b128 v[104:107], v220 offset:22528
	s_add_u32 s8, s8, 128
	s_addc_u32 s9, s9, 0
	s_add_u32 s10, s10, 128
	s_addc_u32 s11, s11, 0
	s_add_i32 s65, s65, 1
	s_cmp_lt_u32 s65, 16
	s_cbranch_scc1 .Ls8_loop
	s_waitcnt lgkmcnt(0)
	s_nop 7
	s_nop 3
	s_lshl_b32 s8, s0, 8
	s_lshl_b32 s1, s1, 7
	v_mov_b32_e32 v80, v225
	v_mov_b32_e32 v193, v163
	s_add_i32 s8, s8, s58
	s_or_b32 s1, s1, s53
	s_lshl_b32 s0, s0, 3
	v_add_u32_e32 v190, s8, v193
	v_lshl_add_u32 v188, v80, 3, s1
	v_ashrrev_i32_e32 v191, 31, v190
	v_ashrrev_i32_e32 v189, 31, v188
	v_lshl_add_u64 v[78:79], v[190:191], 2, s[4:5]
	v_lshlrev_b64 v[90:91], 2, v[188:189]
	global_load_dword v196, v[78:79], off
	global_load_dword v192, v[78:79], off offset:64
	global_load_dword v194, v[78:79], off offset:128
	global_load_dword v200, v[78:79], off offset:192
	global_load_dword v199, v[78:79], off offset:256
	global_load_dword v77, v[78:79], off offset:320
	global_load_dword v76, v[78:79], off offset:384
	global_load_dword v191, v[78:79], off offset:448
	v_lshl_add_u64 v[78:79], s[14:15], 0, v[90:91]
	v_lshl_add_u64 v[80:81], s[20:21], 0, v[90:91]
	global_load_dwordx4 v[102:105], v[78:79], off
	global_load_dwordx4 v[94:97], v[80:81], off
	v_lshl_add_u64 v[78:79], s[22:23], 0, v[90:91]
	global_load_dwordx4 v[98:101], v[78:79], off
	v_lshl_add_u64 v[78:79], s[16:17], 0, v[90:91]
	global_load_dwordx4 v[106:109], v[78:79], off
	v_lshl_add_u64 v[78:79], s[24:25], 0, v[90:91]
	v_lshl_add_u64 v[80:81], s[26:27], 0, v[90:91]
	v_lshl_add_u64 v[82:83], s[28:29], 0, v[90:91]
	v_lshl_add_u64 v[90:91], s[30:31], 0, v[90:91]
	global_load_dwordx4 v[86:89], v[78:79], off
	s_nop 0
	global_load_dwordx4 v[78:81], v[80:81], off
	s_add_i32 s0, s0, s59
	global_load_dwordx4 v[82:85], v[82:83], off
	v_add_u32_e32 v195, s0, v193
	global_load_dwordx4 v[90:93], v[90:91], off
	v_cmp_gt_i32_e64 s[12:13], 2, v193
	s_waitcnt vmcnt(0)
	v_fmamk_f32 v196, v196, 0x3a000000, v230
	v_rsq_f32_e32 v198, v196
	v_mad_i64_i32 v[196:197], s[0:1], v195, s62, 0
	v_lshl_add_u64 v[196:197], s[70:71], 0, v[196:197]
	v_pk_mul_f32 v[160:161], v[160:161], v[198:199] op_sel_hi:[1,0]
	v_pk_mul_f32 v[158:159], v[158:159], v[198:199] op_sel_hi:[1,0]
	v_pk_mul_f32 v[156:157], v[156:157], v[198:199] op_sel_hi:[1,0]
	v_pk_mul_f32 v[154:155], v[154:155], v[198:199] op_sel_hi:[1,0]
	v_lshl_add_u64 v[196:197], v[188:189], 2, v[196:197]
	s_and_saveexec_b64 s[0:1], s[12:13]
	s_cbranch_execz .LBB0_843
	v_add_co_u32_e32 v202, vcc, 0x5000, v196
	global_store_dwordx4 v[196:197], v[158:161], off
	s_nop 0
	v_addc_co_u32_e32 v203, vcc, 0, v197, vcc
	global_store_dwordx4 v[202:203], v[154:157], off offset:2048

.LBB0_969:
	v_readlane_b32 s0, v255, 8
	v_readlane_b32 s1, v255, 9
	s_and_b64 vcc, exec, s[0:1]
	s_cbranch_vccnz .LBB0_1005
	s_add_u32 s18, s92, 0xa700000
	s_addc_u32 s19, s93, 0
	s_lshr_b32 s4, s3, 6
	s_lshr_b32 s5, s3, 8
	s_lshl_b32 s20, s4, 10
	s_mul_i32 s7, s37, 0x2c0000
	s_mul_hi_i32 s6, s37, 0x2c0000
	s_add_u32 s14, s18, s7
	s_addc_u32 s15, s19, s6
	s_add_i32 s21, s20, 0
	s_add_i32 m0, s21, 0x10000
	s_mul_i32 s0, s38, 0x2c0000
	v_and_b32_e32 v136, 63, v222
	v_lshrrev_b32_e32 v137, 3, v136
	v_lshrrev_b32_e32 v138, 6, v222
	v_lshl_add_u32 v139, v138, 3, v137
	v_and_b32_e32 v146, 7, v136
	v_and_b32_e32 v147, 6, v137
	v_xor_b32_e32 v146, v146, v147
	v_lshlrev_b32_e32 v146, 4, v146
	v_mul_u32_u24_e32 v147, 0x2c00, v139
	v_add_u32_e32 v147, v147, v146
	v_mov_b32_e32 v128, v147
	v_add_u32_e32 v130, 0xb0000, v147
	v_mov_b32_e32 v168, v147
	v_add_u32_e32 v172, 0xb0000, v147
	v_add_u32_e32 v130, 0xb0000, v147
	v_add_u32_e32 v172, 0xb0000, v147
	v_and_b32_e32 v147, 31, v139
	v_and_b32_e32 v148, 12, v147
	v_lshlrev_b32_e32 v148, 1, v148
	v_lshrrev_b32_e32 v149, 4, v147
	v_lshlrev_b32_e32 v149, 2, v149
	v_and_b32_e32 v147, 3, v147
	v_or3_b32 v147, v148, v149, v147
	v_and_b32_e32 v148, 0x60, v139
	v_add_u32_e32 v147, v147, v148
	v_mul_u32_u24_e32 v147, 0x2c00, v147
	v_add_u32_e32 v147, v147, v146
	v_mov_b32_e32 v170, v147
	v_add_u32_e32 v174, 0xb0000, v147
	v_add_u32_e32 v174, 0xb0000, v147
	v_and_b32_e32 v147, 15, v136
	v_lshrrev_b32_e32 v148, 4, v136
	v_and_b32_e32 v149, 6, v147
	v_xor_b32_e32 v148, v148, v149
	v_lshlrev_b32_e32 v148, 4, v148
	v_lshl_or_b32 v148, v147, 7, v148
	v_lshrrev_b32_e32 v149, 2, v138
	v_lshl_add_u32 v149, v149, 13, v148
	v_add_u32_e32 v142, 0x0, v149
	v_and_b32_e32 v147, 3, v138
	v_lshl_add_u32 v147, v147, 12, v148
	v_add_u32_e32 v140, 0x0, v147
	v_add_u32_e32 v141, 0x10000, v147
	v_add_u32_e32 v143, 0x14000, v147
	v_add_u32_e32 v145, 0x10000, v147
	s_add_i32 m0, s21, 0x12000
	s_mul_hi_i32 s1, s38, 0x2c0000
	s_add_u32 s0, s96, s0
	s_addc_u32 s1, s97, s1
	s_mov_b32 m0, s21
	s_add_i32 s22, s21, 0x2000
	s_mov_b32 m0, s22
	s_add_u32 s6, s14, 0x160000
	s_addc_u32 s7, s15, 0
	s_add_i32 m0, s21, 0x14000
	v_mov_b32_e32 v171, 0
	s_add_i32 m0, s21, 0x16000
	v_mov_b32_e32 v175, v171
	s_add_u32 s6, s0, 0x160000
	s_addc_u32 s7, s1, 0
	s_add_i32 s23, s21, 0x4000
	s_mov_b32 m0, s23
	s_add_i32 s24, s21, 0x6000
	s_mov_b32 m0, s24
	v_mov_b32_e32 v169, v171
	v_mov_b32_e32 v173, v171
	s_mov_b32 s25, 0
	v_lshl_add_u64 v[6:7], s[14:15], 0, v[170:171]
	v_lshl_add_u64 v[4:5], s[14:15], 0, v[174:175]
	v_lshl_add_u64 v[2:3], s[0:1], 0, v[168:169]
	s_cmp_lg_u32 s5, 1
	v_lshl_add_u64 v[0:1], s[0:1], 0, v[172:173]
	s_cbranch_scc1 .LBB0_972
.LBB0_972:
	s_lshl_b32 s4, s4, 5
	s_lshl_b32 s26, s5, 6
	s_lshl_b32 s6, s5, 13
	s_and_b32 s27, s4, 0x60
	s_add_u32 s10, s92, 0x50000
	s_mov_b64 s[12:13], 0x80
	s_addc_u32 s11, s93, 0
	s_add_i32 m0, s21, 0x18000
	v_lshl_add_u64 v[6:7], v[6:7], 0, s[12:13]
	v_lshl_add_u64 v[4:5], v[4:5], 0, s[12:13]
	s_add_i32 m0, s21, 0x1a000
	s_add_i32 s28, s21, 0x8000
	s_add_i32 s29, s21, 0xa000
	v_lshl_add_u64 v[2:3], v[2:3], 0, s[12:13]
	s_mov_b32 m0, s28
	s_add_u32 s4, s14, 0x160080
	v_lshl_add_u64 v[0:1], v[0:1], 0, s[12:13]
	s_mov_b32 m0, s29
	s_addc_u32 s5, s15, 0
	s_add_i32 m0, s21, 0x1c000
	v_lshl_add_u64 v[0:1], s[4:5], 0, v[170:171]
	v_lshl_add_u64 v[0:1], s[4:5], 0, v[174:175]
	s_add_i32 m0, s21, 0x1e000
	v_lshlrev_b32_e32 v1, 2, v163
	v_lshl_or_b32 v0, v163, 6, v227
	v_and_b32_e32 v1, 32, v1
	v_bitop3_b32 v0, v0, s6, v1 bitop3:0xde
	v_add_u16_e32 v1, v226, v224
	v_lshrrev_b16_e32 v1, 1, v1
	s_add_i32 s33, 0, 0x10000
	s_add_i32 s34, 0, 0x14000
	v_mbcnt_lo_u32_b32 v0, -1, 0
	s_ashr_i32 s30, s94, 31
	s_mov_b32 s31, s94
	v_mov_b32_e32 v129, v171
	v_mov_b32_e32 v131, v171
	v_mov_b64_e32 v[132:133], 0x200
	v_mov_b64_e32 v[134:135], 0x1ff
	v_mbcnt_hi_u32_b32 v144, -1, v0
	v_and_b32_e32 v136, 63, v222
	v_lshrrev_b32_e32 v137, 6, v222
	v_lshrrev_b32_e32 v138, 3, v136
	v_lshl_add_u32 v139, v137, 3, v138
	v_and_b32_e32 v146, 7, v136
	v_and_b32_e32 v147, 6, v138
	v_xor_b32_e32 v146, v146, v147
	v_lshlrev_b32_e32 v146, 4, v146
	v_mul_u32_u24_e32 v147, 0x2c00, v139
	v_add_u32_e32 v145, v147, v146
	v_and_b32_e32 v147, 31, v139
	v_and_b32_e32 v138, 12, v147
	v_lshlrev_b32_e32 v138, 1, v138
	v_lshrrev_b32_e32 v216, 4, v147
	v_lshlrev_b32_e32 v216, 2, v216
	v_and_b32_e32 v147, 3, v147
	v_or3_b32 v147, v138, v216, v147
	v_and_b32_e32 v138, 0x60, v139
	v_add_u32_e32 v147, v147, v138
	v_mul_u32_u24_e32 v147, 0x2c00, v147
	v_add_u32_e32 v216, v147, v146
	v_and_b32_e32 v138, 15, v136
	v_lshrrev_b32_e32 v139, 4, v136
	v_and_b32_e32 v146, 6, v138
	v_xor_b32_e32 v139, v139, v146
	v_lshlrev_b32_e32 v139, 4, v139
	v_lshl_or_b32 v139, v138, 7, v139
	v_lshrrev_b32_e32 v146, 2, v137
	v_lshl_add_u32 v217, v146, 13, v139
	v_xor_b32_e32 v218, 64, v217
	v_and_b32_e32 v146, 3, v137
	v_lshl_add_u32 v219, v146, 12, v139
	v_add_u32_e32 v219, 0x10000, v219
	v_xor_b32_e32 v220, 64, v219
	v_readfirstlane_b32 s44, v222
	s_nop 3
	s_lshr_b32 s44, s44, 6
	s_lshl_b32 s44, s44, 10
	s_mov_b32 s98, 0
	s_mul_i32 s16, s98, s94
	s_add_i32 s16, s16, s2
	s_and_b32 s17, s16, 7
	s_lshr_b32 s16, s16, 3
	s_mul_i32 s17, s17, 0x40
	s_add_i32 s16, s16, s17
	s_mul_i32 s17, s16, 0x80000
	s_lshr_b32 s17, s17, 24
	s_mul_i32 s41, s17, 0x20
	s_sub_i32 s16, s16, s41
	s_and_b32 s40, s16, 3
	s_lshl_b32 s17, s17, 2
	s_add_i32 s40, s40, s17
	s_lshr_b32 s41, s16, 2
	s_mul_i32 s100, s40, 0x2c0000
	s_add_u32 s0, s92, 0xfd00000
	s_addc_u32 s1, s93, 0
	s_add_u32 s0, s0, s100
	s_addc_u32 s1, s1, 0
	s_mul_i32 s100, s41, 0x2c0000
	s_add_u32 s14, s92, 0xa700000
	s_addc_u32 s15, s93, 0
	s_add_u32 s14, s14, s100
	s_addc_u32 s15, s15, 0
	s_add_i32 m0, s44, 0x0
	s_nop 0
	global_load_lds_dwordx4 v145, s[0:1]
	s_add_i32 m0, s44, 0x2000
	s_add_u32 s42, s0, 0xb0000
	s_addc_u32 s43, s1, 0
	s_nop 0
	global_load_lds_dwordx4 v145, s[42:43]
	s_add_i32 m0, s44, 0x4000
	s_add_u32 s42, s0, 0x160000
	s_addc_u32 s43, s1, 0
	s_nop 0
	global_load_lds_dwordx4 v145, s[42:43]
	s_add_i32 m0, s44, 0x6000
	s_add_u32 s42, s0, 0x210000
	s_addc_u32 s43, s1, 0
	s_nop 0
	global_load_lds_dwordx4 v145, s[42:43]
	s_add_i32 m0, s44, 0x10000
	s_nop 0
	global_load_lds_dwordx4 v216, s[14:15]
	s_add_i32 m0, s44, 0x12000
	s_add_u32 s42, s14, 0xb0000
	s_addc_u32 s43, s15, 0
	s_nop 0
	global_load_lds_dwordx4 v216, s[42:43]
	s_add_i32 m0, s44, 0x14000
	s_add_u32 s42, s14, 0x160000
	s_addc_u32 s43, s15, 0
	s_nop 0
	global_load_lds_dwordx4 v216, s[42:43]
	s_add_i32 m0, s44, 0x16000
	s_add_u32 s42, s14, 0x210000
	s_addc_u32 s43, s15, 0
	s_nop 0
	global_load_lds_dwordx4 v216, s[42:43]
	s_add_u32 s0, s0, 128
	s_addc_u32 s1, s1, 0
	s_add_u32 s14, s14, 128
	s_addc_u32 s15, s15, 0
	s_add_i32 m0, s44, 0x8000
	s_nop 0
	global_load_lds_dwordx4 v145, s[0:1]
	s_add_i32 m0, s44, 0xa000
	s_add_u32 s42, s0, 0xb0000
	s_addc_u32 s43, s1, 0
	s_nop 0
	global_load_lds_dwordx4 v145, s[42:43]
	s_add_i32 m0, s44, 0xc000
	s_add_u32 s42, s0, 0x160000
	s_addc_u32 s43, s1, 0
	s_nop 0
	global_load_lds_dwordx4 v145, s[42:43]
	s_add_i32 m0, s44, 0xe000
	s_add_u32 s42, s0, 0x210000
	s_addc_u32 s43, s1, 0
	s_nop 0
	global_load_lds_dwordx4 v145, s[42:43]
	s_add_i32 m0, s44, 0x18000
	s_nop 0
	global_load_lds_dwordx4 v216, s[14:15]
	s_add_i32 m0, s44, 0x1a000
	s_add_u32 s42, s14, 0xb0000
	s_addc_u32 s43, s15, 0
	s_nop 0
	global_load_lds_dwordx4 v216, s[42:43]
	s_add_i32 m0, s44, 0x1c000
	s_add_u32 s42, s14, 0x160000
	s_addc_u32 s43, s15, 0
	s_nop 0
	global_load_lds_dwordx4 v216, s[42:43]
	s_add_i32 m0, s44, 0x1e000
	s_add_u32 s42, s14, 0x210000
	s_addc_u32 s43, s15, 0
	s_nop 0
	global_load_lds_dwordx4 v216, s[42:43]
	s_branch .LBB0_974

.LBB0_984:
	s_add_u32 s0, s0, 0x160080
	s_addc_u32 s1, s1, 0
	s_add_u32 s39, s14, 0x100
	v_mov_b32_e32 v0, 0
	s_addc_u32 s40, s15, 0
	s_mov_b32 s41, -2
	s_waitcnt lgkmcnt(0)
	v_mov_b32_e32 v1, v0
	v_mov_b32_e32 v2, v0
	v_mov_b32_e32 v3, v0
	v_mov_b32_e32 v4, v0
	v_mov_b32_e32 v5, v0
	v_mov_b32_e32 v6, v0
	v_mov_b32_e32 v7, v0
	s_waitcnt vmcnt(0)
	v_mov_b32_e32 v16, v0
	v_mov_b32_e32 v17, v0
	v_mov_b32_e32 v18, v0
	v_mov_b32_e32 v19, v0
	v_mov_b32_e32 v20, v0
	v_mov_b32_e32 v21, v0
	v_mov_b32_e32 v22, v0
	v_mov_b32_e32 v23, v0
	v_mov_b32_e32 v32, v0
	v_mov_b32_e32 v33, v0
	v_mov_b32_e32 v34, v0
	v_mov_b32_e32 v35, v0
	v_mov_b32_e32 v36, v0
	v_mov_b32_e32 v37, v0
	v_mov_b32_e32 v38, v0
	v_mov_b32_e32 v39, v0
	v_mov_b32_e32 v48, v0
	v_mov_b32_e32 v49, v0
	v_mov_b32_e32 v50, v0
	v_mov_b32_e32 v51, v0
	v_mov_b32_e32 v52, v0
	v_mov_b32_e32 v53, v0
	v_mov_b32_e32 v54, v0
	v_mov_b32_e32 v55, v0
	v_mov_b32_e32 v8, v0
	v_mov_b32_e32 v9, v0
	v_mov_b32_e32 v10, v0
	v_mov_b32_e32 v11, v0
	v_mov_b32_e32 v12, v0
	v_mov_b32_e32 v13, v0
	v_mov_b32_e32 v14, v0
	v_mov_b32_e32 v15, v0
	v_mov_b32_e32 v24, v0
	v_mov_b32_e32 v25, v0
	v_mov_b32_e32 v26, v0
	v_mov_b32_e32 v27, v0
	v_mov_b32_e32 v28, v0
	v_mov_b32_e32 v29, v0
	v_mov_b32_e32 v30, v0
	v_mov_b32_e32 v31, v0
	v_mov_b32_e32 v40, v0
	v_mov_b32_e32 v41, v0
	v_mov_b32_e32 v42, v0
	v_mov_b32_e32 v43, v0
	v_mov_b32_e32 v44, v0
	v_mov_b32_e32 v45, v0
	v_mov_b32_e32 v46, v0
	v_mov_b32_e32 v47, v0
	v_mov_b32_e32 v56, v0
	v_mov_b32_e32 v57, v0
	v_mov_b32_e32 v58, v0
	v_mov_b32_e32 v59, v0
	v_mov_b32_e32 v60, v0
	v_mov_b32_e32 v61, v0
	v_mov_b32_e32 v62, v0
	v_mov_b32_e32 v63, v0
	v_mov_b32_e32 v64, v0
	v_mov_b32_e32 v65, v0
	v_mov_b32_e32 v66, v0
	v_mov_b32_e32 v67, v0
	v_mov_b32_e32 v68, v0
	v_mov_b32_e32 v69, v0
	v_mov_b32_e32 v70, v0
	v_mov_b32_e32 v71, v0
	v_mov_b32_e32 v80, v0
	v_mov_b32_e32 v81, v0
	v_mov_b32_e32 v82, v0
	v_mov_b32_e32 v83, v0
	v_mov_b32_e32 v84, v0
	v_mov_b32_e32 v85, v0
	v_mov_b32_e32 v86, v0
	v_mov_b32_e32 v87, v0
	v_mov_b32_e32 v96, v0
	v_mov_b32_e32 v97, v0
	v_mov_b32_e32 v98, v0
	v_mov_b32_e32 v99, v0
	v_mov_b32_e32 v100, v0
	v_mov_b32_e32 v101, v0
	v_mov_b32_e32 v102, v0
	v_mov_b32_e32 v103, v0
	v_mov_b32_e32 v112, v0
	v_mov_b32_e32 v113, v0
	v_mov_b32_e32 v114, v0
	v_mov_b32_e32 v115, v0
	v_mov_b32_e32 v116, v0
	v_mov_b32_e32 v117, v0
	v_mov_b32_e32 v118, v0
	v_mov_b32_e32 v119, v0
	v_mov_b32_e32 v72, v0
	v_mov_b32_e32 v73, v0
	v_mov_b32_e32 v74, v0
	v_mov_b32_e32 v75, v0
	v_mov_b32_e32 v76, v0
	v_mov_b32_e32 v77, v0
	v_mov_b32_e32 v78, v0
	v_mov_b32_e32 v79, v0
	v_mov_b32_e32 v88, v0
	v_mov_b32_e32 v89, v0
	v_mov_b32_e32 v90, v0
	v_mov_b32_e32 v91, v0
	v_mov_b32_e32 v92, v0
	v_mov_b32_e32 v93, v0
	v_mov_b32_e32 v94, v0
	v_mov_b32_e32 v95, v0
	v_mov_b32_e32 v104, v0
	v_mov_b32_e32 v105, v0
	v_mov_b32_e32 v106, v0
	v_mov_b32_e32 v107, v0
	v_mov_b32_e32 v108, v0
	v_mov_b32_e32 v109, v0
	v_mov_b32_e32 v110, v0
	v_mov_b32_e32 v111, v0
	v_mov_b32_e32 v120, v0
	v_mov_b32_e32 v121, v0
	v_mov_b32_e32 v122, v0
	v_mov_b32_e32 v123, v0
	v_mov_b32_e32 v124, v0
	v_mov_b32_e32 v125, v0
	v_mov_b32_e32 v126, v0
	v_mov_b32_e32 v127, v0
	v_and_b32_e32 v136, 63, v222
	v_lshrrev_b32_e32 v137, 6, v222
	v_lshrrev_b32_e32 v138, 3, v136
	v_lshl_add_u32 v139, v137, 3, v138
	v_and_b32_e32 v146, 7, v136
	v_and_b32_e32 v147, 6, v138
	v_xor_b32_e32 v146, v146, v147
	v_lshlrev_b32_e32 v146, 4, v146
	v_mul_u32_u24_e32 v147, 0x2c00, v139
	v_add_u32_e32 v145, v147, v146
	v_and_b32_e32 v147, 31, v139
	v_and_b32_e32 v138, 12, v147
	v_lshlrev_b32_e32 v138, 1, v138
	v_lshrrev_b32_e32 v216, 4, v147
	v_lshlrev_b32_e32 v216, 2, v216
	v_and_b32_e32 v147, 3, v147
	v_or3_b32 v147, v138, v216, v147
	v_and_b32_e32 v138, 0x60, v139
	v_add_u32_e32 v147, v147, v138
	v_mul_u32_u24_e32 v147, 0x2c00, v147
	v_add_u32_e32 v216, v147, v146
	v_and_b32_e32 v138, 15, v136
	v_lshrrev_b32_e32 v139, 4, v136
	v_and_b32_e32 v146, 6, v138
	v_xor_b32_e32 v139, v139, v146
	v_lshlrev_b32_e32 v139, 4, v139
	v_lshl_or_b32 v139, v138, 7, v139
	v_lshrrev_b32_e32 v146, 2, v137
	v_lshl_add_u32 v217, v146, 13, v139
	v_xor_b32_e32 v218, 64, v217
	v_and_b32_e32 v146, 3, v137
	v_lshl_add_u32 v219, v146, 12, v139
	v_add_u32_e32 v219, 0x10000, v219
	v_xor_b32_e32 v220, 64, v219
	v_readfirstlane_b32 s44, v222
	s_nop 3
	s_lshr_b32 s44, s44, 6
	s_lshl_b32 s44, s44, 10
	s_mul_i32 s16, s98, s94
	s_add_i32 s16, s16, s2
	s_and_b32 s17, s16, 7
	s_lshr_b32 s16, s16, 3
	s_mul_i32 s17, s17, 0x40
	s_add_i32 s16, s16, s17
	s_mul_i32 s17, s16, 0x80000
	s_lshr_b32 s17, s17, 24
	s_mul_i32 s100, s17, 0x20
	s_sub_i32 s16, s16, s100
	s_and_b32 s39, s16, 3
	s_lshl_b32 s17, s17, 2
	s_add_i32 s39, s39, s17
	s_lshr_b32 s100, s16, 2
	s_mul_i32 s99, s39, 0x2c0000
	s_add_u32 s0, s92, 0xfd00100
	s_addc_u32 s1, s93, 0
	s_add_u32 s0, s0, s99
	s_addc_u32 s1, s1, 0
	s_mul_i32 s99, s100, 0x2c0000
	s_add_u32 s14, s92, 0xa700100
	s_addc_u32 s15, s93, 0
	s_add_u32 s14, s14, s99
	s_addc_u32 s15, s15, 0
	s_add_i32 s98, s98, 1
	s_mul_i32 s40, s98, s94
	s_add_i32 s40, s40, s2
	s_cmp_lt_u32 s40, 0x200
	s_cbranch_scc0 .Ls9_nonext
	s_mul_i32 s16, s98, s94
	s_add_i32 s16, s16, s2
	s_and_b32 s17, s16, 7
	s_lshr_b32 s16, s16, 3
	s_mul_i32 s17, s17, 0x40
	s_add_i32 s16, s16, s17
	s_mul_i32 s17, s16, 0x80000
	s_lshr_b32 s17, s17, 24
	s_mul_i32 s100, s17, 0x20
	s_sub_i32 s16, s16, s100
	s_and_b32 s39, s16, 3
	s_lshl_b32 s17, s17, 2
	s_add_i32 s39, s39, s17
	s_lshr_b32 s100, s16, 2
.Ls9_nonext:
	s_mul_i32 s99, s39, 0x2c0000
	s_add_u32 s16, s92, 0xfd00000
	s_addc_u32 s17, s93, 0
	s_add_u32 s16, s16, s99
	s_addc_u32 s17, s17, 0
	s_mul_i32 s99, s100, 0x2c0000
	s_add_u32 s40, s92, 0xa700000
	s_addc_u32 s41, s93, 0
	s_add_u32 s40, s40, s99
	s_addc_u32 s41, s41, 0
	s_waitcnt vmcnt(0)
	s_barrier
	ds_read_b128 v[136:139], v217
	ds_read_b128 v[146:149], v217 offset:2048
	ds_read_b128 v[184:187], v219
	ds_read_b128 v[188:191], v219 offset:2048
	ds_read_b128 v[192:195], v219 offset:16384
	ds_read_b128 v[196:199], v219 offset:18432
	ds_read_b128 v[150:153], v217 offset:4096
	ds_read_b128 v[154:157], v217 offset:6144
	ds_read_b128 v[158:161], v217 offset:16384
	ds_read_b128 v[164:167], v217 offset:18432
	ds_read_b128 v[176:179], v217 offset:20480
	ds_read_b128 v[180:183], v217 offset:22528
	s_mov_b32 s39, 0
.Ls9_loop:
	s_cmp_eq_u32 s39, 43
	s_cselect_b32 s0, s16, s0
	s_cselect_b32 s1, s17, s1
	s_cselect_b32 s14, s40, s14
	s_cselect_b32 s15, s41, s15
	s_waitcnt lgkmcnt(6)
	v_mfma_f32_16x16x32_bf16 v[124:127], v[184:187], v[136:139], v[124:127]
	v_mfma_f32_16x16x32_bf16 v[120:123], v[188:191], v[136:139], v[120:123]
	v_mfma_f32_16x16x32_bf16 v[116:119], v[192:195], v[136:139], v[116:119]
	v_mfma_f32_16x16x32_bf16 v[112:115], v[196:199], v[136:139], v[112:115]
	v_mfma_f32_16x16x32_bf16 v[108:111], v[184:187], v[146:149], v[108:111]
	v_mfma_f32_16x16x32_bf16 v[104:107], v[188:191], v[146:149], v[104:107]
	v_mfma_f32_16x16x32_bf16 v[100:103], v[192:195], v[146:149], v[100:103]
	v_mfma_f32_16x16x32_bf16 v[96:99], v[196:199], v[146:149], v[96:99]
	s_waitcnt lgkmcnt(0)
	ds_read_b128 v[136:139], v218
	ds_read_b128 v[146:149], v218 offset:2048
	ds_read_b128 v[200:203], v220
	ds_read_b128 v[204:207], v220 offset:2048
	ds_read_b128 v[208:211], v220 offset:16384
	ds_read_b128 v[212:215], v220 offset:18432
	v_mfma_f32_16x16x32_bf16 v[92:95], v[184:187], v[150:153], v[92:95]
	v_mfma_f32_16x16x32_bf16 v[88:91], v[188:191], v[150:153], v[88:91]
	v_mfma_f32_16x16x32_bf16 v[84:87], v[192:195], v[150:153], v[84:87]
	v_mfma_f32_16x16x32_bf16 v[80:83], v[196:199], v[150:153], v[80:83]
	ds_read_b128 v[150:153], v218 offset:4096
	v_mfma_f32_16x16x32_bf16 v[76:79], v[184:187], v[154:157], v[76:79]
	v_mfma_f32_16x16x32_bf16 v[72:75], v[188:191], v[154:157], v[72:75]
	v_mfma_f32_16x16x32_bf16 v[68:71], v[192:195], v[154:157], v[68:71]
	v_mfma_f32_16x16x32_bf16 v[64:67], v[196:199], v[154:157], v[64:67]
	ds_read_b128 v[154:157], v218 offset:6144
	s_waitcnt lgkmcnt(0)
	s_barrier
	s_add_i32 m0, s44, 0x10000
	v_mfma_f32_16x16x32_bf16 v[60:63], v[184:187], v[158:161], v[60:63]
	v_mfma_f32_16x16x32_bf16 v[56:59], v[188:191], v[158:161], v[56:59]
	v_mfma_f32_16x16x32_bf16 v[52:55], v[192:195], v[158:161], v[52:55]
	v_mfma_f32_16x16x32_bf16 v[48:51], v[196:199], v[158:161], v[48:51]
	ds_read_b128 v[158:161], v218 offset:16384
	global_load_lds_dwordx4 v216, s[14:15]
	s_add_i32 m0, s44, 0x12000
	s_add_u32 s42, s14, 0xb0000
	s_addc_u32 s43, s15, 0
	v_mfma_f32_16x16x32_bf16 v[44:47], v[184:187], v[164:167], v[44:47]
	v_mfma_f32_16x16x32_bf16 v[40:43], v[188:191], v[164:167], v[40:43]
	v_mfma_f32_16x16x32_bf16 v[36:39], v[192:195], v[164:167], v[36:39]
	v_mfma_f32_16x16x32_bf16 v[32:35], v[196:199], v[164:167], v[32:35]
	ds_read_b128 v[164:167], v218 offset:18432
	global_load_lds_dwordx4 v216, s[42:43]
	s_add_i32 m0, s44, 0x14000
	s_add_u32 s42, s14, 0x160000
	s_addc_u32 s43, s15, 0
	v_mfma_f32_16x16x32_bf16 v[28:31], v[184:187], v[176:179], v[28:31]
	v_mfma_f32_16x16x32_bf16 v[24:27], v[188:191], v[176:179], v[24:27]
	v_mfma_f32_16x16x32_bf16 v[20:23], v[192:195], v[176:179], v[20:23]
	v_mfma_f32_16x16x32_bf16 v[16:19], v[196:199], v[176:179], v[16:19]
	ds_read_b128 v[176:179], v218 offset:20480
	global_load_lds_dwordx4 v216, s[42:43]
	s_add_i32 m0, s44, 0x16000
	s_add_u32 s42, s14, 0x210000
	s_addc_u32 s43, s15, 0
	v_mfma_f32_16x16x32_bf16 v[12:15], v[184:187], v[180:183], v[12:15]
	v_mfma_f32_16x16x32_bf16 v[8:11], v[188:191], v[180:183], v[8:11]
	v_mfma_f32_16x16x32_bf16 v[4:7], v[192:195], v[180:183], v[4:7]
	v_mfma_f32_16x16x32_bf16 v[0:3], v[196:199], v[180:183], v[0:3]
	ds_read_b128 v[180:183], v218 offset:22528
	global_load_lds_dwordx4 v216, s[42:43]
	s_waitcnt lgkmcnt(6)
	s_add_i32 m0, s44, 0x0
	v_mfma_f32_16x16x32_bf16 v[124:127], v[200:203], v[136:139], v[124:127]
	v_mfma_f32_16x16x32_bf16 v[120:123], v[204:207], v[136:139], v[120:123]
	v_mfma_f32_16x16x32_bf16 v[116:119], v[208:211], v[136:139], v[116:119]
	v_mfma_f32_16x16x32_bf16 v[112:115], v[212:215], v[136:139], v[112:115]
	global_load_lds_dwordx4 v145, s[0:1]
	s_add_i32 m0, s44, 0x2000
	s_add_u32 s42, s0, 0xb0000
	s_addc_u32 s43, s1, 0
	v_mfma_f32_16x16x32_bf16 v[108:111], v[200:203], v[146:149], v[108:111]
	v_mfma_f32_16x16x32_bf16 v[104:107], v[204:207], v[146:149], v[104:107]
	v_mfma_f32_16x16x32_bf16 v[100:103], v[208:211], v[146:149], v[100:103]
	v_mfma_f32_16x16x32_bf16 v[96:99], v[212:215], v[146:149], v[96:99]
	global_load_lds_dwordx4 v145, s[42:43]
	s_waitcnt lgkmcnt(0)
	s_waitcnt vmcnt(6)
	s_barrier
	ds_read_b128 v[136:139], v217 offset:32768
	ds_read_b128 v[146:149], v217 offset:34816
	ds_read_b128 v[184:187], v219 offset:32768
	ds_read_b128 v[188:191], v219 offset:34816
	ds_read_b128 v[192:195], v219 offset:49152
	ds_read_b128 v[196:199], v219 offset:51200
	s_add_i32 m0, s44, 0x4000
	s_add_u32 s42, s0, 0x160000
	s_addc_u32 s43, s1, 0
	v_mfma_f32_16x16x32_bf16 v[92:95], v[200:203], v[150:153], v[92:95]
	v_mfma_f32_16x16x32_bf16 v[88:91], v[204:207], v[150:153], v[88:91]
	v_mfma_f32_16x16x32_bf16 v[84:87], v[208:211], v[150:153], v[84:87]
	v_mfma_f32_16x16x32_bf16 v[80:83], v[212:215], v[150:153], v[80:83]
	ds_read_b128 v[150:153], v217 offset:36864
	global_load_lds_dwordx4 v145, s[42:43]
	s_add_i32 m0, s44, 0x6000
	s_add_u32 s42, s0, 0x210000
	s_addc_u32 s43, s1, 0
	v_mfma_f32_16x16x32_bf16 v[76:79], v[200:203], v[154:157], v[76:79]
	v_mfma_f32_16x16x32_bf16 v[72:75], v[204:207], v[154:157], v[72:75]
	v_mfma_f32_16x16x32_bf16 v[68:71], v[208:211], v[154:157], v[68:71]
	v_mfma_f32_16x16x32_bf16 v[64:67], v[212:215], v[154:157], v[64:67]
	ds_read_b128 v[154:157], v217 offset:38912
	global_load_lds_dwordx4 v145, s[42:43]
	v_mfma_f32_16x16x32_bf16 v[60:63], v[200:203], v[158:161], v[60:63]
	v_mfma_f32_16x16x32_bf16 v[56:59], v[204:207], v[158:161], v[56:59]
	v_mfma_f32_16x16x32_bf16 v[52:55], v[208:211], v[158:161], v[52:55]
	v_mfma_f32_16x16x32_bf16 v[48:51], v[212:215], v[158:161], v[48:51]
	ds_read_b128 v[158:161], v217 offset:49152
	v_mfma_f32_16x16x32_bf16 v[44:47], v[200:203], v[164:167], v[44:47]
	v_mfma_f32_16x16x32_bf16 v[40:43], v[204:207], v[164:167], v[40:43]
	v_mfma_f32_16x16x32_bf16 v[36:39], v[208:211], v[164:167], v[36:39]
	v_mfma_f32_16x16x32_bf16 v[32:35], v[212:215], v[164:167], v[32:35]
	ds_read_b128 v[164:167], v217 offset:51200
	v_mfma_f32_16x16x32_bf16 v[28:31], v[200:203], v[176:179], v[28:31]
	v_mfma_f32_16x16x32_bf16 v[24:27], v[204:207], v[176:179], v[24:27]
	v_mfma_f32_16x16x32_bf16 v[20:23], v[208:211], v[176:179], v[20:23]
	v_mfma_f32_16x16x32_bf16 v[16:19], v[212:215], v[176:179], v[16:19]
	ds_read_b128 v[176:179], v217 offset:53248
	v_mfma_f32_16x16x32_bf16 v[12:15], v[200:203], v[180:183], v[12:15]
	v_mfma_f32_16x16x32_bf16 v[8:11], v[204:207], v[180:183], v[8:11]
	v_mfma_f32_16x16x32_bf16 v[4:7], v[208:211], v[180:183], v[4:7]
	v_mfma_f32_16x16x32_bf16 v[0:3], v[212:215], v[180:183], v[0:3]
	ds_read_b128 v[180:183], v217 offset:55296
	s_add_u32 s0, s0, 128
	s_addc_u32 s1, s1, 0
	s_add_u32 s14, s14, 128
	s_addc_u32 s15, s15, 0
	s_waitcnt lgkmcnt(6)
	v_mfma_f32_16x16x32_bf16 v[124:127], v[184:187], v[136:139], v[124:127]
	v_mfma_f32_16x16x32_bf16 v[120:123], v[188:191], v[136:139], v[120:123]
	v_mfma_f32_16x16x32_bf16 v[116:119], v[192:195], v[136:139], v[116:119]
	v_mfma_f32_16x16x32_bf16 v[112:115], v[196:199], v[136:139], v[112:115]
	v_mfma_f32_16x16x32_bf16 v[108:111], v[184:187], v[146:149], v[108:111]
	v_mfma_f32_16x16x32_bf16 v[104:107], v[188:191], v[146:149], v[104:107]
	v_mfma_f32_16x16x32_bf16 v[100:103], v[192:195], v[146:149], v[100:103]
	v_mfma_f32_16x16x32_bf16 v[96:99], v[196:199], v[146:149], v[96:99]
	s_waitcnt lgkmcnt(0)
	ds_read_b128 v[136:139], v218 offset:32768
	ds_read_b128 v[146:149], v218 offset:34816
	ds_read_b128 v[200:203], v220 offset:32768
	ds_read_b128 v[204:207], v220 offset:34816
	ds_read_b128 v[208:211], v220 offset:49152
	ds_read_b128 v[212:215], v220 offset:51200
	v_mfma_f32_16x16x32_bf16 v[92:95], v[184:187], v[150:153], v[92:95]
	v_mfma_f32_16x16x32_bf16 v[88:91], v[188:191], v[150:153], v[88:91]
	v_mfma_f32_16x16x32_bf16 v[84:87], v[192:195], v[150:153], v[84:87]
	v_mfma_f32_16x16x32_bf16 v[80:83], v[196:199], v[150:153], v[80:83]
	ds_read_b128 v[150:153], v218 offset:36864
	v_mfma_f32_16x16x32_bf16 v[76:79], v[184:187], v[154:157], v[76:79]
	v_mfma_f32_16x16x32_bf16 v[72:75], v[188:191], v[154:157], v[72:75]
	v_mfma_f32_16x16x32_bf16 v[68:71], v[192:195], v[154:157], v[68:71]
	v_mfma_f32_16x16x32_bf16 v[64:67], v[196:199], v[154:157], v[64:67]
	ds_read_b128 v[154:157], v218 offset:38912
	s_waitcnt lgkmcnt(0)
	s_barrier
	s_add_i32 m0, s44, 0x18000
	v_mfma_f32_16x16x32_bf16 v[60:63], v[184:187], v[158:161], v[60:63]
	v_mfma_f32_16x16x32_bf16 v[56:59], v[188:191], v[158:161], v[56:59]
	v_mfma_f32_16x16x32_bf16 v[52:55], v[192:195], v[158:161], v[52:55]
	v_mfma_f32_16x16x32_bf16 v[48:51], v[196:199], v[158:161], v[48:51]
	ds_read_b128 v[158:161], v218 offset:49152
	global_load_lds_dwordx4 v216, s[14:15]
	s_add_i32 m0, s44, 0x1a000
	s_add_u32 s42, s14, 0xb0000
	s_addc_u32 s43, s15, 0
	v_mfma_f32_16x16x32_bf16 v[44:47], v[184:187], v[164:167], v[44:47]
	v_mfma_f32_16x16x32_bf16 v[40:43], v[188:191], v[164:167], v[40:43]
	v_mfma_f32_16x16x32_bf16 v[36:39], v[192:195], v[164:167], v[36:39]
	v_mfma_f32_16x16x32_bf16 v[32:35], v[196:199], v[164:167], v[32:35]
	ds_read_b128 v[164:167], v218 offset:51200
	global_load_lds_dwordx4 v216, s[42:43]
	s_add_i32 m0, s44, 0x1c000
	s_add_u32 s42, s14, 0x160000
	s_addc_u32 s43, s15, 0
	v_mfma_f32_16x16x32_bf16 v[28:31], v[184:187], v[176:179], v[28:31]
	v_mfma_f32_16x16x32_bf16 v[24:27], v[188:191], v[176:179], v[24:27]
	v_mfma_f32_16x16x32_bf16 v[20:23], v[192:195], v[176:179], v[20:23]
	v_mfma_f32_16x16x32_bf16 v[16:19], v[196:199], v[176:179], v[16:19]
	ds_read_b128 v[176:179], v218 offset:53248
	global_load_lds_dwordx4 v216, s[42:43]
	s_add_i32 m0, s44, 0x1e000
	s_add_u32 s42, s14, 0x210000
	s_addc_u32 s43, s15, 0
	v_mfma_f32_16x16x32_bf16 v[12:15], v[184:187], v[180:183], v[12:15]
	v_mfma_f32_16x16x32_bf16 v[8:11], v[188:191], v[180:183], v[8:11]
	v_mfma_f32_16x16x32_bf16 v[4:7], v[192:195], v[180:183], v[4:7]
	v_mfma_f32_16x16x32_bf16 v[0:3], v[196:199], v[180:183], v[0:3]
	ds_read_b128 v[180:183], v218 offset:55296
	global_load_lds_dwordx4 v216, s[42:43]
	s_waitcnt lgkmcnt(6)
	s_add_i32 m0, s44, 0x8000
	v_mfma_f32_16x16x32_bf16 v[124:127], v[200:203], v[136:139], v[124:127]
	v_mfma_f32_16x16x32_bf16 v[120:123], v[204:207], v[136:139], v[120:123]
	v_mfma_f32_16x16x32_bf16 v[116:119], v[208:211], v[136:139], v[116:119]
	v_mfma_f32_16x16x32_bf16 v[112:115], v[212:215], v[136:139], v[112:115]
	global_load_lds_dwordx4 v145, s[0:1]
	s_add_i32 m0, s44, 0xa000
	s_add_u32 s42, s0, 0xb0000
	s_addc_u32 s43, s1, 0
	v_mfma_f32_16x16x32_bf16 v[108:111], v[200:203], v[146:149], v[108:111]
	v_mfma_f32_16x16x32_bf16 v[104:107], v[204:207], v[146:149], v[104:107]
	v_mfma_f32_16x16x32_bf16 v[100:103], v[208:211], v[146:149], v[100:103]
	v_mfma_f32_16x16x32_bf16 v[96:99], v[212:215], v[146:149], v[96:99]
	global_load_lds_dwordx4 v145, s[42:43]
	s_waitcnt lgkmcnt(0)
	s_waitcnt vmcnt(6)
	s_barrier
	ds_read_b128 v[136:139], v217
	ds_read_b128 v[146:149], v217 offset:2048
	ds_read_b128 v[184:187], v219
	ds_read_b128 v[188:191], v219 offset:2048
	ds_read_b128 v[192:195], v219 offset:16384
	ds_read_b128 v[196:199], v219 offset:18432
	s_add_i32 m0, s44, 0xc000
	s_add_u32 s42, s0, 0x160000
	s_addc_u32 s43, s1, 0
	v_mfma_f32_16x16x32_bf16 v[92:95], v[200:203], v[150:153], v[92:95]
	v_mfma_f32_16x16x32_bf16 v[88:91], v[204:207], v[150:153], v[88:91]
	v_mfma_f32_16x16x32_bf16 v[84:87], v[208:211], v[150:153], v[84:87]
	v_mfma_f32_16x16x32_bf16 v[80:83], v[212:215], v[150:153], v[80:83]
	ds_read_b128 v[150:153], v217 offset:4096
	global_load_lds_dwordx4 v145, s[42:43]
	s_add_i32 m0, s44, 0xe000
	s_add_u32 s42, s0, 0x210000
	s_addc_u32 s43, s1, 0
	v_mfma_f32_16x16x32_bf16 v[76:79], v[200:203], v[154:157], v[76:79]
	v_mfma_f32_16x16x32_bf16 v[72:75], v[204:207], v[154:157], v[72:75]
	v_mfma_f32_16x16x32_bf16 v[68:71], v[208:211], v[154:157], v[68:71]
	v_mfma_f32_16x16x32_bf16 v[64:67], v[212:215], v[154:157], v[64:67]
	ds_read_b128 v[154:157], v217 offset:6144
	global_load_lds_dwordx4 v145, s[42:43]
	v_mfma_f32_16x16x32_bf16 v[60:63], v[200:203], v[158:161], v[60:63]
	v_mfma_f32_16x16x32_bf16 v[56:59], v[204:207], v[158:161], v[56:59]
	v_mfma_f32_16x16x32_bf16 v[52:55], v[208:211], v[158:161], v[52:55]
	v_mfma_f32_16x16x32_bf16 v[48:51], v[212:215], v[158:161], v[48:51]
	ds_read_b128 v[158:161], v217 offset:16384
	v_mfma_f32_16x16x32_bf16 v[44:47], v[200:203], v[164:167], v[44:47]
	v_mfma_f32_16x16x32_bf16 v[40:43], v[204:207], v[164:167], v[40:43]
	v_mfma_f32_16x16x32_bf16 v[36:39], v[208:211], v[164:167], v[36:39]
	v_mfma_f32_16x16x32_bf16 v[32:35], v[212:215], v[164:167], v[32:35]
	ds_read_b128 v[164:167], v217 offset:18432
	v_mfma_f32_16x16x32_bf16 v[28:31], v[200:203], v[176:179], v[28:31]
	v_mfma_f32_16x16x32_bf16 v[24:27], v[204:207], v[176:179], v[24:27]
	v_mfma_f32_16x16x32_bf16 v[20:23], v[208:211], v[176:179], v[20:23]
	v_mfma_f32_16x16x32_bf16 v[16:19], v[212:215], v[176:179], v[16:19]
	ds_read_b128 v[176:179], v217 offset:20480
	v_mfma_f32_16x16x32_bf16 v[12:15], v[200:203], v[180:183], v[12:15]
	v_mfma_f32_16x16x32_bf16 v[8:11], v[204:207], v[180:183], v[8:11]
	v_mfma_f32_16x16x32_bf16 v[4:7], v[208:211], v[180:183], v[4:7]
	v_mfma_f32_16x16x32_bf16 v[0:3], v[212:215], v[180:183], v[0:3]
	ds_read_b128 v[180:183], v217 offset:22528
	s_add_u32 s0, s0, 128
	s_addc_u32 s1, s1, 0
	s_add_u32 s14, s14, 128
	s_addc_u32 s15, s15, 0
	s_add_i32 s39, s39, 1
	s_cmp_lt_u32 s39, 44
	s_cbranch_scc1 .Ls9_loop
	s_waitcnt lgkmcnt(0)
	s_nop 7
	s_nop 3
	v_lshl_add_u32 v217, s38, 8, v163
	v_add_u32_e32 v217, s26, v217
	v_lshlrev_b32_e32 v208, 2, v217
	v_lshl_add_u32 v214, v225, 3, s27
	v_lshl_add_u32 v214, s37, 8, v214
	v_lshl_add_u32 v209, v217, 11, v214
	v_lshlrev_b32_e32 v209, 1, v209
	v_lshlrev_b32_e32 v210, 1, v209
	v_lshl_add_u32 v217, v225, 4, v163
	v_xor_b32_e32 v215, 16, v217
	v_lshlrev_b32_e32 v215, 2, v215
	v_xor_b32_e32 v216, 32, v217
	v_lshlrev_b32_e32 v216, 2, v216
	v_add_u32_e32 v211, 0x0, v209
	global_load_dwordx4 v[176:179], v211, s[80:81]
	global_load_dwordx4 v[180:183], v211, s[80:81] offset:256
	v_add_u32_e32 v211, 0x10000, v209
	global_load_dwordx4 v[192:195], v211, s[80:81]
	global_load_dwordx4 v[196:199], v211, s[80:81] offset:256
	s_waitcnt vmcnt(2)
	v_lshlrev_b32_e32 v184, 16, v176
	v_and_b32_e32 v185, 0xffff0000, v176
	v_lshlrev_b32_e32 v186, 16, v177
	v_and_b32_e32 v187, 0xffff0000, v177
	v_lshlrev_b32_e32 v188, 16, v178
	v_and_b32_e32 v189, 0xffff0000, v178
	v_lshlrev_b32_e32 v190, 16, v179
	v_and_b32_e32 v191, 0xffff0000, v179
	v_pk_add_f32 v[124:125], v[124:125], v[184:185]
	v_pk_add_f32 v[126:127], v[126:127], v[186:187]
	v_pk_add_f32 v[120:121], v[120:121], v[188:189]
	v_pk_add_f32 v[122:123], v[122:123], v[190:191]
	v_mul_f32_e32 v213, v124, v124
	v_fmac_f32_e32 v213, v125, v125
	v_fmac_f32_e32 v213, v126, v126
	v_fmac_f32_e32 v213, v127, v127
	v_fmac_f32_e32 v213, v120, v120
	v_fmac_f32_e32 v213, v121, v121
	v_fmac_f32_e32 v213, v122, v122
	v_fmac_f32_e32 v213, v123, v123
	v_add_u32_e32 v212, 0x0, v210
	global_store_dwordx4 v212, v[124:127], s[90:91]
	global_store_dwordx4 v212, v[120:123], s[90:91] offset:16
	v_lshlrev_b32_e32 v184, 16, v180
	v_and_b32_e32 v185, 0xffff0000, v180
	v_lshlrev_b32_e32 v186, 16, v181
	v_and_b32_e32 v187, 0xffff0000, v181
	v_lshlrev_b32_e32 v188, 16, v182
	v_and_b32_e32 v189, 0xffff0000, v182
	v_lshlrev_b32_e32 v190, 16, v183
	v_and_b32_e32 v191, 0xffff0000, v183
	v_pk_add_f32 v[116:117], v[116:117], v[184:185]
	v_pk_add_f32 v[118:119], v[118:119], v[186:187]
	v_pk_add_f32 v[112:113], v[112:113], v[188:189]
	v_pk_add_f32 v[114:115], v[114:115], v[190:191]
	v_fmac_f32_e32 v213, v116, v116
	v_fmac_f32_e32 v213, v117, v117
	v_fmac_f32_e32 v213, v118, v118
	v_fmac_f32_e32 v213, v119, v119
	v_fmac_f32_e32 v213, v112, v112
	v_fmac_f32_e32 v213, v113, v113
	v_fmac_f32_e32 v213, v114, v114
	v_fmac_f32_e32 v213, v115, v115
	global_store_dwordx4 v212, v[116:119], s[90:91] offset:512
	global_store_dwordx4 v212, v[112:115], s[90:91] offset:528
	ds_bpermute_b32 v214, v215, v213
	s_waitcnt lgkmcnt(0)
	v_add_f32_e32 v213, v213, v214
	ds_bpermute_b32 v214, v216, v213
	s_waitcnt lgkmcnt(0)
	v_add_f32_e32 v213, v213, v214
	s_mov_b64 exec, 0xffff
	global_atomic_add_f32 v208, v213, s[10:11]
	s_mov_b64 exec, -1
	v_add_u32_e32 v211, 0x20000, v209
	global_load_dwordx4 v[176:179], v211, s[80:81]
	global_load_dwordx4 v[180:183], v211, s[80:81] offset:256
	s_waitcnt vmcnt(7)
	v_lshlrev_b32_e32 v200, 16, v192
	v_and_b32_e32 v201, 0xffff0000, v192
	v_lshlrev_b32_e32 v202, 16, v193
	v_and_b32_e32 v203, 0xffff0000, v193
	v_lshlrev_b32_e32 v204, 16, v194
	v_and_b32_e32 v205, 0xffff0000, v194
	v_lshlrev_b32_e32 v206, 16, v195
	v_and_b32_e32 v207, 0xffff0000, v195
	v_pk_add_f32 v[108:109], v[108:109], v[200:201]
	v_pk_add_f32 v[110:111], v[110:111], v[202:203]
	v_pk_add_f32 v[104:105], v[104:105], v[204:205]
	v_pk_add_f32 v[106:107], v[106:107], v[206:207]
	v_mul_f32_e32 v213, v108, v108
	v_fmac_f32_e32 v213, v109, v109
	v_fmac_f32_e32 v213, v110, v110
	v_fmac_f32_e32 v213, v111, v111
	v_fmac_f32_e32 v213, v104, v104
	v_fmac_f32_e32 v213, v105, v105
	v_fmac_f32_e32 v213, v106, v106
	v_fmac_f32_e32 v213, v107, v107
	v_add_u32_e32 v212, 0x20000, v210
	global_store_dwordx4 v212, v[108:111], s[90:91]
	global_store_dwordx4 v212, v[104:107], s[90:91] offset:16
	v_lshlrev_b32_e32 v200, 16, v196
	v_and_b32_e32 v201, 0xffff0000, v196
	v_lshlrev_b32_e32 v202, 16, v197
	v_and_b32_e32 v203, 0xffff0000, v197
	v_lshlrev_b32_e32 v204, 16, v198
	v_and_b32_e32 v205, 0xffff0000, v198
	v_lshlrev_b32_e32 v206, 16, v199
	v_and_b32_e32 v207, 0xffff0000, v199
	v_pk_add_f32 v[100:101], v[100:101], v[200:201]
	v_pk_add_f32 v[102:103], v[102:103], v[202:203]
	v_pk_add_f32 v[96:97], v[96:97], v[204:205]
	v_pk_add_f32 v[98:99], v[98:99], v[206:207]
	v_fmac_f32_e32 v213, v100, v100
	v_fmac_f32_e32 v213, v101, v101
	v_fmac_f32_e32 v213, v102, v102
	v_fmac_f32_e32 v213, v103, v103
	v_fmac_f32_e32 v213, v96, v96
	v_fmac_f32_e32 v213, v97, v97
	v_fmac_f32_e32 v213, v98, v98
	v_fmac_f32_e32 v213, v99, v99
	global_store_dwordx4 v212, v[100:103], s[90:91] offset:512
	global_store_dwordx4 v212, v[96:99], s[90:91] offset:528
	ds_bpermute_b32 v214, v215, v213
	s_waitcnt lgkmcnt(0)
	v_add_f32_e32 v213, v213, v214
	ds_bpermute_b32 v214, v216, v213
	s_waitcnt lgkmcnt(0)
	v_add_f32_e32 v213, v213, v214
	s_mov_b64 exec, 0xffff
	global_atomic_add_f32 v208, v213, s[10:11] offset:64
	s_mov_b64 exec, -1
	v_add_u32_e32 v211, 0x30000, v209
	global_load_dwordx4 v[192:195], v211, s[80:81]
	global_load_dwordx4 v[196:199], v211, s[80:81] offset:256
	s_waitcnt vmcnt(7)
	v_lshlrev_b32_e32 v184, 16, v176
	v_and_b32_e32 v185, 0xffff0000, v176
	v_lshlrev_b32_e32 v186, 16, v177
	v_and_b32_e32 v187, 0xffff0000, v177
	v_lshlrev_b32_e32 v188, 16, v178
	v_and_b32_e32 v189, 0xffff0000, v178
	v_lshlrev_b32_e32 v190, 16, v179
	v_and_b32_e32 v191, 0xffff0000, v179
	v_pk_add_f32 v[92:93], v[92:93], v[184:185]
	v_pk_add_f32 v[94:95], v[94:95], v[186:187]
	v_pk_add_f32 v[88:89], v[88:89], v[188:189]
	v_pk_add_f32 v[90:91], v[90:91], v[190:191]
	v_mul_f32_e32 v213, v92, v92
	v_fmac_f32_e32 v213, v93, v93
	v_fmac_f32_e32 v213, v94, v94
	v_fmac_f32_e32 v213, v95, v95
	v_fmac_f32_e32 v213, v88, v88
	v_fmac_f32_e32 v213, v89, v89
	v_fmac_f32_e32 v213, v90, v90
	v_fmac_f32_e32 v213, v91, v91
	v_add_u32_e32 v212, 0x40000, v210
	global_store_dwordx4 v212, v[92:95], s[90:91]
	global_store_dwordx4 v212, v[88:91], s[90:91] offset:16
	v_lshlrev_b32_e32 v184, 16, v180
	v_and_b32_e32 v185, 0xffff0000, v180
	v_lshlrev_b32_e32 v186, 16, v181
	v_and_b32_e32 v187, 0xffff0000, v181
	v_lshlrev_b32_e32 v188, 16, v182
	v_and_b32_e32 v189, 0xffff0000, v182
	v_lshlrev_b32_e32 v190, 16, v183
	v_and_b32_e32 v191, 0xffff0000, v183
	v_pk_add_f32 v[84:85], v[84:85], v[184:185]
	v_pk_add_f32 v[86:87], v[86:87], v[186:187]
	v_pk_add_f32 v[80:81], v[80:81], v[188:189]
	v_pk_add_f32 v[82:83], v[82:83], v[190:191]
	v_fmac_f32_e32 v213, v84, v84
	v_fmac_f32_e32 v213, v85, v85
	v_fmac_f32_e32 v213, v86, v86
	v_fmac_f32_e32 v213, v87, v87
	v_fmac_f32_e32 v213, v80, v80
	v_fmac_f32_e32 v213, v81, v81
	v_fmac_f32_e32 v213, v82, v82
	v_fmac_f32_e32 v213, v83, v83
	global_store_dwordx4 v212, v[84:87], s[90:91] offset:512
	global_store_dwordx4 v212, v[80:83], s[90:91] offset:528
	ds_bpermute_b32 v214, v215, v213
	s_waitcnt lgkmcnt(0)
	v_add_f32_e32 v213, v213, v214
	ds_bpermute_b32 v214, v216, v213
	s_waitcnt lgkmcnt(0)
	v_add_f32_e32 v213, v213, v214
	s_mov_b64 exec, 0xffff
	global_atomic_add_f32 v208, v213, s[10:11] offset:128
	s_mov_b64 exec, -1
	v_add_u32_e32 v211, 0x80000, v209
	global_load_dwordx4 v[176:179], v211, s[80:81]
	global_load_dwordx4 v[180:183], v211, s[80:81] offset:256
	s_waitcnt vmcnt(7)
	v_lshlrev_b32_e32 v200, 16, v192
	v_and_b32_e32 v201, 0xffff0000, v192
	v_lshlrev_b32_e32 v202, 16, v193
	v_and_b32_e32 v203, 0xffff0000, v193
	v_lshlrev_b32_e32 v204, 16, v194
	v_and_b32_e32 v205, 0xffff0000, v194
	v_lshlrev_b32_e32 v206, 16, v195
	v_and_b32_e32 v207, 0xffff0000, v195
	v_pk_add_f32 v[76:77], v[76:77], v[200:201]
	v_pk_add_f32 v[78:79], v[78:79], v[202:203]
	v_pk_add_f32 v[72:73], v[72:73], v[204:205]
	v_pk_add_f32 v[74:75], v[74:75], v[206:207]
	v_mul_f32_e32 v213, v76, v76
	v_fmac_f32_e32 v213, v77, v77
	v_fmac_f32_e32 v213, v78, v78
	v_fmac_f32_e32 v213, v79, v79
	v_fmac_f32_e32 v213, v72, v72
	v_fmac_f32_e32 v213, v73, v73
	v_fmac_f32_e32 v213, v74, v74
	v_fmac_f32_e32 v213, v75, v75
	v_add_u32_e32 v212, 0x60000, v210
	global_store_dwordx4 v212, v[76:79], s[90:91]
	global_store_dwordx4 v212, v[72:75], s[90:91] offset:16
	v_lshlrev_b32_e32 v200, 16, v196
	v_and_b32_e32 v201, 0xffff0000, v196
	v_lshlrev_b32_e32 v202, 16, v197
	v_and_b32_e32 v203, 0xffff0000, v197
	v_lshlrev_b32_e32 v204, 16, v198
	v_and_b32_e32 v205, 0xffff0000, v198
	v_lshlrev_b32_e32 v206, 16, v199
	v_and_b32_e32 v207, 0xffff0000, v199
	v_pk_add_f32 v[68:69], v[68:69], v[200:201]
	v_pk_add_f32 v[70:71], v[70:71], v[202:203]
	v_pk_add_f32 v[64:65], v[64:65], v[204:205]
	v_pk_add_f32 v[66:67], v[66:67], v[206:207]
	v_fmac_f32_e32 v213, v68, v68
	v_fmac_f32_e32 v213, v69, v69
	v_fmac_f32_e32 v213, v70, v70
	v_fmac_f32_e32 v213, v71, v71
	v_fmac_f32_e32 v213, v64, v64
	v_fmac_f32_e32 v213, v65, v65
	v_fmac_f32_e32 v213, v66, v66
	v_fmac_f32_e32 v213, v67, v67
	global_store_dwordx4 v212, v[68:71], s[90:91] offset:512
	global_store_dwordx4 v212, v[64:67], s[90:91] offset:528
	ds_bpermute_b32 v214, v215, v213
	s_waitcnt lgkmcnt(0)
	v_add_f32_e32 v213, v213, v214
	ds_bpermute_b32 v214, v216, v213
	s_waitcnt lgkmcnt(0)
	v_add_f32_e32 v213, v213, v214
	s_mov_b64 exec, 0xffff
	global_atomic_add_f32 v208, v213, s[10:11] offset:192
	s_mov_b64 exec, -1
	v_add_u32_e32 v211, 0x90000, v209
	global_load_dwordx4 v[192:195], v211, s[80:81]
	global_load_dwordx4 v[196:199], v211, s[80:81] offset:256
	s_waitcnt vmcnt(7)
	v_lshlrev_b32_e32 v184, 16, v176
	v_and_b32_e32 v185, 0xffff0000, v176
	v_lshlrev_b32_e32 v186, 16, v177
	v_and_b32_e32 v187, 0xffff0000, v177
	v_lshlrev_b32_e32 v188, 16, v178
	v_and_b32_e32 v189, 0xffff0000, v178
	v_lshlrev_b32_e32 v190, 16, v179
	v_and_b32_e32 v191, 0xffff0000, v179
	v_pk_add_f32 v[60:61], v[60:61], v[184:185]
	v_pk_add_f32 v[62:63], v[62:63], v[186:187]
	v_pk_add_f32 v[56:57], v[56:57], v[188:189]
	v_pk_add_f32 v[58:59], v[58:59], v[190:191]
	v_mul_f32_e32 v213, v60, v60
	v_fmac_f32_e32 v213, v61, v61
	v_fmac_f32_e32 v213, v62, v62
	v_fmac_f32_e32 v213, v63, v63
	v_fmac_f32_e32 v213, v56, v56
	v_fmac_f32_e32 v213, v57, v57
	v_fmac_f32_e32 v213, v58, v58
	v_fmac_f32_e32 v213, v59, v59
	v_add_u32_e32 v212, 0x100000, v210
	global_store_dwordx4 v212, v[60:63], s[90:91]
	global_store_dwordx4 v212, v[56:59], s[90:91] offset:16
	v_lshlrev_b32_e32 v184, 16, v180
	v_and_b32_e32 v185, 0xffff0000, v180
	v_lshlrev_b32_e32 v186, 16, v181
	v_and_b32_e32 v187, 0xffff0000, v181
	v_lshlrev_b32_e32 v188, 16, v182
	v_and_b32_e32 v189, 0xffff0000, v182
	v_lshlrev_b32_e32 v190, 16, v183
	v_and_b32_e32 v191, 0xffff0000, v183
	v_pk_add_f32 v[52:53], v[52:53], v[184:185]
	v_pk_add_f32 v[54:55], v[54:55], v[186:187]
	v_pk_add_f32 v[48:49], v[48:49], v[188:189]
	v_pk_add_f32 v[50:51], v[50:51], v[190:191]
	v_fmac_f32_e32 v213, v52, v52
	v_fmac_f32_e32 v213, v53, v53
	v_fmac_f32_e32 v213, v54, v54
	v_fmac_f32_e32 v213, v55, v55
	v_fmac_f32_e32 v213, v48, v48
	v_fmac_f32_e32 v213, v49, v49
	v_fmac_f32_e32 v213, v50, v50
	v_fmac_f32_e32 v213, v51, v51
	global_store_dwordx4 v212, v[52:55], s[90:91] offset:512
	global_store_dwordx4 v212, v[48:51], s[90:91] offset:528
	ds_bpermute_b32 v214, v215, v213
	s_waitcnt lgkmcnt(0)
	v_add_f32_e32 v213, v213, v214
	ds_bpermute_b32 v214, v216, v213
	s_waitcnt lgkmcnt(0)
	v_add_f32_e32 v213, v213, v214
	s_mov_b64 exec, 0xffff
	global_atomic_add_f32 v208, v213, s[10:11] offset:512
	s_mov_b64 exec, -1
	v_add_u32_e32 v211, 0xa0000, v209
	global_load_dwordx4 v[176:179], v211, s[80:81]
	global_load_dwordx4 v[180:183], v211, s[80:81] offset:256
	s_waitcnt vmcnt(7)
	v_lshlrev_b32_e32 v200, 16, v192
	v_and_b32_e32 v201, 0xffff0000, v192
	v_lshlrev_b32_e32 v202, 16, v193
	v_and_b32_e32 v203, 0xffff0000, v193
	v_lshlrev_b32_e32 v204, 16, v194
	v_and_b32_e32 v205, 0xffff0000, v194
	v_lshlrev_b32_e32 v206, 16, v195
	v_and_b32_e32 v207, 0xffff0000, v195
	v_pk_add_f32 v[44:45], v[44:45], v[200:201]
	v_pk_add_f32 v[46:47], v[46:47], v[202:203]
	v_pk_add_f32 v[40:41], v[40:41], v[204:205]
	v_pk_add_f32 v[42:43], v[42:43], v[206:207]
	v_mul_f32_e32 v213, v44, v44
	v_fmac_f32_e32 v213, v45, v45
	v_fmac_f32_e32 v213, v46, v46
	v_fmac_f32_e32 v213, v47, v47
	v_fmac_f32_e32 v213, v40, v40
	v_fmac_f32_e32 v213, v41, v41
	v_fmac_f32_e32 v213, v42, v42
	v_fmac_f32_e32 v213, v43, v43
	v_add_u32_e32 v212, 0x120000, v210
	global_store_dwordx4 v212, v[44:47], s[90:91]
	global_store_dwordx4 v212, v[40:43], s[90:91] offset:16
	v_lshlrev_b32_e32 v200, 16, v196
	v_and_b32_e32 v201, 0xffff0000, v196
	v_lshlrev_b32_e32 v202, 16, v197
	v_and_b32_e32 v203, 0xffff0000, v197
	v_lshlrev_b32_e32 v204, 16, v198
	v_and_b32_e32 v205, 0xffff0000, v198
	v_lshlrev_b32_e32 v206, 16, v199
	v_and_b32_e32 v207, 0xffff0000, v199
	v_pk_add_f32 v[36:37], v[36:37], v[200:201]
	v_pk_add_f32 v[38:39], v[38:39], v[202:203]
	v_pk_add_f32 v[32:33], v[32:33], v[204:205]
	v_pk_add_f32 v[34:35], v[34:35], v[206:207]
	v_fmac_f32_e32 v213, v36, v36
	v_fmac_f32_e32 v213, v37, v37
	v_fmac_f32_e32 v213, v38, v38
	v_fmac_f32_e32 v213, v39, v39
	v_fmac_f32_e32 v213, v32, v32
	v_fmac_f32_e32 v213, v33, v33
	v_fmac_f32_e32 v213, v34, v34
	v_fmac_f32_e32 v213, v35, v35
	global_store_dwordx4 v212, v[36:39], s[90:91] offset:512
	global_store_dwordx4 v212, v[32:35], s[90:91] offset:528
	ds_bpermute_b32 v214, v215, v213
	s_waitcnt lgkmcnt(0)
	v_add_f32_e32 v213, v213, v214
	ds_bpermute_b32 v214, v216, v213
	s_waitcnt lgkmcnt(0)
	v_add_f32_e32 v213, v213, v214
	s_mov_b64 exec, 0xffff
	global_atomic_add_f32 v208, v213, s[10:11] offset:576
	s_mov_b64 exec, -1
	v_add_u32_e32 v211, 0xb0000, v209
	global_load_dwordx4 v[192:195], v211, s[80:81]
	global_load_dwordx4 v[196:199], v211, s[80:81] offset:256
	s_waitcnt vmcnt(7)
	v_lshlrev_b32_e32 v184, 16, v176
	v_and_b32_e32 v185, 0xffff0000, v176
	v_lshlrev_b32_e32 v186, 16, v177
	v_and_b32_e32 v187, 0xffff0000, v177
	v_lshlrev_b32_e32 v188, 16, v178
	v_and_b32_e32 v189, 0xffff0000, v178
	v_lshlrev_b32_e32 v190, 16, v179
	v_and_b32_e32 v191, 0xffff0000, v179
	v_pk_add_f32 v[28:29], v[28:29], v[184:185]
	v_pk_add_f32 v[30:31], v[30:31], v[186:187]
	v_pk_add_f32 v[24:25], v[24:25], v[188:189]
	v_pk_add_f32 v[26:27], v[26:27], v[190:191]
	v_mul_f32_e32 v213, v28, v28
	v_fmac_f32_e32 v213, v29, v29
	v_fmac_f32_e32 v213, v30, v30
	v_fmac_f32_e32 v213, v31, v31
	v_fmac_f32_e32 v213, v24, v24
	v_fmac_f32_e32 v213, v25, v25
	v_fmac_f32_e32 v213, v26, v26
	v_fmac_f32_e32 v213, v27, v27
	v_add_u32_e32 v212, 0x140000, v210
	global_store_dwordx4 v212, v[28:31], s[90:91]
	global_store_dwordx4 v212, v[24:27], s[90:91] offset:16
	v_lshlrev_b32_e32 v184, 16, v180
	v_and_b32_e32 v185, 0xffff0000, v180
	v_lshlrev_b32_e32 v186, 16, v181
	v_and_b32_e32 v187, 0xffff0000, v181
	v_lshlrev_b32_e32 v188, 16, v182
	v_and_b32_e32 v189, 0xffff0000, v182
	v_lshlrev_b32_e32 v190, 16, v183
	v_and_b32_e32 v191, 0xffff0000, v183
	v_pk_add_f32 v[20:21], v[20:21], v[184:185]
	v_pk_add_f32 v[22:23], v[22:23], v[186:187]
	v_pk_add_f32 v[16:17], v[16:17], v[188:189]
	v_pk_add_f32 v[18:19], v[18:19], v[190:191]
	v_fmac_f32_e32 v213, v20, v20
	v_fmac_f32_e32 v213, v21, v21
	v_fmac_f32_e32 v213, v22, v22
	v_fmac_f32_e32 v213, v23, v23
	v_fmac_f32_e32 v213, v16, v16
	v_fmac_f32_e32 v213, v17, v17
	v_fmac_f32_e32 v213, v18, v18
	v_fmac_f32_e32 v213, v19, v19
	global_store_dwordx4 v212, v[20:23], s[90:91] offset:512
	global_store_dwordx4 v212, v[16:19], s[90:91] offset:528
	ds_bpermute_b32 v214, v215, v213
	s_waitcnt lgkmcnt(0)
	v_add_f32_e32 v213, v213, v214
	ds_bpermute_b32 v214, v216, v213
	s_waitcnt lgkmcnt(0)
	v_add_f32_e32 v213, v213, v214
	s_mov_b64 exec, 0xffff
	global_atomic_add_f32 v208, v213, s[10:11] offset:640
	s_mov_b64 exec, -1
	s_waitcnt vmcnt(5)
	v_lshlrev_b32_e32 v200, 16, v192
	v_and_b32_e32 v201, 0xffff0000, v192
	v_lshlrev_b32_e32 v202, 16, v193
	v_and_b32_e32 v203, 0xffff0000, v193
	v_lshlrev_b32_e32 v204, 16, v194
	v_and_b32_e32 v205, 0xffff0000, v194
	v_lshlrev_b32_e32 v206, 16, v195
	v_and_b32_e32 v207, 0xffff0000, v195
	v_pk_add_f32 v[12:13], v[12:13], v[200:201]
	v_pk_add_f32 v[14:15], v[14:15], v[202:203]
	v_pk_add_f32 v[8:9], v[8:9], v[204:205]
	v_pk_add_f32 v[10:11], v[10:11], v[206:207]
	v_mul_f32_e32 v213, v12, v12
	v_fmac_f32_e32 v213, v13, v13
	v_fmac_f32_e32 v213, v14, v14
	v_fmac_f32_e32 v213, v15, v15
	v_fmac_f32_e32 v213, v8, v8
	v_fmac_f32_e32 v213, v9, v9
	v_fmac_f32_e32 v213, v10, v10
	v_fmac_f32_e32 v213, v11, v11
	v_add_u32_e32 v212, 0x160000, v210
	global_store_dwordx4 v212, v[12:15], s[90:91]
	global_store_dwordx4 v212, v[8:11], s[90:91] offset:16
	v_lshlrev_b32_e32 v200, 16, v196
	v_and_b32_e32 v201, 0xffff0000, v196
	v_lshlrev_b32_e32 v202, 16, v197
	v_and_b32_e32 v203, 0xffff0000, v197
	v_lshlrev_b32_e32 v204, 16, v198
	v_and_b32_e32 v205, 0xffff0000, v198
	v_lshlrev_b32_e32 v206, 16, v199
	v_and_b32_e32 v207, 0xffff0000, v199
	v_pk_add_f32 v[4:5], v[4:5], v[200:201]
	v_pk_add_f32 v[6:7], v[6:7], v[202:203]
	v_pk_add_f32 v[0:1], v[0:1], v[204:205]
	v_pk_add_f32 v[2:3], v[2:3], v[206:207]
	v_fmac_f32_e32 v213, v4, v4
	v_fmac_f32_e32 v213, v5, v5
	v_fmac_f32_e32 v213, v6, v6
	v_fmac_f32_e32 v213, v7, v7
	v_fmac_f32_e32 v213, v0, v0
	v_fmac_f32_e32 v213, v1, v1
	v_fmac_f32_e32 v213, v2, v2
	v_fmac_f32_e32 v213, v3, v3
	global_store_dwordx4 v212, v[4:7], s[90:91] offset:512
	global_store_dwordx4 v212, v[0:3], s[90:91] offset:528
	ds_bpermute_b32 v214, v215, v213
	s_waitcnt lgkmcnt(0)
	v_add_f32_e32 v213, v213, v214
	ds_bpermute_b32 v214, v216, v213
	s_waitcnt lgkmcnt(0)
	v_add_f32_e32 v213, v213, v214
	s_mov_b64 exec, 0xffff
	global_atomic_add_f32 v208, v213, s[10:11] offset:704
	s_mov_b64 exec, -1
	s_branch .LBB0_973

	.amdhsa_kernel _Z14fwd_megakernel6Params
		.amdhsa_group_segment_fixed_size 0
		.amdhsa_private_segment_fixed_size 0
		.amdhsa_kernarg_size 408
		.amdhsa_user_sgpr_count 2
		.amdhsa_user_sgpr_dispatch_ptr 0
		.amdhsa_user_sgpr_queue_ptr 0
		.amdhsa_user_sgpr_kernarg_segment_ptr 1
		.amdhsa_user_sgpr_dispatch_id 0
		.amdhsa_user_sgpr_kernarg_preload_length 0
		.amdhsa_user_sgpr_kernarg_preload_offset 0
		.amdhsa_user_sgpr_private_segment_size 0
		.amdhsa_uses_dynamic_stack 0
		.amdhsa_enable_private_segment 0
		.amdhsa_system_sgpr_workgroup_id_x 1
		.amdhsa_system_sgpr_workgroup_id_y 0
		.amdhsa_system_sgpr_workgroup_id_z 0
		.amdhsa_system_sgpr_workgroup_info 0
		.amdhsa_system_vgpr_workitem_id 2
		.amdhsa_next_free_vgpr 256
		.amdhsa_next_free_sgpr 102
		.amdhsa_accum_offset 256
		.amdhsa_reserve_vcc 1
		.amdhsa_float_round_mode_32 0
		.amdhsa_float_round_mode_16_64 0
		.amdhsa_float_denorm_mode_32 3
		.amdhsa_float_denorm_mode_16_64 3
		.amdhsa_dx10_clamp 1
		.amdhsa_ieee_mode 1
		.amdhsa_fp16_overflow 0
		.amdhsa_tg_split 0
		.amdhsa_exception_fp_ieee_invalid_op 0
		.amdhsa_exception_fp_denorm_src 0
		.amdhsa_exception_fp_ieee_div_zero 0
		.amdhsa_exception_fp_ieee_overflow 0
		.amdhsa_exception_fp_ieee_underflow 0
		.amdhsa_exception_fp_ieee_inexact 0
		.amdhsa_exception_int_div_zero 0
	.end_amdhsa_kernel

amdhsa.kernels:
  - .agpr_count:     0
    .args:
      - .offset:         0
        .size:           152
        .value_kind:     by_value
      - .offset:         152
        .size:           4
        .value_kind:     hidden_block_count_x
      - .offset:         156
        .size:           4
        .value_kind:     hidden_block_count_y
      - .offset:         160
        .size:           4
        .value_kind:     hidden_block_count_z
      - .offset:         164
        .size:           2
        .value_kind:     hidden_group_size_x
      - .offset:         166
        .size:           2
        .value_kind:     hidden_group_size_y
      - .offset:         168
        .size:           2
        .value_kind:     hidden_group_size_z
      - .offset:         170
        .size:           2
        .value_kind:     hidden_remainder_x
      - .offset:         172
        .size:           2
        .value_kind:     hidden_remainder_y
      - .offset:         174
        .size:           2
        .value_kind:     hidden_remainder_z
      - .offset:         192
        .size:           8
        .value_kind:     hidden_global_offset_x
      - .offset:         200
        .size:           8
        .value_kind:     hidden_global_offset_y
      - .offset:         208
        .size:           8
        .value_kind:     hidden_global_offset_z
      - .offset:         216
        .size:           2
        .value_kind:     hidden_grid_dims
      - .offset:         240
        .size:           8
        .value_kind:     hidden_multigrid_sync_arg
      - .offset:         272
        .size:           4
        .value_kind:     hidden_dynamic_lds_size
    .group_segment_fixed_size: 0
    .kernarg_segment_align: 8
    .kernarg_segment_size: 408
    .language:       OpenCL C
    .language_version:
      - 2
      - 0
    .max_flat_workgroup_size: 512
    .name:           _Z14fwd_megakernel6Params
    .private_segment_fixed_size: 0
    .sgpr_count:     108
    .sgpr_spill_count: 19
    .symbol:         _Z14fwd_megakernel6Params.kd
    .uniform_work_group_size: 1
    .uses_dynamic_stack: false
    .vgpr_count:     256
    .vgpr_spill_count: 0
    .wavefront_size: 64
